# MFMA segment handoff tightened: s_setprio 1 issued before the opening barrier, redundant post-barrier lgkmcnt(0) dropped, s_setprio 0 moved after the closing barrier
# speedup vs baseline: 1.0089x; 1.0044x over previous
; #define PG8_STAGE(bufoff, gbase, voff) do { _Pragma("unroll") for (int _i = 0; _i < 2; ++_i) \
;         __builtin_amdgcn_global_load_lds((const unsigned*)((const char*)(gbase) + (voff)[_i]), (PG8_LAS unsigned*)(lds + (bufoff) + ldsw + _i * 8192), 16, 0, 0); } while (0)
; #define PG8_LDA(dst, b, h) do { _Pragma("unroll") for (int m = 0; m < 4; ++m) _Pragma("unroll") for (int k = 0; k < 2; ++k) dst[m][k] = *(const PG8_LAS bf16x8*)(lds + PG8_SA(b, h) + aoff + m * 2048 + k * 1024); } while (0)
; #define PG8_LDB(dst, b, h) do { _Pragma("unroll") for (int n = 0; n < 2; ++n) _Pragma("unroll") for (int k = 0; k < 2; ++k) dst[n][k] = *(const PG8_LAS bf16x8*)(lds + PG8_SB(b, h) + boff + n * 2048 + k * 1024); } while (0)
; #define PG8_WAIT_V(n) asm volatile("s_waitcnt vmcnt(" #n ")" ::: "memory")
; #define PG8_WAIT_L(n) asm volatile("s_waitcnt lgkmcnt(" #n ")" ::: "memory")
; #define PG8_BAR __builtin_amdgcn_s_barrier()
; #define PG8_SCHED __builtin_amdgcn_sched_barrier(0)
; template <class Epi, class Sched, bool ALIGN_EPI = false, bool SP2 = false>
; __device__ __forceinline__ void gemm_phase(PG8_LAS unsigned char* lds, const Gemm g, const Sched& S, const Epi& E) {
;     ...
;         const char* nA = has_next ? (const char*)g.A + (size_t)nxt.pm * tstep : cA; const char* nB = has_next ? (const char*)g.Bt + (size_t)nxt.pn * tstep : cB;
;         for (int t = 0; t < nt; t += 2) {
;             const bool last = (t == nt - 2);
;             const char* a1 = cA + (size_t)(t + 1) * kstep;
;             const char* a2 = last ? nA : cA + (size_t)(t + 2) * kstep; const char* b2 = last ? nB : cB + (size_t)(t + 2) * kstep;
;             const char* a3 = a2 + kstep; const char* b3 = b2 + kstep;
;             if (last && has_next) S.a_ready(nxt, ui + 1);
;             if constexpr (SP2) {
;             PG8_LDB(B0, 0, 0); PG8_LDB(B1, 0, 1); PG8_SCHED; PG8_LDA(At, 0, 0); PG8_STAGE(PG8_SA(1, 1), a1 + hstep, voffA);
;             PG8_WAIT_V(8); PG8_WAIT_L(0); PG8_BAR; PG8_MMA(0, 0, At, B0); PG8_MMA(0, 1, At, B1); PG8_BAR; PG8_SCHED;
;             PG8_LDA(At, 0, 1); PG8_STAGE(PG8_SB(0, 0), b2, voffB); PG8_STAGE(PG8_SB(0, 1), b2 + hstep, voffB); PG8_STAGE(PG8_SA(0, 0), a2, voffA);
;             PG8_WAIT_V(8); PG8_WAIT_L(0); PG8_BAR; PG8_MMA(1, 0, At, B0); PG8_MMA(1, 1, At, B1); PG8_BAR; PG8_SCHED;
.LBB0_336:
	s_ashr_i32 s17, s16, 31
	s_lshl_b64 s[18:19], s[16:17], 19
	s_add_u32 s18, s36, s18
	s_addc_u32 s19, s37, s19
	s_and_b64 s[20:21], s[0:1], exec
	s_cselect_b32 s17, s19, s25
	s_cselect_b32 s50, s18, s24
	s_ashr_i32 s15, s14, 31
	s_lshl_b64 s[20:21], s[14:15], 19
	s_add_u32 s20, s34, s20
	s_addc_u32 s21, s35, s21
	s_and_b64 s[28:29], s[0:1], exec
	s_cselect_b32 s15, s21, s27
	s_cselect_b32 s51, s20, s26
	s_add_u32 s24, s24, 0x40080
	s_addc_u32 s25, s25, 0
	s_add_u32 s52, s26, 0x100
	s_addc_u32 s53, s27, 0
	s_mov_b32 s54, -2
	s_add_u32 s26, s24, 0xfffc0080
	s_addc_u32 s27, s25, -1
	s_cmp_eq_u32 s54, 12
	s_cselect_b32 s29, s17, s27
	s_cselect_b32 s28, s50, s26
	s_cselect_b32 s27, s15, s53
	s_cselect_b32 s26, s51, s52
	v_lshl_add_u64 v[216:217], s[24:25], 0, v[136:137]
	s_add_i32 m0, s23, 0xc000
	global_load_lds_dwordx4 v[216:217], off
	v_lshl_add_u64 v[216:217], s[24:25], 0, v[138:139]
	s_add_i32 m0, s23, 0xe000
	s_nop 0
	global_load_lds_dwordx4 v[216:217], off
	s_waitcnt vmcnt(8)
	s_waitcnt lgkmcnt(0)
	s_setprio 1
	s_barrier
	v_mfma_f32_16x16x32_bf16 v[124:127], v[152:155], v[184:187], 0
	v_mfma_f32_16x16x32_bf16 v[120:123], v[160:163], v[184:187], 0
	v_mfma_f32_16x16x32_bf16 v[108:111], v[152:155], v[192:195], 0
	v_mfma_f32_16x16x32_bf16 v[104:107], v[160:163], v[192:195], 0
	v_mfma_f32_16x16x32_bf16 v[92:95], v[152:155], v[200:203], 0
	v_mfma_f32_16x16x32_bf16 v[88:91], v[160:163], v[200:203], 0
	v_mfma_f32_16x16x32_bf16 v[76:79], v[152:155], v[208:211], 0
	v_mfma_f32_16x16x32_bf16 v[72:75], v[160:163], v[208:211], 0
	v_mfma_f32_16x16x32_bf16 v[124:127], v[156:159], v[188:191], v[124:127]
	v_mfma_f32_16x16x32_bf16 v[120:123], v[164:167], v[188:191], v[120:123]
	v_mfma_f32_16x16x32_bf16 v[108:111], v[156:159], v[196:199], v[108:111]
	v_mfma_f32_16x16x32_bf16 v[104:107], v[164:167], v[196:199], v[104:107]
	v_mfma_f32_16x16x32_bf16 v[92:95], v[156:159], v[204:207], v[92:95]
	v_mfma_f32_16x16x32_bf16 v[88:91], v[164:167], v[204:207], v[88:91]
	v_mfma_f32_16x16x32_bf16 v[76:79], v[156:159], v[212:215], v[76:79]
	v_mfma_f32_16x16x32_bf16 v[72:75], v[164:167], v[212:215], v[72:75]
	s_setprio 0
	s_setprio 1
	v_mfma_f32_16x16x32_bf16 v[116:119], v[168:171], v[184:187], 0
	v_mfma_f32_16x16x32_bf16 v[112:115], v[176:179], v[184:187], 0
	v_mfma_f32_16x16x32_bf16 v[100:103], v[168:171], v[192:195], 0
	v_mfma_f32_16x16x32_bf16 v[96:99], v[176:179], v[192:195], 0
	v_mfma_f32_16x16x32_bf16 v[84:87], v[168:171], v[200:203], 0
	v_mfma_f32_16x16x32_bf16 v[80:83], v[176:179], v[200:203], 0
	v_mfma_f32_16x16x32_bf16 v[68:71], v[168:171], v[208:211], 0
	v_mfma_f32_16x16x32_bf16 v[64:67], v[176:179], v[208:211], 0
	v_mfma_f32_16x16x32_bf16 v[116:119], v[172:175], v[188:191], v[116:119]
	v_mfma_f32_16x16x32_bf16 v[112:115], v[180:183], v[188:191], v[112:115]
	v_mfma_f32_16x16x32_bf16 v[100:103], v[172:175], v[196:199], v[100:103]
	v_mfma_f32_16x16x32_bf16 v[96:99], v[180:183], v[196:199], v[96:99]
	v_mfma_f32_16x16x32_bf16 v[84:87], v[172:175], v[204:207], v[84:87]
	v_mfma_f32_16x16x32_bf16 v[80:83], v[180:183], v[204:207], v[80:83]
	v_mfma_f32_16x16x32_bf16 v[68:71], v[172:175], v[212:215], v[68:71]
	v_mfma_f32_16x16x32_bf16 v[64:67], v[180:183], v[212:215], v[64:67]
	s_barrier
	s_setprio 0
	s_add_i32 s55, s44, s33
	v_lshl_add_u64 v[216:217], s[26:27], 0, v[132:133]
	s_mov_b32 m0, s55
	ds_read_b128 v[184:187], v150 offset:16384
	ds_read_b128 v[188:191], v150 offset:17408
	ds_read_b128 v[192:195], v150 offset:18432
	ds_read_b128 v[196:199], v150 offset:19456
	ds_read_b128 v[200:203], v150 offset:20480
	ds_read_b128 v[204:207], v150 offset:21504
	ds_read_b128 v[208:211], v150 offset:22528
	ds_read_b128 v[212:215], v150 offset:23552
	global_load_lds_dwordx4 v[216:217], off
	s_add_i32 m0, s55, 0x2000
	s_add_u32 s56, s26, 0x40000
	v_lshl_add_u64 v[218:219], s[26:27], 0, v[128:129]
	s_addc_u32 s57, s27, 0
	s_add_i32 s55, s45, s33
	global_load_lds_dwordx4 v[218:219], off
	v_lshl_add_u64 v[220:221], s[56:57], 0, v[132:133]
	s_mov_b32 m0, s55
	v_lshl_add_u64 v[222:223], s[28:29], 0, v[130:131]
	global_load_lds_dwordx4 v[220:221], off
	v_lshl_add_u64 v[220:221], s[56:57], 0, v[128:129]
	s_add_i32 m0, s55, 0x2000
	s_nop 0
	global_load_lds_dwordx4 v[220:221], off
	v_lshl_add_u64 v[220:221], s[28:29], 0, v[134:135]
	s_mov_b32 m0, s23
	s_nop 0
	global_load_lds_dwordx4 v[220:221], off
	s_mov_b32 m0, s39
	s_nop 0
	global_load_lds_dwordx4 v[222:223], off
	s_waitcnt vmcnt(8)
	s_waitcnt lgkmcnt(0)
	s_setprio 1
	s_barrier
	v_mfma_f32_16x16x32_bf16 v[60:63], v[152:155], v[184:187], 0
	v_mfma_f32_16x16x32_bf16 v[56:59], v[160:163], v[184:187], 0
	v_mfma_f32_16x16x32_bf16 v[44:47], v[152:155], v[192:195], 0
	v_mfma_f32_16x16x32_bf16 v[40:43], v[160:163], v[192:195], 0
	v_mfma_f32_16x16x32_bf16 v[28:31], v[152:155], v[200:203], 0
	v_mfma_f32_16x16x32_bf16 v[24:27], v[160:163], v[200:203], 0
	v_mfma_f32_16x16x32_bf16 v[12:15], v[152:155], v[208:211], 0
	v_mfma_f32_16x16x32_bf16 v[8:11], v[160:163], v[208:211], 0
	v_mfma_f32_16x16x32_bf16 v[60:63], v[156:159], v[188:191], v[60:63]
	v_mfma_f32_16x16x32_bf16 v[56:59], v[164:167], v[188:191], v[56:59]
	v_mfma_f32_16x16x32_bf16 v[44:47], v[156:159], v[196:199], v[44:47]
	v_mfma_f32_16x16x32_bf16 v[40:43], v[164:167], v[196:199], v[40:43]
	v_mfma_f32_16x16x32_bf16 v[28:31], v[156:159], v[204:207], v[28:31]
	v_mfma_f32_16x16x32_bf16 v[24:27], v[164:167], v[204:207], v[24:27]
	v_mfma_f32_16x16x32_bf16 v[12:15], v[156:159], v[212:215], v[12:15]
	v_mfma_f32_16x16x32_bf16 v[8:11], v[164:167], v[212:215], v[8:11]
	s_setprio 0
	s_setprio 1
	v_mfma_f32_16x16x32_bf16 v[52:55], v[168:171], v[184:187], 0
	v_mfma_f32_16x16x32_bf16 v[48:51], v[176:179], v[184:187], 0
	v_mfma_f32_16x16x32_bf16 v[36:39], v[168:171], v[192:195], 0
	v_mfma_f32_16x16x32_bf16 v[32:35], v[176:179], v[192:195], 0
	v_mfma_f32_16x16x32_bf16 v[20:23], v[168:171], v[200:203], 0
	v_mfma_f32_16x16x32_bf16 v[16:19], v[176:179], v[200:203], 0
	v_mfma_f32_16x16x32_bf16 v[4:7], v[168:171], v[208:211], 0
	v_mfma_f32_16x16x32_bf16 v[0:3], v[176:179], v[208:211], 0
	v_mfma_f32_16x16x32_bf16 v[52:55], v[172:175], v[188:191], v[52:55]
	v_mfma_f32_16x16x32_bf16 v[48:51], v[180:183], v[188:191], v[48:51]
	v_mfma_f32_16x16x32_bf16 v[36:39], v[172:175], v[196:199], v[36:39]
	v_mfma_f32_16x16x32_bf16 v[32:35], v[180:183], v[196:199], v[32:35]
	v_mfma_f32_16x16x32_bf16 v[20:23], v[172:175], v[204:207], v[20:23]
	v_mfma_f32_16x16x32_bf16 v[16:19], v[180:183], v[204:207], v[16:19]
	v_mfma_f32_16x16x32_bf16 v[4:7], v[172:175], v[212:215], v[4:7]
	v_mfma_f32_16x16x32_bf16 v[0:3], v[180:183], v[212:215], v[0:3]
	s_barrier
; #define PG8_STAGE(bufoff, gbase, voff) do { _Pragma("unroll") for (int _i = 0; _i < 2; ++_i) \
;         __builtin_amdgcn_global_load_lds((const unsigned*)((const char*)(gbase) + (voff)[_i]), (PG8_LAS unsigned*)(lds + (bufoff) + ldsw + _i * 8192), 16, 0, 0); } while (0)
; #define PG8_LDA(dst, b, h) do { _Pragma("unroll") for (int m = 0; m < 4; ++m) _Pragma("unroll") for (int k = 0; k < 2; ++k) dst[m][k] = *(const PG8_LAS bf16x8*)(lds + PG8_SA(b, h) + aoff + m * 2048 + k * 1024); } while (0)
; #define PG8_LDB(dst, b, h) do { _Pragma("unroll") for (int n = 0; n < 2; ++n) _Pragma("unroll") for (int k = 0; k < 2; ++k) dst[n][k] = *(const PG8_LAS bf16x8*)(lds + PG8_SB(b, h) + boff + n * 2048 + k * 1024); } while (0)
; #define PG8_MMA(ai, bj, At, Bt) do { __builtin_amdgcn_s_setprio(1); _Pragma("unroll") for (int m = 0; m < 4; ++m) _Pragma("unroll") for (int n = 0; n < 2; ++n) _Pragma("unroll") for (int k = 0; k < 2; ++k) \
;         acc[ai][bj][m][n] = __builtin_amdgcn_mfma_f32_16x16x32_bf16(Bt[n][k], At[m][k], acc[ai][bj][m][n], 0, 0, 0); __builtin_amdgcn_s_setprio(0); } while (0)
; #define PG8_WAIT_V(n) asm volatile("s_waitcnt vmcnt(" #n ")" ::: "memory")
; #define PG8_WAIT_L(n) asm volatile("s_waitcnt lgkmcnt(" #n ")" ::: "memory")
; #define PG8_BAR __builtin_amdgcn_s_barrier()
; #define PG8_SCHED __builtin_amdgcn_sched_barrier(0)
; template <class Epi, class Sched, bool ALIGN_EPI = false, bool SP2 = false>
; __device__ __forceinline__ void gemm_phase(PG8_LAS unsigned char* lds, const Gemm g, const Sched& S, const Epi& E) {
;     ...
;             PG8_WAIT_V(8); PG8_WAIT_L(0); PG8_BAR; PG8_MMA(1, 0, At, B0); PG8_MMA(1, 1, At, B1); PG8_BAR; PG8_SCHED;
;             PG8_LDB(B0, 1, 0); PG8_LDB(B1, 1, 1); PG8_SCHED; PG8_LDA(At, 1, 0); PG8_STAGE(PG8_SA(0, 1), a2 + hstep, voffA);
;             PG8_WAIT_V(8); PG8_WAIT_L(0); PG8_BAR; PG8_MMA(0, 0, At, B0); PG8_MMA(0, 1, At, B1); PG8_BAR; PG8_SCHED;
;             PG8_LDA(At, 1, 1); PG8_STAGE(PG8_SB(1, 0), b3, voffB); PG8_STAGE(PG8_SB(1, 1), b3 + hstep, voffB); PG8_STAGE(PG8_SA(1, 0), a3, voffA);
	s_setprio 0
	s_add_i32 s55, 0, 0x18000
	v_add_u32_e32 v151, s55, v145
	s_add_i32 s56, 0, 0x1c000
	ds_read_b128 v[152:155], v151
	ds_read_b128 v[156:159], v151 offset:1024
	ds_read_b128 v[160:163], v151 offset:2048
	ds_read_b128 v[164:167], v151 offset:3072
	v_add_u32_e32 v151, s56, v145
	ds_read_b128 v[168:171], v151
	ds_read_b128 v[172:175], v151 offset:1024
	ds_read_b128 v[176:179], v151 offset:2048
	ds_read_b128 v[180:183], v151 offset:3072
	s_add_u32 s28, s28, 0x40000
	s_addc_u32 s29, s29, 0
	s_mov_b32 m0, s40
	v_lshl_add_u64 v[224:225], s[28:29], 0, v[134:135]
	ds_read_b128 v[184:187], v150 offset:32768
	ds_read_b128 v[188:191], v150 offset:33792
	ds_read_b128 v[192:195], v150 offset:34816
	ds_read_b128 v[196:199], v150 offset:35840
	ds_read_b128 v[200:203], v150 offset:36864
	ds_read_b128 v[204:207], v150 offset:37888
	ds_read_b128 v[208:211], v150 offset:38912
	ds_read_b128 v[212:215], v150 offset:39936
	global_load_lds_dwordx4 v[224:225], off
	v_lshl_add_u64 v[224:225], s[28:29], 0, v[130:131]
	s_mov_b32 m0, s41
	s_nop 0
	global_load_lds_dwordx4 v[224:225], off
	s_waitcnt vmcnt(8)
	s_waitcnt lgkmcnt(0)
	s_setprio 1
	s_barrier
	v_mfma_f32_16x16x32_bf16 v[124:127], v[152:155], v[184:187], v[124:127]
	v_mfma_f32_16x16x32_bf16 v[120:123], v[160:163], v[184:187], v[120:123]
	v_mfma_f32_16x16x32_bf16 v[108:111], v[152:155], v[192:195], v[108:111]
	v_mfma_f32_16x16x32_bf16 v[104:107], v[160:163], v[192:195], v[104:107]
	v_mfma_f32_16x16x32_bf16 v[92:95], v[152:155], v[200:203], v[92:95]
	v_mfma_f32_16x16x32_bf16 v[88:91], v[160:163], v[200:203], v[88:91]
	v_mfma_f32_16x16x32_bf16 v[76:79], v[152:155], v[208:211], v[76:79]
	v_mfma_f32_16x16x32_bf16 v[72:75], v[160:163], v[208:211], v[72:75]
	v_mfma_f32_16x16x32_bf16 v[124:127], v[156:159], v[188:191], v[124:127]
	v_mfma_f32_16x16x32_bf16 v[120:123], v[164:167], v[188:191], v[120:123]
	v_mfma_f32_16x16x32_bf16 v[108:111], v[156:159], v[196:199], v[108:111]
	v_mfma_f32_16x16x32_bf16 v[104:107], v[164:167], v[196:199], v[104:107]
	v_mfma_f32_16x16x32_bf16 v[92:95], v[156:159], v[204:207], v[92:95]
	v_mfma_f32_16x16x32_bf16 v[88:91], v[164:167], v[204:207], v[88:91]
	v_mfma_f32_16x16x32_bf16 v[76:79], v[156:159], v[212:215], v[76:79]
	v_mfma_f32_16x16x32_bf16 v[72:75], v[164:167], v[212:215], v[72:75]
	s_setprio 0
	s_setprio 1
	v_mfma_f32_16x16x32_bf16 v[116:119], v[168:171], v[184:187], v[116:119]
	v_mfma_f32_16x16x32_bf16 v[112:115], v[176:179], v[184:187], v[112:115]
	v_mfma_f32_16x16x32_bf16 v[100:103], v[168:171], v[192:195], v[100:103]
	v_mfma_f32_16x16x32_bf16 v[96:99], v[176:179], v[192:195], v[96:99]
	v_mfma_f32_16x16x32_bf16 v[84:87], v[168:171], v[200:203], v[84:87]
	v_mfma_f32_16x16x32_bf16 v[80:83], v[176:179], v[200:203], v[80:83]
	v_mfma_f32_16x16x32_bf16 v[68:71], v[168:171], v[208:211], v[68:71]
	v_mfma_f32_16x16x32_bf16 v[64:67], v[176:179], v[208:211], v[64:67]
	v_mfma_f32_16x16x32_bf16 v[116:119], v[172:175], v[188:191], v[116:119]
	v_mfma_f32_16x16x32_bf16 v[112:115], v[180:183], v[188:191], v[112:115]
	v_mfma_f32_16x16x32_bf16 v[100:103], v[172:175], v[196:199], v[100:103]
	v_mfma_f32_16x16x32_bf16 v[96:99], v[180:183], v[196:199], v[96:99]
	v_mfma_f32_16x16x32_bf16 v[84:87], v[172:175], v[204:207], v[84:87]
	v_mfma_f32_16x16x32_bf16 v[80:83], v[180:183], v[204:207], v[80:83]
	v_mfma_f32_16x16x32_bf16 v[68:71], v[172:175], v[212:215], v[68:71]
	v_mfma_f32_16x16x32_bf16 v[64:67], v[180:183], v[212:215], v[64:67]
	s_barrier
	s_setprio 0
	s_add_i32 s28, s55, s33
	v_lshl_add_u64 v[216:217], v[216:217], 0, s[8:9]
	s_mov_b32 m0, s28
	ds_read_b128 v[184:187], v150 offset:49152
	ds_read_b128 v[188:191], v150 offset:50176
	ds_read_b128 v[192:195], v150 offset:51200
	ds_read_b128 v[196:199], v150 offset:52224
	ds_read_b128 v[200:203], v150 offset:53248
	ds_read_b128 v[204:207], v150 offset:54272
	ds_read_b128 v[208:211], v150 offset:55296
	ds_read_b128 v[212:215], v150 offset:56320
	global_load_lds_dwordx4 v[216:217], off
	s_add_i32 m0, s28, 0x2000
	s_add_u32 s26, s26, 0x40080
	v_lshl_add_u64 v[216:217], v[218:219], 0, s[8:9]
	s_addc_u32 s27, s27, 0
	s_add_i32 s28, s56, s33
	global_load_lds_dwordx4 v[216:217], off
	v_lshl_add_u64 v[216:217], s[26:27], 0, v[132:133]
	s_mov_b32 m0, s28
	s_nop 0
	global_load_lds_dwordx4 v[216:217], off
	v_lshl_add_u64 v[216:217], s[26:27], 0, v[128:129]
	s_add_i32 m0, s28, 0x2000
	s_nop 0
	global_load_lds_dwordx4 v[216:217], off
	v_lshl_add_u64 v[216:217], v[220:221], 0, s[8:9]
	s_mov_b32 m0, s42
	s_nop 0
	global_load_lds_dwordx4 v[216:217], off
	v_lshl_add_u64 v[216:217], v[222:223], 0, s[8:9]
	s_mov_b32 m0, s43
	s_nop 0
	global_load_lds_dwordx4 v[216:217], off
	s_waitcnt vmcnt(8)
	s_waitcnt lgkmcnt(0)
	s_setprio 1
	s_barrier
; #define PG8_STAGE(bufoff, gbase, voff) do { _Pragma("unroll") for (int _i = 0; _i < 2; ++_i) \
;         __builtin_amdgcn_global_load_lds((const unsigned*)((const char*)(gbase) + (voff)[_i]), (PG8_LAS unsigned*)(lds + (bufoff) + ldsw + _i * 8192), 16, 0, 0); } while (0)
; #define PG8_LDA(dst, b, h) do { _Pragma("unroll") for (int m = 0; m < 4; ++m) _Pragma("unroll") for (int k = 0; k < 2; ++k) dst[m][k] = *(const PG8_LAS bf16x8*)(lds + PG8_SA(b, h) + aoff + m * 2048 + k * 1024); } while (0)
; #define PG8_LDB(dst, b, h) do { _Pragma("unroll") for (int n = 0; n < 2; ++n) _Pragma("unroll") for (int k = 0; k < 2; ++k) dst[n][k] = *(const PG8_LAS bf16x8*)(lds + PG8_SB(b, h) + boff + n * 2048 + k * 1024); } while (0)
; #define PG8_MMA(ai, bj, At, Bt) do { __builtin_amdgcn_s_setprio(1); _Pragma("unroll") for (int m = 0; m < 4; ++m) _Pragma("unroll") for (int n = 0; n < 2; ++n) _Pragma("unroll") for (int k = 0; k < 2; ++k) \
;         acc[ai][bj][m][n] = __builtin_amdgcn_mfma_f32_16x16x32_bf16(Bt[n][k], At[m][k], acc[ai][bj][m][n], 0, 0, 0); __builtin_amdgcn_s_setprio(0); } while (0)
; #define PG8_WAIT_V(n) asm volatile("s_waitcnt vmcnt(" #n ")" ::: "memory")
; template <class Epi, class Sched, bool ALIGN_EPI = false, bool SP2 = false>
; __device__ __forceinline__ void gemm_phase(PG8_LAS unsigned char* lds, const Gemm g, const Sched& S, const Epi& E) {
;     ...
;             PG8_LDB(B0, 0, 0); PG8_LDB(B1, 0, 1); PG8_SCHED; PG8_LDA(At, 0, 0); PG8_STAGE(PG8_SA(1, 1), a1 + hstep, voffA);
;             PG8_WAIT_V(8); PG8_WAIT_L(0); PG8_BAR; PG8_MMA(0, 0, At, B0); PG8_MMA(0, 1, At, B1); PG8_BAR; PG8_SCHED;
;             PG8_LDA(At, 0, 1); PG8_STAGE(PG8_SB(0, 0), b2, voffB); PG8_STAGE(PG8_SB(0, 1), b2 + hstep, voffB); PG8_STAGE(PG8_SA(0, 0), a2, voffA);
;             PG8_WAIT_V(8); PG8_WAIT_L(0); PG8_BAR; PG8_MMA(1, 0, At, B0); PG8_MMA(1, 1, At, B1); PG8_BAR; PG8_SCHED;
;             PG8_LDB(B0, 1, 0); PG8_LDB(B1, 1, 1); PG8_SCHED; PG8_LDA(At, 1, 0); PG8_STAGE(PG8_SA(0, 1), a2 + hstep, voffA);
;             PG8_WAIT_V(8); PG8_WAIT_L(0); PG8_BAR; PG8_MMA(0, 0, At, B0); PG8_MMA(0, 1, At, B1); PG8_BAR; PG8_SCHED;
;             PG8_LDA(At, 1, 1); PG8_STAGE(PG8_SB(1, 0), b3, voffB); PG8_STAGE(PG8_SB(1, 1), b3 + hstep, voffB); PG8_STAGE(PG8_SA(1, 0), a3, voffA);
;             PG8_WAIT_V(8); PG8_WAIT_L(0); PG8_BAR; PG8_MMA(1, 0, At, B0); PG8_MMA(1, 1, At, B1); PG8_BAR; PG8_SCHED;
	v_mfma_f32_16x16x32_bf16 v[60:63], v[152:155], v[184:187], v[60:63]
	v_mfma_f32_16x16x32_bf16 v[56:59], v[160:163], v[184:187], v[56:59]
	v_mfma_f32_16x16x32_bf16 v[44:47], v[152:155], v[192:195], v[44:47]
	v_mfma_f32_16x16x32_bf16 v[40:43], v[160:163], v[192:195], v[40:43]
	v_mfma_f32_16x16x32_bf16 v[28:31], v[152:155], v[200:203], v[28:31]
	v_mfma_f32_16x16x32_bf16 v[24:27], v[160:163], v[200:203], v[24:27]
	v_mfma_f32_16x16x32_bf16 v[12:15], v[152:155], v[208:211], v[12:15]
	v_mfma_f32_16x16x32_bf16 v[8:11], v[160:163], v[208:211], v[8:11]
	v_mfma_f32_16x16x32_bf16 v[60:63], v[156:159], v[188:191], v[60:63]
	v_mfma_f32_16x16x32_bf16 v[56:59], v[164:167], v[188:191], v[56:59]
	v_mfma_f32_16x16x32_bf16 v[44:47], v[156:159], v[196:199], v[44:47]
	v_mfma_f32_16x16x32_bf16 v[40:43], v[164:167], v[196:199], v[40:43]
	v_mfma_f32_16x16x32_bf16 v[28:31], v[156:159], v[204:207], v[28:31]
	v_mfma_f32_16x16x32_bf16 v[24:27], v[164:167], v[204:207], v[24:27]
	v_mfma_f32_16x16x32_bf16 v[12:15], v[156:159], v[212:215], v[12:15]
	v_mfma_f32_16x16x32_bf16 v[8:11], v[164:167], v[212:215], v[8:11]
	s_setprio 0
	s_setprio 1
	v_mfma_f32_16x16x32_bf16 v[52:55], v[168:171], v[184:187], v[52:55]
	v_mfma_f32_16x16x32_bf16 v[48:51], v[176:179], v[184:187], v[48:51]
	v_mfma_f32_16x16x32_bf16 v[36:39], v[168:171], v[192:195], v[36:39]
	v_mfma_f32_16x16x32_bf16 v[32:35], v[176:179], v[192:195], v[32:35]
	v_mfma_f32_16x16x32_bf16 v[20:23], v[168:171], v[200:203], v[20:23]
	v_mfma_f32_16x16x32_bf16 v[16:19], v[176:179], v[200:203], v[16:19]
	v_mfma_f32_16x16x32_bf16 v[4:7], v[168:171], v[208:211], v[4:7]
	v_mfma_f32_16x16x32_bf16 v[0:3], v[176:179], v[208:211], v[0:3]
	v_mfma_f32_16x16x32_bf16 v[52:55], v[172:175], v[188:191], v[52:55]
	v_mfma_f32_16x16x32_bf16 v[48:51], v[180:183], v[188:191], v[48:51]
	v_mfma_f32_16x16x32_bf16 v[36:39], v[172:175], v[196:199], v[36:39]
	v_mfma_f32_16x16x32_bf16 v[32:35], v[180:183], v[196:199], v[32:35]
	v_mfma_f32_16x16x32_bf16 v[20:23], v[172:175], v[204:207], v[20:23]
	v_mfma_f32_16x16x32_bf16 v[16:19], v[180:183], v[204:207], v[16:19]
	v_mfma_f32_16x16x32_bf16 v[4:7], v[172:175], v[212:215], v[4:7]
	v_mfma_f32_16x16x32_bf16 v[0:3], v[180:183], v[212:215], v[0:3]
	s_barrier
	s_setprio 0
	s_add_i32 s54, s54, 2
	s_add_u32 s24, s24, 0x100
	s_addc_u32 s25, s25, 0
	s_add_u32 s52, s52, 0x100
	s_addc_u32 s53, s53, 0
	s_cmp_gt_u32 s54, 13
.LBB0_337:
	ds_read_b128 v[152:155], v148
	ds_read_b128 v[156:159], v148 offset:1024
	ds_read_b128 v[160:163], v148 offset:2048
	ds_read_b128 v[164:167], v148 offset:3072
	ds_read_b128 v[168:171], v149
	ds_read_b128 v[172:175], v149 offset:1024
	ds_read_b128 v[176:179], v149 offset:2048
	ds_read_b128 v[180:183], v149 offset:3072
	s_add_u32 s26, s24, 0xfffc0080
	s_addc_u32 s27, s25, -1
	s_cmp_eq_u32 s54, 12
	s_cselect_b32 s29, s17, s27
	s_cselect_b32 s28, s50, s26
	s_cselect_b32 s27, s15, s53
	s_cselect_b32 s26, s51, s52
	v_lshl_add_u64 v[216:217], s[24:25], 0, v[136:137]
	s_add_i32 m0, s23, 0xc000
	ds_read_b128 v[184:187], v150
	ds_read_b128 v[188:191], v150 offset:1024
	ds_read_b128 v[192:195], v150 offset:2048
	ds_read_b128 v[196:199], v150 offset:3072
	ds_read_b128 v[200:203], v150 offset:4096
	ds_read_b128 v[204:207], v150 offset:5120
	ds_read_b128 v[208:211], v150 offset:6144
	ds_read_b128 v[212:215], v150 offset:7168
	global_load_lds_dwordx4 v[216:217], off
	v_lshl_add_u64 v[216:217], s[24:25], 0, v[138:139]
	s_add_i32 m0, s23, 0xe000
	s_nop 0
	global_load_lds_dwordx4 v[216:217], off
	s_waitcnt vmcnt(8)
	s_waitcnt lgkmcnt(0)
	s_setprio 1
	s_barrier
	v_mfma_f32_16x16x32_bf16 v[124:127], v[152:155], v[184:187], v[124:127]
	v_mfma_f32_16x16x32_bf16 v[120:123], v[160:163], v[184:187], v[120:123]
	v_mfma_f32_16x16x32_bf16 v[108:111], v[152:155], v[192:195], v[108:111]
	v_mfma_f32_16x16x32_bf16 v[104:107], v[160:163], v[192:195], v[104:107]
	v_mfma_f32_16x16x32_bf16 v[92:95], v[152:155], v[200:203], v[92:95]
	v_mfma_f32_16x16x32_bf16 v[88:91], v[160:163], v[200:203], v[88:91]
	v_mfma_f32_16x16x32_bf16 v[76:79], v[152:155], v[208:211], v[76:79]
	v_mfma_f32_16x16x32_bf16 v[72:75], v[160:163], v[208:211], v[72:75]
	v_mfma_f32_16x16x32_bf16 v[124:127], v[156:159], v[188:191], v[124:127]
	v_mfma_f32_16x16x32_bf16 v[120:123], v[164:167], v[188:191], v[120:123]
	v_mfma_f32_16x16x32_bf16 v[108:111], v[156:159], v[196:199], v[108:111]
	v_mfma_f32_16x16x32_bf16 v[104:107], v[164:167], v[196:199], v[104:107]
	v_mfma_f32_16x16x32_bf16 v[92:95], v[156:159], v[204:207], v[92:95]
	v_mfma_f32_16x16x32_bf16 v[88:91], v[164:167], v[204:207], v[88:91]
	v_mfma_f32_16x16x32_bf16 v[76:79], v[156:159], v[212:215], v[76:79]
	v_mfma_f32_16x16x32_bf16 v[72:75], v[164:167], v[212:215], v[72:75]
	s_setprio 0
	s_setprio 1
	v_mfma_f32_16x16x32_bf16 v[116:119], v[168:171], v[184:187], v[116:119]
	v_mfma_f32_16x16x32_bf16 v[112:115], v[176:179], v[184:187], v[112:115]
	v_mfma_f32_16x16x32_bf16 v[100:103], v[168:171], v[192:195], v[100:103]
	v_mfma_f32_16x16x32_bf16 v[96:99], v[176:179], v[192:195], v[96:99]
	v_mfma_f32_16x16x32_bf16 v[84:87], v[168:171], v[200:203], v[84:87]
	v_mfma_f32_16x16x32_bf16 v[80:83], v[176:179], v[200:203], v[80:83]
	v_mfma_f32_16x16x32_bf16 v[68:71], v[168:171], v[208:211], v[68:71]
	v_mfma_f32_16x16x32_bf16 v[64:67], v[176:179], v[208:211], v[64:67]
	v_mfma_f32_16x16x32_bf16 v[116:119], v[172:175], v[188:191], v[116:119]
	v_mfma_f32_16x16x32_bf16 v[112:115], v[180:183], v[188:191], v[112:115]
	v_mfma_f32_16x16x32_bf16 v[100:103], v[172:175], v[196:199], v[100:103]
	v_mfma_f32_16x16x32_bf16 v[96:99], v[180:183], v[196:199], v[96:99]
	v_mfma_f32_16x16x32_bf16 v[84:87], v[172:175], v[204:207], v[84:87]
	v_mfma_f32_16x16x32_bf16 v[80:83], v[180:183], v[204:207], v[80:83]
	v_mfma_f32_16x16x32_bf16 v[68:71], v[172:175], v[212:215], v[68:71]
	v_mfma_f32_16x16x32_bf16 v[64:67], v[180:183], v[212:215], v[64:67]
	s_barrier
; #define PG8_STAGE(bufoff, gbase, voff) do { _Pragma("unroll") for (int _i = 0; _i < 2; ++_i) \
;         __builtin_amdgcn_global_load_lds((const unsigned*)((const char*)(gbase) + (voff)[_i]), (PG8_LAS unsigned*)(lds + (bufoff) + ldsw + _i * 8192), 16, 0, 0); } while (0)
; #define PG8_LDA(dst, b, h) do { _Pragma("unroll") for (int m = 0; m < 4; ++m) _Pragma("unroll") for (int k = 0; k < 2; ++k) dst[m][k] = *(const PG8_LAS bf16x8*)(lds + PG8_SA(b, h) + aoff + m * 2048 + k * 1024); } while (0)
; #define PG8_LDB(dst, b, h) do { _Pragma("unroll") for (int n = 0; n < 2; ++n) _Pragma("unroll") for (int k = 0; k < 2; ++k) dst[n][k] = *(const PG8_LAS bf16x8*)(lds + PG8_SB(b, h) + boff + n * 2048 + k * 1024); } while (0)
; #define PG8_MMA(ai, bj, At, Bt) do { __builtin_amdgcn_s_setprio(1); _Pragma("unroll") for (int m = 0; m < 4; ++m) _Pragma("unroll") for (int n = 0; n < 2; ++n) _Pragma("unroll") for (int k = 0; k < 2; ++k) \
;         acc[ai][bj][m][n] = __builtin_amdgcn_mfma_f32_16x16x32_bf16(Bt[n][k], At[m][k], acc[ai][bj][m][n], 0, 0, 0); __builtin_amdgcn_s_setprio(0); } while (0)
; #define PG8_WAIT_V(n) asm volatile("s_waitcnt vmcnt(" #n ")" ::: "memory")
; #define PG8_WAIT_L(n) asm volatile("s_waitcnt lgkmcnt(" #n ")" ::: "memory")
; #define PG8_BAR __builtin_amdgcn_s_barrier()
; #define PG8_SCHED __builtin_amdgcn_sched_barrier(0)
; template <class Epi, class Sched, bool ALIGN_EPI = false, bool SP2 = false>
; __device__ __forceinline__ void gemm_phase(PG8_LAS unsigned char* lds, const Gemm g, const Sched& S, const Epi& E) {
;     ...
;             PG8_WAIT_V(8); PG8_WAIT_L(0); PG8_BAR; PG8_MMA(0, 0, At, B0); PG8_MMA(0, 1, At, B1); PG8_BAR; PG8_SCHED;
;             PG8_LDA(At, 0, 1); PG8_STAGE(PG8_SB(0, 0), b2, voffB); PG8_STAGE(PG8_SB(0, 1), b2 + hstep, voffB); PG8_STAGE(PG8_SA(0, 0), a2, voffA);
;             PG8_WAIT_V(8); PG8_WAIT_L(0); PG8_BAR; PG8_MMA(1, 0, At, B0); PG8_MMA(1, 1, At, B1); PG8_BAR; PG8_SCHED;
;             PG8_LDB(B0, 1, 0); PG8_LDB(B1, 1, 1); PG8_SCHED; PG8_LDA(At, 1, 0); PG8_STAGE(PG8_SA(0, 1), a2 + hstep, voffA);
;             PG8_WAIT_V(8); PG8_WAIT_L(0); PG8_BAR; PG8_MMA(0, 0, At, B0); PG8_MMA(0, 1, At, B1); PG8_BAR; PG8_SCHED;
	s_setprio 0
	s_add_i32 s55, s44, s33
	v_lshl_add_u64 v[216:217], s[26:27], 0, v[132:133]
	s_mov_b32 m0, s55
	ds_read_b128 v[184:187], v150 offset:16384
	ds_read_b128 v[188:191], v150 offset:17408
	ds_read_b128 v[192:195], v150 offset:18432
	ds_read_b128 v[196:199], v150 offset:19456
	ds_read_b128 v[200:203], v150 offset:20480
	ds_read_b128 v[204:207], v150 offset:21504
	ds_read_b128 v[208:211], v150 offset:22528
	ds_read_b128 v[212:215], v150 offset:23552
	global_load_lds_dwordx4 v[216:217], off
	s_add_i32 m0, s55, 0x2000
	s_add_u32 s56, s26, 0x40000
	v_lshl_add_u64 v[218:219], s[26:27], 0, v[128:129]
	s_addc_u32 s57, s27, 0
	s_add_i32 s55, s45, s33
	global_load_lds_dwordx4 v[218:219], off
	v_lshl_add_u64 v[220:221], s[56:57], 0, v[132:133]
	s_mov_b32 m0, s55
	v_lshl_add_u64 v[222:223], s[28:29], 0, v[130:131]
	global_load_lds_dwordx4 v[220:221], off
	v_lshl_add_u64 v[220:221], s[56:57], 0, v[128:129]
	s_add_i32 m0, s55, 0x2000
	s_nop 0
	global_load_lds_dwordx4 v[220:221], off
	v_lshl_add_u64 v[220:221], s[28:29], 0, v[134:135]
	s_mov_b32 m0, s23
	s_nop 0
	global_load_lds_dwordx4 v[220:221], off
	s_mov_b32 m0, s39
	s_nop 0
	global_load_lds_dwordx4 v[222:223], off
	s_waitcnt vmcnt(8)
	s_waitcnt lgkmcnt(0)
	s_setprio 1
	s_barrier
	v_mfma_f32_16x16x32_bf16 v[60:63], v[152:155], v[184:187], v[60:63]
	v_mfma_f32_16x16x32_bf16 v[56:59], v[160:163], v[184:187], v[56:59]
	v_mfma_f32_16x16x32_bf16 v[44:47], v[152:155], v[192:195], v[44:47]
	v_mfma_f32_16x16x32_bf16 v[40:43], v[160:163], v[192:195], v[40:43]
	v_mfma_f32_16x16x32_bf16 v[28:31], v[152:155], v[200:203], v[28:31]
	v_mfma_f32_16x16x32_bf16 v[24:27], v[160:163], v[200:203], v[24:27]
	v_mfma_f32_16x16x32_bf16 v[12:15], v[152:155], v[208:211], v[12:15]
	v_mfma_f32_16x16x32_bf16 v[8:11], v[160:163], v[208:211], v[8:11]
	v_mfma_f32_16x16x32_bf16 v[60:63], v[156:159], v[188:191], v[60:63]
	v_mfma_f32_16x16x32_bf16 v[56:59], v[164:167], v[188:191], v[56:59]
	v_mfma_f32_16x16x32_bf16 v[44:47], v[156:159], v[196:199], v[44:47]
	v_mfma_f32_16x16x32_bf16 v[40:43], v[164:167], v[196:199], v[40:43]
	v_mfma_f32_16x16x32_bf16 v[28:31], v[156:159], v[204:207], v[28:31]
	v_mfma_f32_16x16x32_bf16 v[24:27], v[164:167], v[204:207], v[24:27]
	v_mfma_f32_16x16x32_bf16 v[12:15], v[156:159], v[212:215], v[12:15]
	v_mfma_f32_16x16x32_bf16 v[8:11], v[164:167], v[212:215], v[8:11]
	s_setprio 0
	s_setprio 1
	v_mfma_f32_16x16x32_bf16 v[52:55], v[168:171], v[184:187], v[52:55]
	v_mfma_f32_16x16x32_bf16 v[48:51], v[176:179], v[184:187], v[48:51]
	v_mfma_f32_16x16x32_bf16 v[36:39], v[168:171], v[192:195], v[36:39]
	v_mfma_f32_16x16x32_bf16 v[32:35], v[176:179], v[192:195], v[32:35]
	v_mfma_f32_16x16x32_bf16 v[20:23], v[168:171], v[200:203], v[20:23]
	v_mfma_f32_16x16x32_bf16 v[16:19], v[176:179], v[200:203], v[16:19]
	v_mfma_f32_16x16x32_bf16 v[4:7], v[168:171], v[208:211], v[4:7]
	v_mfma_f32_16x16x32_bf16 v[0:3], v[176:179], v[208:211], v[0:3]
	v_mfma_f32_16x16x32_bf16 v[52:55], v[172:175], v[188:191], v[52:55]
	v_mfma_f32_16x16x32_bf16 v[48:51], v[180:183], v[188:191], v[48:51]
	v_mfma_f32_16x16x32_bf16 v[36:39], v[172:175], v[196:199], v[36:39]
	v_mfma_f32_16x16x32_bf16 v[32:35], v[180:183], v[196:199], v[32:35]
	v_mfma_f32_16x16x32_bf16 v[20:23], v[172:175], v[204:207], v[20:23]
	v_mfma_f32_16x16x32_bf16 v[16:19], v[180:183], v[204:207], v[16:19]
	v_mfma_f32_16x16x32_bf16 v[4:7], v[172:175], v[212:215], v[4:7]
	v_mfma_f32_16x16x32_bf16 v[0:3], v[180:183], v[212:215], v[0:3]
	s_barrier
	s_setprio 0
	s_add_i32 s55, 0, 0x18000
	v_add_u32_e32 v151, s55, v145
	s_add_i32 s56, 0, 0x1c000
	ds_read_b128 v[152:155], v151
	ds_read_b128 v[156:159], v151 offset:1024
	ds_read_b128 v[160:163], v151 offset:2048
	ds_read_b128 v[164:167], v151 offset:3072
	v_add_u32_e32 v151, s56, v145
	ds_read_b128 v[168:171], v151
	ds_read_b128 v[172:175], v151 offset:1024
	ds_read_b128 v[176:179], v151 offset:2048
	ds_read_b128 v[180:183], v151 offset:3072
	s_add_u32 s28, s28, 0x40000
	s_addc_u32 s29, s29, 0
	s_mov_b32 m0, s40
	v_lshl_add_u64 v[224:225], s[28:29], 0, v[134:135]
	ds_read_b128 v[184:187], v150 offset:32768
	ds_read_b128 v[188:191], v150 offset:33792
	ds_read_b128 v[192:195], v150 offset:34816
	ds_read_b128 v[196:199], v150 offset:35840
	ds_read_b128 v[200:203], v150 offset:36864
	ds_read_b128 v[204:207], v150 offset:37888
	ds_read_b128 v[208:211], v150 offset:38912
	ds_read_b128 v[212:215], v150 offset:39936
	global_load_lds_dwordx4 v[224:225], off
	v_lshl_add_u64 v[224:225], s[28:29], 0, v[130:131]
	s_mov_b32 m0, s41
	s_nop 0
	global_load_lds_dwordx4 v[224:225], off
	s_waitcnt vmcnt(8)
	s_waitcnt lgkmcnt(0)
	s_setprio 1
	s_barrier
; #define PG8_STAGE(bufoff, gbase, voff) do { _Pragma("unroll") for (int _i = 0; _i < 2; ++_i) \
;         __builtin_amdgcn_global_load_lds((const unsigned*)((const char*)(gbase) + (voff)[_i]), (PG8_LAS unsigned*)(lds + (bufoff) + ldsw + _i * 8192), 16, 0, 0); } while (0)
; #define PG8_LDA(dst, b, h) do { _Pragma("unroll") for (int m = 0; m < 4; ++m) _Pragma("unroll") for (int k = 0; k < 2; ++k) dst[m][k] = *(const PG8_LAS bf16x8*)(lds + PG8_SA(b, h) + aoff + m * 2048 + k * 1024); } while (0)
; #define PG8_MMA(ai, bj, At, Bt) do { __builtin_amdgcn_s_setprio(1); _Pragma("unroll") for (int m = 0; m < 4; ++m) _Pragma("unroll") for (int n = 0; n < 2; ++n) _Pragma("unroll") for (int k = 0; k < 2; ++k) \
;         acc[ai][bj][m][n] = __builtin_amdgcn_mfma_f32_16x16x32_bf16(Bt[n][k], At[m][k], acc[ai][bj][m][n], 0, 0, 0); __builtin_amdgcn_s_setprio(0); } while (0)
; #define PG8_WAIT_V(n) asm volatile("s_waitcnt vmcnt(" #n ")" ::: "memory")
; #define PG8_WAIT_L(n) asm volatile("s_waitcnt lgkmcnt(" #n ")" ::: "memory")
; #define PG8_BAR __builtin_amdgcn_s_barrier()
; #define PG8_SCHED __builtin_amdgcn_sched_barrier(0)
; template <class Epi, class Sched, bool ALIGN_EPI = false, bool SP2 = false>
; __device__ __forceinline__ void gemm_phase(PG8_LAS unsigned char* lds, const Gemm g, const Sched& S, const Epi& E) {
;     ...
;             PG8_WAIT_V(8); PG8_WAIT_L(0); PG8_BAR; PG8_MMA(0, 0, At, B0); PG8_MMA(0, 1, At, B1); PG8_BAR; PG8_SCHED;
;             PG8_LDA(At, 1, 1); PG8_STAGE(PG8_SB(1, 0), b3, voffB); PG8_STAGE(PG8_SB(1, 1), b3 + hstep, voffB); PG8_STAGE(PG8_SA(1, 0), a3, voffA);
;             PG8_WAIT_V(8); PG8_WAIT_L(0); PG8_BAR; PG8_MMA(1, 0, At, B0); PG8_MMA(1, 1, At, B1); PG8_BAR; PG8_SCHED;
;     ...
;         if constexpr (ALIGN_EPI) { if (wr == 0) PG8_BAR; }
	v_mfma_f32_16x16x32_bf16 v[124:127], v[152:155], v[184:187], v[124:127]
	v_mfma_f32_16x16x32_bf16 v[120:123], v[160:163], v[184:187], v[120:123]
	v_mfma_f32_16x16x32_bf16 v[108:111], v[152:155], v[192:195], v[108:111]
	v_mfma_f32_16x16x32_bf16 v[104:107], v[160:163], v[192:195], v[104:107]
	v_mfma_f32_16x16x32_bf16 v[92:95], v[152:155], v[200:203], v[92:95]
	v_mfma_f32_16x16x32_bf16 v[88:91], v[160:163], v[200:203], v[88:91]
	v_mfma_f32_16x16x32_bf16 v[76:79], v[152:155], v[208:211], v[76:79]
	v_mfma_f32_16x16x32_bf16 v[72:75], v[160:163], v[208:211], v[72:75]
	v_mfma_f32_16x16x32_bf16 v[124:127], v[156:159], v[188:191], v[124:127]
	v_mfma_f32_16x16x32_bf16 v[120:123], v[164:167], v[188:191], v[120:123]
	v_mfma_f32_16x16x32_bf16 v[108:111], v[156:159], v[196:199], v[108:111]
	v_mfma_f32_16x16x32_bf16 v[104:107], v[164:167], v[196:199], v[104:107]
	v_mfma_f32_16x16x32_bf16 v[92:95], v[156:159], v[204:207], v[92:95]
	v_mfma_f32_16x16x32_bf16 v[88:91], v[164:167], v[204:207], v[88:91]
	v_mfma_f32_16x16x32_bf16 v[76:79], v[156:159], v[212:215], v[76:79]
	v_mfma_f32_16x16x32_bf16 v[72:75], v[164:167], v[212:215], v[72:75]
	s_setprio 0
	s_setprio 1
	v_mfma_f32_16x16x32_bf16 v[116:119], v[168:171], v[184:187], v[116:119]
	v_mfma_f32_16x16x32_bf16 v[112:115], v[176:179], v[184:187], v[112:115]
	v_mfma_f32_16x16x32_bf16 v[100:103], v[168:171], v[192:195], v[100:103]
	v_mfma_f32_16x16x32_bf16 v[96:99], v[176:179], v[192:195], v[96:99]
	v_mfma_f32_16x16x32_bf16 v[84:87], v[168:171], v[200:203], v[84:87]
	v_mfma_f32_16x16x32_bf16 v[80:83], v[176:179], v[200:203], v[80:83]
	v_mfma_f32_16x16x32_bf16 v[68:71], v[168:171], v[208:211], v[68:71]
	v_mfma_f32_16x16x32_bf16 v[64:67], v[176:179], v[208:211], v[64:67]
	v_mfma_f32_16x16x32_bf16 v[116:119], v[172:175], v[188:191], v[116:119]
	v_mfma_f32_16x16x32_bf16 v[112:115], v[180:183], v[188:191], v[112:115]
	v_mfma_f32_16x16x32_bf16 v[100:103], v[172:175], v[196:199], v[100:103]
	v_mfma_f32_16x16x32_bf16 v[96:99], v[180:183], v[196:199], v[96:99]
	v_mfma_f32_16x16x32_bf16 v[84:87], v[172:175], v[204:207], v[84:87]
	v_mfma_f32_16x16x32_bf16 v[80:83], v[180:183], v[204:207], v[80:83]
	v_mfma_f32_16x16x32_bf16 v[68:71], v[172:175], v[212:215], v[68:71]
	v_mfma_f32_16x16x32_bf16 v[64:67], v[180:183], v[212:215], v[64:67]
	s_barrier
	s_setprio 0
	s_add_i32 s28, s55, s33
	v_lshl_add_u64 v[216:217], v[216:217], 0, s[8:9]
	s_mov_b32 m0, s28
	ds_read_b128 v[184:187], v150 offset:49152
	ds_read_b128 v[188:191], v150 offset:50176
	ds_read_b128 v[192:195], v150 offset:51200
	ds_read_b128 v[196:199], v150 offset:52224
	ds_read_b128 v[200:203], v150 offset:53248
	ds_read_b128 v[204:207], v150 offset:54272
	ds_read_b128 v[208:211], v150 offset:55296
	ds_read_b128 v[212:215], v150 offset:56320
	global_load_lds_dwordx4 v[216:217], off
	s_add_i32 m0, s28, 0x2000
	s_add_u32 s26, s26, 0x40080
	v_lshl_add_u64 v[216:217], v[218:219], 0, s[8:9]
	s_addc_u32 s27, s27, 0
	s_add_i32 s28, s56, s33
	global_load_lds_dwordx4 v[216:217], off
	v_lshl_add_u64 v[216:217], s[26:27], 0, v[132:133]
	s_mov_b32 m0, s28
	s_nop 0
	global_load_lds_dwordx4 v[216:217], off
	v_lshl_add_u64 v[216:217], s[26:27], 0, v[128:129]
	s_add_i32 m0, s28, 0x2000
	s_nop 0
	global_load_lds_dwordx4 v[216:217], off
	v_lshl_add_u64 v[216:217], v[220:221], 0, s[8:9]
	s_mov_b32 m0, s42
	s_nop 0
	global_load_lds_dwordx4 v[216:217], off
	v_lshl_add_u64 v[216:217], v[222:223], 0, s[8:9]
	s_mov_b32 m0, s43
	s_nop 0
	global_load_lds_dwordx4 v[216:217], off
	s_waitcnt vmcnt(8)
	s_waitcnt lgkmcnt(0)
	s_setprio 1
	s_barrier
	v_mfma_f32_16x16x32_bf16 v[60:63], v[152:155], v[184:187], v[60:63]
	v_mfma_f32_16x16x32_bf16 v[56:59], v[160:163], v[184:187], v[56:59]
	v_mfma_f32_16x16x32_bf16 v[44:47], v[152:155], v[192:195], v[44:47]
	v_mfma_f32_16x16x32_bf16 v[40:43], v[160:163], v[192:195], v[40:43]
	v_mfma_f32_16x16x32_bf16 v[28:31], v[152:155], v[200:203], v[28:31]
	v_mfma_f32_16x16x32_bf16 v[24:27], v[160:163], v[200:203], v[24:27]
	v_mfma_f32_16x16x32_bf16 v[12:15], v[152:155], v[208:211], v[12:15]
	v_mfma_f32_16x16x32_bf16 v[8:11], v[160:163], v[208:211], v[8:11]
	v_mfma_f32_16x16x32_bf16 v[60:63], v[156:159], v[188:191], v[60:63]
	v_mfma_f32_16x16x32_bf16 v[56:59], v[164:167], v[188:191], v[56:59]
	v_mfma_f32_16x16x32_bf16 v[44:47], v[156:159], v[196:199], v[44:47]
	v_mfma_f32_16x16x32_bf16 v[40:43], v[164:167], v[196:199], v[40:43]
	v_mfma_f32_16x16x32_bf16 v[28:31], v[156:159], v[204:207], v[28:31]
	v_mfma_f32_16x16x32_bf16 v[24:27], v[164:167], v[204:207], v[24:27]
	v_mfma_f32_16x16x32_bf16 v[12:15], v[156:159], v[212:215], v[12:15]
	v_mfma_f32_16x16x32_bf16 v[8:11], v[164:167], v[212:215], v[8:11]
	s_setprio 0
	s_setprio 1
	v_mfma_f32_16x16x32_bf16 v[52:55], v[168:171], v[184:187], v[52:55]
	v_mfma_f32_16x16x32_bf16 v[48:51], v[176:179], v[184:187], v[48:51]
	v_mfma_f32_16x16x32_bf16 v[36:39], v[168:171], v[192:195], v[36:39]
	v_mfma_f32_16x16x32_bf16 v[32:35], v[176:179], v[192:195], v[32:35]
	v_mfma_f32_16x16x32_bf16 v[20:23], v[168:171], v[200:203], v[20:23]
	v_mfma_f32_16x16x32_bf16 v[16:19], v[176:179], v[200:203], v[16:19]
	v_mfma_f32_16x16x32_bf16 v[4:7], v[168:171], v[208:211], v[4:7]
	v_mfma_f32_16x16x32_bf16 v[0:3], v[176:179], v[208:211], v[0:3]
	v_mfma_f32_16x16x32_bf16 v[52:55], v[172:175], v[188:191], v[52:55]
	v_mfma_f32_16x16x32_bf16 v[48:51], v[180:183], v[188:191], v[48:51]
	v_mfma_f32_16x16x32_bf16 v[36:39], v[172:175], v[196:199], v[36:39]
	v_mfma_f32_16x16x32_bf16 v[32:35], v[180:183], v[196:199], v[32:35]
	v_mfma_f32_16x16x32_bf16 v[20:23], v[172:175], v[204:207], v[20:23]
	v_mfma_f32_16x16x32_bf16 v[16:19], v[180:183], v[204:207], v[16:19]
	v_mfma_f32_16x16x32_bf16 v[4:7], v[172:175], v[212:215], v[4:7]
	v_mfma_f32_16x16x32_bf16 v[0:3], v[180:183], v[212:215], v[0:3]
	s_barrier
	s_setprio 0
	s_add_i32 s54, s54, 2
	s_add_u32 s24, s24, 0x100
	s_addc_u32 s25, s25, 0
	s_add_u32 s52, s52, 0x100
	s_addc_u32 s53, s53, 0
	s_cmp_gt_u32 s54, 13
	s_cbranch_scc0 .LBB0_337
	s_and_b64 vcc, exec, s[12:13]
	s_cbranch_vccz .LBB0_340
	s_barrier

; #define PG8_STAGE(bufoff, gbase, voff) do { _Pragma("unroll") for (int _i = 0; _i < 2; ++_i) \
;         __builtin_amdgcn_global_load_lds((const unsigned*)((const char*)(gbase) + (voff)[_i]), (PG8_LAS unsigned*)(lds + (bufoff) + ldsw + _i * 8192), 16, 0, 0); } while (0)
; #define PG8_LDA(dst, b, h) do { _Pragma("unroll") for (int m = 0; m < 4; ++m) _Pragma("unroll") for (int k = 0; k < 2; ++k) dst[m][k] = *(const PG8_LAS bf16x8*)(lds + PG8_SA(b, h) + aoff + m * 2048 + k * 1024); } while (0)
; #define PG8_LDB(dst, b, h) do { _Pragma("unroll") for (int n = 0; n < 2; ++n) _Pragma("unroll") for (int k = 0; k < 2; ++k) dst[n][k] = *(const PG8_LAS bf16x8*)(lds + PG8_SB(b, h) + boff + n * 2048 + k * 1024); } while (0)
; #define PG8_MMA(ai, bj, At, Bt) do { __builtin_amdgcn_s_setprio(1); _Pragma("unroll") for (int m = 0; m < 4; ++m) _Pragma("unroll") for (int n = 0; n < 2; ++n) _Pragma("unroll") for (int k = 0; k < 2; ++k) \
;         acc[ai][bj][m][n] = __builtin_amdgcn_mfma_f32_16x16x32_bf16(Bt[n][k], At[m][k], acc[ai][bj][m][n], 0, 0, 0); __builtin_amdgcn_s_setprio(0); } while (0)
; #define PG8_WAIT_V(n) asm volatile("s_waitcnt vmcnt(" #n ")" ::: "memory")
; #define PG8_WAIT_L(n) asm volatile("s_waitcnt lgkmcnt(" #n ")" ::: "memory")
; template <class Epi, class Sched, bool ALIGN_EPI = false, bool SP2 = false>
; __device__ __forceinline__ void gemm_phase(PG8_LAS unsigned char* lds, const Gemm g, const Sched& S, const Epi& E) {
;     ...
;             const bool last = (t == nt - 2);
;             const char* a1 = cA + (size_t)(t + 1) * kstep;
;             const char* a2 = last ? nA : cA + (size_t)(t + 2) * kstep; const char* b2 = last ? nB : cB + (size_t)(t + 2) * kstep;
;             const char* a3 = a2 + kstep; const char* b3 = b2 + kstep;
;             if (last && has_next) S.a_ready(nxt, ui + 1);
;             if constexpr (SP2) {
;             PG8_LDB(B0, 0, 0); PG8_LDB(B1, 0, 1); PG8_SCHED; PG8_LDA(At, 0, 0); PG8_STAGE(PG8_SA(1, 1), a1 + hstep, voffA);
;             PG8_WAIT_V(8); PG8_WAIT_L(0); PG8_BAR; PG8_MMA(0, 0, At, B0); PG8_MMA(0, 1, At, B1); PG8_BAR; PG8_SCHED;
;             PG8_LDA(At, 0, 1); PG8_STAGE(PG8_SB(0, 0), b2, voffB); PG8_STAGE(PG8_SB(0, 1), b2 + hstep, voffB); PG8_STAGE(PG8_SA(0, 0), a2, voffA);
;             PG8_WAIT_V(8); PG8_WAIT_L(0); PG8_BAR; PG8_MMA(1, 0, At, B0); PG8_MMA(1, 1, At, B1); PG8_BAR; PG8_SCHED;
.LBB0_417:
	s_add_u32 s24, s24, 0xb0080
	s_addc_u32 s25, s25, 0
	s_add_u32 s51, s26, 0x100
	s_addc_u32 s52, s27, 0
	s_mov_b32 s53, -2
	s_waitcnt lgkmcnt(0)
	s_add_u32 s26, s24, 0xfff50080
	s_addc_u32 s27, s25, -1
	s_cmp_eq_u32 s53, 40
	s_cselect_b32 s29, s7, s27
	s_cselect_b32 s28, s6, s26
	s_cselect_b32 s27, s23, s52
	s_cselect_b32 s26, s22, s51
	v_lshl_add_u64 v[204:205], s[24:25], 0, v[200:201]
	s_add_i32 m0, s35, 0xc000
	global_load_lds_dwordx4 v[204:205], off
	v_lshl_add_u64 v[204:205], s[24:25], 0, v[202:203]
	s_add_i32 m0, s35, 0xe000
	s_nop 0
	global_load_lds_dwordx4 v[204:205], off
	s_waitcnt vmcnt(8)
	s_waitcnt lgkmcnt(0)
	s_setprio 1
	s_barrier
	v_mfma_f32_16x16x32_bf16 v[132:135], v[120:123], v[160:163], 0
	v_mfma_f32_16x16x32_bf16 v[124:127], v[136:139], v[160:163], 0
	v_mfma_f32_16x16x32_bf16 v[108:111], v[120:123], v[168:171], 0
	v_mfma_f32_16x16x32_bf16 v[104:107], v[136:139], v[168:171], 0
	v_mfma_f32_16x16x32_bf16 v[92:95], v[120:123], v[176:179], 0
	v_mfma_f32_16x16x32_bf16 v[88:91], v[136:139], v[176:179], 0
	v_mfma_f32_16x16x32_bf16 v[76:79], v[120:123], v[184:187], 0
	v_mfma_f32_16x16x32_bf16 v[72:75], v[136:139], v[184:187], 0
	v_mfma_f32_16x16x32_bf16 v[132:135], v[128:131], v[164:167], v[132:135]
	v_mfma_f32_16x16x32_bf16 v[124:127], v[140:143], v[164:167], v[124:127]
	v_mfma_f32_16x16x32_bf16 v[108:111], v[128:131], v[172:175], v[108:111]
	v_mfma_f32_16x16x32_bf16 v[104:107], v[140:143], v[172:175], v[104:107]
	v_mfma_f32_16x16x32_bf16 v[92:95], v[128:131], v[180:183], v[92:95]
	v_mfma_f32_16x16x32_bf16 v[88:91], v[140:143], v[180:183], v[88:91]
	v_mfma_f32_16x16x32_bf16 v[76:79], v[128:131], v[188:191], v[76:79]
	v_mfma_f32_16x16x32_bf16 v[72:75], v[140:143], v[188:191], v[72:75]
	s_setprio 0
	s_setprio 1
	v_mfma_f32_16x16x32_bf16 v[116:119], v[144:147], v[160:163], 0
	v_mfma_f32_16x16x32_bf16 v[112:115], v[152:155], v[160:163], 0
	v_mfma_f32_16x16x32_bf16 v[100:103], v[144:147], v[168:171], 0
	v_mfma_f32_16x16x32_bf16 v[96:99], v[152:155], v[168:171], 0
	v_mfma_f32_16x16x32_bf16 v[84:87], v[144:147], v[176:179], 0
	v_mfma_f32_16x16x32_bf16 v[80:83], v[152:155], v[176:179], 0
	v_mfma_f32_16x16x32_bf16 v[68:71], v[144:147], v[184:187], 0
	v_mfma_f32_16x16x32_bf16 v[64:67], v[152:155], v[184:187], 0
	v_mfma_f32_16x16x32_bf16 v[116:119], v[148:151], v[164:167], v[116:119]
	v_mfma_f32_16x16x32_bf16 v[112:115], v[156:159], v[164:167], v[112:115]
	v_mfma_f32_16x16x32_bf16 v[100:103], v[148:151], v[172:175], v[100:103]
	v_mfma_f32_16x16x32_bf16 v[96:99], v[156:159], v[172:175], v[96:99]
	v_mfma_f32_16x16x32_bf16 v[84:87], v[148:151], v[180:183], v[84:87]
	v_mfma_f32_16x16x32_bf16 v[80:83], v[156:159], v[180:183], v[80:83]
	v_mfma_f32_16x16x32_bf16 v[68:71], v[148:151], v[188:191], v[68:71]
	v_mfma_f32_16x16x32_bf16 v[64:67], v[156:159], v[188:191], v[64:67]
	s_barrier
	s_setprio 0
	s_add_i32 s54, s45, s34
	v_lshl_add_u64 v[204:205], s[26:27], 0, v[194:195]
	s_mov_b32 m0, s54
	ds_read_b128 v[160:163], v247 offset:16384
	ds_read_b128 v[164:167], v247 offset:17408
	ds_read_b128 v[168:171], v247 offset:18432
	ds_read_b128 v[172:175], v247 offset:19456
	ds_read_b128 v[176:179], v247 offset:20480
	ds_read_b128 v[180:183], v247 offset:21504
	ds_read_b128 v[184:187], v247 offset:22528
	ds_read_b128 v[188:191], v247 offset:23552
	global_load_lds_dwordx4 v[204:205], off
	s_add_i32 m0, s54, 0x2000
	s_add_u32 s54, s26, 0xb0000
	v_lshl_add_u64 v[206:207], s[26:27], 0, v[198:199]
	s_addc_u32 s55, s27, 0
	s_add_i32 s56, s46, s34
	global_load_lds_dwordx4 v[206:207], off
	v_lshl_add_u64 v[208:209], s[54:55], 0, v[194:195]
	s_mov_b32 m0, s56
	v_lshl_add_u64 v[210:211], s[28:29], 0, v[196:197]
	global_load_lds_dwordx4 v[208:209], off
	v_lshl_add_u64 v[208:209], s[54:55], 0, v[198:199]
	s_add_i32 m0, s56, 0x2000
	s_nop 0
	global_load_lds_dwordx4 v[208:209], off
	v_lshl_add_u64 v[208:209], s[28:29], 0, v[192:193]
	s_mov_b32 m0, s35
	s_nop 0
	global_load_lds_dwordx4 v[208:209], off
	s_mov_b32 m0, s36
	s_nop 0
	global_load_lds_dwordx4 v[210:211], off
	s_waitcnt vmcnt(8)
	s_waitcnt lgkmcnt(0)
	s_setprio 1
	s_barrier
	v_mfma_f32_16x16x32_bf16 v[60:63], v[120:123], v[160:163], 0
	v_mfma_f32_16x16x32_bf16 v[56:59], v[136:139], v[160:163], 0
	v_mfma_f32_16x16x32_bf16 v[44:47], v[120:123], v[168:171], 0
	v_mfma_f32_16x16x32_bf16 v[40:43], v[136:139], v[168:171], 0
	v_mfma_f32_16x16x32_bf16 v[28:31], v[120:123], v[176:179], 0
	v_mfma_f32_16x16x32_bf16 v[24:27], v[136:139], v[176:179], 0
	v_mfma_f32_16x16x32_bf16 v[12:15], v[120:123], v[184:187], 0
	v_mfma_f32_16x16x32_bf16 v[8:11], v[136:139], v[184:187], 0
	v_mfma_f32_16x16x32_bf16 v[60:63], v[128:131], v[164:167], v[60:63]
	v_mfma_f32_16x16x32_bf16 v[56:59], v[140:143], v[164:167], v[56:59]
	v_mfma_f32_16x16x32_bf16 v[44:47], v[128:131], v[172:175], v[44:47]
	v_mfma_f32_16x16x32_bf16 v[40:43], v[140:143], v[172:175], v[40:43]
	v_mfma_f32_16x16x32_bf16 v[28:31], v[128:131], v[180:183], v[28:31]
	v_mfma_f32_16x16x32_bf16 v[24:27], v[140:143], v[180:183], v[24:27]
	v_mfma_f32_16x16x32_bf16 v[12:15], v[128:131], v[188:191], v[12:15]
	v_mfma_f32_16x16x32_bf16 v[8:11], v[140:143], v[188:191], v[8:11]
	s_setprio 0
	s_setprio 1
	v_mfma_f32_16x16x32_bf16 v[52:55], v[144:147], v[160:163], 0
	v_mfma_f32_16x16x32_bf16 v[48:51], v[152:155], v[160:163], 0
	v_mfma_f32_16x16x32_bf16 v[36:39], v[144:147], v[168:171], 0
	v_mfma_f32_16x16x32_bf16 v[32:35], v[152:155], v[168:171], 0
	v_mfma_f32_16x16x32_bf16 v[20:23], v[144:147], v[176:179], 0
	v_mfma_f32_16x16x32_bf16 v[16:19], v[152:155], v[176:179], 0
	v_mfma_f32_16x16x32_bf16 v[4:7], v[144:147], v[184:187], 0
	v_mfma_f32_16x16x32_bf16 v[0:3], v[152:155], v[184:187], 0
	v_mfma_f32_16x16x32_bf16 v[52:55], v[148:151], v[164:167], v[52:55]
	v_mfma_f32_16x16x32_bf16 v[48:51], v[156:159], v[164:167], v[48:51]
	v_mfma_f32_16x16x32_bf16 v[36:39], v[148:151], v[172:175], v[36:39]
	v_mfma_f32_16x16x32_bf16 v[32:35], v[156:159], v[172:175], v[32:35]
	v_mfma_f32_16x16x32_bf16 v[20:23], v[148:151], v[180:183], v[20:23]
	v_mfma_f32_16x16x32_bf16 v[16:19], v[156:159], v[180:183], v[16:19]
	v_mfma_f32_16x16x32_bf16 v[4:7], v[148:151], v[188:191], v[4:7]
	v_mfma_f32_16x16x32_bf16 v[0:3], v[156:159], v[188:191], v[0:3]
	s_barrier
; #define PG8_STAGE(bufoff, gbase, voff) do { _Pragma("unroll") for (int _i = 0; _i < 2; ++_i) \
;         __builtin_amdgcn_global_load_lds((const unsigned*)((const char*)(gbase) + (voff)[_i]), (PG8_LAS unsigned*)(lds + (bufoff) + ldsw + _i * 8192), 16, 0, 0); } while (0)
; #define PG8_LDA(dst, b, h) do { _Pragma("unroll") for (int m = 0; m < 4; ++m) _Pragma("unroll") for (int k = 0; k < 2; ++k) dst[m][k] = *(const PG8_LAS bf16x8*)(lds + PG8_SA(b, h) + aoff + m * 2048 + k * 1024); } while (0)
; #define PG8_LDB(dst, b, h) do { _Pragma("unroll") for (int n = 0; n < 2; ++n) _Pragma("unroll") for (int k = 0; k < 2; ++k) dst[n][k] = *(const PG8_LAS bf16x8*)(lds + PG8_SB(b, h) + boff + n * 2048 + k * 1024); } while (0)
; #define PG8_MMA(ai, bj, At, Bt) do { __builtin_amdgcn_s_setprio(1); _Pragma("unroll") for (int m = 0; m < 4; ++m) _Pragma("unroll") for (int n = 0; n < 2; ++n) _Pragma("unroll") for (int k = 0; k < 2; ++k) \
;         acc[ai][bj][m][n] = __builtin_amdgcn_mfma_f32_16x16x32_bf16(Bt[n][k], At[m][k], acc[ai][bj][m][n], 0, 0, 0); __builtin_amdgcn_s_setprio(0); } while (0)
; #define PG8_WAIT_V(n) asm volatile("s_waitcnt vmcnt(" #n ")" ::: "memory")
; #define PG8_WAIT_L(n) asm volatile("s_waitcnt lgkmcnt(" #n ")" ::: "memory")
; #define PG8_BAR __builtin_amdgcn_s_barrier()
; #define PG8_SCHED __builtin_amdgcn_sched_barrier(0)
; template <class Epi, class Sched, bool ALIGN_EPI = false, bool SP2 = false>
; __device__ __forceinline__ void gemm_phase(PG8_LAS unsigned char* lds, const Gemm g, const Sched& S, const Epi& E) {
;     ...
;             PG8_WAIT_V(8); PG8_WAIT_L(0); PG8_BAR; PG8_MMA(1, 0, At, B0); PG8_MMA(1, 1, At, B1); PG8_BAR; PG8_SCHED;
;             PG8_LDB(B0, 1, 0); PG8_LDB(B1, 1, 1); PG8_SCHED; PG8_LDA(At, 1, 0); PG8_STAGE(PG8_SA(0, 1), a2 + hstep, voffA);
;             PG8_WAIT_V(8); PG8_WAIT_L(0); PG8_BAR; PG8_MMA(0, 0, At, B0); PG8_MMA(0, 1, At, B1); PG8_BAR; PG8_SCHED;
;             PG8_LDA(At, 1, 1); PG8_STAGE(PG8_SB(1, 0), b3, voffB); PG8_STAGE(PG8_SB(1, 1), b3 + hstep, voffB); PG8_STAGE(PG8_SA(1, 0), a3, voffA);
	s_setprio 0
	s_add_i32 s54, 0, 0x18000
	s_add_i32 s55, 0, 0x1c000
	v_add_u32_e32 v140, s54, v243
	v_add_u32_e32 v156, s55, v243
	ds_read_b128 v[120:123], v140
	ds_read_b128 v[128:131], v140 offset:1024
	ds_read_b128 v[136:139], v140 offset:2048
	ds_read_b128 v[140:143], v140 offset:3072
	ds_read_b128 v[144:147], v156
	ds_read_b128 v[148:151], v156 offset:1024
	ds_read_b128 v[152:155], v156 offset:2048
	ds_read_b128 v[156:159], v156 offset:3072
	s_add_u32 s28, s28, 0xb0000
	s_addc_u32 s29, s29, 0
	s_mov_b32 m0, s37
	v_lshl_add_u64 v[212:213], s[28:29], 0, v[192:193]
	ds_read_b128 v[160:163], v247 offset:32768
	ds_read_b128 v[164:167], v247 offset:33792
	ds_read_b128 v[168:171], v247 offset:34816
	ds_read_b128 v[172:175], v247 offset:35840
	ds_read_b128 v[176:179], v247 offset:36864
	ds_read_b128 v[180:183], v247 offset:37888
	ds_read_b128 v[184:187], v247 offset:38912
	ds_read_b128 v[188:191], v247 offset:39936
	global_load_lds_dwordx4 v[212:213], off
	v_lshl_add_u64 v[212:213], s[28:29], 0, v[196:197]
	s_mov_b32 m0, s38
	s_nop 0
	global_load_lds_dwordx4 v[212:213], off
	s_waitcnt vmcnt(8)
	s_waitcnt lgkmcnt(0)
	s_setprio 1
	s_barrier
	v_mfma_f32_16x16x32_bf16 v[132:135], v[120:123], v[160:163], v[132:135]
	v_mfma_f32_16x16x32_bf16 v[124:127], v[136:139], v[160:163], v[124:127]
	v_mfma_f32_16x16x32_bf16 v[108:111], v[120:123], v[168:171], v[108:111]
	v_mfma_f32_16x16x32_bf16 v[104:107], v[136:139], v[168:171], v[104:107]
	v_mfma_f32_16x16x32_bf16 v[92:95], v[120:123], v[176:179], v[92:95]
	v_mfma_f32_16x16x32_bf16 v[88:91], v[136:139], v[176:179], v[88:91]
	v_mfma_f32_16x16x32_bf16 v[76:79], v[120:123], v[184:187], v[76:79]
	v_mfma_f32_16x16x32_bf16 v[72:75], v[136:139], v[184:187], v[72:75]
	v_mfma_f32_16x16x32_bf16 v[132:135], v[128:131], v[164:167], v[132:135]
	v_mfma_f32_16x16x32_bf16 v[124:127], v[140:143], v[164:167], v[124:127]
	v_mfma_f32_16x16x32_bf16 v[108:111], v[128:131], v[172:175], v[108:111]
	v_mfma_f32_16x16x32_bf16 v[104:107], v[140:143], v[172:175], v[104:107]
	v_mfma_f32_16x16x32_bf16 v[92:95], v[128:131], v[180:183], v[92:95]
	v_mfma_f32_16x16x32_bf16 v[88:91], v[140:143], v[180:183], v[88:91]
	v_mfma_f32_16x16x32_bf16 v[76:79], v[128:131], v[188:191], v[76:79]
	v_mfma_f32_16x16x32_bf16 v[72:75], v[140:143], v[188:191], v[72:75]
	s_setprio 0
	s_setprio 1
	v_mfma_f32_16x16x32_bf16 v[116:119], v[144:147], v[160:163], v[116:119]
	v_mfma_f32_16x16x32_bf16 v[112:115], v[152:155], v[160:163], v[112:115]
	v_mfma_f32_16x16x32_bf16 v[100:103], v[144:147], v[168:171], v[100:103]
	v_mfma_f32_16x16x32_bf16 v[96:99], v[152:155], v[168:171], v[96:99]
	v_mfma_f32_16x16x32_bf16 v[84:87], v[144:147], v[176:179], v[84:87]
	v_mfma_f32_16x16x32_bf16 v[80:83], v[152:155], v[176:179], v[80:83]
	v_mfma_f32_16x16x32_bf16 v[68:71], v[144:147], v[184:187], v[68:71]
	v_mfma_f32_16x16x32_bf16 v[64:67], v[152:155], v[184:187], v[64:67]
	v_mfma_f32_16x16x32_bf16 v[116:119], v[148:151], v[164:167], v[116:119]
	v_mfma_f32_16x16x32_bf16 v[112:115], v[156:159], v[164:167], v[112:115]
	v_mfma_f32_16x16x32_bf16 v[100:103], v[148:151], v[172:175], v[100:103]
	v_mfma_f32_16x16x32_bf16 v[96:99], v[156:159], v[172:175], v[96:99]
	v_mfma_f32_16x16x32_bf16 v[84:87], v[148:151], v[180:183], v[84:87]
	v_mfma_f32_16x16x32_bf16 v[80:83], v[156:159], v[180:183], v[80:83]
	v_mfma_f32_16x16x32_bf16 v[68:71], v[148:151], v[188:191], v[68:71]
	v_mfma_f32_16x16x32_bf16 v[64:67], v[156:159], v[188:191], v[64:67]
	s_barrier
	s_setprio 0
	s_add_i32 s28, s54, s34
	v_lshl_add_u64 v[204:205], v[204:205], 0, s[18:19]
	s_mov_b32 m0, s28
	ds_read_b128 v[160:163], v247 offset:49152
	ds_read_b128 v[164:167], v247 offset:50176
	ds_read_b128 v[168:171], v247 offset:51200
	ds_read_b128 v[172:175], v247 offset:52224
	ds_read_b128 v[176:179], v247 offset:53248
	ds_read_b128 v[180:183], v247 offset:54272
	ds_read_b128 v[184:187], v247 offset:55296
	ds_read_b128 v[188:191], v247 offset:56320
	global_load_lds_dwordx4 v[204:205], off
	s_add_i32 m0, s28, 0x2000
	s_add_u32 s26, s26, 0xb0080
	v_lshl_add_u64 v[204:205], v[206:207], 0, s[18:19]
	s_addc_u32 s27, s27, 0
	s_add_i32 s28, s55, s34
	global_load_lds_dwordx4 v[204:205], off
	v_lshl_add_u64 v[204:205], s[26:27], 0, v[194:195]
	s_mov_b32 m0, s28
	s_nop 0
	global_load_lds_dwordx4 v[204:205], off
	v_lshl_add_u64 v[204:205], s[26:27], 0, v[198:199]
	s_add_i32 m0, s28, 0x2000
	s_nop 0
	global_load_lds_dwordx4 v[204:205], off
	v_lshl_add_u64 v[204:205], v[208:209], 0, s[18:19]
	s_mov_b32 m0, s40
	s_nop 0
	global_load_lds_dwordx4 v[204:205], off
	v_lshl_add_u64 v[204:205], v[210:211], 0, s[18:19]
	s_mov_b32 m0, s41
	s_nop 0
	global_load_lds_dwordx4 v[204:205], off
	s_waitcnt vmcnt(8)
	s_waitcnt lgkmcnt(0)
	s_setprio 1
	s_barrier
; #define PG8_STAGE(bufoff, gbase, voff) do { _Pragma("unroll") for (int _i = 0; _i < 2; ++_i) \
;         __builtin_amdgcn_global_load_lds((const unsigned*)((const char*)(gbase) + (voff)[_i]), (PG8_LAS unsigned*)(lds + (bufoff) + ldsw + _i * 8192), 16, 0, 0); } while (0)
; #define PG8_LDA(dst, b, h) do { _Pragma("unroll") for (int m = 0; m < 4; ++m) _Pragma("unroll") for (int k = 0; k < 2; ++k) dst[m][k] = *(const PG8_LAS bf16x8*)(lds + PG8_SA(b, h) + aoff + m * 2048 + k * 1024); } while (0)
; #define PG8_LDB(dst, b, h) do { _Pragma("unroll") for (int n = 0; n < 2; ++n) _Pragma("unroll") for (int k = 0; k < 2; ++k) dst[n][k] = *(const PG8_LAS bf16x8*)(lds + PG8_SB(b, h) + boff + n * 2048 + k * 1024); } while (0)
; template <class Epi, class Sched, bool ALIGN_EPI = false, bool SP2 = false>
; __device__ __forceinline__ void gemm_phase(PG8_LAS unsigned char* lds, const Gemm g, const Sched& S, const Epi& E) {
;     ...
;         for (int t = 0; t < nt; t += 2) {
;             const bool last = (t == nt - 2);
;             const char* a1 = cA + (size_t)(t + 1) * kstep;
;             const char* a2 = last ? nA : cA + (size_t)(t + 2) * kstep; const char* b2 = last ? nB : cB + (size_t)(t + 2) * kstep;
;             const char* a3 = a2 + kstep; const char* b3 = b2 + kstep;
;             if (last && has_next) S.a_ready(nxt, ui + 1);
;             if constexpr (SP2) {
;             PG8_LDB(B0, 0, 0); PG8_LDB(B1, 0, 1); PG8_SCHED; PG8_LDA(At, 0, 0); PG8_STAGE(PG8_SA(1, 1), a1 + hstep, voffA);
;             PG8_WAIT_V(8); PG8_WAIT_L(0); PG8_BAR; PG8_MMA(0, 0, At, B0); PG8_MMA(0, 1, At, B1); PG8_BAR; PG8_SCHED;
;             PG8_LDA(At, 0, 1); PG8_STAGE(PG8_SB(0, 0), b2, voffB); PG8_STAGE(PG8_SB(0, 1), b2 + hstep, voffB); PG8_STAGE(PG8_SA(0, 0), a2, voffA);
;             PG8_WAIT_V(8); PG8_WAIT_L(0); PG8_BAR; PG8_MMA(1, 0, At, B0); PG8_MMA(1, 1, At, B1); PG8_BAR; PG8_SCHED;
;             PG8_LDB(B0, 1, 0); PG8_LDB(B1, 1, 1); PG8_SCHED; PG8_LDA(At, 1, 0); PG8_STAGE(PG8_SA(0, 1), a2 + hstep, voffA);
;             PG8_WAIT_V(8); PG8_WAIT_L(0); PG8_BAR; PG8_MMA(0, 0, At, B0); PG8_MMA(0, 1, At, B1); PG8_BAR; PG8_SCHED;
;             PG8_LDA(At, 1, 1); PG8_STAGE(PG8_SB(1, 0), b3, voffB); PG8_STAGE(PG8_SB(1, 1), b3 + hstep, voffB); PG8_STAGE(PG8_SA(1, 0), a3, voffA);
;             PG8_WAIT_V(8); PG8_WAIT_L(0); PG8_BAR; PG8_MMA(1, 0, At, B0); PG8_MMA(1, 1, At, B1); PG8_BAR; PG8_SCHED;
	v_mfma_f32_16x16x32_bf16 v[60:63], v[120:123], v[160:163], v[60:63]
	v_mfma_f32_16x16x32_bf16 v[56:59], v[136:139], v[160:163], v[56:59]
	v_mfma_f32_16x16x32_bf16 v[44:47], v[120:123], v[168:171], v[44:47]
	v_mfma_f32_16x16x32_bf16 v[40:43], v[136:139], v[168:171], v[40:43]
	v_mfma_f32_16x16x32_bf16 v[28:31], v[120:123], v[176:179], v[28:31]
	v_mfma_f32_16x16x32_bf16 v[24:27], v[136:139], v[176:179], v[24:27]
	v_mfma_f32_16x16x32_bf16 v[12:15], v[120:123], v[184:187], v[12:15]
	v_mfma_f32_16x16x32_bf16 v[8:11], v[136:139], v[184:187], v[8:11]
	v_mfma_f32_16x16x32_bf16 v[60:63], v[128:131], v[164:167], v[60:63]
	v_mfma_f32_16x16x32_bf16 v[56:59], v[140:143], v[164:167], v[56:59]
	v_mfma_f32_16x16x32_bf16 v[44:47], v[128:131], v[172:175], v[44:47]
	v_mfma_f32_16x16x32_bf16 v[40:43], v[140:143], v[172:175], v[40:43]
	v_mfma_f32_16x16x32_bf16 v[28:31], v[128:131], v[180:183], v[28:31]
	v_mfma_f32_16x16x32_bf16 v[24:27], v[140:143], v[180:183], v[24:27]
	v_mfma_f32_16x16x32_bf16 v[12:15], v[128:131], v[188:191], v[12:15]
	v_mfma_f32_16x16x32_bf16 v[8:11], v[140:143], v[188:191], v[8:11]
	s_setprio 0
	s_setprio 1
	v_mfma_f32_16x16x32_bf16 v[52:55], v[144:147], v[160:163], v[52:55]
	v_mfma_f32_16x16x32_bf16 v[48:51], v[152:155], v[160:163], v[48:51]
	v_mfma_f32_16x16x32_bf16 v[36:39], v[144:147], v[168:171], v[36:39]
	v_mfma_f32_16x16x32_bf16 v[32:35], v[152:155], v[168:171], v[32:35]
	v_mfma_f32_16x16x32_bf16 v[20:23], v[144:147], v[176:179], v[20:23]
	v_mfma_f32_16x16x32_bf16 v[16:19], v[152:155], v[176:179], v[16:19]
	v_mfma_f32_16x16x32_bf16 v[4:7], v[144:147], v[184:187], v[4:7]
	v_mfma_f32_16x16x32_bf16 v[0:3], v[152:155], v[184:187], v[0:3]
	v_mfma_f32_16x16x32_bf16 v[52:55], v[148:151], v[164:167], v[52:55]
	v_mfma_f32_16x16x32_bf16 v[48:51], v[156:159], v[164:167], v[48:51]
	v_mfma_f32_16x16x32_bf16 v[36:39], v[148:151], v[172:175], v[36:39]
	v_mfma_f32_16x16x32_bf16 v[32:35], v[156:159], v[172:175], v[32:35]
	v_mfma_f32_16x16x32_bf16 v[20:23], v[148:151], v[180:183], v[20:23]
	v_mfma_f32_16x16x32_bf16 v[16:19], v[156:159], v[180:183], v[16:19]
	v_mfma_f32_16x16x32_bf16 v[4:7], v[148:151], v[188:191], v[4:7]
	v_mfma_f32_16x16x32_bf16 v[0:3], v[156:159], v[188:191], v[0:3]
	s_barrier
	s_setprio 0
	s_add_i32 s53, s53, 2
	s_add_u32 s24, s24, 0x100
	s_addc_u32 s25, s25, 0
	s_add_u32 s51, s51, 0x100
	s_addc_u32 s52, s52, 0
	s_cmp_gt_u32 s53, 41
.LBB0_418:
	ds_read_b128 v[120:123], v245
	ds_read_b128 v[128:131], v245 offset:1024
	ds_read_b128 v[136:139], v245 offset:2048
	ds_read_b128 v[140:143], v245 offset:3072
	ds_read_b128 v[144:147], v246
	ds_read_b128 v[148:151], v246 offset:1024
	ds_read_b128 v[152:155], v246 offset:2048
	ds_read_b128 v[156:159], v246 offset:3072
	s_add_u32 s26, s24, 0xfff50080
	s_addc_u32 s27, s25, -1
	s_cmp_eq_u32 s53, 40
	s_cselect_b32 s29, s7, s27
	s_cselect_b32 s28, s6, s26
	s_cselect_b32 s27, s23, s52
	s_cselect_b32 s26, s22, s51
	v_lshl_add_u64 v[204:205], s[24:25], 0, v[200:201]
	s_add_i32 m0, s35, 0xc000
	ds_read_b128 v[160:163], v247
	ds_read_b128 v[164:167], v247 offset:1024
	ds_read_b128 v[168:171], v247 offset:2048
	ds_read_b128 v[172:175], v247 offset:3072
	ds_read_b128 v[176:179], v247 offset:4096
	ds_read_b128 v[180:183], v247 offset:5120
	ds_read_b128 v[184:187], v247 offset:6144
	ds_read_b128 v[188:191], v247 offset:7168
	global_load_lds_dwordx4 v[204:205], off
	v_lshl_add_u64 v[204:205], s[24:25], 0, v[202:203]
	s_add_i32 m0, s35, 0xe000
	s_nop 0
	global_load_lds_dwordx4 v[204:205], off
	s_waitcnt vmcnt(8)
	s_waitcnt lgkmcnt(0)
	s_setprio 1
	s_barrier
	v_mfma_f32_16x16x32_bf16 v[132:135], v[120:123], v[160:163], v[132:135]
	v_mfma_f32_16x16x32_bf16 v[124:127], v[136:139], v[160:163], v[124:127]
	v_mfma_f32_16x16x32_bf16 v[108:111], v[120:123], v[168:171], v[108:111]
	v_mfma_f32_16x16x32_bf16 v[104:107], v[136:139], v[168:171], v[104:107]
	v_mfma_f32_16x16x32_bf16 v[92:95], v[120:123], v[176:179], v[92:95]
	v_mfma_f32_16x16x32_bf16 v[88:91], v[136:139], v[176:179], v[88:91]
	v_mfma_f32_16x16x32_bf16 v[76:79], v[120:123], v[184:187], v[76:79]
	v_mfma_f32_16x16x32_bf16 v[72:75], v[136:139], v[184:187], v[72:75]
	v_mfma_f32_16x16x32_bf16 v[132:135], v[128:131], v[164:167], v[132:135]
	v_mfma_f32_16x16x32_bf16 v[124:127], v[140:143], v[164:167], v[124:127]
	v_mfma_f32_16x16x32_bf16 v[108:111], v[128:131], v[172:175], v[108:111]
	v_mfma_f32_16x16x32_bf16 v[104:107], v[140:143], v[172:175], v[104:107]
	v_mfma_f32_16x16x32_bf16 v[92:95], v[128:131], v[180:183], v[92:95]
	v_mfma_f32_16x16x32_bf16 v[88:91], v[140:143], v[180:183], v[88:91]
	v_mfma_f32_16x16x32_bf16 v[76:79], v[128:131], v[188:191], v[76:79]
	v_mfma_f32_16x16x32_bf16 v[72:75], v[140:143], v[188:191], v[72:75]
	s_setprio 0
	s_setprio 1
	v_mfma_f32_16x16x32_bf16 v[116:119], v[144:147], v[160:163], v[116:119]
	v_mfma_f32_16x16x32_bf16 v[112:115], v[152:155], v[160:163], v[112:115]
	v_mfma_f32_16x16x32_bf16 v[100:103], v[144:147], v[168:171], v[100:103]
	v_mfma_f32_16x16x32_bf16 v[96:99], v[152:155], v[168:171], v[96:99]
	v_mfma_f32_16x16x32_bf16 v[84:87], v[144:147], v[176:179], v[84:87]
	v_mfma_f32_16x16x32_bf16 v[80:83], v[152:155], v[176:179], v[80:83]
	v_mfma_f32_16x16x32_bf16 v[68:71], v[144:147], v[184:187], v[68:71]
	v_mfma_f32_16x16x32_bf16 v[64:67], v[152:155], v[184:187], v[64:67]
	v_mfma_f32_16x16x32_bf16 v[116:119], v[148:151], v[164:167], v[116:119]
	v_mfma_f32_16x16x32_bf16 v[112:115], v[156:159], v[164:167], v[112:115]
	v_mfma_f32_16x16x32_bf16 v[100:103], v[148:151], v[172:175], v[100:103]
	v_mfma_f32_16x16x32_bf16 v[96:99], v[156:159], v[172:175], v[96:99]
	v_mfma_f32_16x16x32_bf16 v[84:87], v[148:151], v[180:183], v[84:87]
	v_mfma_f32_16x16x32_bf16 v[80:83], v[156:159], v[180:183], v[80:83]
	v_mfma_f32_16x16x32_bf16 v[68:71], v[148:151], v[188:191], v[68:71]
	v_mfma_f32_16x16x32_bf16 v[64:67], v[156:159], v[188:191], v[64:67]
	s_barrier
; #define PG8_STAGE(bufoff, gbase, voff) do { _Pragma("unroll") for (int _i = 0; _i < 2; ++_i) \
;         __builtin_amdgcn_global_load_lds((const unsigned*)((const char*)(gbase) + (voff)[_i]), (PG8_LAS unsigned*)(lds + (bufoff) + ldsw + _i * 8192), 16, 0, 0); } while (0)
; #define PG8_LDA(dst, b, h) do { _Pragma("unroll") for (int m = 0; m < 4; ++m) _Pragma("unroll") for (int k = 0; k < 2; ++k) dst[m][k] = *(const PG8_LAS bf16x8*)(lds + PG8_SA(b, h) + aoff + m * 2048 + k * 1024); } while (0)
; #define PG8_LDB(dst, b, h) do { _Pragma("unroll") for (int n = 0; n < 2; ++n) _Pragma("unroll") for (int k = 0; k < 2; ++k) dst[n][k] = *(const PG8_LAS bf16x8*)(lds + PG8_SB(b, h) + boff + n * 2048 + k * 1024); } while (0)
; #define PG8_MMA(ai, bj, At, Bt) do { __builtin_amdgcn_s_setprio(1); _Pragma("unroll") for (int m = 0; m < 4; ++m) _Pragma("unroll") for (int n = 0; n < 2; ++n) _Pragma("unroll") for (int k = 0; k < 2; ++k) \
;         acc[ai][bj][m][n] = __builtin_amdgcn_mfma_f32_16x16x32_bf16(Bt[n][k], At[m][k], acc[ai][bj][m][n], 0, 0, 0); __builtin_amdgcn_s_setprio(0); } while (0)
; #define PG8_WAIT_V(n) asm volatile("s_waitcnt vmcnt(" #n ")" ::: "memory")
; template <class Epi, class Sched, bool ALIGN_EPI = false, bool SP2 = false>
; __device__ __forceinline__ void gemm_phase(PG8_LAS unsigned char* lds, const Gemm g, const Sched& S, const Epi& E) {
;     ...
;             PG8_LDB(B0, 0, 0); PG8_LDB(B1, 0, 1); PG8_SCHED; PG8_LDA(At, 0, 0); PG8_STAGE(PG8_SA(1, 1), a1 + hstep, voffA);
;             PG8_WAIT_V(8); PG8_WAIT_L(0); PG8_BAR; PG8_MMA(0, 0, At, B0); PG8_MMA(0, 1, At, B1); PG8_BAR; PG8_SCHED;
;             PG8_LDA(At, 0, 1); PG8_STAGE(PG8_SB(0, 0), b2, voffB); PG8_STAGE(PG8_SB(0, 1), b2 + hstep, voffB); PG8_STAGE(PG8_SA(0, 0), a2, voffA);
;             PG8_WAIT_V(8); PG8_WAIT_L(0); PG8_BAR; PG8_MMA(1, 0, At, B0); PG8_MMA(1, 1, At, B1); PG8_BAR; PG8_SCHED;
;             PG8_LDB(B0, 1, 0); PG8_LDB(B1, 1, 1); PG8_SCHED; PG8_LDA(At, 1, 0); PG8_STAGE(PG8_SA(0, 1), a2 + hstep, voffA);
;             PG8_WAIT_V(8); PG8_WAIT_L(0); PG8_BAR; PG8_MMA(0, 0, At, B0); PG8_MMA(0, 1, At, B1); PG8_BAR; PG8_SCHED;
;             PG8_LDA(At, 1, 1); PG8_STAGE(PG8_SB(1, 0), b3, voffB); PG8_STAGE(PG8_SB(1, 1), b3 + hstep, voffB); PG8_STAGE(PG8_SA(1, 0), a3, voffA);
;             PG8_WAIT_V(8); PG8_WAIT_L(0); PG8_BAR; PG8_MMA(1, 0, At, B0); PG8_MMA(1, 1, At, B1); PG8_BAR; PG8_SCHED;
	s_setprio 0
	s_add_i32 s54, s45, s34
	v_lshl_add_u64 v[204:205], s[26:27], 0, v[194:195]
	s_mov_b32 m0, s54
	ds_read_b128 v[160:163], v247 offset:16384
	ds_read_b128 v[164:167], v247 offset:17408
	ds_read_b128 v[168:171], v247 offset:18432
	ds_read_b128 v[172:175], v247 offset:19456
	ds_read_b128 v[176:179], v247 offset:20480
	ds_read_b128 v[180:183], v247 offset:21504
	ds_read_b128 v[184:187], v247 offset:22528
	ds_read_b128 v[188:191], v247 offset:23552
	global_load_lds_dwordx4 v[204:205], off
	s_add_i32 m0, s54, 0x2000
	s_add_u32 s54, s26, 0xb0000
	v_lshl_add_u64 v[206:207], s[26:27], 0, v[198:199]
	s_addc_u32 s55, s27, 0
	s_add_i32 s56, s46, s34
	global_load_lds_dwordx4 v[206:207], off
	v_lshl_add_u64 v[208:209], s[54:55], 0, v[194:195]
	s_mov_b32 m0, s56
	v_lshl_add_u64 v[210:211], s[28:29], 0, v[196:197]
	global_load_lds_dwordx4 v[208:209], off
	v_lshl_add_u64 v[208:209], s[54:55], 0, v[198:199]
	s_add_i32 m0, s56, 0x2000
	s_nop 0
	global_load_lds_dwordx4 v[208:209], off
	v_lshl_add_u64 v[208:209], s[28:29], 0, v[192:193]
	s_mov_b32 m0, s35
	s_nop 0
	global_load_lds_dwordx4 v[208:209], off
	s_mov_b32 m0, s36
	s_nop 0
	global_load_lds_dwordx4 v[210:211], off
	s_waitcnt vmcnt(8)
	s_waitcnt lgkmcnt(0)
	s_setprio 1
	s_barrier
	v_mfma_f32_16x16x32_bf16 v[60:63], v[120:123], v[160:163], v[60:63]
	v_mfma_f32_16x16x32_bf16 v[56:59], v[136:139], v[160:163], v[56:59]
	v_mfma_f32_16x16x32_bf16 v[44:47], v[120:123], v[168:171], v[44:47]
	v_mfma_f32_16x16x32_bf16 v[40:43], v[136:139], v[168:171], v[40:43]
	v_mfma_f32_16x16x32_bf16 v[28:31], v[120:123], v[176:179], v[28:31]
	v_mfma_f32_16x16x32_bf16 v[24:27], v[136:139], v[176:179], v[24:27]
	v_mfma_f32_16x16x32_bf16 v[12:15], v[120:123], v[184:187], v[12:15]
	v_mfma_f32_16x16x32_bf16 v[8:11], v[136:139], v[184:187], v[8:11]
	v_mfma_f32_16x16x32_bf16 v[60:63], v[128:131], v[164:167], v[60:63]
	v_mfma_f32_16x16x32_bf16 v[56:59], v[140:143], v[164:167], v[56:59]
	v_mfma_f32_16x16x32_bf16 v[44:47], v[128:131], v[172:175], v[44:47]
	v_mfma_f32_16x16x32_bf16 v[40:43], v[140:143], v[172:175], v[40:43]
	v_mfma_f32_16x16x32_bf16 v[28:31], v[128:131], v[180:183], v[28:31]
	v_mfma_f32_16x16x32_bf16 v[24:27], v[140:143], v[180:183], v[24:27]
	v_mfma_f32_16x16x32_bf16 v[12:15], v[128:131], v[188:191], v[12:15]
	v_mfma_f32_16x16x32_bf16 v[8:11], v[140:143], v[188:191], v[8:11]
	s_setprio 0
	s_setprio 1
	v_mfma_f32_16x16x32_bf16 v[52:55], v[144:147], v[160:163], v[52:55]
	v_mfma_f32_16x16x32_bf16 v[48:51], v[152:155], v[160:163], v[48:51]
	v_mfma_f32_16x16x32_bf16 v[36:39], v[144:147], v[168:171], v[36:39]
	v_mfma_f32_16x16x32_bf16 v[32:35], v[152:155], v[168:171], v[32:35]
	v_mfma_f32_16x16x32_bf16 v[20:23], v[144:147], v[176:179], v[20:23]
	v_mfma_f32_16x16x32_bf16 v[16:19], v[152:155], v[176:179], v[16:19]
	v_mfma_f32_16x16x32_bf16 v[4:7], v[144:147], v[184:187], v[4:7]
	v_mfma_f32_16x16x32_bf16 v[0:3], v[152:155], v[184:187], v[0:3]
	v_mfma_f32_16x16x32_bf16 v[52:55], v[148:151], v[164:167], v[52:55]
	v_mfma_f32_16x16x32_bf16 v[48:51], v[156:159], v[164:167], v[48:51]
	v_mfma_f32_16x16x32_bf16 v[36:39], v[148:151], v[172:175], v[36:39]
	v_mfma_f32_16x16x32_bf16 v[32:35], v[156:159], v[172:175], v[32:35]
	v_mfma_f32_16x16x32_bf16 v[20:23], v[148:151], v[180:183], v[20:23]
	v_mfma_f32_16x16x32_bf16 v[16:19], v[156:159], v[180:183], v[16:19]
	v_mfma_f32_16x16x32_bf16 v[4:7], v[148:151], v[188:191], v[4:7]
	v_mfma_f32_16x16x32_bf16 v[0:3], v[156:159], v[188:191], v[0:3]
	s_barrier
	s_setprio 0
	s_add_i32 s54, 0, 0x18000
	s_add_i32 s55, 0, 0x1c000
	v_add_u32_e32 v140, s54, v243
	v_add_u32_e32 v156, s55, v243
	ds_read_b128 v[120:123], v140
	ds_read_b128 v[128:131], v140 offset:1024
	ds_read_b128 v[136:139], v140 offset:2048
	ds_read_b128 v[140:143], v140 offset:3072
	ds_read_b128 v[144:147], v156
	ds_read_b128 v[148:151], v156 offset:1024
	ds_read_b128 v[152:155], v156 offset:2048
	ds_read_b128 v[156:159], v156 offset:3072
	s_add_u32 s28, s28, 0xb0000
	s_addc_u32 s29, s29, 0
	s_mov_b32 m0, s37
	v_lshl_add_u64 v[212:213], s[28:29], 0, v[192:193]
	ds_read_b128 v[160:163], v247 offset:32768
	ds_read_b128 v[164:167], v247 offset:33792
	ds_read_b128 v[168:171], v247 offset:34816
	ds_read_b128 v[172:175], v247 offset:35840
	ds_read_b128 v[176:179], v247 offset:36864
	ds_read_b128 v[180:183], v247 offset:37888
	ds_read_b128 v[184:187], v247 offset:38912
	ds_read_b128 v[188:191], v247 offset:39936
	global_load_lds_dwordx4 v[212:213], off
	v_lshl_add_u64 v[212:213], s[28:29], 0, v[196:197]
	s_mov_b32 m0, s38
	s_nop 0
	global_load_lds_dwordx4 v[212:213], off
	s_waitcnt vmcnt(8)
	s_waitcnt lgkmcnt(0)
	s_setprio 1
	s_barrier
; #define PG8_STAGE(bufoff, gbase, voff) do { _Pragma("unroll") for (int _i = 0; _i < 2; ++_i) \
;         __builtin_amdgcn_global_load_lds((const unsigned*)((const char*)(gbase) + (voff)[_i]), (PG8_LAS unsigned*)(lds + (bufoff) + ldsw + _i * 8192), 16, 0, 0); } while (0)
; #define PG8_LDA(dst, b, h) do { _Pragma("unroll") for (int m = 0; m < 4; ++m) _Pragma("unroll") for (int k = 0; k < 2; ++k) dst[m][k] = *(const PG8_LAS bf16x8*)(lds + PG8_SA(b, h) + aoff + m * 2048 + k * 1024); } while (0)
; #define PG8_LDB(dst, b, h) do { _Pragma("unroll") for (int n = 0; n < 2; ++n) _Pragma("unroll") for (int k = 0; k < 2; ++k) dst[n][k] = *(const PG8_LAS bf16x8*)(lds + PG8_SB(b, h) + boff + n * 2048 + k * 1024); } while (0)
; #define PG8_MMA(ai, bj, At, Bt) do { __builtin_amdgcn_s_setprio(1); _Pragma("unroll") for (int m = 0; m < 4; ++m) _Pragma("unroll") for (int n = 0; n < 2; ++n) _Pragma("unroll") for (int k = 0; k < 2; ++k) \
;         acc[ai][bj][m][n] = __builtin_amdgcn_mfma_f32_16x16x32_bf16(Bt[n][k], At[m][k], acc[ai][bj][m][n], 0, 0, 0); __builtin_amdgcn_s_setprio(0); } while (0)
; template <class Epi, class Sched, bool ALIGN_EPI = false, bool SP2 = false>
; __device__ __forceinline__ void gemm_phase(PG8_LAS unsigned char* lds, const Gemm g, const Sched& S, const Epi& E) {
;     ...
;             PG8_LDB(B0, 0, 0); PG8_LDB(B1, 0, 1); PG8_SCHED; PG8_LDA(At, 0, 0); PG8_STAGE(PG8_SA(1, 1), a1 + hstep, voffA);
;             PG8_WAIT_V(8); PG8_WAIT_L(0); PG8_BAR; PG8_MMA(0, 0, At, B0); PG8_MMA(0, 1, At, B1); PG8_BAR; PG8_SCHED;
;             PG8_LDA(At, 0, 1); PG8_STAGE(PG8_SB(0, 0), b2, voffB); PG8_STAGE(PG8_SB(0, 1), b2 + hstep, voffB); PG8_STAGE(PG8_SA(0, 0), a2, voffA);
;             PG8_WAIT_V(8); PG8_WAIT_L(0); PG8_BAR; PG8_MMA(1, 0, At, B0); PG8_MMA(1, 1, At, B1); PG8_BAR; PG8_SCHED;
;             PG8_LDB(B0, 1, 0); PG8_LDB(B1, 1, 1); PG8_SCHED; PG8_LDA(At, 1, 0); PG8_STAGE(PG8_SA(0, 1), a2 + hstep, voffA);
;             PG8_WAIT_V(8); PG8_WAIT_L(0); PG8_BAR; PG8_MMA(0, 0, At, B0); PG8_MMA(0, 1, At, B1); PG8_BAR; PG8_SCHED;
;             PG8_LDA(At, 1, 1); PG8_STAGE(PG8_SB(1, 0), b3, voffB); PG8_STAGE(PG8_SB(1, 1), b3 + hstep, voffB); PG8_STAGE(PG8_SA(1, 0), a3, voffA);
;             PG8_WAIT_V(8); PG8_WAIT_L(0); PG8_BAR; PG8_MMA(1, 0, At, B0); PG8_MMA(1, 1, At, B1); PG8_BAR; PG8_SCHED;
;     ...
;         if constexpr (ALIGN_EPI) { if (wr == 0) PG8_BAR; }
	v_mfma_f32_16x16x32_bf16 v[132:135], v[120:123], v[160:163], v[132:135]
	v_mfma_f32_16x16x32_bf16 v[124:127], v[136:139], v[160:163], v[124:127]
	v_mfma_f32_16x16x32_bf16 v[108:111], v[120:123], v[168:171], v[108:111]
	v_mfma_f32_16x16x32_bf16 v[104:107], v[136:139], v[168:171], v[104:107]
	v_mfma_f32_16x16x32_bf16 v[92:95], v[120:123], v[176:179], v[92:95]
	v_mfma_f32_16x16x32_bf16 v[88:91], v[136:139], v[176:179], v[88:91]
	v_mfma_f32_16x16x32_bf16 v[76:79], v[120:123], v[184:187], v[76:79]
	v_mfma_f32_16x16x32_bf16 v[72:75], v[136:139], v[184:187], v[72:75]
	v_mfma_f32_16x16x32_bf16 v[132:135], v[128:131], v[164:167], v[132:135]
	v_mfma_f32_16x16x32_bf16 v[124:127], v[140:143], v[164:167], v[124:127]
	v_mfma_f32_16x16x32_bf16 v[108:111], v[128:131], v[172:175], v[108:111]
	v_mfma_f32_16x16x32_bf16 v[104:107], v[140:143], v[172:175], v[104:107]
	v_mfma_f32_16x16x32_bf16 v[92:95], v[128:131], v[180:183], v[92:95]
	v_mfma_f32_16x16x32_bf16 v[88:91], v[140:143], v[180:183], v[88:91]
	v_mfma_f32_16x16x32_bf16 v[76:79], v[128:131], v[188:191], v[76:79]
	v_mfma_f32_16x16x32_bf16 v[72:75], v[140:143], v[188:191], v[72:75]
	s_setprio 0
	s_setprio 1
	v_mfma_f32_16x16x32_bf16 v[116:119], v[144:147], v[160:163], v[116:119]
	v_mfma_f32_16x16x32_bf16 v[112:115], v[152:155], v[160:163], v[112:115]
	v_mfma_f32_16x16x32_bf16 v[100:103], v[144:147], v[168:171], v[100:103]
	v_mfma_f32_16x16x32_bf16 v[96:99], v[152:155], v[168:171], v[96:99]
	v_mfma_f32_16x16x32_bf16 v[84:87], v[144:147], v[176:179], v[84:87]
	v_mfma_f32_16x16x32_bf16 v[80:83], v[152:155], v[176:179], v[80:83]
	v_mfma_f32_16x16x32_bf16 v[68:71], v[144:147], v[184:187], v[68:71]
	v_mfma_f32_16x16x32_bf16 v[64:67], v[152:155], v[184:187], v[64:67]
	v_mfma_f32_16x16x32_bf16 v[116:119], v[148:151], v[164:167], v[116:119]
	v_mfma_f32_16x16x32_bf16 v[112:115], v[156:159], v[164:167], v[112:115]
	v_mfma_f32_16x16x32_bf16 v[100:103], v[148:151], v[172:175], v[100:103]
	v_mfma_f32_16x16x32_bf16 v[96:99], v[156:159], v[172:175], v[96:99]
	v_mfma_f32_16x16x32_bf16 v[84:87], v[148:151], v[180:183], v[84:87]
	v_mfma_f32_16x16x32_bf16 v[80:83], v[156:159], v[180:183], v[80:83]
	v_mfma_f32_16x16x32_bf16 v[68:71], v[148:151], v[188:191], v[68:71]
	v_mfma_f32_16x16x32_bf16 v[64:67], v[156:159], v[188:191], v[64:67]
	s_barrier
	s_setprio 0
	s_add_i32 s28, s54, s34
	v_lshl_add_u64 v[204:205], v[204:205], 0, s[18:19]
	s_mov_b32 m0, s28
	ds_read_b128 v[160:163], v247 offset:49152
	ds_read_b128 v[164:167], v247 offset:50176
	ds_read_b128 v[168:171], v247 offset:51200
	ds_read_b128 v[172:175], v247 offset:52224
	ds_read_b128 v[176:179], v247 offset:53248
	ds_read_b128 v[180:183], v247 offset:54272
	ds_read_b128 v[184:187], v247 offset:55296
	ds_read_b128 v[188:191], v247 offset:56320
	global_load_lds_dwordx4 v[204:205], off
	s_add_i32 m0, s28, 0x2000
	s_add_u32 s26, s26, 0xb0080
	v_lshl_add_u64 v[204:205], v[206:207], 0, s[18:19]
	s_addc_u32 s27, s27, 0
	s_add_i32 s28, s55, s34
	global_load_lds_dwordx4 v[204:205], off
	v_lshl_add_u64 v[204:205], s[26:27], 0, v[194:195]
	s_mov_b32 m0, s28
	s_nop 0
	global_load_lds_dwordx4 v[204:205], off
	v_lshl_add_u64 v[204:205], s[26:27], 0, v[198:199]
	s_add_i32 m0, s28, 0x2000
	s_nop 0
	global_load_lds_dwordx4 v[204:205], off
	v_lshl_add_u64 v[204:205], v[208:209], 0, s[18:19]
	s_mov_b32 m0, s40
	s_nop 0
	global_load_lds_dwordx4 v[204:205], off
	v_lshl_add_u64 v[204:205], v[210:211], 0, s[18:19]
	s_mov_b32 m0, s41
	s_nop 0
	global_load_lds_dwordx4 v[204:205], off
	s_waitcnt vmcnt(8)
	s_waitcnt lgkmcnt(0)
	s_setprio 1
	s_barrier
	v_mfma_f32_16x16x32_bf16 v[60:63], v[120:123], v[160:163], v[60:63]
	v_mfma_f32_16x16x32_bf16 v[56:59], v[136:139], v[160:163], v[56:59]
	v_mfma_f32_16x16x32_bf16 v[44:47], v[120:123], v[168:171], v[44:47]
	v_mfma_f32_16x16x32_bf16 v[40:43], v[136:139], v[168:171], v[40:43]
	v_mfma_f32_16x16x32_bf16 v[28:31], v[120:123], v[176:179], v[28:31]
	v_mfma_f32_16x16x32_bf16 v[24:27], v[136:139], v[176:179], v[24:27]
	v_mfma_f32_16x16x32_bf16 v[12:15], v[120:123], v[184:187], v[12:15]
	v_mfma_f32_16x16x32_bf16 v[8:11], v[136:139], v[184:187], v[8:11]
	v_mfma_f32_16x16x32_bf16 v[60:63], v[128:131], v[164:167], v[60:63]
	v_mfma_f32_16x16x32_bf16 v[56:59], v[140:143], v[164:167], v[56:59]
	v_mfma_f32_16x16x32_bf16 v[44:47], v[128:131], v[172:175], v[44:47]
	v_mfma_f32_16x16x32_bf16 v[40:43], v[140:143], v[172:175], v[40:43]
	v_mfma_f32_16x16x32_bf16 v[28:31], v[128:131], v[180:183], v[28:31]
	v_mfma_f32_16x16x32_bf16 v[24:27], v[140:143], v[180:183], v[24:27]
	v_mfma_f32_16x16x32_bf16 v[12:15], v[128:131], v[188:191], v[12:15]
	v_mfma_f32_16x16x32_bf16 v[8:11], v[140:143], v[188:191], v[8:11]
	s_setprio 0
	s_setprio 1
	v_mfma_f32_16x16x32_bf16 v[52:55], v[144:147], v[160:163], v[52:55]
	v_mfma_f32_16x16x32_bf16 v[48:51], v[152:155], v[160:163], v[48:51]
	v_mfma_f32_16x16x32_bf16 v[36:39], v[144:147], v[168:171], v[36:39]
	v_mfma_f32_16x16x32_bf16 v[32:35], v[152:155], v[168:171], v[32:35]
	v_mfma_f32_16x16x32_bf16 v[20:23], v[144:147], v[176:179], v[20:23]
	v_mfma_f32_16x16x32_bf16 v[16:19], v[152:155], v[176:179], v[16:19]
	v_mfma_f32_16x16x32_bf16 v[4:7], v[144:147], v[184:187], v[4:7]
	v_mfma_f32_16x16x32_bf16 v[0:3], v[152:155], v[184:187], v[0:3]
	v_mfma_f32_16x16x32_bf16 v[52:55], v[148:151], v[164:167], v[52:55]
	v_mfma_f32_16x16x32_bf16 v[48:51], v[156:159], v[164:167], v[48:51]
	v_mfma_f32_16x16x32_bf16 v[36:39], v[148:151], v[172:175], v[36:39]
	v_mfma_f32_16x16x32_bf16 v[32:35], v[156:159], v[172:175], v[32:35]
	v_mfma_f32_16x16x32_bf16 v[20:23], v[148:151], v[180:183], v[20:23]
	v_mfma_f32_16x16x32_bf16 v[16:19], v[156:159], v[180:183], v[16:19]
	v_mfma_f32_16x16x32_bf16 v[4:7], v[148:151], v[188:191], v[4:7]
	v_mfma_f32_16x16x32_bf16 v[0:3], v[156:159], v[188:191], v[0:3]
	s_barrier
	s_setprio 0
	s_add_i32 s53, s53, 2
	s_add_u32 s24, s24, 0x100
	s_addc_u32 s25, s25, 0
	s_add_u32 s51, s51, 0x100
	s_addc_u32 s52, s52, 0
	s_cmp_gt_u32 s53, 41
	s_cbranch_scc0 .LBB0_418
	s_and_b64 vcc, exec, s[20:21]
	s_cbranch_vccz .LBB0_421
	s_barrier

; #define PG8_STAGE(bufoff, gbase, voff) do { _Pragma("unroll") for (int _i = 0; _i < 2; ++_i) \
;         __builtin_amdgcn_global_load_lds((const unsigned*)((const char*)(gbase) + (voff)[_i]), (PG8_LAS unsigned*)(lds + (bufoff) + ldsw + _i * 8192), 16, 0, 0); } while (0)
; #define PG8_LDA(dst, b, h) do { _Pragma("unroll") for (int m = 0; m < 4; ++m) _Pragma("unroll") for (int k = 0; k < 2; ++k) dst[m][k] = *(const PG8_LAS bf16x8*)(lds + PG8_SA(b, h) + aoff + m * 2048 + k * 1024); } while (0)
; template <class Epi, class Sched, bool ALIGN_EPI = false, bool SP2 = false>
; __device__ __forceinline__ void gemm_phase(PG8_LAS unsigned char* lds, const Gemm g, const Sched& S, const Epi& E) {
;     ...
;         const bool has_next = S.next(ui + 1, nxt);
;         const char* nA = has_next ? (const char*)g.A + (size_t)nxt.pm * tstep : cA; const char* nB = has_next ? (const char*)g.Bt + (size_t)nxt.pn * tstep : cB;
;         for (int t = 0; t < nt; t += 2) {
;             const bool last = (t == nt - 2);
;             const char* a1 = cA + (size_t)(t + 1) * kstep;
;             const char* a2 = last ? nA : cA + (size_t)(t + 2) * kstep; const char* b2 = last ? nB : cB + (size_t)(t + 2) * kstep;
;             const char* a3 = a2 + kstep; const char* b3 = b2 + kstep;
;             if (last && has_next) S.a_ready(nxt, ui + 1);
;             if constexpr (SP2) {
;             PG8_LDB(B0, 0, 0); PG8_LDB(B1, 0, 1); PG8_SCHED; PG8_LDA(At, 0, 0); PG8_STAGE(PG8_SA(1, 1), a1 + hstep, voffA);
;             PG8_WAIT_V(8); PG8_WAIT_L(0); PG8_BAR; PG8_MMA(0, 0, At, B0); PG8_MMA(0, 1, At, B1); PG8_BAR; PG8_SCHED;
;             PG8_LDA(At, 0, 1); PG8_STAGE(PG8_SB(0, 0), b2, voffB); PG8_STAGE(PG8_SB(0, 1), b2 + hstep, voffB); PG8_STAGE(PG8_SA(0, 0), a2, voffA);
;             PG8_WAIT_V(8); PG8_WAIT_L(0); PG8_BAR; PG8_MMA(1, 0, At, B0); PG8_MMA(1, 1, At, B1); PG8_BAR; PG8_SCHED;
;             PG8_LDB(B0, 1, 0); PG8_LDB(B1, 1, 1); PG8_SCHED; PG8_LDA(At, 1, 0); PG8_STAGE(PG8_SA(0, 1), a2 + hstep, voffA);
;             PG8_WAIT_V(8); PG8_WAIT_L(0); PG8_BAR; PG8_MMA(0, 0, At, B0); PG8_MMA(0, 1, At, B1); PG8_BAR; PG8_SCHED;
;             PG8_LDA(At, 1, 1); PG8_STAGE(PG8_SB(1, 0), b3, voffB); PG8_STAGE(PG8_SB(1, 1), b3 + hstep, voffB); PG8_STAGE(PG8_SA(1, 0), a3, voffA);
;             PG8_WAIT_V(8); PG8_WAIT_L(0); PG8_BAR; PG8_MMA(1, 0, At, B0); PG8_MMA(1, 1, At, B1); PG8_BAR; PG8_SCHED;
.LBB0_508:
	s_ashr_i32 s31, s30, 31
	s_lshl_b64 s[34:35], s[30:31], 19
	s_add_u32 s34, s48, s34
	s_addc_u32 s35, s49, s35
	s_and_b64 s[36:37], s[4:5], exec
	s_cselect_b32 s9, s35, s39
	s_cselect_b32 s14, s34, s38
	s_ashr_i32 s29, s28, 31
	s_lshl_b64 s[36:37], s[28:29], 19
	s_add_u32 s36, s50, s36
	s_addc_u32 s37, s51, s37
	s_and_b64 s[42:43], s[4:5], exec
	s_cselect_b32 s29, s37, s41
	s_cselect_b32 s31, s36, s40
	s_add_u32 s38, s38, 0x40080
	s_addc_u32 s39, s39, 0
	s_add_u32 s44, s40, 0x100
	s_addc_u32 s45, s41, 0
	s_mov_b32 s70, -2
	s_add_u32 s40, s38, 0xfffc0080
	s_addc_u32 s41, s39, -1
	s_cmp_eq_u32 s70, 12
	s_cselect_b32 s43, s9, s41
	s_cselect_b32 s42, s14, s40
	s_cselect_b32 s41, s29, s45
	s_cselect_b32 s40, s31, s44
	v_lshl_add_u64 v[226:227], s[38:39], 0, v[132:133]
	s_add_i32 m0, s52, 0xc000
	global_load_lds_dwordx4 v[226:227], off
	v_lshl_add_u64 v[226:227], s[38:39], 0, v[134:135]
	s_add_i32 m0, s52, 0xe000
	s_nop 0
	global_load_lds_dwordx4 v[226:227], off
	s_waitcnt vmcnt(8)
	s_waitcnt lgkmcnt(0)
	s_setprio 1
	s_barrier
	v_mfma_f32_16x16x32_bf16 v[124:127], v[148:151], v[194:197], 0
	v_mfma_f32_16x16x32_bf16 v[120:123], v[170:173], v[194:197], 0
	v_mfma_f32_16x16x32_bf16 v[108:111], v[148:151], v[202:205], 0
	v_mfma_f32_16x16x32_bf16 v[104:107], v[170:173], v[202:205], 0
	v_mfma_f32_16x16x32_bf16 v[92:95], v[148:151], v[210:213], 0
	v_mfma_f32_16x16x32_bf16 v[88:91], v[170:173], v[210:213], 0
	v_mfma_f32_16x16x32_bf16 v[76:79], v[148:151], v[218:221], 0
	v_mfma_f32_16x16x32_bf16 v[72:75], v[170:173], v[218:221], 0
	v_mfma_f32_16x16x32_bf16 v[124:127], v[166:169], v[198:201], v[124:127]
	v_mfma_f32_16x16x32_bf16 v[120:123], v[174:177], v[198:201], v[120:123]
	v_mfma_f32_16x16x32_bf16 v[108:111], v[166:169], v[206:209], v[108:111]
	v_mfma_f32_16x16x32_bf16 v[104:107], v[174:177], v[206:209], v[104:107]
	v_mfma_f32_16x16x32_bf16 v[92:95], v[166:169], v[214:217], v[92:95]
	v_mfma_f32_16x16x32_bf16 v[88:91], v[174:177], v[214:217], v[88:91]
	v_mfma_f32_16x16x32_bf16 v[76:79], v[166:169], v[222:225], v[76:79]
	v_mfma_f32_16x16x32_bf16 v[72:75], v[174:177], v[222:225], v[72:75]
	s_setprio 0
	s_setprio 1
	v_mfma_f32_16x16x32_bf16 v[116:119], v[178:181], v[194:197], 0
	v_mfma_f32_16x16x32_bf16 v[112:115], v[186:189], v[194:197], 0
	v_mfma_f32_16x16x32_bf16 v[100:103], v[178:181], v[202:205], 0
	v_mfma_f32_16x16x32_bf16 v[96:99], v[186:189], v[202:205], 0
	v_mfma_f32_16x16x32_bf16 v[84:87], v[178:181], v[210:213], 0
	v_mfma_f32_16x16x32_bf16 v[80:83], v[186:189], v[210:213], 0
	v_mfma_f32_16x16x32_bf16 v[68:71], v[178:181], v[218:221], 0
	v_mfma_f32_16x16x32_bf16 v[64:67], v[186:189], v[218:221], 0
	v_mfma_f32_16x16x32_bf16 v[116:119], v[182:185], v[198:201], v[116:119]
	v_mfma_f32_16x16x32_bf16 v[112:115], v[190:193], v[198:201], v[112:115]
	v_mfma_f32_16x16x32_bf16 v[100:103], v[182:185], v[206:209], v[100:103]
	v_mfma_f32_16x16x32_bf16 v[96:99], v[190:193], v[206:209], v[96:99]
	v_mfma_f32_16x16x32_bf16 v[84:87], v[182:185], v[214:217], v[84:87]
	v_mfma_f32_16x16x32_bf16 v[80:83], v[190:193], v[214:217], v[80:83]
	v_mfma_f32_16x16x32_bf16 v[68:71], v[182:185], v[222:225], v[68:71]
	v_mfma_f32_16x16x32_bf16 v[64:67], v[190:193], v[222:225], v[64:67]
	s_barrier
	s_setprio 0
	s_add_i32 s71, s61, s33
	v_lshl_add_u64 v[226:227], s[40:41], 0, v[138:139]
	s_mov_b32 m0, s71
	ds_read_b128 v[194:197], v164 offset:16384
	ds_read_b128 v[198:201], v164 offset:17408
	ds_read_b128 v[202:205], v164 offset:18432
	ds_read_b128 v[206:209], v164 offset:19456
	ds_read_b128 v[210:213], v164 offset:20480
	ds_read_b128 v[214:217], v164 offset:21504
	ds_read_b128 v[218:221], v164 offset:22528
	ds_read_b128 v[222:225], v164 offset:23552
	global_load_lds_dwordx4 v[226:227], off
	s_add_i32 m0, s71, 0x2000
	s_add_u32 s72, s40, 0x40000
	v_lshl_add_u64 v[228:229], s[40:41], 0, v[142:143]
	s_addc_u32 s73, s41, 0
	s_add_i32 s71, s62, s33
	global_load_lds_dwordx4 v[228:229], off
	v_lshl_add_u64 v[230:231], s[72:73], 0, v[138:139]
	s_mov_b32 m0, s71
	v_lshl_add_u64 v[232:233], s[42:43], 0, v[140:141]
	global_load_lds_dwordx4 v[230:231], off
	v_lshl_add_u64 v[230:231], s[72:73], 0, v[142:143]
	s_add_i32 m0, s71, 0x2000
	s_nop 0
	global_load_lds_dwordx4 v[230:231], off
	v_lshl_add_u64 v[230:231], s[42:43], 0, v[136:137]
	s_mov_b32 m0, s52
	s_nop 0
	global_load_lds_dwordx4 v[230:231], off
	s_mov_b32 m0, s53
	s_nop 0
	global_load_lds_dwordx4 v[232:233], off
	s_waitcnt vmcnt(8)
	s_waitcnt lgkmcnt(0)
	s_setprio 1
	s_barrier
	v_mfma_f32_16x16x32_bf16 v[60:63], v[148:151], v[194:197], 0
	v_mfma_f32_16x16x32_bf16 v[56:59], v[170:173], v[194:197], 0
	v_mfma_f32_16x16x32_bf16 v[44:47], v[148:151], v[202:205], 0
	v_mfma_f32_16x16x32_bf16 v[40:43], v[170:173], v[202:205], 0
	v_mfma_f32_16x16x32_bf16 v[28:31], v[148:151], v[210:213], 0
	v_mfma_f32_16x16x32_bf16 v[24:27], v[170:173], v[210:213], 0
	v_mfma_f32_16x16x32_bf16 v[12:15], v[148:151], v[218:221], 0
	v_mfma_f32_16x16x32_bf16 v[8:11], v[170:173], v[218:221], 0
	v_mfma_f32_16x16x32_bf16 v[60:63], v[166:169], v[198:201], v[60:63]
	v_mfma_f32_16x16x32_bf16 v[56:59], v[174:177], v[198:201], v[56:59]
	v_mfma_f32_16x16x32_bf16 v[44:47], v[166:169], v[206:209], v[44:47]
	v_mfma_f32_16x16x32_bf16 v[40:43], v[174:177], v[206:209], v[40:43]
	v_mfma_f32_16x16x32_bf16 v[28:31], v[166:169], v[214:217], v[28:31]
	v_mfma_f32_16x16x32_bf16 v[24:27], v[174:177], v[214:217], v[24:27]
	v_mfma_f32_16x16x32_bf16 v[12:15], v[166:169], v[222:225], v[12:15]
	v_mfma_f32_16x16x32_bf16 v[8:11], v[174:177], v[222:225], v[8:11]
	s_setprio 0
	s_setprio 1
	v_mfma_f32_16x16x32_bf16 v[52:55], v[178:181], v[194:197], 0
	v_mfma_f32_16x16x32_bf16 v[48:51], v[186:189], v[194:197], 0
	v_mfma_f32_16x16x32_bf16 v[36:39], v[178:181], v[202:205], 0
	v_mfma_f32_16x16x32_bf16 v[32:35], v[186:189], v[202:205], 0
	v_mfma_f32_16x16x32_bf16 v[20:23], v[178:181], v[210:213], 0
	v_mfma_f32_16x16x32_bf16 v[16:19], v[186:189], v[210:213], 0
	v_mfma_f32_16x16x32_bf16 v[4:7], v[178:181], v[218:221], 0
	v_mfma_f32_16x16x32_bf16 v[0:3], v[186:189], v[218:221], 0
	v_mfma_f32_16x16x32_bf16 v[52:55], v[182:185], v[198:201], v[52:55]
	v_mfma_f32_16x16x32_bf16 v[48:51], v[190:193], v[198:201], v[48:51]
	v_mfma_f32_16x16x32_bf16 v[36:39], v[182:185], v[206:209], v[36:39]
	v_mfma_f32_16x16x32_bf16 v[32:35], v[190:193], v[206:209], v[32:35]
	v_mfma_f32_16x16x32_bf16 v[20:23], v[182:185], v[214:217], v[20:23]
	v_mfma_f32_16x16x32_bf16 v[16:19], v[190:193], v[214:217], v[16:19]
	v_mfma_f32_16x16x32_bf16 v[4:7], v[182:185], v[222:225], v[4:7]
	v_mfma_f32_16x16x32_bf16 v[0:3], v[190:193], v[222:225], v[0:3]
	s_barrier
; #define PG8_STAGE(bufoff, gbase, voff) do { _Pragma("unroll") for (int _i = 0; _i < 2; ++_i) \
;         __builtin_amdgcn_global_load_lds((const unsigned*)((const char*)(gbase) + (voff)[_i]), (PG8_LAS unsigned*)(lds + (bufoff) + ldsw + _i * 8192), 16, 0, 0); } while (0)
; #define PG8_LDA(dst, b, h) do { _Pragma("unroll") for (int m = 0; m < 4; ++m) _Pragma("unroll") for (int k = 0; k < 2; ++k) dst[m][k] = *(const PG8_LAS bf16x8*)(lds + PG8_SA(b, h) + aoff + m * 2048 + k * 1024); } while (0)
; #define PG8_LDB(dst, b, h) do { _Pragma("unroll") for (int n = 0; n < 2; ++n) _Pragma("unroll") for (int k = 0; k < 2; ++k) dst[n][k] = *(const PG8_LAS bf16x8*)(lds + PG8_SB(b, h) + boff + n * 2048 + k * 1024); } while (0)
; #define PG8_MMA(ai, bj, At, Bt) do { __builtin_amdgcn_s_setprio(1); _Pragma("unroll") for (int m = 0; m < 4; ++m) _Pragma("unroll") for (int n = 0; n < 2; ++n) _Pragma("unroll") for (int k = 0; k < 2; ++k) \
;         acc[ai][bj][m][n] = __builtin_amdgcn_mfma_f32_16x16x32_bf16(Bt[n][k], At[m][k], acc[ai][bj][m][n], 0, 0, 0); __builtin_amdgcn_s_setprio(0); } while (0)
; #define PG8_WAIT_V(n) asm volatile("s_waitcnt vmcnt(" #n ")" ::: "memory")
; template <class Epi, class Sched, bool ALIGN_EPI = false, bool SP2 = false>
; __device__ __forceinline__ void gemm_phase(PG8_LAS unsigned char* lds, const Gemm g, const Sched& S, const Epi& E) {
;     ...
;             PG8_LDB(B0, 0, 0); PG8_LDB(B1, 0, 1); PG8_SCHED; PG8_LDA(At, 0, 0); PG8_STAGE(PG8_SA(1, 1), a1 + hstep, voffA);
;             PG8_WAIT_V(8); PG8_WAIT_L(0); PG8_BAR; PG8_MMA(0, 0, At, B0); PG8_MMA(0, 1, At, B1); PG8_BAR; PG8_SCHED;
;             PG8_LDA(At, 0, 1); PG8_STAGE(PG8_SB(0, 0), b2, voffB); PG8_STAGE(PG8_SB(0, 1), b2 + hstep, voffB); PG8_STAGE(PG8_SA(0, 0), a2, voffA);
;             PG8_WAIT_V(8); PG8_WAIT_L(0); PG8_BAR; PG8_MMA(1, 0, At, B0); PG8_MMA(1, 1, At, B1); PG8_BAR; PG8_SCHED;
;             PG8_LDB(B0, 1, 0); PG8_LDB(B1, 1, 1); PG8_SCHED; PG8_LDA(At, 1, 0); PG8_STAGE(PG8_SA(0, 1), a2 + hstep, voffA);
;             PG8_WAIT_V(8); PG8_WAIT_L(0); PG8_BAR; PG8_MMA(0, 0, At, B0); PG8_MMA(0, 1, At, B1); PG8_BAR; PG8_SCHED;
;             PG8_LDA(At, 1, 1); PG8_STAGE(PG8_SB(1, 0), b3, voffB); PG8_STAGE(PG8_SB(1, 1), b3 + hstep, voffB); PG8_STAGE(PG8_SA(1, 0), a3, voffA);
;             PG8_WAIT_V(8); PG8_WAIT_L(0); PG8_BAR; PG8_MMA(1, 0, At, B0); PG8_MMA(1, 1, At, B1); PG8_BAR; PG8_SCHED;
	s_setprio 0
	s_add_i32 s71, 0, 0x18000
	v_add_u32_e32 v130, s71, v160
	s_add_i32 s72, 0, 0x1c000
	ds_read_b128 v[148:151], v130
	ds_read_b128 v[166:169], v130 offset:1024
	ds_read_b128 v[170:173], v130 offset:2048
	ds_read_b128 v[174:177], v130 offset:3072
	v_add_u32_e32 v130, s72, v160
	ds_read_b128 v[178:181], v130
	ds_read_b128 v[182:185], v130 offset:1024
	ds_read_b128 v[186:189], v130 offset:2048
	ds_read_b128 v[190:193], v130 offset:3072
	s_add_u32 s42, s42, 0x40000
	s_addc_u32 s43, s43, 0
	s_mov_b32 m0, s54
	v_lshl_add_u64 v[234:235], s[42:43], 0, v[136:137]
	ds_read_b128 v[194:197], v164 offset:32768
	ds_read_b128 v[198:201], v164 offset:33792
	ds_read_b128 v[202:205], v164 offset:34816
	ds_read_b128 v[206:209], v164 offset:35840
	ds_read_b128 v[210:213], v164 offset:36864
	ds_read_b128 v[214:217], v164 offset:37888
	ds_read_b128 v[218:221], v164 offset:38912
	ds_read_b128 v[222:225], v164 offset:39936
	global_load_lds_dwordx4 v[234:235], off
	v_lshl_add_u64 v[234:235], s[42:43], 0, v[140:141]
	s_mov_b32 m0, s55
	s_nop 0
	global_load_lds_dwordx4 v[234:235], off
	s_waitcnt vmcnt(8)
	s_waitcnt lgkmcnt(0)
	s_setprio 1
	s_barrier
	v_mfma_f32_16x16x32_bf16 v[124:127], v[148:151], v[194:197], v[124:127]
	v_mfma_f32_16x16x32_bf16 v[120:123], v[170:173], v[194:197], v[120:123]
	v_mfma_f32_16x16x32_bf16 v[108:111], v[148:151], v[202:205], v[108:111]
	v_mfma_f32_16x16x32_bf16 v[104:107], v[170:173], v[202:205], v[104:107]
	v_mfma_f32_16x16x32_bf16 v[92:95], v[148:151], v[210:213], v[92:95]
	v_mfma_f32_16x16x32_bf16 v[88:91], v[170:173], v[210:213], v[88:91]
	v_mfma_f32_16x16x32_bf16 v[76:79], v[148:151], v[218:221], v[76:79]
	v_mfma_f32_16x16x32_bf16 v[72:75], v[170:173], v[218:221], v[72:75]
	v_mfma_f32_16x16x32_bf16 v[124:127], v[166:169], v[198:201], v[124:127]
	v_mfma_f32_16x16x32_bf16 v[120:123], v[174:177], v[198:201], v[120:123]
	v_mfma_f32_16x16x32_bf16 v[108:111], v[166:169], v[206:209], v[108:111]
	v_mfma_f32_16x16x32_bf16 v[104:107], v[174:177], v[206:209], v[104:107]
	v_mfma_f32_16x16x32_bf16 v[92:95], v[166:169], v[214:217], v[92:95]
	v_mfma_f32_16x16x32_bf16 v[88:91], v[174:177], v[214:217], v[88:91]
	v_mfma_f32_16x16x32_bf16 v[76:79], v[166:169], v[222:225], v[76:79]
	v_mfma_f32_16x16x32_bf16 v[72:75], v[174:177], v[222:225], v[72:75]
	s_setprio 0
	s_setprio 1
	v_mfma_f32_16x16x32_bf16 v[116:119], v[178:181], v[194:197], v[116:119]
	v_mfma_f32_16x16x32_bf16 v[112:115], v[186:189], v[194:197], v[112:115]
	v_mfma_f32_16x16x32_bf16 v[100:103], v[178:181], v[202:205], v[100:103]
	v_mfma_f32_16x16x32_bf16 v[96:99], v[186:189], v[202:205], v[96:99]
	v_mfma_f32_16x16x32_bf16 v[84:87], v[178:181], v[210:213], v[84:87]
	v_mfma_f32_16x16x32_bf16 v[80:83], v[186:189], v[210:213], v[80:83]
	v_mfma_f32_16x16x32_bf16 v[68:71], v[178:181], v[218:221], v[68:71]
	v_mfma_f32_16x16x32_bf16 v[64:67], v[186:189], v[218:221], v[64:67]
	v_mfma_f32_16x16x32_bf16 v[116:119], v[182:185], v[198:201], v[116:119]
	v_mfma_f32_16x16x32_bf16 v[112:115], v[190:193], v[198:201], v[112:115]
	v_mfma_f32_16x16x32_bf16 v[100:103], v[182:185], v[206:209], v[100:103]
	v_mfma_f32_16x16x32_bf16 v[96:99], v[190:193], v[206:209], v[96:99]
	v_mfma_f32_16x16x32_bf16 v[84:87], v[182:185], v[214:217], v[84:87]
	v_mfma_f32_16x16x32_bf16 v[80:83], v[190:193], v[214:217], v[80:83]
	v_mfma_f32_16x16x32_bf16 v[68:71], v[182:185], v[222:225], v[68:71]
	v_mfma_f32_16x16x32_bf16 v[64:67], v[190:193], v[222:225], v[64:67]
	s_barrier
	s_setprio 0
	s_add_i32 s42, s71, s33
	v_lshl_add_u64 v[226:227], v[226:227], 0, s[24:25]
	s_mov_b32 m0, s42
	ds_read_b128 v[194:197], v164 offset:49152
	ds_read_b128 v[198:201], v164 offset:50176
	ds_read_b128 v[202:205], v164 offset:51200
	ds_read_b128 v[206:209], v164 offset:52224
	ds_read_b128 v[210:213], v164 offset:53248
	ds_read_b128 v[214:217], v164 offset:54272
	ds_read_b128 v[218:221], v164 offset:55296
	ds_read_b128 v[222:225], v164 offset:56320
	global_load_lds_dwordx4 v[226:227], off
	s_add_i32 m0, s42, 0x2000
	s_add_u32 s40, s40, 0x40080
	v_lshl_add_u64 v[226:227], v[228:229], 0, s[24:25]
	s_addc_u32 s41, s41, 0
	s_add_i32 s42, s72, s33
	global_load_lds_dwordx4 v[226:227], off
	v_lshl_add_u64 v[226:227], s[40:41], 0, v[138:139]
	s_mov_b32 m0, s42
	s_nop 0
	global_load_lds_dwordx4 v[226:227], off
	v_lshl_add_u64 v[226:227], s[40:41], 0, v[142:143]
	s_add_i32 m0, s42, 0x2000
	s_nop 0
	global_load_lds_dwordx4 v[226:227], off
	v_lshl_add_u64 v[226:227], v[230:231], 0, s[24:25]
	s_mov_b32 m0, s57
	s_nop 0
	global_load_lds_dwordx4 v[226:227], off
	v_lshl_add_u64 v[226:227], v[232:233], 0, s[24:25]
	s_mov_b32 m0, s58
	s_nop 0
	global_load_lds_dwordx4 v[226:227], off
	s_waitcnt vmcnt(8)
	s_waitcnt lgkmcnt(0)
	s_setprio 1
	s_barrier
; #define PG8_STAGE(bufoff, gbase, voff) do { _Pragma("unroll") for (int _i = 0; _i < 2; ++_i) \
;         __builtin_amdgcn_global_load_lds((const unsigned*)((const char*)(gbase) + (voff)[_i]), (PG8_LAS unsigned*)(lds + (bufoff) + ldsw + _i * 8192), 16, 0, 0); } while (0)
; #define PG8_LDA(dst, b, h) do { _Pragma("unroll") for (int m = 0; m < 4; ++m) _Pragma("unroll") for (int k = 0; k < 2; ++k) dst[m][k] = *(const PG8_LAS bf16x8*)(lds + PG8_SA(b, h) + aoff + m * 2048 + k * 1024); } while (0)
; #define PG8_LDB(dst, b, h) do { _Pragma("unroll") for (int n = 0; n < 2; ++n) _Pragma("unroll") for (int k = 0; k < 2; ++k) dst[n][k] = *(const PG8_LAS bf16x8*)(lds + PG8_SB(b, h) + boff + n * 2048 + k * 1024); } while (0)
; template <class Epi, class Sched, bool ALIGN_EPI = false, bool SP2 = false>
; __device__ __forceinline__ void gemm_phase(PG8_LAS unsigned char* lds, const Gemm g, const Sched& S, const Epi& E) {
;     ...
;         for (int t = 0; t < nt; t += 2) {
;             const bool last = (t == nt - 2);
;             const char* a1 = cA + (size_t)(t + 1) * kstep;
;             const char* a2 = last ? nA : cA + (size_t)(t + 2) * kstep; const char* b2 = last ? nB : cB + (size_t)(t + 2) * kstep;
;             const char* a3 = a2 + kstep; const char* b3 = b2 + kstep;
;             if (last && has_next) S.a_ready(nxt, ui + 1);
;             if constexpr (SP2) {
;             PG8_LDB(B0, 0, 0); PG8_LDB(B1, 0, 1); PG8_SCHED; PG8_LDA(At, 0, 0); PG8_STAGE(PG8_SA(1, 1), a1 + hstep, voffA);
;             PG8_WAIT_V(8); PG8_WAIT_L(0); PG8_BAR; PG8_MMA(0, 0, At, B0); PG8_MMA(0, 1, At, B1); PG8_BAR; PG8_SCHED;
;             PG8_LDA(At, 0, 1); PG8_STAGE(PG8_SB(0, 0), b2, voffB); PG8_STAGE(PG8_SB(0, 1), b2 + hstep, voffB); PG8_STAGE(PG8_SA(0, 0), a2, voffA);
;             PG8_WAIT_V(8); PG8_WAIT_L(0); PG8_BAR; PG8_MMA(1, 0, At, B0); PG8_MMA(1, 1, At, B1); PG8_BAR; PG8_SCHED;
;             PG8_LDB(B0, 1, 0); PG8_LDB(B1, 1, 1); PG8_SCHED; PG8_LDA(At, 1, 0); PG8_STAGE(PG8_SA(0, 1), a2 + hstep, voffA);
;             PG8_WAIT_V(8); PG8_WAIT_L(0); PG8_BAR; PG8_MMA(0, 0, At, B0); PG8_MMA(0, 1, At, B1); PG8_BAR; PG8_SCHED;
;             PG8_LDA(At, 1, 1); PG8_STAGE(PG8_SB(1, 0), b3, voffB); PG8_STAGE(PG8_SB(1, 1), b3 + hstep, voffB); PG8_STAGE(PG8_SA(1, 0), a3, voffA);
;             PG8_WAIT_V(8); PG8_WAIT_L(0); PG8_BAR; PG8_MMA(1, 0, At, B0); PG8_MMA(1, 1, At, B1); PG8_BAR; PG8_SCHED;
	v_mfma_f32_16x16x32_bf16 v[60:63], v[148:151], v[194:197], v[60:63]
	v_mfma_f32_16x16x32_bf16 v[56:59], v[170:173], v[194:197], v[56:59]
	v_mfma_f32_16x16x32_bf16 v[44:47], v[148:151], v[202:205], v[44:47]
	v_mfma_f32_16x16x32_bf16 v[40:43], v[170:173], v[202:205], v[40:43]
	v_mfma_f32_16x16x32_bf16 v[28:31], v[148:151], v[210:213], v[28:31]
	v_mfma_f32_16x16x32_bf16 v[24:27], v[170:173], v[210:213], v[24:27]
	v_mfma_f32_16x16x32_bf16 v[12:15], v[148:151], v[218:221], v[12:15]
	v_mfma_f32_16x16x32_bf16 v[8:11], v[170:173], v[218:221], v[8:11]
	v_mfma_f32_16x16x32_bf16 v[60:63], v[166:169], v[198:201], v[60:63]
	v_mfma_f32_16x16x32_bf16 v[56:59], v[174:177], v[198:201], v[56:59]
	v_mfma_f32_16x16x32_bf16 v[44:47], v[166:169], v[206:209], v[44:47]
	v_mfma_f32_16x16x32_bf16 v[40:43], v[174:177], v[206:209], v[40:43]
	v_mfma_f32_16x16x32_bf16 v[28:31], v[166:169], v[214:217], v[28:31]
	v_mfma_f32_16x16x32_bf16 v[24:27], v[174:177], v[214:217], v[24:27]
	v_mfma_f32_16x16x32_bf16 v[12:15], v[166:169], v[222:225], v[12:15]
	v_mfma_f32_16x16x32_bf16 v[8:11], v[174:177], v[222:225], v[8:11]
	s_setprio 0
	s_setprio 1
	v_mfma_f32_16x16x32_bf16 v[52:55], v[178:181], v[194:197], v[52:55]
	v_mfma_f32_16x16x32_bf16 v[48:51], v[186:189], v[194:197], v[48:51]
	v_mfma_f32_16x16x32_bf16 v[36:39], v[178:181], v[202:205], v[36:39]
	v_mfma_f32_16x16x32_bf16 v[32:35], v[186:189], v[202:205], v[32:35]
	v_mfma_f32_16x16x32_bf16 v[20:23], v[178:181], v[210:213], v[20:23]
	v_mfma_f32_16x16x32_bf16 v[16:19], v[186:189], v[210:213], v[16:19]
	v_mfma_f32_16x16x32_bf16 v[4:7], v[178:181], v[218:221], v[4:7]
	v_mfma_f32_16x16x32_bf16 v[0:3], v[186:189], v[218:221], v[0:3]
	v_mfma_f32_16x16x32_bf16 v[52:55], v[182:185], v[198:201], v[52:55]
	v_mfma_f32_16x16x32_bf16 v[48:51], v[190:193], v[198:201], v[48:51]
	v_mfma_f32_16x16x32_bf16 v[36:39], v[182:185], v[206:209], v[36:39]
	v_mfma_f32_16x16x32_bf16 v[32:35], v[190:193], v[206:209], v[32:35]
	v_mfma_f32_16x16x32_bf16 v[20:23], v[182:185], v[214:217], v[20:23]
	v_mfma_f32_16x16x32_bf16 v[16:19], v[190:193], v[214:217], v[16:19]
	v_mfma_f32_16x16x32_bf16 v[4:7], v[182:185], v[222:225], v[4:7]
	v_mfma_f32_16x16x32_bf16 v[0:3], v[190:193], v[222:225], v[0:3]
	s_barrier
	s_setprio 0
	s_add_i32 s70, s70, 2
	s_add_u32 s38, s38, 0x100
	s_addc_u32 s39, s39, 0
	s_add_u32 s44, s44, 0x100
	s_addc_u32 s45, s45, 0
	s_cmp_gt_u32 s70, 13
.LBB0_509:
	ds_read_b128 v[148:151], v162
	ds_read_b128 v[166:169], v162 offset:1024
	ds_read_b128 v[170:173], v162 offset:2048
	ds_read_b128 v[174:177], v162 offset:3072
	ds_read_b128 v[178:181], v163
	ds_read_b128 v[182:185], v163 offset:1024
	ds_read_b128 v[186:189], v163 offset:2048
	ds_read_b128 v[190:193], v163 offset:3072
	s_add_u32 s40, s38, 0xfffc0080
	s_addc_u32 s41, s39, -1
	s_cmp_eq_u32 s70, 12
	s_cselect_b32 s43, s9, s41
	s_cselect_b32 s42, s14, s40
	s_cselect_b32 s41, s29, s45
	s_cselect_b32 s40, s31, s44
	v_lshl_add_u64 v[226:227], s[38:39], 0, v[132:133]
	s_add_i32 m0, s52, 0xc000
	ds_read_b128 v[194:197], v164
	ds_read_b128 v[198:201], v164 offset:1024
	ds_read_b128 v[202:205], v164 offset:2048
	ds_read_b128 v[206:209], v164 offset:3072
	ds_read_b128 v[210:213], v164 offset:4096
	ds_read_b128 v[214:217], v164 offset:5120
	ds_read_b128 v[218:221], v164 offset:6144
	ds_read_b128 v[222:225], v164 offset:7168
	global_load_lds_dwordx4 v[226:227], off
	v_lshl_add_u64 v[226:227], s[38:39], 0, v[134:135]
	s_add_i32 m0, s52, 0xe000
	s_nop 0
	global_load_lds_dwordx4 v[226:227], off
	s_waitcnt vmcnt(8)
	s_waitcnt lgkmcnt(0)
	s_setprio 1
	s_barrier
	v_mfma_f32_16x16x32_bf16 v[124:127], v[148:151], v[194:197], v[124:127]
	v_mfma_f32_16x16x32_bf16 v[120:123], v[170:173], v[194:197], v[120:123]
	v_mfma_f32_16x16x32_bf16 v[108:111], v[148:151], v[202:205], v[108:111]
	v_mfma_f32_16x16x32_bf16 v[104:107], v[170:173], v[202:205], v[104:107]
	v_mfma_f32_16x16x32_bf16 v[92:95], v[148:151], v[210:213], v[92:95]
	v_mfma_f32_16x16x32_bf16 v[88:91], v[170:173], v[210:213], v[88:91]
	v_mfma_f32_16x16x32_bf16 v[76:79], v[148:151], v[218:221], v[76:79]
	v_mfma_f32_16x16x32_bf16 v[72:75], v[170:173], v[218:221], v[72:75]
	v_mfma_f32_16x16x32_bf16 v[124:127], v[166:169], v[198:201], v[124:127]
	v_mfma_f32_16x16x32_bf16 v[120:123], v[174:177], v[198:201], v[120:123]
	v_mfma_f32_16x16x32_bf16 v[108:111], v[166:169], v[206:209], v[108:111]
	v_mfma_f32_16x16x32_bf16 v[104:107], v[174:177], v[206:209], v[104:107]
	v_mfma_f32_16x16x32_bf16 v[92:95], v[166:169], v[214:217], v[92:95]
	v_mfma_f32_16x16x32_bf16 v[88:91], v[174:177], v[214:217], v[88:91]
	v_mfma_f32_16x16x32_bf16 v[76:79], v[166:169], v[222:225], v[76:79]
	v_mfma_f32_16x16x32_bf16 v[72:75], v[174:177], v[222:225], v[72:75]
	s_setprio 0
	s_setprio 1
	v_mfma_f32_16x16x32_bf16 v[116:119], v[178:181], v[194:197], v[116:119]
	v_mfma_f32_16x16x32_bf16 v[112:115], v[186:189], v[194:197], v[112:115]
	v_mfma_f32_16x16x32_bf16 v[100:103], v[178:181], v[202:205], v[100:103]
	v_mfma_f32_16x16x32_bf16 v[96:99], v[186:189], v[202:205], v[96:99]
	v_mfma_f32_16x16x32_bf16 v[84:87], v[178:181], v[210:213], v[84:87]
	v_mfma_f32_16x16x32_bf16 v[80:83], v[186:189], v[210:213], v[80:83]
	v_mfma_f32_16x16x32_bf16 v[68:71], v[178:181], v[218:221], v[68:71]
	v_mfma_f32_16x16x32_bf16 v[64:67], v[186:189], v[218:221], v[64:67]
	v_mfma_f32_16x16x32_bf16 v[116:119], v[182:185], v[198:201], v[116:119]
	v_mfma_f32_16x16x32_bf16 v[112:115], v[190:193], v[198:201], v[112:115]
	v_mfma_f32_16x16x32_bf16 v[100:103], v[182:185], v[206:209], v[100:103]
	v_mfma_f32_16x16x32_bf16 v[96:99], v[190:193], v[206:209], v[96:99]
	v_mfma_f32_16x16x32_bf16 v[84:87], v[182:185], v[214:217], v[84:87]
	v_mfma_f32_16x16x32_bf16 v[80:83], v[190:193], v[214:217], v[80:83]
	v_mfma_f32_16x16x32_bf16 v[68:71], v[182:185], v[222:225], v[68:71]
	v_mfma_f32_16x16x32_bf16 v[64:67], v[190:193], v[222:225], v[64:67]
	s_barrier
; #define PG8_STAGE(bufoff, gbase, voff) do { _Pragma("unroll") for (int _i = 0; _i < 2; ++_i) \
;         __builtin_amdgcn_global_load_lds((const unsigned*)((const char*)(gbase) + (voff)[_i]), (PG8_LAS unsigned*)(lds + (bufoff) + ldsw + _i * 8192), 16, 0, 0); } while (0)
; #define PG8_LDA(dst, b, h) do { _Pragma("unroll") for (int m = 0; m < 4; ++m) _Pragma("unroll") for (int k = 0; k < 2; ++k) dst[m][k] = *(const PG8_LAS bf16x8*)(lds + PG8_SA(b, h) + aoff + m * 2048 + k * 1024); } while (0)
; #define PG8_LDB(dst, b, h) do { _Pragma("unroll") for (int n = 0; n < 2; ++n) _Pragma("unroll") for (int k = 0; k < 2; ++k) dst[n][k] = *(const PG8_LAS bf16x8*)(lds + PG8_SB(b, h) + boff + n * 2048 + k * 1024); } while (0)
; #define PG8_MMA(ai, bj, At, Bt) do { __builtin_amdgcn_s_setprio(1); _Pragma("unroll") for (int m = 0; m < 4; ++m) _Pragma("unroll") for (int n = 0; n < 2; ++n) _Pragma("unroll") for (int k = 0; k < 2; ++k) \
;         acc[ai][bj][m][n] = __builtin_amdgcn_mfma_f32_16x16x32_bf16(Bt[n][k], At[m][k], acc[ai][bj][m][n], 0, 0, 0); __builtin_amdgcn_s_setprio(0); } while (0)
; #define PG8_WAIT_V(n) asm volatile("s_waitcnt vmcnt(" #n ")" ::: "memory")
; template <class Epi, class Sched, bool ALIGN_EPI = false, bool SP2 = false>
; __device__ __forceinline__ void gemm_phase(PG8_LAS unsigned char* lds, const Gemm g, const Sched& S, const Epi& E) {
;     ...
;             PG8_LDB(B0, 0, 0); PG8_LDB(B1, 0, 1); PG8_SCHED; PG8_LDA(At, 0, 0); PG8_STAGE(PG8_SA(1, 1), a1 + hstep, voffA);
;             PG8_WAIT_V(8); PG8_WAIT_L(0); PG8_BAR; PG8_MMA(0, 0, At, B0); PG8_MMA(0, 1, At, B1); PG8_BAR; PG8_SCHED;
;             PG8_LDA(At, 0, 1); PG8_STAGE(PG8_SB(0, 0), b2, voffB); PG8_STAGE(PG8_SB(0, 1), b2 + hstep, voffB); PG8_STAGE(PG8_SA(0, 0), a2, voffA);
;             PG8_WAIT_V(8); PG8_WAIT_L(0); PG8_BAR; PG8_MMA(1, 0, At, B0); PG8_MMA(1, 1, At, B1); PG8_BAR; PG8_SCHED;
;             PG8_LDB(B0, 1, 0); PG8_LDB(B1, 1, 1); PG8_SCHED; PG8_LDA(At, 1, 0); PG8_STAGE(PG8_SA(0, 1), a2 + hstep, voffA);
;             PG8_WAIT_V(8); PG8_WAIT_L(0); PG8_BAR; PG8_MMA(0, 0, At, B0); PG8_MMA(0, 1, At, B1); PG8_BAR; PG8_SCHED;
;             PG8_LDA(At, 1, 1); PG8_STAGE(PG8_SB(1, 0), b3, voffB); PG8_STAGE(PG8_SB(1, 1), b3 + hstep, voffB); PG8_STAGE(PG8_SA(1, 0), a3, voffA);
;             PG8_WAIT_V(8); PG8_WAIT_L(0); PG8_BAR; PG8_MMA(1, 0, At, B0); PG8_MMA(1, 1, At, B1); PG8_BAR; PG8_SCHED;
	s_setprio 0
	s_add_i32 s71, s61, s33
	v_lshl_add_u64 v[226:227], s[40:41], 0, v[138:139]
	s_mov_b32 m0, s71
	ds_read_b128 v[194:197], v164 offset:16384
	ds_read_b128 v[198:201], v164 offset:17408
	ds_read_b128 v[202:205], v164 offset:18432
	ds_read_b128 v[206:209], v164 offset:19456
	ds_read_b128 v[210:213], v164 offset:20480
	ds_read_b128 v[214:217], v164 offset:21504
	ds_read_b128 v[218:221], v164 offset:22528
	ds_read_b128 v[222:225], v164 offset:23552
	global_load_lds_dwordx4 v[226:227], off
	s_add_i32 m0, s71, 0x2000
	s_add_u32 s72, s40, 0x40000
	v_lshl_add_u64 v[228:229], s[40:41], 0, v[142:143]
	s_addc_u32 s73, s41, 0
	s_add_i32 s71, s62, s33
	global_load_lds_dwordx4 v[228:229], off
	v_lshl_add_u64 v[230:231], s[72:73], 0, v[138:139]
	s_mov_b32 m0, s71
	v_lshl_add_u64 v[232:233], s[42:43], 0, v[140:141]
	global_load_lds_dwordx4 v[230:231], off
	v_lshl_add_u64 v[230:231], s[72:73], 0, v[142:143]
	s_add_i32 m0, s71, 0x2000
	s_nop 0
	global_load_lds_dwordx4 v[230:231], off
	v_lshl_add_u64 v[230:231], s[42:43], 0, v[136:137]
	s_mov_b32 m0, s52
	s_nop 0
	global_load_lds_dwordx4 v[230:231], off
	s_mov_b32 m0, s53
	s_nop 0
	global_load_lds_dwordx4 v[232:233], off
	s_waitcnt vmcnt(8)
	s_waitcnt lgkmcnt(0)
	s_setprio 1
	s_barrier
	v_mfma_f32_16x16x32_bf16 v[60:63], v[148:151], v[194:197], v[60:63]
	v_mfma_f32_16x16x32_bf16 v[56:59], v[170:173], v[194:197], v[56:59]
	v_mfma_f32_16x16x32_bf16 v[44:47], v[148:151], v[202:205], v[44:47]
	v_mfma_f32_16x16x32_bf16 v[40:43], v[170:173], v[202:205], v[40:43]
	v_mfma_f32_16x16x32_bf16 v[28:31], v[148:151], v[210:213], v[28:31]
	v_mfma_f32_16x16x32_bf16 v[24:27], v[170:173], v[210:213], v[24:27]
	v_mfma_f32_16x16x32_bf16 v[12:15], v[148:151], v[218:221], v[12:15]
	v_mfma_f32_16x16x32_bf16 v[8:11], v[170:173], v[218:221], v[8:11]
	v_mfma_f32_16x16x32_bf16 v[60:63], v[166:169], v[198:201], v[60:63]
	v_mfma_f32_16x16x32_bf16 v[56:59], v[174:177], v[198:201], v[56:59]
	v_mfma_f32_16x16x32_bf16 v[44:47], v[166:169], v[206:209], v[44:47]
	v_mfma_f32_16x16x32_bf16 v[40:43], v[174:177], v[206:209], v[40:43]
	v_mfma_f32_16x16x32_bf16 v[28:31], v[166:169], v[214:217], v[28:31]
	v_mfma_f32_16x16x32_bf16 v[24:27], v[174:177], v[214:217], v[24:27]
	v_mfma_f32_16x16x32_bf16 v[12:15], v[166:169], v[222:225], v[12:15]
	v_mfma_f32_16x16x32_bf16 v[8:11], v[174:177], v[222:225], v[8:11]
	s_setprio 0
	s_setprio 1
	v_mfma_f32_16x16x32_bf16 v[52:55], v[178:181], v[194:197], v[52:55]
	v_mfma_f32_16x16x32_bf16 v[48:51], v[186:189], v[194:197], v[48:51]
	v_mfma_f32_16x16x32_bf16 v[36:39], v[178:181], v[202:205], v[36:39]
	v_mfma_f32_16x16x32_bf16 v[32:35], v[186:189], v[202:205], v[32:35]
	v_mfma_f32_16x16x32_bf16 v[20:23], v[178:181], v[210:213], v[20:23]
	v_mfma_f32_16x16x32_bf16 v[16:19], v[186:189], v[210:213], v[16:19]
	v_mfma_f32_16x16x32_bf16 v[4:7], v[178:181], v[218:221], v[4:7]
	v_mfma_f32_16x16x32_bf16 v[0:3], v[186:189], v[218:221], v[0:3]
	v_mfma_f32_16x16x32_bf16 v[52:55], v[182:185], v[198:201], v[52:55]
	v_mfma_f32_16x16x32_bf16 v[48:51], v[190:193], v[198:201], v[48:51]
	v_mfma_f32_16x16x32_bf16 v[36:39], v[182:185], v[206:209], v[36:39]
	v_mfma_f32_16x16x32_bf16 v[32:35], v[190:193], v[206:209], v[32:35]
	v_mfma_f32_16x16x32_bf16 v[20:23], v[182:185], v[214:217], v[20:23]
	v_mfma_f32_16x16x32_bf16 v[16:19], v[190:193], v[214:217], v[16:19]
	v_mfma_f32_16x16x32_bf16 v[4:7], v[182:185], v[222:225], v[4:7]
	v_mfma_f32_16x16x32_bf16 v[0:3], v[190:193], v[222:225], v[0:3]
	s_barrier
	s_setprio 0
	s_add_i32 s71, 0, 0x18000
	v_add_u32_e32 v130, s71, v160
	s_add_i32 s72, 0, 0x1c000
	ds_read_b128 v[148:151], v130
	ds_read_b128 v[166:169], v130 offset:1024
	ds_read_b128 v[170:173], v130 offset:2048
	ds_read_b128 v[174:177], v130 offset:3072
	v_add_u32_e32 v130, s72, v160
	ds_read_b128 v[178:181], v130
	ds_read_b128 v[182:185], v130 offset:1024
	ds_read_b128 v[186:189], v130 offset:2048
	ds_read_b128 v[190:193], v130 offset:3072
	s_add_u32 s42, s42, 0x40000
	s_addc_u32 s43, s43, 0
	s_mov_b32 m0, s54
	v_lshl_add_u64 v[234:235], s[42:43], 0, v[136:137]
	ds_read_b128 v[194:197], v164 offset:32768
	ds_read_b128 v[198:201], v164 offset:33792
	ds_read_b128 v[202:205], v164 offset:34816
	ds_read_b128 v[206:209], v164 offset:35840
	ds_read_b128 v[210:213], v164 offset:36864
	ds_read_b128 v[214:217], v164 offset:37888
	ds_read_b128 v[218:221], v164 offset:38912
	ds_read_b128 v[222:225], v164 offset:39936
	global_load_lds_dwordx4 v[234:235], off
	v_lshl_add_u64 v[234:235], s[42:43], 0, v[140:141]
	s_mov_b32 m0, s55
	s_nop 0
	global_load_lds_dwordx4 v[234:235], off
	s_waitcnt vmcnt(8)
	s_waitcnt lgkmcnt(0)
	s_setprio 1
	s_barrier
; #define PG8_STAGE(bufoff, gbase, voff) do { _Pragma("unroll") for (int _i = 0; _i < 2; ++_i) \
;         __builtin_amdgcn_global_load_lds((const unsigned*)((const char*)(gbase) + (voff)[_i]), (PG8_LAS unsigned*)(lds + (bufoff) + ldsw + _i * 8192), 16, 0, 0); } while (0)
; #define PG8_LDA(dst, b, h) do { _Pragma("unroll") for (int m = 0; m < 4; ++m) _Pragma("unroll") for (int k = 0; k < 2; ++k) dst[m][k] = *(const PG8_LAS bf16x8*)(lds + PG8_SA(b, h) + aoff + m * 2048 + k * 1024); } while (0)
; #define PG8_LDB(dst, b, h) do { _Pragma("unroll") for (int n = 0; n < 2; ++n) _Pragma("unroll") for (int k = 0; k < 2; ++k) dst[n][k] = *(const PG8_LAS bf16x8*)(lds + PG8_SB(b, h) + boff + n * 2048 + k * 1024); } while (0)
; #define PG8_MMA(ai, bj, At, Bt) do { __builtin_amdgcn_s_setprio(1); _Pragma("unroll") for (int m = 0; m < 4; ++m) _Pragma("unroll") for (int n = 0; n < 2; ++n) _Pragma("unroll") for (int k = 0; k < 2; ++k) \
;         acc[ai][bj][m][n] = __builtin_amdgcn_mfma_f32_16x16x32_bf16(Bt[n][k], At[m][k], acc[ai][bj][m][n], 0, 0, 0); __builtin_amdgcn_s_setprio(0); } while (0)
; template <class Epi, class Sched, bool ALIGN_EPI = false, bool SP2 = false>
; __device__ __forceinline__ void gemm_phase(PG8_LAS unsigned char* lds, const Gemm g, const Sched& S, const Epi& E) {
;     ...
;             PG8_LDB(B0, 0, 0); PG8_LDB(B1, 0, 1); PG8_SCHED; PG8_LDA(At, 0, 0); PG8_STAGE(PG8_SA(1, 1), a1 + hstep, voffA);
;             PG8_WAIT_V(8); PG8_WAIT_L(0); PG8_BAR; PG8_MMA(0, 0, At, B0); PG8_MMA(0, 1, At, B1); PG8_BAR; PG8_SCHED;
;             PG8_LDA(At, 0, 1); PG8_STAGE(PG8_SB(0, 0), b2, voffB); PG8_STAGE(PG8_SB(0, 1), b2 + hstep, voffB); PG8_STAGE(PG8_SA(0, 0), a2, voffA);
;             PG8_WAIT_V(8); PG8_WAIT_L(0); PG8_BAR; PG8_MMA(1, 0, At, B0); PG8_MMA(1, 1, At, B1); PG8_BAR; PG8_SCHED;
;             PG8_LDB(B0, 1, 0); PG8_LDB(B1, 1, 1); PG8_SCHED; PG8_LDA(At, 1, 0); PG8_STAGE(PG8_SA(0, 1), a2 + hstep, voffA);
;             PG8_WAIT_V(8); PG8_WAIT_L(0); PG8_BAR; PG8_MMA(0, 0, At, B0); PG8_MMA(0, 1, At, B1); PG8_BAR; PG8_SCHED;
;             PG8_LDA(At, 1, 1); PG8_STAGE(PG8_SB(1, 0), b3, voffB); PG8_STAGE(PG8_SB(1, 1), b3 + hstep, voffB); PG8_STAGE(PG8_SA(1, 0), a3, voffA);
;             PG8_WAIT_V(8); PG8_WAIT_L(0); PG8_BAR; PG8_MMA(1, 0, At, B0); PG8_MMA(1, 1, At, B1); PG8_BAR; PG8_SCHED;
;     ...
;         if constexpr (ALIGN_EPI) { if (wr == 0) PG8_BAR; }
	v_mfma_f32_16x16x32_bf16 v[124:127], v[148:151], v[194:197], v[124:127]
	v_mfma_f32_16x16x32_bf16 v[120:123], v[170:173], v[194:197], v[120:123]
	v_mfma_f32_16x16x32_bf16 v[108:111], v[148:151], v[202:205], v[108:111]
	v_mfma_f32_16x16x32_bf16 v[104:107], v[170:173], v[202:205], v[104:107]
	v_mfma_f32_16x16x32_bf16 v[92:95], v[148:151], v[210:213], v[92:95]
	v_mfma_f32_16x16x32_bf16 v[88:91], v[170:173], v[210:213], v[88:91]
	v_mfma_f32_16x16x32_bf16 v[76:79], v[148:151], v[218:221], v[76:79]
	v_mfma_f32_16x16x32_bf16 v[72:75], v[170:173], v[218:221], v[72:75]
	v_mfma_f32_16x16x32_bf16 v[124:127], v[166:169], v[198:201], v[124:127]
	v_mfma_f32_16x16x32_bf16 v[120:123], v[174:177], v[198:201], v[120:123]
	v_mfma_f32_16x16x32_bf16 v[108:111], v[166:169], v[206:209], v[108:111]
	v_mfma_f32_16x16x32_bf16 v[104:107], v[174:177], v[206:209], v[104:107]
	v_mfma_f32_16x16x32_bf16 v[92:95], v[166:169], v[214:217], v[92:95]
	v_mfma_f32_16x16x32_bf16 v[88:91], v[174:177], v[214:217], v[88:91]
	v_mfma_f32_16x16x32_bf16 v[76:79], v[166:169], v[222:225], v[76:79]
	v_mfma_f32_16x16x32_bf16 v[72:75], v[174:177], v[222:225], v[72:75]
	s_setprio 0
	s_setprio 1
	v_mfma_f32_16x16x32_bf16 v[116:119], v[178:181], v[194:197], v[116:119]
	v_mfma_f32_16x16x32_bf16 v[112:115], v[186:189], v[194:197], v[112:115]
	v_mfma_f32_16x16x32_bf16 v[100:103], v[178:181], v[202:205], v[100:103]
	v_mfma_f32_16x16x32_bf16 v[96:99], v[186:189], v[202:205], v[96:99]
	v_mfma_f32_16x16x32_bf16 v[84:87], v[178:181], v[210:213], v[84:87]
	v_mfma_f32_16x16x32_bf16 v[80:83], v[186:189], v[210:213], v[80:83]
	v_mfma_f32_16x16x32_bf16 v[68:71], v[178:181], v[218:221], v[68:71]
	v_mfma_f32_16x16x32_bf16 v[64:67], v[186:189], v[218:221], v[64:67]
	v_mfma_f32_16x16x32_bf16 v[116:119], v[182:185], v[198:201], v[116:119]
	v_mfma_f32_16x16x32_bf16 v[112:115], v[190:193], v[198:201], v[112:115]
	v_mfma_f32_16x16x32_bf16 v[100:103], v[182:185], v[206:209], v[100:103]
	v_mfma_f32_16x16x32_bf16 v[96:99], v[190:193], v[206:209], v[96:99]
	v_mfma_f32_16x16x32_bf16 v[84:87], v[182:185], v[214:217], v[84:87]
	v_mfma_f32_16x16x32_bf16 v[80:83], v[190:193], v[214:217], v[80:83]
	v_mfma_f32_16x16x32_bf16 v[68:71], v[182:185], v[222:225], v[68:71]
	v_mfma_f32_16x16x32_bf16 v[64:67], v[190:193], v[222:225], v[64:67]
	s_barrier
	s_setprio 0
	s_add_i32 s42, s71, s33
	v_lshl_add_u64 v[226:227], v[226:227], 0, s[24:25]
	s_mov_b32 m0, s42
	ds_read_b128 v[194:197], v164 offset:49152
	ds_read_b128 v[198:201], v164 offset:50176
	ds_read_b128 v[202:205], v164 offset:51200
	ds_read_b128 v[206:209], v164 offset:52224
	ds_read_b128 v[210:213], v164 offset:53248
	ds_read_b128 v[214:217], v164 offset:54272
	ds_read_b128 v[218:221], v164 offset:55296
	ds_read_b128 v[222:225], v164 offset:56320
	global_load_lds_dwordx4 v[226:227], off
	s_add_i32 m0, s42, 0x2000
	s_add_u32 s40, s40, 0x40080
	v_lshl_add_u64 v[226:227], v[228:229], 0, s[24:25]
	s_addc_u32 s41, s41, 0
	s_add_i32 s42, s72, s33
	global_load_lds_dwordx4 v[226:227], off
	v_lshl_add_u64 v[226:227], s[40:41], 0, v[138:139]
	s_mov_b32 m0, s42
	s_nop 0
	global_load_lds_dwordx4 v[226:227], off
	v_lshl_add_u64 v[226:227], s[40:41], 0, v[142:143]
	s_add_i32 m0, s42, 0x2000
	s_nop 0
	global_load_lds_dwordx4 v[226:227], off
	v_lshl_add_u64 v[226:227], v[230:231], 0, s[24:25]
	s_mov_b32 m0, s57
	s_nop 0
	global_load_lds_dwordx4 v[226:227], off
	v_lshl_add_u64 v[226:227], v[232:233], 0, s[24:25]
	s_mov_b32 m0, s58
	s_nop 0
	global_load_lds_dwordx4 v[226:227], off
	s_waitcnt vmcnt(8)
	s_waitcnt lgkmcnt(0)
	s_setprio 1
	s_barrier
	v_mfma_f32_16x16x32_bf16 v[60:63], v[148:151], v[194:197], v[60:63]
	v_mfma_f32_16x16x32_bf16 v[56:59], v[170:173], v[194:197], v[56:59]
	v_mfma_f32_16x16x32_bf16 v[44:47], v[148:151], v[202:205], v[44:47]
	v_mfma_f32_16x16x32_bf16 v[40:43], v[170:173], v[202:205], v[40:43]
	v_mfma_f32_16x16x32_bf16 v[28:31], v[148:151], v[210:213], v[28:31]
	v_mfma_f32_16x16x32_bf16 v[24:27], v[170:173], v[210:213], v[24:27]
	v_mfma_f32_16x16x32_bf16 v[12:15], v[148:151], v[218:221], v[12:15]
	v_mfma_f32_16x16x32_bf16 v[8:11], v[170:173], v[218:221], v[8:11]
	v_mfma_f32_16x16x32_bf16 v[60:63], v[166:169], v[198:201], v[60:63]
	v_mfma_f32_16x16x32_bf16 v[56:59], v[174:177], v[198:201], v[56:59]
	v_mfma_f32_16x16x32_bf16 v[44:47], v[166:169], v[206:209], v[44:47]
	v_mfma_f32_16x16x32_bf16 v[40:43], v[174:177], v[206:209], v[40:43]
	v_mfma_f32_16x16x32_bf16 v[28:31], v[166:169], v[214:217], v[28:31]
	v_mfma_f32_16x16x32_bf16 v[24:27], v[174:177], v[214:217], v[24:27]
	v_mfma_f32_16x16x32_bf16 v[12:15], v[166:169], v[222:225], v[12:15]
	v_mfma_f32_16x16x32_bf16 v[8:11], v[174:177], v[222:225], v[8:11]
	s_setprio 0
	s_setprio 1
	v_mfma_f32_16x16x32_bf16 v[52:55], v[178:181], v[194:197], v[52:55]
	v_mfma_f32_16x16x32_bf16 v[48:51], v[186:189], v[194:197], v[48:51]
	v_mfma_f32_16x16x32_bf16 v[36:39], v[178:181], v[202:205], v[36:39]
	v_mfma_f32_16x16x32_bf16 v[32:35], v[186:189], v[202:205], v[32:35]
	v_mfma_f32_16x16x32_bf16 v[20:23], v[178:181], v[210:213], v[20:23]
	v_mfma_f32_16x16x32_bf16 v[16:19], v[186:189], v[210:213], v[16:19]
	v_mfma_f32_16x16x32_bf16 v[4:7], v[178:181], v[218:221], v[4:7]
	v_mfma_f32_16x16x32_bf16 v[0:3], v[186:189], v[218:221], v[0:3]
	v_mfma_f32_16x16x32_bf16 v[52:55], v[182:185], v[198:201], v[52:55]
	v_mfma_f32_16x16x32_bf16 v[48:51], v[190:193], v[198:201], v[48:51]
	v_mfma_f32_16x16x32_bf16 v[36:39], v[182:185], v[206:209], v[36:39]
	v_mfma_f32_16x16x32_bf16 v[32:35], v[190:193], v[206:209], v[32:35]
	v_mfma_f32_16x16x32_bf16 v[20:23], v[182:185], v[214:217], v[20:23]
	v_mfma_f32_16x16x32_bf16 v[16:19], v[190:193], v[214:217], v[16:19]
	v_mfma_f32_16x16x32_bf16 v[4:7], v[182:185], v[222:225], v[4:7]
	v_mfma_f32_16x16x32_bf16 v[0:3], v[190:193], v[222:225], v[0:3]
	s_barrier
	s_setprio 0
	s_add_i32 s70, s70, 2
	s_add_u32 s38, s38, 0x100
	s_addc_u32 s39, s39, 0
	s_add_u32 s44, s44, 0x100
	s_addc_u32 s45, s45, 0
	s_cmp_gt_u32 s70, 13
	s_cbranch_scc0 .LBB0_509
	s_and_b64 vcc, exec, s[26:27]
	s_cbranch_vccz .LBB0_512
	s_barrier

; #define PG8_STAGE(bufoff, gbase, voff) do { _Pragma("unroll") for (int _i = 0; _i < 2; ++_i) \
;         __builtin_amdgcn_global_load_lds((const unsigned*)((const char*)(gbase) + (voff)[_i]), (PG8_LAS unsigned*)(lds + (bufoff) + ldsw + _i * 8192), 16, 0, 0); } while (0)
; #define PG8_LDA(dst, b, h) do { _Pragma("unroll") for (int m = 0; m < 4; ++m) _Pragma("unroll") for (int k = 0; k < 2; ++k) dst[m][k] = *(const PG8_LAS bf16x8*)(lds + PG8_SA(b, h) + aoff + m * 2048 + k * 1024); } while (0)
; template <class Epi, class Sched, bool ALIGN_EPI = false, bool SP2 = false>
; __device__ __forceinline__ void gemm_phase(PG8_LAS unsigned char* lds, const Gemm g, const Sched& S, const Epi& E) {
;     ...
;         const bool has_next = S.next(ui + 1, nxt);
;         const char* nA = has_next ? (const char*)g.A + (size_t)nxt.pm * tstep : cA; const char* nB = has_next ? (const char*)g.Bt + (size_t)nxt.pn * tstep : cB;
;         for (int t = 0; t < nt; t += 2) {
;             const bool last = (t == nt - 2);
;             const char* a1 = cA + (size_t)(t + 1) * kstep;
;             const char* a2 = last ? nA : cA + (size_t)(t + 2) * kstep; const char* b2 = last ? nB : cB + (size_t)(t + 2) * kstep;
;             const char* a3 = a2 + kstep; const char* b3 = b2 + kstep;
;             if (last && has_next) S.a_ready(nxt, ui + 1);
;             if constexpr (SP2) {
;             PG8_LDB(B0, 0, 0); PG8_LDB(B1, 0, 1); PG8_SCHED; PG8_LDA(At, 0, 0); PG8_STAGE(PG8_SA(1, 1), a1 + hstep, voffA);
;             PG8_WAIT_V(8); PG8_WAIT_L(0); PG8_BAR; PG8_MMA(0, 0, At, B0); PG8_MMA(0, 1, At, B1); PG8_BAR; PG8_SCHED;
;             PG8_LDA(At, 0, 1); PG8_STAGE(PG8_SB(0, 0), b2, voffB); PG8_STAGE(PG8_SB(0, 1), b2 + hstep, voffB); PG8_STAGE(PG8_SA(0, 0), a2, voffA);
;             PG8_WAIT_V(8); PG8_WAIT_L(0); PG8_BAR; PG8_MMA(1, 0, At, B0); PG8_MMA(1, 1, At, B1); PG8_BAR; PG8_SCHED;
;             PG8_LDB(B0, 1, 0); PG8_LDB(B1, 1, 1); PG8_SCHED; PG8_LDA(At, 1, 0); PG8_STAGE(PG8_SA(0, 1), a2 + hstep, voffA);
;             PG8_WAIT_V(8); PG8_WAIT_L(0); PG8_BAR; PG8_MMA(0, 0, At, B0); PG8_MMA(0, 1, At, B1); PG8_BAR; PG8_SCHED;
;             PG8_LDA(At, 1, 1); PG8_STAGE(PG8_SB(1, 0), b3, voffB); PG8_STAGE(PG8_SB(1, 1), b3 + hstep, voffB); PG8_STAGE(PG8_SA(1, 0), a3, voffA);
;             PG8_WAIT_V(8); PG8_WAIT_L(0); PG8_BAR; PG8_MMA(1, 0, At, B0); PG8_MMA(1, 1, At, B1); PG8_BAR; PG8_SCHED;
.LBB0_606:
	s_ashr_i32 s21, s20, 31
	s_lshl_b64 s[22:23], s[20:21], 19
	s_add_u32 s22, s36, s22
	s_addc_u32 s23, s37, s23
	s_and_b64 s[24:25], s[4:5], exec
	s_cselect_b32 s21, s23, s29
	s_cselect_b32 s55, s22, s28
	s_ashr_i32 s19, s18, 31
	s_lshl_b64 s[24:25], s[18:19], 19
	s_add_u32 s24, s48, s24
	s_addc_u32 s25, s49, s25
	s_and_b64 s[34:35], s[4:5], exec
	s_cselect_b32 s19, s25, s31
	s_cselect_b32 s56, s24, s30
	s_add_u32 s28, s28, 0x40080
	s_addc_u32 s29, s29, 0
	s_add_u32 s57, s30, 0x100
	s_addc_u32 s58, s31, 0
	s_mov_b32 s59, -2
	s_add_u32 s30, s28, 0xfffc0080
	s_addc_u32 s31, s29, -1
	s_cmp_eq_u32 s59, 12
	s_cselect_b32 s35, s21, s31
	s_cselect_b32 s34, s55, s30
	s_cselect_b32 s31, s19, s58
	s_cselect_b32 s30, s56, s57
	v_lshl_add_u64 v[160:161], s[28:29], 0, v[152:153]
	s_add_i32 m0, s38, 0xc000
	global_load_lds_dwordx4 v[160:161], off
	v_lshl_add_u64 v[160:161], s[28:29], 0, v[154:155]
	s_add_i32 m0, s38, 0xe000
	s_nop 0
	global_load_lds_dwordx4 v[160:161], off
	s_waitcnt vmcnt(8)
	s_waitcnt lgkmcnt(0)
	s_setprio 1
	s_barrier
	v_mfma_f32_16x16x32_bf16 v[124:127], v[128:131], v[198:201], 0
	v_mfma_f32_16x16x32_bf16 v[120:123], v[174:177], v[198:201], 0
	v_mfma_f32_16x16x32_bf16 v[116:119], v[128:131], v[206:209], 0
	v_mfma_f32_16x16x32_bf16 v[112:115], v[174:177], v[206:209], 0
	v_mfma_f32_16x16x32_bf16 v[108:111], v[128:131], v[214:217], 0
	v_mfma_f32_16x16x32_bf16 v[104:107], v[174:177], v[214:217], 0
	v_mfma_f32_16x16x32_bf16 v[100:103], v[128:131], v[222:225], 0
	v_mfma_f32_16x16x32_bf16 v[96:99], v[174:177], v[222:225], 0
	v_mfma_f32_16x16x32_bf16 v[124:127], v[132:135], v[202:205], v[124:127]
	v_mfma_f32_16x16x32_bf16 v[120:123], v[178:181], v[202:205], v[120:123]
	v_mfma_f32_16x16x32_bf16 v[116:119], v[132:135], v[210:213], v[116:119]
	v_mfma_f32_16x16x32_bf16 v[112:115], v[178:181], v[210:213], v[112:115]
	v_mfma_f32_16x16x32_bf16 v[108:111], v[132:135], v[218:221], v[108:111]
	v_mfma_f32_16x16x32_bf16 v[104:107], v[178:181], v[218:221], v[104:107]
	v_mfma_f32_16x16x32_bf16 v[100:103], v[132:135], v[226:229], v[100:103]
	v_mfma_f32_16x16x32_bf16 v[96:99], v[178:181], v[226:229], v[96:99]
	s_setprio 0
	s_setprio 1
	v_mfma_f32_16x16x32_bf16 v[60:63], v[182:185], v[198:201], 0
	v_mfma_f32_16x16x32_bf16 v[56:59], v[190:193], v[198:201], 0
	v_mfma_f32_16x16x32_bf16 v[52:55], v[182:185], v[206:209], 0
	v_mfma_f32_16x16x32_bf16 v[48:51], v[190:193], v[206:209], 0
	v_mfma_f32_16x16x32_bf16 v[44:47], v[182:185], v[214:217], 0
	v_mfma_f32_16x16x32_bf16 v[40:43], v[190:193], v[214:217], 0
	v_mfma_f32_16x16x32_bf16 v[36:39], v[182:185], v[222:225], 0
	v_mfma_f32_16x16x32_bf16 v[32:35], v[190:193], v[222:225], 0
	v_mfma_f32_16x16x32_bf16 v[60:63], v[186:189], v[202:205], v[60:63]
	v_mfma_f32_16x16x32_bf16 v[56:59], v[194:197], v[202:205], v[56:59]
	v_mfma_f32_16x16x32_bf16 v[52:55], v[186:189], v[210:213], v[52:55]
	v_mfma_f32_16x16x32_bf16 v[48:51], v[194:197], v[210:213], v[48:51]
	v_mfma_f32_16x16x32_bf16 v[44:47], v[186:189], v[218:221], v[44:47]
	v_mfma_f32_16x16x32_bf16 v[40:43], v[194:197], v[218:221], v[40:43]
	v_mfma_f32_16x16x32_bf16 v[36:39], v[186:189], v[226:229], v[36:39]
	v_mfma_f32_16x16x32_bf16 v[32:35], v[194:197], v[226:229], v[32:35]
	s_barrier
	s_setprio 0
	s_add_i32 s60, s45, s33
	v_lshl_add_u64 v[160:161], s[30:31], 0, v[138:139]
	s_mov_b32 m0, s60
	ds_read_b128 v[198:201], v172 offset:16384
	ds_read_b128 v[202:205], v172 offset:17408
	ds_read_b128 v[206:209], v172 offset:18432
	ds_read_b128 v[210:213], v172 offset:19456
	ds_read_b128 v[214:217], v172 offset:20480
	ds_read_b128 v[218:221], v172 offset:21504
	ds_read_b128 v[222:225], v172 offset:22528
	ds_read_b128 v[226:229], v172 offset:23552
	global_load_lds_dwordx4 v[160:161], off
	s_add_i32 m0, s60, 0x2000
	s_add_u32 s60, s30, 0x40000
	v_lshl_add_u64 v[230:231], s[30:31], 0, v[142:143]
	s_addc_u32 s61, s31, 0
	s_add_i32 s62, s50, s33
	global_load_lds_dwordx4 v[230:231], off
	v_lshl_add_u64 v[232:233], s[60:61], 0, v[138:139]
	s_mov_b32 m0, s62
	v_lshl_add_u64 v[234:235], s[34:35], 0, v[140:141]
	global_load_lds_dwordx4 v[232:233], off
	v_lshl_add_u64 v[232:233], s[60:61], 0, v[142:143]
	s_add_i32 m0, s62, 0x2000
	s_nop 0
	global_load_lds_dwordx4 v[232:233], off
	v_lshl_add_u64 v[232:233], s[34:35], 0, v[136:137]
	s_mov_b32 m0, s38
	s_nop 0
	global_load_lds_dwordx4 v[232:233], off
	s_mov_b32 m0, s39
	s_nop 0
	global_load_lds_dwordx4 v[234:235], off
	s_waitcnt vmcnt(8)
	s_waitcnt lgkmcnt(0)
	s_setprio 1
	s_barrier
	v_mfma_f32_16x16x32_bf16 v[92:95], v[128:131], v[198:201], 0
	v_mfma_f32_16x16x32_bf16 v[88:91], v[174:177], v[198:201], 0
	v_mfma_f32_16x16x32_bf16 v[84:87], v[128:131], v[206:209], 0
	v_mfma_f32_16x16x32_bf16 v[80:83], v[174:177], v[206:209], 0
	v_mfma_f32_16x16x32_bf16 v[76:79], v[128:131], v[214:217], 0
	v_mfma_f32_16x16x32_bf16 v[72:75], v[174:177], v[214:217], 0
	v_mfma_f32_16x16x32_bf16 v[68:71], v[128:131], v[222:225], 0
	v_mfma_f32_16x16x32_bf16 v[64:67], v[174:177], v[222:225], 0
	v_mfma_f32_16x16x32_bf16 v[92:95], v[132:135], v[202:205], v[92:95]
	v_mfma_f32_16x16x32_bf16 v[88:91], v[178:181], v[202:205], v[88:91]
	v_mfma_f32_16x16x32_bf16 v[84:87], v[132:135], v[210:213], v[84:87]
	v_mfma_f32_16x16x32_bf16 v[80:83], v[178:181], v[210:213], v[80:83]
	v_mfma_f32_16x16x32_bf16 v[76:79], v[132:135], v[218:221], v[76:79]
	v_mfma_f32_16x16x32_bf16 v[72:75], v[178:181], v[218:221], v[72:75]
	v_mfma_f32_16x16x32_bf16 v[68:71], v[132:135], v[226:229], v[68:71]
	v_mfma_f32_16x16x32_bf16 v[64:67], v[178:181], v[226:229], v[64:67]
	s_setprio 0
	s_setprio 1
	v_mfma_f32_16x16x32_bf16 v[28:31], v[182:185], v[198:201], 0
	v_mfma_f32_16x16x32_bf16 v[24:27], v[190:193], v[198:201], 0
	v_mfma_f32_16x16x32_bf16 v[20:23], v[182:185], v[206:209], 0
	v_mfma_f32_16x16x32_bf16 v[16:19], v[190:193], v[206:209], 0
	v_mfma_f32_16x16x32_bf16 v[12:15], v[182:185], v[214:217], 0
	v_mfma_f32_16x16x32_bf16 v[8:11], v[190:193], v[214:217], 0
	v_mfma_f32_16x16x32_bf16 v[4:7], v[182:185], v[222:225], 0
	v_mfma_f32_16x16x32_bf16 v[0:3], v[190:193], v[222:225], 0
	v_mfma_f32_16x16x32_bf16 v[28:31], v[186:189], v[202:205], v[28:31]
	v_mfma_f32_16x16x32_bf16 v[24:27], v[194:197], v[202:205], v[24:27]
	v_mfma_f32_16x16x32_bf16 v[20:23], v[186:189], v[210:213], v[20:23]
	v_mfma_f32_16x16x32_bf16 v[16:19], v[194:197], v[210:213], v[16:19]
	v_mfma_f32_16x16x32_bf16 v[12:15], v[186:189], v[218:221], v[12:15]
	v_mfma_f32_16x16x32_bf16 v[8:11], v[194:197], v[218:221], v[8:11]
	v_mfma_f32_16x16x32_bf16 v[4:7], v[186:189], v[226:229], v[4:7]
	v_mfma_f32_16x16x32_bf16 v[0:3], v[194:197], v[226:229], v[0:3]
	s_barrier
; #define PG8_STAGE(bufoff, gbase, voff) do { _Pragma("unroll") for (int _i = 0; _i < 2; ++_i) \
;         __builtin_amdgcn_global_load_lds((const unsigned*)((const char*)(gbase) + (voff)[_i]), (PG8_LAS unsigned*)(lds + (bufoff) + ldsw + _i * 8192), 16, 0, 0); } while (0)
; #define PG8_LDA(dst, b, h) do { _Pragma("unroll") for (int m = 0; m < 4; ++m) _Pragma("unroll") for (int k = 0; k < 2; ++k) dst[m][k] = *(const PG8_LAS bf16x8*)(lds + PG8_SA(b, h) + aoff + m * 2048 + k * 1024); } while (0)
; #define PG8_LDB(dst, b, h) do { _Pragma("unroll") for (int n = 0; n < 2; ++n) _Pragma("unroll") for (int k = 0; k < 2; ++k) dst[n][k] = *(const PG8_LAS bf16x8*)(lds + PG8_SB(b, h) + boff + n * 2048 + k * 1024); } while (0)
; #define PG8_MMA(ai, bj, At, Bt) do { __builtin_amdgcn_s_setprio(1); _Pragma("unroll") for (int m = 0; m < 4; ++m) _Pragma("unroll") for (int n = 0; n < 2; ++n) _Pragma("unroll") for (int k = 0; k < 2; ++k) \
;         acc[ai][bj][m][n] = __builtin_amdgcn_mfma_f32_16x16x32_bf16(Bt[n][k], At[m][k], acc[ai][bj][m][n], 0, 0, 0); __builtin_amdgcn_s_setprio(0); } while (0)
; #define PG8_WAIT_V(n) asm volatile("s_waitcnt vmcnt(" #n ")" ::: "memory")
; template <class Epi, class Sched, bool ALIGN_EPI = false, bool SP2 = false>
; __device__ __forceinline__ void gemm_phase(PG8_LAS unsigned char* lds, const Gemm g, const Sched& S, const Epi& E) {
;     ...
;             PG8_LDB(B0, 0, 0); PG8_LDB(B1, 0, 1); PG8_SCHED; PG8_LDA(At, 0, 0); PG8_STAGE(PG8_SA(1, 1), a1 + hstep, voffA);
;             PG8_WAIT_V(8); PG8_WAIT_L(0); PG8_BAR; PG8_MMA(0, 0, At, B0); PG8_MMA(0, 1, At, B1); PG8_BAR; PG8_SCHED;
;             PG8_LDA(At, 0, 1); PG8_STAGE(PG8_SB(0, 0), b2, voffB); PG8_STAGE(PG8_SB(0, 1), b2 + hstep, voffB); PG8_STAGE(PG8_SA(0, 0), a2, voffA);
;             PG8_WAIT_V(8); PG8_WAIT_L(0); PG8_BAR; PG8_MMA(1, 0, At, B0); PG8_MMA(1, 1, At, B1); PG8_BAR; PG8_SCHED;
;             PG8_LDB(B0, 1, 0); PG8_LDB(B1, 1, 1); PG8_SCHED; PG8_LDA(At, 1, 0); PG8_STAGE(PG8_SA(0, 1), a2 + hstep, voffA);
;             PG8_WAIT_V(8); PG8_WAIT_L(0); PG8_BAR; PG8_MMA(0, 0, At, B0); PG8_MMA(0, 1, At, B1); PG8_BAR; PG8_SCHED;
;             PG8_LDA(At, 1, 1); PG8_STAGE(PG8_SB(1, 0), b3, voffB); PG8_STAGE(PG8_SB(1, 1), b3 + hstep, voffB); PG8_STAGE(PG8_SA(1, 0), a3, voffA);
;             PG8_WAIT_V(8); PG8_WAIT_L(0); PG8_BAR; PG8_MMA(1, 0, At, B0); PG8_MMA(1, 1, At, B1); PG8_BAR; PG8_SCHED;
	s_setprio 0
	s_add_i32 s60, 0, 0x18000
	s_add_i32 s61, 0, 0x1c000
	v_add_u32_e32 v178, s60, v163
	v_add_u32_e32 v194, s61, v163
	ds_read_b128 v[128:131], v178
	ds_read_b128 v[132:135], v178 offset:1024
	ds_read_b128 v[174:177], v178 offset:2048
	ds_read_b128 v[178:181], v178 offset:3072
	ds_read_b128 v[182:185], v194
	ds_read_b128 v[186:189], v194 offset:1024
	ds_read_b128 v[190:193], v194 offset:2048
	ds_read_b128 v[194:197], v194 offset:3072
	s_add_u32 s34, s34, 0x40000
	s_addc_u32 s35, s35, 0
	s_mov_b32 m0, s40
	v_lshl_add_u64 v[236:237], s[34:35], 0, v[136:137]
	ds_read_b128 v[198:201], v172 offset:32768
	ds_read_b128 v[202:205], v172 offset:33792
	ds_read_b128 v[206:209], v172 offset:34816
	ds_read_b128 v[210:213], v172 offset:35840
	ds_read_b128 v[214:217], v172 offset:36864
	ds_read_b128 v[218:221], v172 offset:37888
	ds_read_b128 v[222:225], v172 offset:38912
	ds_read_b128 v[226:229], v172 offset:39936
	global_load_lds_dwordx4 v[236:237], off
	v_lshl_add_u64 v[236:237], s[34:35], 0, v[140:141]
	s_mov_b32 m0, s41
	s_nop 0
	global_load_lds_dwordx4 v[236:237], off
	s_waitcnt vmcnt(8)
	s_waitcnt lgkmcnt(0)
	s_setprio 1
	s_barrier
	v_mfma_f32_16x16x32_bf16 v[124:127], v[128:131], v[198:201], v[124:127]
	v_mfma_f32_16x16x32_bf16 v[120:123], v[174:177], v[198:201], v[120:123]
	v_mfma_f32_16x16x32_bf16 v[116:119], v[128:131], v[206:209], v[116:119]
	v_mfma_f32_16x16x32_bf16 v[112:115], v[174:177], v[206:209], v[112:115]
	v_mfma_f32_16x16x32_bf16 v[108:111], v[128:131], v[214:217], v[108:111]
	v_mfma_f32_16x16x32_bf16 v[104:107], v[174:177], v[214:217], v[104:107]
	v_mfma_f32_16x16x32_bf16 v[100:103], v[128:131], v[222:225], v[100:103]
	v_mfma_f32_16x16x32_bf16 v[96:99], v[174:177], v[222:225], v[96:99]
	v_mfma_f32_16x16x32_bf16 v[124:127], v[132:135], v[202:205], v[124:127]
	v_mfma_f32_16x16x32_bf16 v[120:123], v[178:181], v[202:205], v[120:123]
	v_mfma_f32_16x16x32_bf16 v[116:119], v[132:135], v[210:213], v[116:119]
	v_mfma_f32_16x16x32_bf16 v[112:115], v[178:181], v[210:213], v[112:115]
	v_mfma_f32_16x16x32_bf16 v[108:111], v[132:135], v[218:221], v[108:111]
	v_mfma_f32_16x16x32_bf16 v[104:107], v[178:181], v[218:221], v[104:107]
	v_mfma_f32_16x16x32_bf16 v[100:103], v[132:135], v[226:229], v[100:103]
	v_mfma_f32_16x16x32_bf16 v[96:99], v[178:181], v[226:229], v[96:99]
	s_setprio 0
	s_setprio 1
	v_mfma_f32_16x16x32_bf16 v[60:63], v[182:185], v[198:201], v[60:63]
	v_mfma_f32_16x16x32_bf16 v[56:59], v[190:193], v[198:201], v[56:59]
	v_mfma_f32_16x16x32_bf16 v[52:55], v[182:185], v[206:209], v[52:55]
	v_mfma_f32_16x16x32_bf16 v[48:51], v[190:193], v[206:209], v[48:51]
	v_mfma_f32_16x16x32_bf16 v[44:47], v[182:185], v[214:217], v[44:47]
	v_mfma_f32_16x16x32_bf16 v[40:43], v[190:193], v[214:217], v[40:43]
	v_mfma_f32_16x16x32_bf16 v[36:39], v[182:185], v[222:225], v[36:39]
	v_mfma_f32_16x16x32_bf16 v[32:35], v[190:193], v[222:225], v[32:35]
	v_mfma_f32_16x16x32_bf16 v[60:63], v[186:189], v[202:205], v[60:63]
	v_mfma_f32_16x16x32_bf16 v[56:59], v[194:197], v[202:205], v[56:59]
	v_mfma_f32_16x16x32_bf16 v[52:55], v[186:189], v[210:213], v[52:55]
	v_mfma_f32_16x16x32_bf16 v[48:51], v[194:197], v[210:213], v[48:51]
	v_mfma_f32_16x16x32_bf16 v[44:47], v[186:189], v[218:221], v[44:47]
	v_mfma_f32_16x16x32_bf16 v[40:43], v[194:197], v[218:221], v[40:43]
	v_mfma_f32_16x16x32_bf16 v[36:39], v[186:189], v[226:229], v[36:39]
	v_mfma_f32_16x16x32_bf16 v[32:35], v[194:197], v[226:229], v[32:35]
	s_barrier
	s_setprio 0
	s_add_i32 s34, s60, s33
	v_lshl_add_u64 v[160:161], v[160:161], 0, s[16:17]
	s_mov_b32 m0, s34
	ds_read_b128 v[198:201], v172 offset:49152
	ds_read_b128 v[202:205], v172 offset:50176
	ds_read_b128 v[206:209], v172 offset:51200
	ds_read_b128 v[210:213], v172 offset:52224
	ds_read_b128 v[214:217], v172 offset:53248
	ds_read_b128 v[218:221], v172 offset:54272
	ds_read_b128 v[222:225], v172 offset:55296
	ds_read_b128 v[226:229], v172 offset:56320
	global_load_lds_dwordx4 v[160:161], off
	s_add_i32 m0, s34, 0x2000
	s_add_u32 s30, s30, 0x40080
	v_lshl_add_u64 v[160:161], v[230:231], 0, s[16:17]
	s_addc_u32 s31, s31, 0
	s_add_i32 s34, s61, s33
	global_load_lds_dwordx4 v[160:161], off
	v_lshl_add_u64 v[160:161], s[30:31], 0, v[138:139]
	s_mov_b32 m0, s34
	s_nop 0
	global_load_lds_dwordx4 v[160:161], off
	v_lshl_add_u64 v[160:161], s[30:31], 0, v[142:143]
	s_add_i32 m0, s34, 0x2000
	s_nop 0
	global_load_lds_dwordx4 v[160:161], off
	v_lshl_add_u64 v[160:161], v[232:233], 0, s[16:17]
	s_mov_b32 m0, s42
	s_nop 0
	global_load_lds_dwordx4 v[160:161], off
	v_lshl_add_u64 v[160:161], v[234:235], 0, s[16:17]
	s_mov_b32 m0, s43
	s_nop 0
	global_load_lds_dwordx4 v[160:161], off
	s_waitcnt vmcnt(8)
	s_waitcnt lgkmcnt(0)
	s_setprio 1
	s_barrier
; #define PG8_STAGE(bufoff, gbase, voff) do { _Pragma("unroll") for (int _i = 0; _i < 2; ++_i) \
;         __builtin_amdgcn_global_load_lds((const unsigned*)((const char*)(gbase) + (voff)[_i]), (PG8_LAS unsigned*)(lds + (bufoff) + ldsw + _i * 8192), 16, 0, 0); } while (0)
; #define PG8_LDA(dst, b, h) do { _Pragma("unroll") for (int m = 0; m < 4; ++m) _Pragma("unroll") for (int k = 0; k < 2; ++k) dst[m][k] = *(const PG8_LAS bf16x8*)(lds + PG8_SA(b, h) + aoff + m * 2048 + k * 1024); } while (0)
; #define PG8_LDB(dst, b, h) do { _Pragma("unroll") for (int n = 0; n < 2; ++n) _Pragma("unroll") for (int k = 0; k < 2; ++k) dst[n][k] = *(const PG8_LAS bf16x8*)(lds + PG8_SB(b, h) + boff + n * 2048 + k * 1024); } while (0)
; template <class Epi, class Sched, bool ALIGN_EPI = false, bool SP2 = false>
; __device__ __forceinline__ void gemm_phase(PG8_LAS unsigned char* lds, const Gemm g, const Sched& S, const Epi& E) {
;     ...
;         for (int t = 0; t < nt; t += 2) {
;             const bool last = (t == nt - 2);
;             const char* a1 = cA + (size_t)(t + 1) * kstep;
;             const char* a2 = last ? nA : cA + (size_t)(t + 2) * kstep; const char* b2 = last ? nB : cB + (size_t)(t + 2) * kstep;
;             const char* a3 = a2 + kstep; const char* b3 = b2 + kstep;
;             if (last && has_next) S.a_ready(nxt, ui + 1);
;             if constexpr (SP2) {
;             PG8_LDB(B0, 0, 0); PG8_LDB(B1, 0, 1); PG8_SCHED; PG8_LDA(At, 0, 0); PG8_STAGE(PG8_SA(1, 1), a1 + hstep, voffA);
;             PG8_WAIT_V(8); PG8_WAIT_L(0); PG8_BAR; PG8_MMA(0, 0, At, B0); PG8_MMA(0, 1, At, B1); PG8_BAR; PG8_SCHED;
;             PG8_LDA(At, 0, 1); PG8_STAGE(PG8_SB(0, 0), b2, voffB); PG8_STAGE(PG8_SB(0, 1), b2 + hstep, voffB); PG8_STAGE(PG8_SA(0, 0), a2, voffA);
;             PG8_WAIT_V(8); PG8_WAIT_L(0); PG8_BAR; PG8_MMA(1, 0, At, B0); PG8_MMA(1, 1, At, B1); PG8_BAR; PG8_SCHED;
;             PG8_LDB(B0, 1, 0); PG8_LDB(B1, 1, 1); PG8_SCHED; PG8_LDA(At, 1, 0); PG8_STAGE(PG8_SA(0, 1), a2 + hstep, voffA);
;             PG8_WAIT_V(8); PG8_WAIT_L(0); PG8_BAR; PG8_MMA(0, 0, At, B0); PG8_MMA(0, 1, At, B1); PG8_BAR; PG8_SCHED;
;             PG8_LDA(At, 1, 1); PG8_STAGE(PG8_SB(1, 0), b3, voffB); PG8_STAGE(PG8_SB(1, 1), b3 + hstep, voffB); PG8_STAGE(PG8_SA(1, 0), a3, voffA);
;             PG8_WAIT_V(8); PG8_WAIT_L(0); PG8_BAR; PG8_MMA(1, 0, At, B0); PG8_MMA(1, 1, At, B1); PG8_BAR; PG8_SCHED;
	v_mfma_f32_16x16x32_bf16 v[92:95], v[128:131], v[198:201], v[92:95]
	v_mfma_f32_16x16x32_bf16 v[88:91], v[174:177], v[198:201], v[88:91]
	v_mfma_f32_16x16x32_bf16 v[84:87], v[128:131], v[206:209], v[84:87]
	v_mfma_f32_16x16x32_bf16 v[80:83], v[174:177], v[206:209], v[80:83]
	v_mfma_f32_16x16x32_bf16 v[76:79], v[128:131], v[214:217], v[76:79]
	v_mfma_f32_16x16x32_bf16 v[72:75], v[174:177], v[214:217], v[72:75]
	v_mfma_f32_16x16x32_bf16 v[68:71], v[128:131], v[222:225], v[68:71]
	v_mfma_f32_16x16x32_bf16 v[64:67], v[174:177], v[222:225], v[64:67]
	v_mfma_f32_16x16x32_bf16 v[92:95], v[132:135], v[202:205], v[92:95]
	v_mfma_f32_16x16x32_bf16 v[88:91], v[178:181], v[202:205], v[88:91]
	v_mfma_f32_16x16x32_bf16 v[84:87], v[132:135], v[210:213], v[84:87]
	v_mfma_f32_16x16x32_bf16 v[80:83], v[178:181], v[210:213], v[80:83]
	v_mfma_f32_16x16x32_bf16 v[76:79], v[132:135], v[218:221], v[76:79]
	v_mfma_f32_16x16x32_bf16 v[72:75], v[178:181], v[218:221], v[72:75]
	v_mfma_f32_16x16x32_bf16 v[68:71], v[132:135], v[226:229], v[68:71]
	v_mfma_f32_16x16x32_bf16 v[64:67], v[178:181], v[226:229], v[64:67]
	s_setprio 0
	s_setprio 1
	v_mfma_f32_16x16x32_bf16 v[28:31], v[182:185], v[198:201], v[28:31]
	v_mfma_f32_16x16x32_bf16 v[24:27], v[190:193], v[198:201], v[24:27]
	v_mfma_f32_16x16x32_bf16 v[20:23], v[182:185], v[206:209], v[20:23]
	v_mfma_f32_16x16x32_bf16 v[16:19], v[190:193], v[206:209], v[16:19]
	v_mfma_f32_16x16x32_bf16 v[12:15], v[182:185], v[214:217], v[12:15]
	v_mfma_f32_16x16x32_bf16 v[8:11], v[190:193], v[214:217], v[8:11]
	v_mfma_f32_16x16x32_bf16 v[4:7], v[182:185], v[222:225], v[4:7]
	v_mfma_f32_16x16x32_bf16 v[0:3], v[190:193], v[222:225], v[0:3]
	v_mfma_f32_16x16x32_bf16 v[28:31], v[186:189], v[202:205], v[28:31]
	v_mfma_f32_16x16x32_bf16 v[24:27], v[194:197], v[202:205], v[24:27]
	v_mfma_f32_16x16x32_bf16 v[20:23], v[186:189], v[210:213], v[20:23]
	v_mfma_f32_16x16x32_bf16 v[16:19], v[194:197], v[210:213], v[16:19]
	v_mfma_f32_16x16x32_bf16 v[12:15], v[186:189], v[218:221], v[12:15]
	v_mfma_f32_16x16x32_bf16 v[8:11], v[194:197], v[218:221], v[8:11]
	v_mfma_f32_16x16x32_bf16 v[4:7], v[186:189], v[226:229], v[4:7]
	v_mfma_f32_16x16x32_bf16 v[0:3], v[194:197], v[226:229], v[0:3]
	s_barrier
	s_setprio 0
	s_add_i32 s59, s59, 2
	s_add_u32 s28, s28, 0x100
	s_addc_u32 s29, s29, 0
	s_add_u32 s57, s57, 0x100
	s_addc_u32 s58, s58, 0
	s_cmp_gt_u32 s59, 13
.LBB0_607:
	ds_read_b128 v[128:131], v170
	ds_read_b128 v[132:135], v170 offset:1024
	ds_read_b128 v[174:177], v170 offset:2048
	ds_read_b128 v[178:181], v170 offset:3072
	ds_read_b128 v[182:185], v171
	ds_read_b128 v[186:189], v171 offset:1024
	ds_read_b128 v[190:193], v171 offset:2048
	ds_read_b128 v[194:197], v171 offset:3072
	s_add_u32 s30, s28, 0xfffc0080
	s_addc_u32 s31, s29, -1
	s_cmp_eq_u32 s59, 12
	s_cselect_b32 s35, s21, s31
	s_cselect_b32 s34, s55, s30
	s_cselect_b32 s31, s19, s58
	s_cselect_b32 s30, s56, s57
	v_lshl_add_u64 v[160:161], s[28:29], 0, v[152:153]
	s_add_i32 m0, s38, 0xc000
	ds_read_b128 v[198:201], v172
	ds_read_b128 v[202:205], v172 offset:1024
	ds_read_b128 v[206:209], v172 offset:2048
	ds_read_b128 v[210:213], v172 offset:3072
	ds_read_b128 v[214:217], v172 offset:4096
	ds_read_b128 v[218:221], v172 offset:5120
	ds_read_b128 v[222:225], v172 offset:6144
	ds_read_b128 v[226:229], v172 offset:7168
	global_load_lds_dwordx4 v[160:161], off
	v_lshl_add_u64 v[160:161], s[28:29], 0, v[154:155]
	s_add_i32 m0, s38, 0xe000
	s_nop 0
	global_load_lds_dwordx4 v[160:161], off
	s_waitcnt vmcnt(8)
	s_waitcnt lgkmcnt(0)
	s_setprio 1
	s_barrier
	v_mfma_f32_16x16x32_bf16 v[124:127], v[128:131], v[198:201], v[124:127]
	v_mfma_f32_16x16x32_bf16 v[120:123], v[174:177], v[198:201], v[120:123]
	v_mfma_f32_16x16x32_bf16 v[116:119], v[128:131], v[206:209], v[116:119]
	v_mfma_f32_16x16x32_bf16 v[112:115], v[174:177], v[206:209], v[112:115]
	v_mfma_f32_16x16x32_bf16 v[108:111], v[128:131], v[214:217], v[108:111]
	v_mfma_f32_16x16x32_bf16 v[104:107], v[174:177], v[214:217], v[104:107]
	v_mfma_f32_16x16x32_bf16 v[100:103], v[128:131], v[222:225], v[100:103]
	v_mfma_f32_16x16x32_bf16 v[96:99], v[174:177], v[222:225], v[96:99]
	v_mfma_f32_16x16x32_bf16 v[124:127], v[132:135], v[202:205], v[124:127]
	v_mfma_f32_16x16x32_bf16 v[120:123], v[178:181], v[202:205], v[120:123]
	v_mfma_f32_16x16x32_bf16 v[116:119], v[132:135], v[210:213], v[116:119]
	v_mfma_f32_16x16x32_bf16 v[112:115], v[178:181], v[210:213], v[112:115]
	v_mfma_f32_16x16x32_bf16 v[108:111], v[132:135], v[218:221], v[108:111]
	v_mfma_f32_16x16x32_bf16 v[104:107], v[178:181], v[218:221], v[104:107]
	v_mfma_f32_16x16x32_bf16 v[100:103], v[132:135], v[226:229], v[100:103]
	v_mfma_f32_16x16x32_bf16 v[96:99], v[178:181], v[226:229], v[96:99]
	s_setprio 0
	s_setprio 1
	v_mfma_f32_16x16x32_bf16 v[60:63], v[182:185], v[198:201], v[60:63]
	v_mfma_f32_16x16x32_bf16 v[56:59], v[190:193], v[198:201], v[56:59]
	v_mfma_f32_16x16x32_bf16 v[52:55], v[182:185], v[206:209], v[52:55]
	v_mfma_f32_16x16x32_bf16 v[48:51], v[190:193], v[206:209], v[48:51]
	v_mfma_f32_16x16x32_bf16 v[44:47], v[182:185], v[214:217], v[44:47]
	v_mfma_f32_16x16x32_bf16 v[40:43], v[190:193], v[214:217], v[40:43]
	v_mfma_f32_16x16x32_bf16 v[36:39], v[182:185], v[222:225], v[36:39]
	v_mfma_f32_16x16x32_bf16 v[32:35], v[190:193], v[222:225], v[32:35]
	v_mfma_f32_16x16x32_bf16 v[60:63], v[186:189], v[202:205], v[60:63]
	v_mfma_f32_16x16x32_bf16 v[56:59], v[194:197], v[202:205], v[56:59]
	v_mfma_f32_16x16x32_bf16 v[52:55], v[186:189], v[210:213], v[52:55]
	v_mfma_f32_16x16x32_bf16 v[48:51], v[194:197], v[210:213], v[48:51]
	v_mfma_f32_16x16x32_bf16 v[44:47], v[186:189], v[218:221], v[44:47]
	v_mfma_f32_16x16x32_bf16 v[40:43], v[194:197], v[218:221], v[40:43]
	v_mfma_f32_16x16x32_bf16 v[36:39], v[186:189], v[226:229], v[36:39]
	v_mfma_f32_16x16x32_bf16 v[32:35], v[194:197], v[226:229], v[32:35]
	s_barrier
; #define PG8_STAGE(bufoff, gbase, voff) do { _Pragma("unroll") for (int _i = 0; _i < 2; ++_i) \
;         __builtin_amdgcn_global_load_lds((const unsigned*)((const char*)(gbase) + (voff)[_i]), (PG8_LAS unsigned*)(lds + (bufoff) + ldsw + _i * 8192), 16, 0, 0); } while (0)
; #define PG8_LDA(dst, b, h) do { _Pragma("unroll") for (int m = 0; m < 4; ++m) _Pragma("unroll") for (int k = 0; k < 2; ++k) dst[m][k] = *(const PG8_LAS bf16x8*)(lds + PG8_SA(b, h) + aoff + m * 2048 + k * 1024); } while (0)
; #define PG8_LDB(dst, b, h) do { _Pragma("unroll") for (int n = 0; n < 2; ++n) _Pragma("unroll") for (int k = 0; k < 2; ++k) dst[n][k] = *(const PG8_LAS bf16x8*)(lds + PG8_SB(b, h) + boff + n * 2048 + k * 1024); } while (0)
; #define PG8_MMA(ai, bj, At, Bt) do { __builtin_amdgcn_s_setprio(1); _Pragma("unroll") for (int m = 0; m < 4; ++m) _Pragma("unroll") for (int n = 0; n < 2; ++n) _Pragma("unroll") for (int k = 0; k < 2; ++k) \
;         acc[ai][bj][m][n] = __builtin_amdgcn_mfma_f32_16x16x32_bf16(Bt[n][k], At[m][k], acc[ai][bj][m][n], 0, 0, 0); __builtin_amdgcn_s_setprio(0); } while (0)
; #define PG8_WAIT_V(n) asm volatile("s_waitcnt vmcnt(" #n ")" ::: "memory")
; template <class Epi, class Sched, bool ALIGN_EPI = false, bool SP2 = false>
; __device__ __forceinline__ void gemm_phase(PG8_LAS unsigned char* lds, const Gemm g, const Sched& S, const Epi& E) {
;     ...
;             PG8_LDB(B0, 0, 0); PG8_LDB(B1, 0, 1); PG8_SCHED; PG8_LDA(At, 0, 0); PG8_STAGE(PG8_SA(1, 1), a1 + hstep, voffA);
;             PG8_WAIT_V(8); PG8_WAIT_L(0); PG8_BAR; PG8_MMA(0, 0, At, B0); PG8_MMA(0, 1, At, B1); PG8_BAR; PG8_SCHED;
;             PG8_LDA(At, 0, 1); PG8_STAGE(PG8_SB(0, 0), b2, voffB); PG8_STAGE(PG8_SB(0, 1), b2 + hstep, voffB); PG8_STAGE(PG8_SA(0, 0), a2, voffA);
;             PG8_WAIT_V(8); PG8_WAIT_L(0); PG8_BAR; PG8_MMA(1, 0, At, B0); PG8_MMA(1, 1, At, B1); PG8_BAR; PG8_SCHED;
;             PG8_LDB(B0, 1, 0); PG8_LDB(B1, 1, 1); PG8_SCHED; PG8_LDA(At, 1, 0); PG8_STAGE(PG8_SA(0, 1), a2 + hstep, voffA);
;             PG8_WAIT_V(8); PG8_WAIT_L(0); PG8_BAR; PG8_MMA(0, 0, At, B0); PG8_MMA(0, 1, At, B1); PG8_BAR; PG8_SCHED;
;             PG8_LDA(At, 1, 1); PG8_STAGE(PG8_SB(1, 0), b3, voffB); PG8_STAGE(PG8_SB(1, 1), b3 + hstep, voffB); PG8_STAGE(PG8_SA(1, 0), a3, voffA);
;             PG8_WAIT_V(8); PG8_WAIT_L(0); PG8_BAR; PG8_MMA(1, 0, At, B0); PG8_MMA(1, 1, At, B1); PG8_BAR; PG8_SCHED;
	s_setprio 0
	s_add_i32 s60, s45, s33
	v_lshl_add_u64 v[160:161], s[30:31], 0, v[138:139]
	s_mov_b32 m0, s60
	ds_read_b128 v[198:201], v172 offset:16384
	ds_read_b128 v[202:205], v172 offset:17408
	ds_read_b128 v[206:209], v172 offset:18432
	ds_read_b128 v[210:213], v172 offset:19456
	ds_read_b128 v[214:217], v172 offset:20480
	ds_read_b128 v[218:221], v172 offset:21504
	ds_read_b128 v[222:225], v172 offset:22528
	ds_read_b128 v[226:229], v172 offset:23552
	global_load_lds_dwordx4 v[160:161], off
	s_add_i32 m0, s60, 0x2000
	s_add_u32 s60, s30, 0x40000
	v_lshl_add_u64 v[230:231], s[30:31], 0, v[142:143]
	s_addc_u32 s61, s31, 0
	s_add_i32 s62, s50, s33
	global_load_lds_dwordx4 v[230:231], off
	v_lshl_add_u64 v[232:233], s[60:61], 0, v[138:139]
	s_mov_b32 m0, s62
	v_lshl_add_u64 v[234:235], s[34:35], 0, v[140:141]
	global_load_lds_dwordx4 v[232:233], off
	v_lshl_add_u64 v[232:233], s[60:61], 0, v[142:143]
	s_add_i32 m0, s62, 0x2000
	s_nop 0
	global_load_lds_dwordx4 v[232:233], off
	v_lshl_add_u64 v[232:233], s[34:35], 0, v[136:137]
	s_mov_b32 m0, s38
	s_nop 0
	global_load_lds_dwordx4 v[232:233], off
	s_mov_b32 m0, s39
	s_nop 0
	global_load_lds_dwordx4 v[234:235], off
	s_waitcnt vmcnt(8)
	s_waitcnt lgkmcnt(0)
	s_setprio 1
	s_barrier
	v_mfma_f32_16x16x32_bf16 v[92:95], v[128:131], v[198:201], v[92:95]
	v_mfma_f32_16x16x32_bf16 v[88:91], v[174:177], v[198:201], v[88:91]
	v_mfma_f32_16x16x32_bf16 v[84:87], v[128:131], v[206:209], v[84:87]
	v_mfma_f32_16x16x32_bf16 v[80:83], v[174:177], v[206:209], v[80:83]
	v_mfma_f32_16x16x32_bf16 v[76:79], v[128:131], v[214:217], v[76:79]
	v_mfma_f32_16x16x32_bf16 v[72:75], v[174:177], v[214:217], v[72:75]
	v_mfma_f32_16x16x32_bf16 v[68:71], v[128:131], v[222:225], v[68:71]
	v_mfma_f32_16x16x32_bf16 v[64:67], v[174:177], v[222:225], v[64:67]
	v_mfma_f32_16x16x32_bf16 v[92:95], v[132:135], v[202:205], v[92:95]
	v_mfma_f32_16x16x32_bf16 v[88:91], v[178:181], v[202:205], v[88:91]
	v_mfma_f32_16x16x32_bf16 v[84:87], v[132:135], v[210:213], v[84:87]
	v_mfma_f32_16x16x32_bf16 v[80:83], v[178:181], v[210:213], v[80:83]
	v_mfma_f32_16x16x32_bf16 v[76:79], v[132:135], v[218:221], v[76:79]
	v_mfma_f32_16x16x32_bf16 v[72:75], v[178:181], v[218:221], v[72:75]
	v_mfma_f32_16x16x32_bf16 v[68:71], v[132:135], v[226:229], v[68:71]
	v_mfma_f32_16x16x32_bf16 v[64:67], v[178:181], v[226:229], v[64:67]
	s_setprio 0
	s_setprio 1
	v_mfma_f32_16x16x32_bf16 v[28:31], v[182:185], v[198:201], v[28:31]
	v_mfma_f32_16x16x32_bf16 v[24:27], v[190:193], v[198:201], v[24:27]
	v_mfma_f32_16x16x32_bf16 v[20:23], v[182:185], v[206:209], v[20:23]
	v_mfma_f32_16x16x32_bf16 v[16:19], v[190:193], v[206:209], v[16:19]
	v_mfma_f32_16x16x32_bf16 v[12:15], v[182:185], v[214:217], v[12:15]
	v_mfma_f32_16x16x32_bf16 v[8:11], v[190:193], v[214:217], v[8:11]
	v_mfma_f32_16x16x32_bf16 v[4:7], v[182:185], v[222:225], v[4:7]
	v_mfma_f32_16x16x32_bf16 v[0:3], v[190:193], v[222:225], v[0:3]
	v_mfma_f32_16x16x32_bf16 v[28:31], v[186:189], v[202:205], v[28:31]
	v_mfma_f32_16x16x32_bf16 v[24:27], v[194:197], v[202:205], v[24:27]
	v_mfma_f32_16x16x32_bf16 v[20:23], v[186:189], v[210:213], v[20:23]
	v_mfma_f32_16x16x32_bf16 v[16:19], v[194:197], v[210:213], v[16:19]
	v_mfma_f32_16x16x32_bf16 v[12:15], v[186:189], v[218:221], v[12:15]
	v_mfma_f32_16x16x32_bf16 v[8:11], v[194:197], v[218:221], v[8:11]
	v_mfma_f32_16x16x32_bf16 v[4:7], v[186:189], v[226:229], v[4:7]
	v_mfma_f32_16x16x32_bf16 v[0:3], v[194:197], v[226:229], v[0:3]
	s_barrier
	s_setprio 0
	s_add_i32 s60, 0, 0x18000
	s_add_i32 s61, 0, 0x1c000
	v_add_u32_e32 v178, s60, v163
	v_add_u32_e32 v194, s61, v163
	ds_read_b128 v[128:131], v178
	ds_read_b128 v[132:135], v178 offset:1024
	ds_read_b128 v[174:177], v178 offset:2048
	ds_read_b128 v[178:181], v178 offset:3072
	ds_read_b128 v[182:185], v194
	ds_read_b128 v[186:189], v194 offset:1024
	ds_read_b128 v[190:193], v194 offset:2048
	ds_read_b128 v[194:197], v194 offset:3072
	s_add_u32 s34, s34, 0x40000
	s_addc_u32 s35, s35, 0
	s_mov_b32 m0, s40
	v_lshl_add_u64 v[236:237], s[34:35], 0, v[136:137]
	ds_read_b128 v[198:201], v172 offset:32768
	ds_read_b128 v[202:205], v172 offset:33792
	ds_read_b128 v[206:209], v172 offset:34816
	ds_read_b128 v[210:213], v172 offset:35840
	ds_read_b128 v[214:217], v172 offset:36864
	ds_read_b128 v[218:221], v172 offset:37888
	ds_read_b128 v[222:225], v172 offset:38912
	ds_read_b128 v[226:229], v172 offset:39936
	global_load_lds_dwordx4 v[236:237], off
	v_lshl_add_u64 v[236:237], s[34:35], 0, v[140:141]
	s_mov_b32 m0, s41
	s_nop 0
	global_load_lds_dwordx4 v[236:237], off
	s_waitcnt vmcnt(8)
	s_waitcnt lgkmcnt(0)
	s_setprio 1
	s_barrier
; #define PG8_STAGE(bufoff, gbase, voff) do { _Pragma("unroll") for (int _i = 0; _i < 2; ++_i) \
;         __builtin_amdgcn_global_load_lds((const unsigned*)((const char*)(gbase) + (voff)[_i]), (PG8_LAS unsigned*)(lds + (bufoff) + ldsw + _i * 8192), 16, 0, 0); } while (0)
; #define PG8_LDA(dst, b, h) do { _Pragma("unroll") for (int m = 0; m < 4; ++m) _Pragma("unroll") for (int k = 0; k < 2; ++k) dst[m][k] = *(const PG8_LAS bf16x8*)(lds + PG8_SA(b, h) + aoff + m * 2048 + k * 1024); } while (0)
; #define PG8_LDB(dst, b, h) do { _Pragma("unroll") for (int n = 0; n < 2; ++n) _Pragma("unroll") for (int k = 0; k < 2; ++k) dst[n][k] = *(const PG8_LAS bf16x8*)(lds + PG8_SB(b, h) + boff + n * 2048 + k * 1024); } while (0)
; #define PG8_MMA(ai, bj, At, Bt) do { __builtin_amdgcn_s_setprio(1); _Pragma("unroll") for (int m = 0; m < 4; ++m) _Pragma("unroll") for (int n = 0; n < 2; ++n) _Pragma("unroll") for (int k = 0; k < 2; ++k) \
;         acc[ai][bj][m][n] = __builtin_amdgcn_mfma_f32_16x16x32_bf16(Bt[n][k], At[m][k], acc[ai][bj][m][n], 0, 0, 0); __builtin_amdgcn_s_setprio(0); } while (0)
; template <class Epi, class Sched, bool ALIGN_EPI = false, bool SP2 = false>
; __device__ __forceinline__ void gemm_phase(PG8_LAS unsigned char* lds, const Gemm g, const Sched& S, const Epi& E) {
;     ...
;             PG8_LDB(B0, 0, 0); PG8_LDB(B1, 0, 1); PG8_SCHED; PG8_LDA(At, 0, 0); PG8_STAGE(PG8_SA(1, 1), a1 + hstep, voffA);
;             PG8_WAIT_V(8); PG8_WAIT_L(0); PG8_BAR; PG8_MMA(0, 0, At, B0); PG8_MMA(0, 1, At, B1); PG8_BAR; PG8_SCHED;
;             PG8_LDA(At, 0, 1); PG8_STAGE(PG8_SB(0, 0), b2, voffB); PG8_STAGE(PG8_SB(0, 1), b2 + hstep, voffB); PG8_STAGE(PG8_SA(0, 0), a2, voffA);
;             PG8_WAIT_V(8); PG8_WAIT_L(0); PG8_BAR; PG8_MMA(1, 0, At, B0); PG8_MMA(1, 1, At, B1); PG8_BAR; PG8_SCHED;
;             PG8_LDB(B0, 1, 0); PG8_LDB(B1, 1, 1); PG8_SCHED; PG8_LDA(At, 1, 0); PG8_STAGE(PG8_SA(0, 1), a2 + hstep, voffA);
;             PG8_WAIT_V(8); PG8_WAIT_L(0); PG8_BAR; PG8_MMA(0, 0, At, B0); PG8_MMA(0, 1, At, B1); PG8_BAR; PG8_SCHED;
;             PG8_LDA(At, 1, 1); PG8_STAGE(PG8_SB(1, 0), b3, voffB); PG8_STAGE(PG8_SB(1, 1), b3 + hstep, voffB); PG8_STAGE(PG8_SA(1, 0), a3, voffA);
;             PG8_WAIT_V(8); PG8_WAIT_L(0); PG8_BAR; PG8_MMA(1, 0, At, B0); PG8_MMA(1, 1, At, B1); PG8_BAR; PG8_SCHED;
;     ...
;         if constexpr (ALIGN_EPI) { if (wr == 0) PG8_BAR; }
	v_mfma_f32_16x16x32_bf16 v[124:127], v[128:131], v[198:201], v[124:127]
	v_mfma_f32_16x16x32_bf16 v[120:123], v[174:177], v[198:201], v[120:123]
	v_mfma_f32_16x16x32_bf16 v[116:119], v[128:131], v[206:209], v[116:119]
	v_mfma_f32_16x16x32_bf16 v[112:115], v[174:177], v[206:209], v[112:115]
	v_mfma_f32_16x16x32_bf16 v[108:111], v[128:131], v[214:217], v[108:111]
	v_mfma_f32_16x16x32_bf16 v[104:107], v[174:177], v[214:217], v[104:107]
	v_mfma_f32_16x16x32_bf16 v[100:103], v[128:131], v[222:225], v[100:103]
	v_mfma_f32_16x16x32_bf16 v[96:99], v[174:177], v[222:225], v[96:99]
	v_mfma_f32_16x16x32_bf16 v[124:127], v[132:135], v[202:205], v[124:127]
	v_mfma_f32_16x16x32_bf16 v[120:123], v[178:181], v[202:205], v[120:123]
	v_mfma_f32_16x16x32_bf16 v[116:119], v[132:135], v[210:213], v[116:119]
	v_mfma_f32_16x16x32_bf16 v[112:115], v[178:181], v[210:213], v[112:115]
	v_mfma_f32_16x16x32_bf16 v[108:111], v[132:135], v[218:221], v[108:111]
	v_mfma_f32_16x16x32_bf16 v[104:107], v[178:181], v[218:221], v[104:107]
	v_mfma_f32_16x16x32_bf16 v[100:103], v[132:135], v[226:229], v[100:103]
	v_mfma_f32_16x16x32_bf16 v[96:99], v[178:181], v[226:229], v[96:99]
	s_setprio 0
	s_setprio 1
	v_mfma_f32_16x16x32_bf16 v[60:63], v[182:185], v[198:201], v[60:63]
	v_mfma_f32_16x16x32_bf16 v[56:59], v[190:193], v[198:201], v[56:59]
	v_mfma_f32_16x16x32_bf16 v[52:55], v[182:185], v[206:209], v[52:55]
	v_mfma_f32_16x16x32_bf16 v[48:51], v[190:193], v[206:209], v[48:51]
	v_mfma_f32_16x16x32_bf16 v[44:47], v[182:185], v[214:217], v[44:47]
	v_mfma_f32_16x16x32_bf16 v[40:43], v[190:193], v[214:217], v[40:43]
	v_mfma_f32_16x16x32_bf16 v[36:39], v[182:185], v[222:225], v[36:39]
	v_mfma_f32_16x16x32_bf16 v[32:35], v[190:193], v[222:225], v[32:35]
	v_mfma_f32_16x16x32_bf16 v[60:63], v[186:189], v[202:205], v[60:63]
	v_mfma_f32_16x16x32_bf16 v[56:59], v[194:197], v[202:205], v[56:59]
	v_mfma_f32_16x16x32_bf16 v[52:55], v[186:189], v[210:213], v[52:55]
	v_mfma_f32_16x16x32_bf16 v[48:51], v[194:197], v[210:213], v[48:51]
	v_mfma_f32_16x16x32_bf16 v[44:47], v[186:189], v[218:221], v[44:47]
	v_mfma_f32_16x16x32_bf16 v[40:43], v[194:197], v[218:221], v[40:43]
	v_mfma_f32_16x16x32_bf16 v[36:39], v[186:189], v[226:229], v[36:39]
	v_mfma_f32_16x16x32_bf16 v[32:35], v[194:197], v[226:229], v[32:35]
	s_barrier
	s_setprio 0
	s_add_i32 s34, s60, s33
	v_lshl_add_u64 v[160:161], v[160:161], 0, s[16:17]
	s_mov_b32 m0, s34
	ds_read_b128 v[198:201], v172 offset:49152
	ds_read_b128 v[202:205], v172 offset:50176
	ds_read_b128 v[206:209], v172 offset:51200
	ds_read_b128 v[210:213], v172 offset:52224
	ds_read_b128 v[214:217], v172 offset:53248
	ds_read_b128 v[218:221], v172 offset:54272
	ds_read_b128 v[222:225], v172 offset:55296
	ds_read_b128 v[226:229], v172 offset:56320
	global_load_lds_dwordx4 v[160:161], off
	s_add_i32 m0, s34, 0x2000
	s_add_u32 s30, s30, 0x40080
	v_lshl_add_u64 v[160:161], v[230:231], 0, s[16:17]
	s_addc_u32 s31, s31, 0
	s_add_i32 s34, s61, s33
	global_load_lds_dwordx4 v[160:161], off
	v_lshl_add_u64 v[160:161], s[30:31], 0, v[138:139]
	s_mov_b32 m0, s34
	s_nop 0
	global_load_lds_dwordx4 v[160:161], off
	v_lshl_add_u64 v[160:161], s[30:31], 0, v[142:143]
	s_add_i32 m0, s34, 0x2000
	s_nop 0
	global_load_lds_dwordx4 v[160:161], off
	v_lshl_add_u64 v[160:161], v[232:233], 0, s[16:17]
	s_mov_b32 m0, s42
	s_nop 0
	global_load_lds_dwordx4 v[160:161], off
	v_lshl_add_u64 v[160:161], v[234:235], 0, s[16:17]
	s_mov_b32 m0, s43
	s_nop 0
	global_load_lds_dwordx4 v[160:161], off
	s_waitcnt vmcnt(8)
	s_waitcnt lgkmcnt(0)
	s_setprio 1
	s_barrier
	v_mfma_f32_16x16x32_bf16 v[92:95], v[128:131], v[198:201], v[92:95]
	v_mfma_f32_16x16x32_bf16 v[88:91], v[174:177], v[198:201], v[88:91]
	v_mfma_f32_16x16x32_bf16 v[84:87], v[128:131], v[206:209], v[84:87]
	v_mfma_f32_16x16x32_bf16 v[80:83], v[174:177], v[206:209], v[80:83]
	v_mfma_f32_16x16x32_bf16 v[76:79], v[128:131], v[214:217], v[76:79]
	v_mfma_f32_16x16x32_bf16 v[72:75], v[174:177], v[214:217], v[72:75]
	v_mfma_f32_16x16x32_bf16 v[68:71], v[128:131], v[222:225], v[68:71]
	v_mfma_f32_16x16x32_bf16 v[64:67], v[174:177], v[222:225], v[64:67]
	v_mfma_f32_16x16x32_bf16 v[92:95], v[132:135], v[202:205], v[92:95]
	v_mfma_f32_16x16x32_bf16 v[88:91], v[178:181], v[202:205], v[88:91]
	v_mfma_f32_16x16x32_bf16 v[84:87], v[132:135], v[210:213], v[84:87]
	v_mfma_f32_16x16x32_bf16 v[80:83], v[178:181], v[210:213], v[80:83]
	v_mfma_f32_16x16x32_bf16 v[76:79], v[132:135], v[218:221], v[76:79]
	v_mfma_f32_16x16x32_bf16 v[72:75], v[178:181], v[218:221], v[72:75]
	v_mfma_f32_16x16x32_bf16 v[68:71], v[132:135], v[226:229], v[68:71]
	v_mfma_f32_16x16x32_bf16 v[64:67], v[178:181], v[226:229], v[64:67]
	s_setprio 0
	s_setprio 1
	v_mfma_f32_16x16x32_bf16 v[28:31], v[182:185], v[198:201], v[28:31]
	v_mfma_f32_16x16x32_bf16 v[24:27], v[190:193], v[198:201], v[24:27]
	v_mfma_f32_16x16x32_bf16 v[20:23], v[182:185], v[206:209], v[20:23]
	v_mfma_f32_16x16x32_bf16 v[16:19], v[190:193], v[206:209], v[16:19]
	v_mfma_f32_16x16x32_bf16 v[12:15], v[182:185], v[214:217], v[12:15]
	v_mfma_f32_16x16x32_bf16 v[8:11], v[190:193], v[214:217], v[8:11]
	v_mfma_f32_16x16x32_bf16 v[4:7], v[182:185], v[222:225], v[4:7]
	v_mfma_f32_16x16x32_bf16 v[0:3], v[190:193], v[222:225], v[0:3]
	v_mfma_f32_16x16x32_bf16 v[28:31], v[186:189], v[202:205], v[28:31]
	v_mfma_f32_16x16x32_bf16 v[24:27], v[194:197], v[202:205], v[24:27]
	v_mfma_f32_16x16x32_bf16 v[20:23], v[186:189], v[210:213], v[20:23]
	v_mfma_f32_16x16x32_bf16 v[16:19], v[194:197], v[210:213], v[16:19]
	v_mfma_f32_16x16x32_bf16 v[12:15], v[186:189], v[218:221], v[12:15]
	v_mfma_f32_16x16x32_bf16 v[8:11], v[194:197], v[218:221], v[8:11]
	v_mfma_f32_16x16x32_bf16 v[4:7], v[186:189], v[226:229], v[4:7]
	v_mfma_f32_16x16x32_bf16 v[0:3], v[194:197], v[226:229], v[0:3]
	s_barrier
	s_setprio 0
	s_add_i32 s59, s59, 2
	s_add_u32 s28, s28, 0x100
	s_addc_u32 s29, s29, 0
	s_add_u32 s57, s57, 0x100
	s_addc_u32 s58, s58, 0
	s_cmp_gt_u32 s59, 13
	s_cbranch_scc0 .LBB0_607
	s_and_b64 vcc, exec, s[0:1]
	s_cbranch_vccz .LBB0_610
	s_barrier

; #define PG8_STAGE(bufoff, gbase, voff) do { _Pragma("unroll") for (int _i = 0; _i < 2; ++_i) \
;         __builtin_amdgcn_global_load_lds((const unsigned*)((const char*)(gbase) + (voff)[_i]), (PG8_LAS unsigned*)(lds + (bufoff) + ldsw + _i * 8192), 16, 0, 0); } while (0)
; #define PG8_LDA(dst, b, h) do { _Pragma("unroll") for (int m = 0; m < 4; ++m) _Pragma("unroll") for (int k = 0; k < 2; ++k) dst[m][k] = *(const PG8_LAS bf16x8*)(lds + PG8_SA(b, h) + aoff + m * 2048 + k * 1024); } while (0)
; template <class Epi, class Sched, bool ALIGN_EPI = false, bool SP2 = false>
; __device__ __forceinline__ void gemm_phase(PG8_LAS unsigned char* lds, const Gemm g, const Sched& S, const Epi& E) {
;     ...
;         const bool has_next = S.next(ui + 1, nxt);
;         const char* nA = has_next ? (const char*)g.A + (size_t)nxt.pm * tstep : cA; const char* nB = has_next ? (const char*)g.Bt + (size_t)nxt.pn * tstep : cB;
;         for (int t = 0; t < nt; t += 2) {
;             const bool last = (t == nt - 2);
;             const char* a1 = cA + (size_t)(t + 1) * kstep;
;             const char* a2 = last ? nA : cA + (size_t)(t + 2) * kstep; const char* b2 = last ? nB : cB + (size_t)(t + 2) * kstep;
;             const char* a3 = a2 + kstep; const char* b3 = b2 + kstep;
;             if (last && has_next) S.a_ready(nxt, ui + 1);
;             if constexpr (SP2) {
;             PG8_LDB(B0, 0, 0); PG8_LDB(B1, 0, 1); PG8_SCHED; PG8_LDA(At, 0, 0); PG8_STAGE(PG8_SA(1, 1), a1 + hstep, voffA);
;             PG8_WAIT_V(8); PG8_WAIT_L(0); PG8_BAR; PG8_MMA(0, 0, At, B0); PG8_MMA(0, 1, At, B1); PG8_BAR; PG8_SCHED;
;             PG8_LDA(At, 0, 1); PG8_STAGE(PG8_SB(0, 0), b2, voffB); PG8_STAGE(PG8_SB(0, 1), b2 + hstep, voffB); PG8_STAGE(PG8_SA(0, 0), a2, voffA);
;             PG8_WAIT_V(8); PG8_WAIT_L(0); PG8_BAR; PG8_MMA(1, 0, At, B0); PG8_MMA(1, 1, At, B1); PG8_BAR; PG8_SCHED;
;             PG8_LDB(B0, 1, 0); PG8_LDB(B1, 1, 1); PG8_SCHED; PG8_LDA(At, 1, 0); PG8_STAGE(PG8_SA(0, 1), a2 + hstep, voffA);
;             PG8_WAIT_V(8); PG8_WAIT_L(0); PG8_BAR; PG8_MMA(0, 0, At, B0); PG8_MMA(0, 1, At, B1); PG8_BAR; PG8_SCHED;
;             PG8_LDA(At, 1, 1); PG8_STAGE(PG8_SB(1, 0), b3, voffB); PG8_STAGE(PG8_SB(1, 1), b3 + hstep, voffB); PG8_STAGE(PG8_SA(1, 0), a3, voffA);
;             PG8_WAIT_V(8); PG8_WAIT_L(0); PG8_BAR; PG8_MMA(1, 0, At, B0); PG8_MMA(1, 1, At, B1); PG8_BAR; PG8_SCHED;
.LBB0_959:
	s_ashr_i32 s23, s22, 31
	s_lshl_b64 s[24:25], s[22:23], 19
	s_add_u32 s24, s3, s24
	s_addc_u32 s25, s33, s25
	s_and_b64 s[26:27], s[4:5], exec
	s_cselect_b32 s23, s25, s31
	s_cselect_b32 s29, s24, s30
	s_ashr_i32 s21, s20, 31
	s_lshl_b64 s[26:27], s[20:21], 19
	s_add_u32 s26, s38, s26
	s_addc_u32 s27, s39, s27
	s_and_b64 s[36:37], s[4:5], exec
	s_cselect_b32 s21, s27, s35
	s_cselect_b32 s54, s26, s34
	s_add_u32 s30, s30, 0x40080
	s_addc_u32 s31, s31, 0
	s_add_u32 s55, s34, 0x100
	s_addc_u32 s56, s35, 0
	s_mov_b32 s57, -2
	s_add_u32 s34, s30, 0xfffc0080
	s_addc_u32 s35, s31, -1
	s_cmp_eq_u32 s57, 12
	s_cselect_b32 s37, s23, s35
	s_cselect_b32 s36, s29, s34
	s_cselect_b32 s35, s21, s56
	s_cselect_b32 s34, s54, s55
	v_lshl_add_u64 v[204:205], s[30:31], 0, v[200:201]
	s_add_i32 m0, s41, 0xc000
	global_load_lds_dwordx4 v[204:205], off
	v_lshl_add_u64 v[204:205], s[30:31], 0, v[202:203]
	s_add_i32 m0, s41, 0xe000
	s_nop 0
	global_load_lds_dwordx4 v[204:205], off
	s_waitcnt vmcnt(8)
	s_waitcnt lgkmcnt(0)
	s_setprio 1
	s_barrier
	v_mfma_f32_16x16x32_bf16 v[132:135], v[120:123], v[160:163], 0
	v_mfma_f32_16x16x32_bf16 v[124:127], v[136:139], v[160:163], 0
	v_mfma_f32_16x16x32_bf16 v[108:111], v[120:123], v[168:171], 0
	v_mfma_f32_16x16x32_bf16 v[104:107], v[136:139], v[168:171], 0
	v_mfma_f32_16x16x32_bf16 v[92:95], v[120:123], v[176:179], 0
	v_mfma_f32_16x16x32_bf16 v[88:91], v[136:139], v[176:179], 0
	v_mfma_f32_16x16x32_bf16 v[76:79], v[120:123], v[184:187], 0
	v_mfma_f32_16x16x32_bf16 v[72:75], v[136:139], v[184:187], 0
	v_mfma_f32_16x16x32_bf16 v[132:135], v[128:131], v[164:167], v[132:135]
	v_mfma_f32_16x16x32_bf16 v[124:127], v[140:143], v[164:167], v[124:127]
	v_mfma_f32_16x16x32_bf16 v[108:111], v[128:131], v[172:175], v[108:111]
	v_mfma_f32_16x16x32_bf16 v[104:107], v[140:143], v[172:175], v[104:107]
	v_mfma_f32_16x16x32_bf16 v[92:95], v[128:131], v[180:183], v[92:95]
	v_mfma_f32_16x16x32_bf16 v[88:91], v[140:143], v[180:183], v[88:91]
	v_mfma_f32_16x16x32_bf16 v[76:79], v[128:131], v[188:191], v[76:79]
	v_mfma_f32_16x16x32_bf16 v[72:75], v[140:143], v[188:191], v[72:75]
	s_setprio 0
	s_setprio 1
	v_mfma_f32_16x16x32_bf16 v[116:119], v[144:147], v[160:163], 0
	v_mfma_f32_16x16x32_bf16 v[112:115], v[152:155], v[160:163], 0
	v_mfma_f32_16x16x32_bf16 v[100:103], v[144:147], v[168:171], 0
	v_mfma_f32_16x16x32_bf16 v[96:99], v[152:155], v[168:171], 0
	v_mfma_f32_16x16x32_bf16 v[84:87], v[144:147], v[176:179], 0
	v_mfma_f32_16x16x32_bf16 v[80:83], v[152:155], v[176:179], 0
	v_mfma_f32_16x16x32_bf16 v[68:71], v[144:147], v[184:187], 0
	v_mfma_f32_16x16x32_bf16 v[64:67], v[152:155], v[184:187], 0
	v_mfma_f32_16x16x32_bf16 v[116:119], v[148:151], v[164:167], v[116:119]
	v_mfma_f32_16x16x32_bf16 v[112:115], v[156:159], v[164:167], v[112:115]
	v_mfma_f32_16x16x32_bf16 v[100:103], v[148:151], v[172:175], v[100:103]
	v_mfma_f32_16x16x32_bf16 v[96:99], v[156:159], v[172:175], v[96:99]
	v_mfma_f32_16x16x32_bf16 v[84:87], v[148:151], v[180:183], v[84:87]
	v_mfma_f32_16x16x32_bf16 v[80:83], v[156:159], v[180:183], v[80:83]
	v_mfma_f32_16x16x32_bf16 v[68:71], v[148:151], v[188:191], v[68:71]
	v_mfma_f32_16x16x32_bf16 v[64:67], v[156:159], v[188:191], v[64:67]
	s_barrier
	s_setprio 0
	s_add_i32 s58, s51, s40
	v_lshl_add_u64 v[204:205], s[34:35], 0, v[194:195]
	s_mov_b32 m0, s58
	ds_read_b128 v[160:163], v247 offset:16384
	ds_read_b128 v[164:167], v247 offset:17408
	ds_read_b128 v[168:171], v247 offset:18432
	ds_read_b128 v[172:175], v247 offset:19456
	ds_read_b128 v[176:179], v247 offset:20480
	ds_read_b128 v[180:183], v247 offset:21504
	ds_read_b128 v[184:187], v247 offset:22528
	ds_read_b128 v[188:191], v247 offset:23552
	global_load_lds_dwordx4 v[204:205], off
	s_add_i32 m0, s58, 0x2000
	s_add_u32 s58, s34, 0x40000
	v_lshl_add_u64 v[206:207], s[34:35], 0, v[198:199]
	s_addc_u32 s59, s35, 0
	s_add_i32 s60, s52, s40
	global_load_lds_dwordx4 v[206:207], off
	v_lshl_add_u64 v[208:209], s[58:59], 0, v[194:195]
	s_mov_b32 m0, s60
	v_lshl_add_u64 v[210:211], s[36:37], 0, v[196:197]
	global_load_lds_dwordx4 v[208:209], off
	v_lshl_add_u64 v[208:209], s[58:59], 0, v[198:199]
	s_add_i32 m0, s60, 0x2000
	s_nop 0
	global_load_lds_dwordx4 v[208:209], off
	v_lshl_add_u64 v[208:209], s[36:37], 0, v[192:193]
	s_mov_b32 m0, s41
	s_nop 0
	global_load_lds_dwordx4 v[208:209], off
	s_mov_b32 m0, s42
	s_nop 0
	global_load_lds_dwordx4 v[210:211], off
	s_waitcnt vmcnt(8)
	s_waitcnt lgkmcnt(0)
	s_setprio 1
	s_barrier
	v_mfma_f32_16x16x32_bf16 v[60:63], v[120:123], v[160:163], 0
	v_mfma_f32_16x16x32_bf16 v[56:59], v[136:139], v[160:163], 0
	v_mfma_f32_16x16x32_bf16 v[44:47], v[120:123], v[168:171], 0
	v_mfma_f32_16x16x32_bf16 v[40:43], v[136:139], v[168:171], 0
	v_mfma_f32_16x16x32_bf16 v[28:31], v[120:123], v[176:179], 0
	v_mfma_f32_16x16x32_bf16 v[24:27], v[136:139], v[176:179], 0
	v_mfma_f32_16x16x32_bf16 v[12:15], v[120:123], v[184:187], 0
	v_mfma_f32_16x16x32_bf16 v[8:11], v[136:139], v[184:187], 0
	v_mfma_f32_16x16x32_bf16 v[60:63], v[128:131], v[164:167], v[60:63]
	v_mfma_f32_16x16x32_bf16 v[56:59], v[140:143], v[164:167], v[56:59]
	v_mfma_f32_16x16x32_bf16 v[44:47], v[128:131], v[172:175], v[44:47]
	v_mfma_f32_16x16x32_bf16 v[40:43], v[140:143], v[172:175], v[40:43]
	v_mfma_f32_16x16x32_bf16 v[28:31], v[128:131], v[180:183], v[28:31]
	v_mfma_f32_16x16x32_bf16 v[24:27], v[140:143], v[180:183], v[24:27]
	v_mfma_f32_16x16x32_bf16 v[12:15], v[128:131], v[188:191], v[12:15]
	v_mfma_f32_16x16x32_bf16 v[8:11], v[140:143], v[188:191], v[8:11]
	s_setprio 0
	s_setprio 1
	v_mfma_f32_16x16x32_bf16 v[52:55], v[144:147], v[160:163], 0
	v_mfma_f32_16x16x32_bf16 v[48:51], v[152:155], v[160:163], 0
	v_mfma_f32_16x16x32_bf16 v[36:39], v[144:147], v[168:171], 0
	v_mfma_f32_16x16x32_bf16 v[32:35], v[152:155], v[168:171], 0
	v_mfma_f32_16x16x32_bf16 v[20:23], v[144:147], v[176:179], 0
	v_mfma_f32_16x16x32_bf16 v[16:19], v[152:155], v[176:179], 0
	v_mfma_f32_16x16x32_bf16 v[4:7], v[144:147], v[184:187], 0
	v_mfma_f32_16x16x32_bf16 v[0:3], v[152:155], v[184:187], 0
	v_mfma_f32_16x16x32_bf16 v[52:55], v[148:151], v[164:167], v[52:55]
	v_mfma_f32_16x16x32_bf16 v[48:51], v[156:159], v[164:167], v[48:51]
	v_mfma_f32_16x16x32_bf16 v[36:39], v[148:151], v[172:175], v[36:39]
	v_mfma_f32_16x16x32_bf16 v[32:35], v[156:159], v[172:175], v[32:35]
	v_mfma_f32_16x16x32_bf16 v[20:23], v[148:151], v[180:183], v[20:23]
	v_mfma_f32_16x16x32_bf16 v[16:19], v[156:159], v[180:183], v[16:19]
	v_mfma_f32_16x16x32_bf16 v[4:7], v[148:151], v[188:191], v[4:7]
	v_mfma_f32_16x16x32_bf16 v[0:3], v[156:159], v[188:191], v[0:3]
	s_barrier
; #define PG8_STAGE(bufoff, gbase, voff) do { _Pragma("unroll") for (int _i = 0; _i < 2; ++_i) \
;         __builtin_amdgcn_global_load_lds((const unsigned*)((const char*)(gbase) + (voff)[_i]), (PG8_LAS unsigned*)(lds + (bufoff) + ldsw + _i * 8192), 16, 0, 0); } while (0)
; #define PG8_LDA(dst, b, h) do { _Pragma("unroll") for (int m = 0; m < 4; ++m) _Pragma("unroll") for (int k = 0; k < 2; ++k) dst[m][k] = *(const PG8_LAS bf16x8*)(lds + PG8_SA(b, h) + aoff + m * 2048 + k * 1024); } while (0)
; #define PG8_LDB(dst, b, h) do { _Pragma("unroll") for (int n = 0; n < 2; ++n) _Pragma("unroll") for (int k = 0; k < 2; ++k) dst[n][k] = *(const PG8_LAS bf16x8*)(lds + PG8_SB(b, h) + boff + n * 2048 + k * 1024); } while (0)
; #define PG8_MMA(ai, bj, At, Bt) do { __builtin_amdgcn_s_setprio(1); _Pragma("unroll") for (int m = 0; m < 4; ++m) _Pragma("unroll") for (int n = 0; n < 2; ++n) _Pragma("unroll") for (int k = 0; k < 2; ++k) \
;         acc[ai][bj][m][n] = __builtin_amdgcn_mfma_f32_16x16x32_bf16(Bt[n][k], At[m][k], acc[ai][bj][m][n], 0, 0, 0); __builtin_amdgcn_s_setprio(0); } while (0)
; #define PG8_WAIT_V(n) asm volatile("s_waitcnt vmcnt(" #n ")" ::: "memory")
; template <class Epi, class Sched, bool ALIGN_EPI = false, bool SP2 = false>
; __device__ __forceinline__ void gemm_phase(PG8_LAS unsigned char* lds, const Gemm g, const Sched& S, const Epi& E) {
;     ...
;             PG8_LDB(B0, 0, 0); PG8_LDB(B1, 0, 1); PG8_SCHED; PG8_LDA(At, 0, 0); PG8_STAGE(PG8_SA(1, 1), a1 + hstep, voffA);
;             PG8_WAIT_V(8); PG8_WAIT_L(0); PG8_BAR; PG8_MMA(0, 0, At, B0); PG8_MMA(0, 1, At, B1); PG8_BAR; PG8_SCHED;
;             PG8_LDA(At, 0, 1); PG8_STAGE(PG8_SB(0, 0), b2, voffB); PG8_STAGE(PG8_SB(0, 1), b2 + hstep, voffB); PG8_STAGE(PG8_SA(0, 0), a2, voffA);
;             PG8_WAIT_V(8); PG8_WAIT_L(0); PG8_BAR; PG8_MMA(1, 0, At, B0); PG8_MMA(1, 1, At, B1); PG8_BAR; PG8_SCHED;
;             PG8_LDB(B0, 1, 0); PG8_LDB(B1, 1, 1); PG8_SCHED; PG8_LDA(At, 1, 0); PG8_STAGE(PG8_SA(0, 1), a2 + hstep, voffA);
;             PG8_WAIT_V(8); PG8_WAIT_L(0); PG8_BAR; PG8_MMA(0, 0, At, B0); PG8_MMA(0, 1, At, B1); PG8_BAR; PG8_SCHED;
;             PG8_LDA(At, 1, 1); PG8_STAGE(PG8_SB(1, 0), b3, voffB); PG8_STAGE(PG8_SB(1, 1), b3 + hstep, voffB); PG8_STAGE(PG8_SA(1, 0), a3, voffA);
;             PG8_WAIT_V(8); PG8_WAIT_L(0); PG8_BAR; PG8_MMA(1, 0, At, B0); PG8_MMA(1, 1, At, B1); PG8_BAR; PG8_SCHED;
	s_setprio 0
	s_add_i32 s58, 0, 0x18000
	s_add_i32 s59, 0, 0x1c000
	v_add_u32_e32 v140, s58, v243
	v_add_u32_e32 v156, s59, v243
	ds_read_b128 v[120:123], v140
	ds_read_b128 v[128:131], v140 offset:1024
	ds_read_b128 v[136:139], v140 offset:2048
	ds_read_b128 v[140:143], v140 offset:3072
	ds_read_b128 v[144:147], v156
	ds_read_b128 v[148:151], v156 offset:1024
	ds_read_b128 v[152:155], v156 offset:2048
	ds_read_b128 v[156:159], v156 offset:3072
	s_add_u32 s36, s36, 0x40000
	s_addc_u32 s37, s37, 0
	s_mov_b32 m0, s43
	v_lshl_add_u64 v[212:213], s[36:37], 0, v[192:193]
	ds_read_b128 v[160:163], v247 offset:32768
	ds_read_b128 v[164:167], v247 offset:33792
	ds_read_b128 v[168:171], v247 offset:34816
	ds_read_b128 v[172:175], v247 offset:35840
	ds_read_b128 v[176:179], v247 offset:36864
	ds_read_b128 v[180:183], v247 offset:37888
	ds_read_b128 v[184:187], v247 offset:38912
	ds_read_b128 v[188:191], v247 offset:39936
	global_load_lds_dwordx4 v[212:213], off
	v_lshl_add_u64 v[212:213], s[36:37], 0, v[196:197]
	s_mov_b32 m0, s44
	s_nop 0
	global_load_lds_dwordx4 v[212:213], off
	s_waitcnt vmcnt(8)
	s_waitcnt lgkmcnt(0)
	s_setprio 1
	s_barrier
	v_mfma_f32_16x16x32_bf16 v[132:135], v[120:123], v[160:163], v[132:135]
	v_mfma_f32_16x16x32_bf16 v[124:127], v[136:139], v[160:163], v[124:127]
	v_mfma_f32_16x16x32_bf16 v[108:111], v[120:123], v[168:171], v[108:111]
	v_mfma_f32_16x16x32_bf16 v[104:107], v[136:139], v[168:171], v[104:107]
	v_mfma_f32_16x16x32_bf16 v[92:95], v[120:123], v[176:179], v[92:95]
	v_mfma_f32_16x16x32_bf16 v[88:91], v[136:139], v[176:179], v[88:91]
	v_mfma_f32_16x16x32_bf16 v[76:79], v[120:123], v[184:187], v[76:79]
	v_mfma_f32_16x16x32_bf16 v[72:75], v[136:139], v[184:187], v[72:75]
	v_mfma_f32_16x16x32_bf16 v[132:135], v[128:131], v[164:167], v[132:135]
	v_mfma_f32_16x16x32_bf16 v[124:127], v[140:143], v[164:167], v[124:127]
	v_mfma_f32_16x16x32_bf16 v[108:111], v[128:131], v[172:175], v[108:111]
	v_mfma_f32_16x16x32_bf16 v[104:107], v[140:143], v[172:175], v[104:107]
	v_mfma_f32_16x16x32_bf16 v[92:95], v[128:131], v[180:183], v[92:95]
	v_mfma_f32_16x16x32_bf16 v[88:91], v[140:143], v[180:183], v[88:91]
	v_mfma_f32_16x16x32_bf16 v[76:79], v[128:131], v[188:191], v[76:79]
	v_mfma_f32_16x16x32_bf16 v[72:75], v[140:143], v[188:191], v[72:75]
	s_setprio 0
	s_setprio 1
	v_mfma_f32_16x16x32_bf16 v[116:119], v[144:147], v[160:163], v[116:119]
	v_mfma_f32_16x16x32_bf16 v[112:115], v[152:155], v[160:163], v[112:115]
	v_mfma_f32_16x16x32_bf16 v[100:103], v[144:147], v[168:171], v[100:103]
	v_mfma_f32_16x16x32_bf16 v[96:99], v[152:155], v[168:171], v[96:99]
	v_mfma_f32_16x16x32_bf16 v[84:87], v[144:147], v[176:179], v[84:87]
	v_mfma_f32_16x16x32_bf16 v[80:83], v[152:155], v[176:179], v[80:83]
	v_mfma_f32_16x16x32_bf16 v[68:71], v[144:147], v[184:187], v[68:71]
	v_mfma_f32_16x16x32_bf16 v[64:67], v[152:155], v[184:187], v[64:67]
	v_mfma_f32_16x16x32_bf16 v[116:119], v[148:151], v[164:167], v[116:119]
	v_mfma_f32_16x16x32_bf16 v[112:115], v[156:159], v[164:167], v[112:115]
	v_mfma_f32_16x16x32_bf16 v[100:103], v[148:151], v[172:175], v[100:103]
	v_mfma_f32_16x16x32_bf16 v[96:99], v[156:159], v[172:175], v[96:99]
	v_mfma_f32_16x16x32_bf16 v[84:87], v[148:151], v[180:183], v[84:87]
	v_mfma_f32_16x16x32_bf16 v[80:83], v[156:159], v[180:183], v[80:83]
	v_mfma_f32_16x16x32_bf16 v[68:71], v[148:151], v[188:191], v[68:71]
	v_mfma_f32_16x16x32_bf16 v[64:67], v[156:159], v[188:191], v[64:67]
	s_barrier
	s_setprio 0
	s_add_i32 s36, s58, s40
	v_lshl_add_u64 v[204:205], v[204:205], 0, s[16:17]
	s_mov_b32 m0, s36
	ds_read_b128 v[160:163], v247 offset:49152
	ds_read_b128 v[164:167], v247 offset:50176
	ds_read_b128 v[168:171], v247 offset:51200
	ds_read_b128 v[172:175], v247 offset:52224
	ds_read_b128 v[176:179], v247 offset:53248
	ds_read_b128 v[180:183], v247 offset:54272
	ds_read_b128 v[184:187], v247 offset:55296
	ds_read_b128 v[188:191], v247 offset:56320
	global_load_lds_dwordx4 v[204:205], off
	s_add_i32 m0, s36, 0x2000
	s_add_u32 s34, s34, 0x40080
	v_lshl_add_u64 v[204:205], v[206:207], 0, s[16:17]
	s_addc_u32 s35, s35, 0
	s_add_i32 s36, s59, s40
	global_load_lds_dwordx4 v[204:205], off
	v_lshl_add_u64 v[204:205], s[34:35], 0, v[194:195]
	s_mov_b32 m0, s36
	s_nop 0
	global_load_lds_dwordx4 v[204:205], off
	v_lshl_add_u64 v[204:205], s[34:35], 0, v[198:199]
	s_add_i32 m0, s36, 0x2000
	s_nop 0
	global_load_lds_dwordx4 v[204:205], off
	v_lshl_add_u64 v[204:205], v[208:209], 0, s[16:17]
	s_mov_b32 m0, s46
	s_nop 0
	global_load_lds_dwordx4 v[204:205], off
	v_lshl_add_u64 v[204:205], v[210:211], 0, s[16:17]
	s_mov_b32 m0, s47
	s_nop 0
	global_load_lds_dwordx4 v[204:205], off
	s_waitcnt vmcnt(8)
	s_waitcnt lgkmcnt(0)
	s_setprio 1
	s_barrier
; #define PG8_STAGE(bufoff, gbase, voff) do { _Pragma("unroll") for (int _i = 0; _i < 2; ++_i) \
;         __builtin_amdgcn_global_load_lds((const unsigned*)((const char*)(gbase) + (voff)[_i]), (PG8_LAS unsigned*)(lds + (bufoff) + ldsw + _i * 8192), 16, 0, 0); } while (0)
; #define PG8_LDA(dst, b, h) do { _Pragma("unroll") for (int m = 0; m < 4; ++m) _Pragma("unroll") for (int k = 0; k < 2; ++k) dst[m][k] = *(const PG8_LAS bf16x8*)(lds + PG8_SA(b, h) + aoff + m * 2048 + k * 1024); } while (0)
; #define PG8_LDB(dst, b, h) do { _Pragma("unroll") for (int n = 0; n < 2; ++n) _Pragma("unroll") for (int k = 0; k < 2; ++k) dst[n][k] = *(const PG8_LAS bf16x8*)(lds + PG8_SB(b, h) + boff + n * 2048 + k * 1024); } while (0)
; template <class Epi, class Sched, bool ALIGN_EPI = false, bool SP2 = false>
; __device__ __forceinline__ void gemm_phase(PG8_LAS unsigned char* lds, const Gemm g, const Sched& S, const Epi& E) {
;     ...
;         for (int t = 0; t < nt; t += 2) {
;             const bool last = (t == nt - 2);
;             const char* a1 = cA + (size_t)(t + 1) * kstep;
;             const char* a2 = last ? nA : cA + (size_t)(t + 2) * kstep; const char* b2 = last ? nB : cB + (size_t)(t + 2) * kstep;
;             const char* a3 = a2 + kstep; const char* b3 = b2 + kstep;
;             if (last && has_next) S.a_ready(nxt, ui + 1);
;             if constexpr (SP2) {
;             PG8_LDB(B0, 0, 0); PG8_LDB(B1, 0, 1); PG8_SCHED; PG8_LDA(At, 0, 0); PG8_STAGE(PG8_SA(1, 1), a1 + hstep, voffA);
;             PG8_WAIT_V(8); PG8_WAIT_L(0); PG8_BAR; PG8_MMA(0, 0, At, B0); PG8_MMA(0, 1, At, B1); PG8_BAR; PG8_SCHED;
;             PG8_LDA(At, 0, 1); PG8_STAGE(PG8_SB(0, 0), b2, voffB); PG8_STAGE(PG8_SB(0, 1), b2 + hstep, voffB); PG8_STAGE(PG8_SA(0, 0), a2, voffA);
;             PG8_WAIT_V(8); PG8_WAIT_L(0); PG8_BAR; PG8_MMA(1, 0, At, B0); PG8_MMA(1, 1, At, B1); PG8_BAR; PG8_SCHED;
;             PG8_LDB(B0, 1, 0); PG8_LDB(B1, 1, 1); PG8_SCHED; PG8_LDA(At, 1, 0); PG8_STAGE(PG8_SA(0, 1), a2 + hstep, voffA);
;             PG8_WAIT_V(8); PG8_WAIT_L(0); PG8_BAR; PG8_MMA(0, 0, At, B0); PG8_MMA(0, 1, At, B1); PG8_BAR; PG8_SCHED;
;             PG8_LDA(At, 1, 1); PG8_STAGE(PG8_SB(1, 0), b3, voffB); PG8_STAGE(PG8_SB(1, 1), b3 + hstep, voffB); PG8_STAGE(PG8_SA(1, 0), a3, voffA);
;             PG8_WAIT_V(8); PG8_WAIT_L(0); PG8_BAR; PG8_MMA(1, 0, At, B0); PG8_MMA(1, 1, At, B1); PG8_BAR; PG8_SCHED;
	v_mfma_f32_16x16x32_bf16 v[60:63], v[120:123], v[160:163], v[60:63]
	v_mfma_f32_16x16x32_bf16 v[56:59], v[136:139], v[160:163], v[56:59]
	v_mfma_f32_16x16x32_bf16 v[44:47], v[120:123], v[168:171], v[44:47]
	v_mfma_f32_16x16x32_bf16 v[40:43], v[136:139], v[168:171], v[40:43]
	v_mfma_f32_16x16x32_bf16 v[28:31], v[120:123], v[176:179], v[28:31]
	v_mfma_f32_16x16x32_bf16 v[24:27], v[136:139], v[176:179], v[24:27]
	v_mfma_f32_16x16x32_bf16 v[12:15], v[120:123], v[184:187], v[12:15]
	v_mfma_f32_16x16x32_bf16 v[8:11], v[136:139], v[184:187], v[8:11]
	v_mfma_f32_16x16x32_bf16 v[60:63], v[128:131], v[164:167], v[60:63]
	v_mfma_f32_16x16x32_bf16 v[56:59], v[140:143], v[164:167], v[56:59]
	v_mfma_f32_16x16x32_bf16 v[44:47], v[128:131], v[172:175], v[44:47]
	v_mfma_f32_16x16x32_bf16 v[40:43], v[140:143], v[172:175], v[40:43]
	v_mfma_f32_16x16x32_bf16 v[28:31], v[128:131], v[180:183], v[28:31]
	v_mfma_f32_16x16x32_bf16 v[24:27], v[140:143], v[180:183], v[24:27]
	v_mfma_f32_16x16x32_bf16 v[12:15], v[128:131], v[188:191], v[12:15]
	v_mfma_f32_16x16x32_bf16 v[8:11], v[140:143], v[188:191], v[8:11]
	s_setprio 0
	s_setprio 1
	v_mfma_f32_16x16x32_bf16 v[52:55], v[144:147], v[160:163], v[52:55]
	v_mfma_f32_16x16x32_bf16 v[48:51], v[152:155], v[160:163], v[48:51]
	v_mfma_f32_16x16x32_bf16 v[36:39], v[144:147], v[168:171], v[36:39]
	v_mfma_f32_16x16x32_bf16 v[32:35], v[152:155], v[168:171], v[32:35]
	v_mfma_f32_16x16x32_bf16 v[20:23], v[144:147], v[176:179], v[20:23]
	v_mfma_f32_16x16x32_bf16 v[16:19], v[152:155], v[176:179], v[16:19]
	v_mfma_f32_16x16x32_bf16 v[4:7], v[144:147], v[184:187], v[4:7]
	v_mfma_f32_16x16x32_bf16 v[0:3], v[152:155], v[184:187], v[0:3]
	v_mfma_f32_16x16x32_bf16 v[52:55], v[148:151], v[164:167], v[52:55]
	v_mfma_f32_16x16x32_bf16 v[48:51], v[156:159], v[164:167], v[48:51]
	v_mfma_f32_16x16x32_bf16 v[36:39], v[148:151], v[172:175], v[36:39]
	v_mfma_f32_16x16x32_bf16 v[32:35], v[156:159], v[172:175], v[32:35]
	v_mfma_f32_16x16x32_bf16 v[20:23], v[148:151], v[180:183], v[20:23]
	v_mfma_f32_16x16x32_bf16 v[16:19], v[156:159], v[180:183], v[16:19]
	v_mfma_f32_16x16x32_bf16 v[4:7], v[148:151], v[188:191], v[4:7]
	v_mfma_f32_16x16x32_bf16 v[0:3], v[156:159], v[188:191], v[0:3]
	s_barrier
	s_setprio 0
	s_add_i32 s57, s57, 2
	s_add_u32 s30, s30, 0x100
	s_addc_u32 s31, s31, 0
	s_add_u32 s55, s55, 0x100
	s_addc_u32 s56, s56, 0
	s_cmp_gt_u32 s57, 13
.LBB0_960:
	ds_read_b128 v[120:123], v245
	ds_read_b128 v[128:131], v245 offset:1024
	ds_read_b128 v[136:139], v245 offset:2048
	ds_read_b128 v[140:143], v245 offset:3072
	ds_read_b128 v[144:147], v246
	ds_read_b128 v[148:151], v246 offset:1024
	ds_read_b128 v[152:155], v246 offset:2048
	ds_read_b128 v[156:159], v246 offset:3072
	s_add_u32 s34, s30, 0xfffc0080
	s_addc_u32 s35, s31, -1
	s_cmp_eq_u32 s57, 12
	s_cselect_b32 s37, s23, s35
	s_cselect_b32 s36, s29, s34
	s_cselect_b32 s35, s21, s56
	s_cselect_b32 s34, s54, s55
	v_lshl_add_u64 v[204:205], s[30:31], 0, v[200:201]
	s_add_i32 m0, s41, 0xc000
	ds_read_b128 v[160:163], v247
	ds_read_b128 v[164:167], v247 offset:1024
	ds_read_b128 v[168:171], v247 offset:2048
	ds_read_b128 v[172:175], v247 offset:3072
	ds_read_b128 v[176:179], v247 offset:4096
	ds_read_b128 v[180:183], v247 offset:5120
	ds_read_b128 v[184:187], v247 offset:6144
	ds_read_b128 v[188:191], v247 offset:7168
	global_load_lds_dwordx4 v[204:205], off
	v_lshl_add_u64 v[204:205], s[30:31], 0, v[202:203]
	s_add_i32 m0, s41, 0xe000
	s_nop 0
	global_load_lds_dwordx4 v[204:205], off
	s_waitcnt vmcnt(8)
	s_waitcnt lgkmcnt(0)
	s_setprio 1
	s_barrier
	v_mfma_f32_16x16x32_bf16 v[132:135], v[120:123], v[160:163], v[132:135]
	v_mfma_f32_16x16x32_bf16 v[124:127], v[136:139], v[160:163], v[124:127]
	v_mfma_f32_16x16x32_bf16 v[108:111], v[120:123], v[168:171], v[108:111]
	v_mfma_f32_16x16x32_bf16 v[104:107], v[136:139], v[168:171], v[104:107]
	v_mfma_f32_16x16x32_bf16 v[92:95], v[120:123], v[176:179], v[92:95]
	v_mfma_f32_16x16x32_bf16 v[88:91], v[136:139], v[176:179], v[88:91]
	v_mfma_f32_16x16x32_bf16 v[76:79], v[120:123], v[184:187], v[76:79]
	v_mfma_f32_16x16x32_bf16 v[72:75], v[136:139], v[184:187], v[72:75]
	v_mfma_f32_16x16x32_bf16 v[132:135], v[128:131], v[164:167], v[132:135]
	v_mfma_f32_16x16x32_bf16 v[124:127], v[140:143], v[164:167], v[124:127]
	v_mfma_f32_16x16x32_bf16 v[108:111], v[128:131], v[172:175], v[108:111]
	v_mfma_f32_16x16x32_bf16 v[104:107], v[140:143], v[172:175], v[104:107]
	v_mfma_f32_16x16x32_bf16 v[92:95], v[128:131], v[180:183], v[92:95]
	v_mfma_f32_16x16x32_bf16 v[88:91], v[140:143], v[180:183], v[88:91]
	v_mfma_f32_16x16x32_bf16 v[76:79], v[128:131], v[188:191], v[76:79]
	v_mfma_f32_16x16x32_bf16 v[72:75], v[140:143], v[188:191], v[72:75]
	s_setprio 0
	s_setprio 1
	v_mfma_f32_16x16x32_bf16 v[116:119], v[144:147], v[160:163], v[116:119]
	v_mfma_f32_16x16x32_bf16 v[112:115], v[152:155], v[160:163], v[112:115]
	v_mfma_f32_16x16x32_bf16 v[100:103], v[144:147], v[168:171], v[100:103]
	v_mfma_f32_16x16x32_bf16 v[96:99], v[152:155], v[168:171], v[96:99]
	v_mfma_f32_16x16x32_bf16 v[84:87], v[144:147], v[176:179], v[84:87]
	v_mfma_f32_16x16x32_bf16 v[80:83], v[152:155], v[176:179], v[80:83]
	v_mfma_f32_16x16x32_bf16 v[68:71], v[144:147], v[184:187], v[68:71]
	v_mfma_f32_16x16x32_bf16 v[64:67], v[152:155], v[184:187], v[64:67]
	v_mfma_f32_16x16x32_bf16 v[116:119], v[148:151], v[164:167], v[116:119]
	v_mfma_f32_16x16x32_bf16 v[112:115], v[156:159], v[164:167], v[112:115]
	v_mfma_f32_16x16x32_bf16 v[100:103], v[148:151], v[172:175], v[100:103]
	v_mfma_f32_16x16x32_bf16 v[96:99], v[156:159], v[172:175], v[96:99]
	v_mfma_f32_16x16x32_bf16 v[84:87], v[148:151], v[180:183], v[84:87]
	v_mfma_f32_16x16x32_bf16 v[80:83], v[156:159], v[180:183], v[80:83]
	v_mfma_f32_16x16x32_bf16 v[68:71], v[148:151], v[188:191], v[68:71]
	v_mfma_f32_16x16x32_bf16 v[64:67], v[156:159], v[188:191], v[64:67]
	s_barrier
; #define PG8_STAGE(bufoff, gbase, voff) do { _Pragma("unroll") for (int _i = 0; _i < 2; ++_i) \
;         __builtin_amdgcn_global_load_lds((const unsigned*)((const char*)(gbase) + (voff)[_i]), (PG8_LAS unsigned*)(lds + (bufoff) + ldsw + _i * 8192), 16, 0, 0); } while (0)
; #define PG8_LDA(dst, b, h) do { _Pragma("unroll") for (int m = 0; m < 4; ++m) _Pragma("unroll") for (int k = 0; k < 2; ++k) dst[m][k] = *(const PG8_LAS bf16x8*)(lds + PG8_SA(b, h) + aoff + m * 2048 + k * 1024); } while (0)
; #define PG8_LDB(dst, b, h) do { _Pragma("unroll") for (int n = 0; n < 2; ++n) _Pragma("unroll") for (int k = 0; k < 2; ++k) dst[n][k] = *(const PG8_LAS bf16x8*)(lds + PG8_SB(b, h) + boff + n * 2048 + k * 1024); } while (0)
; #define PG8_MMA(ai, bj, At, Bt) do { __builtin_amdgcn_s_setprio(1); _Pragma("unroll") for (int m = 0; m < 4; ++m) _Pragma("unroll") for (int n = 0; n < 2; ++n) _Pragma("unroll") for (int k = 0; k < 2; ++k) \
;         acc[ai][bj][m][n] = __builtin_amdgcn_mfma_f32_16x16x32_bf16(Bt[n][k], At[m][k], acc[ai][bj][m][n], 0, 0, 0); __builtin_amdgcn_s_setprio(0); } while (0)
; #define PG8_WAIT_V(n) asm volatile("s_waitcnt vmcnt(" #n ")" ::: "memory")
; template <class Epi, class Sched, bool ALIGN_EPI = false, bool SP2 = false>
; __device__ __forceinline__ void gemm_phase(PG8_LAS unsigned char* lds, const Gemm g, const Sched& S, const Epi& E) {
;     ...
;             PG8_LDB(B0, 0, 0); PG8_LDB(B1, 0, 1); PG8_SCHED; PG8_LDA(At, 0, 0); PG8_STAGE(PG8_SA(1, 1), a1 + hstep, voffA);
;             PG8_WAIT_V(8); PG8_WAIT_L(0); PG8_BAR; PG8_MMA(0, 0, At, B0); PG8_MMA(0, 1, At, B1); PG8_BAR; PG8_SCHED;
;             PG8_LDA(At, 0, 1); PG8_STAGE(PG8_SB(0, 0), b2, voffB); PG8_STAGE(PG8_SB(0, 1), b2 + hstep, voffB); PG8_STAGE(PG8_SA(0, 0), a2, voffA);
;             PG8_WAIT_V(8); PG8_WAIT_L(0); PG8_BAR; PG8_MMA(1, 0, At, B0); PG8_MMA(1, 1, At, B1); PG8_BAR; PG8_SCHED;
;             PG8_LDB(B0, 1, 0); PG8_LDB(B1, 1, 1); PG8_SCHED; PG8_LDA(At, 1, 0); PG8_STAGE(PG8_SA(0, 1), a2 + hstep, voffA);
;             PG8_WAIT_V(8); PG8_WAIT_L(0); PG8_BAR; PG8_MMA(0, 0, At, B0); PG8_MMA(0, 1, At, B1); PG8_BAR; PG8_SCHED;
;             PG8_LDA(At, 1, 1); PG8_STAGE(PG8_SB(1, 0), b3, voffB); PG8_STAGE(PG8_SB(1, 1), b3 + hstep, voffB); PG8_STAGE(PG8_SA(1, 0), a3, voffA);
;             PG8_WAIT_V(8); PG8_WAIT_L(0); PG8_BAR; PG8_MMA(1, 0, At, B0); PG8_MMA(1, 1, At, B1); PG8_BAR; PG8_SCHED;
	s_setprio 0
	s_add_i32 s58, s51, s40
	v_lshl_add_u64 v[204:205], s[34:35], 0, v[194:195]
	s_mov_b32 m0, s58
	ds_read_b128 v[160:163], v247 offset:16384
	ds_read_b128 v[164:167], v247 offset:17408
	ds_read_b128 v[168:171], v247 offset:18432
	ds_read_b128 v[172:175], v247 offset:19456
	ds_read_b128 v[176:179], v247 offset:20480
	ds_read_b128 v[180:183], v247 offset:21504
	ds_read_b128 v[184:187], v247 offset:22528
	ds_read_b128 v[188:191], v247 offset:23552
	global_load_lds_dwordx4 v[204:205], off
	s_add_i32 m0, s58, 0x2000
	s_add_u32 s58, s34, 0x40000
	v_lshl_add_u64 v[206:207], s[34:35], 0, v[198:199]
	s_addc_u32 s59, s35, 0
	s_add_i32 s60, s52, s40
	global_load_lds_dwordx4 v[206:207], off
	v_lshl_add_u64 v[208:209], s[58:59], 0, v[194:195]
	s_mov_b32 m0, s60
	v_lshl_add_u64 v[210:211], s[36:37], 0, v[196:197]
	global_load_lds_dwordx4 v[208:209], off
	v_lshl_add_u64 v[208:209], s[58:59], 0, v[198:199]
	s_add_i32 m0, s60, 0x2000
	s_nop 0
	global_load_lds_dwordx4 v[208:209], off
	v_lshl_add_u64 v[208:209], s[36:37], 0, v[192:193]
	s_mov_b32 m0, s41
	s_nop 0
	global_load_lds_dwordx4 v[208:209], off
	s_mov_b32 m0, s42
	s_nop 0
	global_load_lds_dwordx4 v[210:211], off
	s_waitcnt vmcnt(8)
	s_waitcnt lgkmcnt(0)
	s_setprio 1
	s_barrier
	v_mfma_f32_16x16x32_bf16 v[60:63], v[120:123], v[160:163], v[60:63]
	v_mfma_f32_16x16x32_bf16 v[56:59], v[136:139], v[160:163], v[56:59]
	v_mfma_f32_16x16x32_bf16 v[44:47], v[120:123], v[168:171], v[44:47]
	v_mfma_f32_16x16x32_bf16 v[40:43], v[136:139], v[168:171], v[40:43]
	v_mfma_f32_16x16x32_bf16 v[28:31], v[120:123], v[176:179], v[28:31]
	v_mfma_f32_16x16x32_bf16 v[24:27], v[136:139], v[176:179], v[24:27]
	v_mfma_f32_16x16x32_bf16 v[12:15], v[120:123], v[184:187], v[12:15]
	v_mfma_f32_16x16x32_bf16 v[8:11], v[136:139], v[184:187], v[8:11]
	v_mfma_f32_16x16x32_bf16 v[60:63], v[128:131], v[164:167], v[60:63]
	v_mfma_f32_16x16x32_bf16 v[56:59], v[140:143], v[164:167], v[56:59]
	v_mfma_f32_16x16x32_bf16 v[44:47], v[128:131], v[172:175], v[44:47]
	v_mfma_f32_16x16x32_bf16 v[40:43], v[140:143], v[172:175], v[40:43]
	v_mfma_f32_16x16x32_bf16 v[28:31], v[128:131], v[180:183], v[28:31]
	v_mfma_f32_16x16x32_bf16 v[24:27], v[140:143], v[180:183], v[24:27]
	v_mfma_f32_16x16x32_bf16 v[12:15], v[128:131], v[188:191], v[12:15]
	v_mfma_f32_16x16x32_bf16 v[8:11], v[140:143], v[188:191], v[8:11]
	s_setprio 0
	s_setprio 1
	v_mfma_f32_16x16x32_bf16 v[52:55], v[144:147], v[160:163], v[52:55]
	v_mfma_f32_16x16x32_bf16 v[48:51], v[152:155], v[160:163], v[48:51]
	v_mfma_f32_16x16x32_bf16 v[36:39], v[144:147], v[168:171], v[36:39]
	v_mfma_f32_16x16x32_bf16 v[32:35], v[152:155], v[168:171], v[32:35]
	v_mfma_f32_16x16x32_bf16 v[20:23], v[144:147], v[176:179], v[20:23]
	v_mfma_f32_16x16x32_bf16 v[16:19], v[152:155], v[176:179], v[16:19]
	v_mfma_f32_16x16x32_bf16 v[4:7], v[144:147], v[184:187], v[4:7]
	v_mfma_f32_16x16x32_bf16 v[0:3], v[152:155], v[184:187], v[0:3]
	v_mfma_f32_16x16x32_bf16 v[52:55], v[148:151], v[164:167], v[52:55]
	v_mfma_f32_16x16x32_bf16 v[48:51], v[156:159], v[164:167], v[48:51]
	v_mfma_f32_16x16x32_bf16 v[36:39], v[148:151], v[172:175], v[36:39]
	v_mfma_f32_16x16x32_bf16 v[32:35], v[156:159], v[172:175], v[32:35]
	v_mfma_f32_16x16x32_bf16 v[20:23], v[148:151], v[180:183], v[20:23]
	v_mfma_f32_16x16x32_bf16 v[16:19], v[156:159], v[180:183], v[16:19]
	v_mfma_f32_16x16x32_bf16 v[4:7], v[148:151], v[188:191], v[4:7]
	v_mfma_f32_16x16x32_bf16 v[0:3], v[156:159], v[188:191], v[0:3]
	s_barrier
	s_setprio 0
	s_add_i32 s58, 0, 0x18000
	s_add_i32 s59, 0, 0x1c000
	v_add_u32_e32 v140, s58, v243
	v_add_u32_e32 v156, s59, v243
	ds_read_b128 v[120:123], v140
	ds_read_b128 v[128:131], v140 offset:1024
	ds_read_b128 v[136:139], v140 offset:2048
	ds_read_b128 v[140:143], v140 offset:3072
	ds_read_b128 v[144:147], v156
	ds_read_b128 v[148:151], v156 offset:1024
	ds_read_b128 v[152:155], v156 offset:2048
	ds_read_b128 v[156:159], v156 offset:3072
	s_add_u32 s36, s36, 0x40000
	s_addc_u32 s37, s37, 0
	s_mov_b32 m0, s43
	v_lshl_add_u64 v[212:213], s[36:37], 0, v[192:193]
	ds_read_b128 v[160:163], v247 offset:32768
	ds_read_b128 v[164:167], v247 offset:33792
	ds_read_b128 v[168:171], v247 offset:34816
	ds_read_b128 v[172:175], v247 offset:35840
	ds_read_b128 v[176:179], v247 offset:36864
	ds_read_b128 v[180:183], v247 offset:37888
	ds_read_b128 v[184:187], v247 offset:38912
	ds_read_b128 v[188:191], v247 offset:39936
	global_load_lds_dwordx4 v[212:213], off
	v_lshl_add_u64 v[212:213], s[36:37], 0, v[196:197]
	s_mov_b32 m0, s44
	s_nop 0
	global_load_lds_dwordx4 v[212:213], off
	s_waitcnt vmcnt(8)
	s_waitcnt lgkmcnt(0)
	s_setprio 1
	s_barrier
; #define PG8_STAGE(bufoff, gbase, voff) do { _Pragma("unroll") for (int _i = 0; _i < 2; ++_i) \
;         __builtin_amdgcn_global_load_lds((const unsigned*)((const char*)(gbase) + (voff)[_i]), (PG8_LAS unsigned*)(lds + (bufoff) + ldsw + _i * 8192), 16, 0, 0); } while (0)
; #define PG8_LDA(dst, b, h) do { _Pragma("unroll") for (int m = 0; m < 4; ++m) _Pragma("unroll") for (int k = 0; k < 2; ++k) dst[m][k] = *(const PG8_LAS bf16x8*)(lds + PG8_SA(b, h) + aoff + m * 2048 + k * 1024); } while (0)
; #define PG8_LDB(dst, b, h) do { _Pragma("unroll") for (int n = 0; n < 2; ++n) _Pragma("unroll") for (int k = 0; k < 2; ++k) dst[n][k] = *(const PG8_LAS bf16x8*)(lds + PG8_SB(b, h) + boff + n * 2048 + k * 1024); } while (0)
; #define PG8_MMA(ai, bj, At, Bt) do { __builtin_amdgcn_s_setprio(1); _Pragma("unroll") for (int m = 0; m < 4; ++m) _Pragma("unroll") for (int n = 0; n < 2; ++n) _Pragma("unroll") for (int k = 0; k < 2; ++k) \
;         acc[ai][bj][m][n] = __builtin_amdgcn_mfma_f32_16x16x32_bf16(Bt[n][k], At[m][k], acc[ai][bj][m][n], 0, 0, 0); __builtin_amdgcn_s_setprio(0); } while (0)
; template <class Epi, class Sched, bool ALIGN_EPI = false, bool SP2 = false>
; __device__ __forceinline__ void gemm_phase(PG8_LAS unsigned char* lds, const Gemm g, const Sched& S, const Epi& E) {
;     ...
;             PG8_LDB(B0, 0, 0); PG8_LDB(B1, 0, 1); PG8_SCHED; PG8_LDA(At, 0, 0); PG8_STAGE(PG8_SA(1, 1), a1 + hstep, voffA);
;             PG8_WAIT_V(8); PG8_WAIT_L(0); PG8_BAR; PG8_MMA(0, 0, At, B0); PG8_MMA(0, 1, At, B1); PG8_BAR; PG8_SCHED;
;             PG8_LDA(At, 0, 1); PG8_STAGE(PG8_SB(0, 0), b2, voffB); PG8_STAGE(PG8_SB(0, 1), b2 + hstep, voffB); PG8_STAGE(PG8_SA(0, 0), a2, voffA);
;             PG8_WAIT_V(8); PG8_WAIT_L(0); PG8_BAR; PG8_MMA(1, 0, At, B0); PG8_MMA(1, 1, At, B1); PG8_BAR; PG8_SCHED;
;             PG8_LDB(B0, 1, 0); PG8_LDB(B1, 1, 1); PG8_SCHED; PG8_LDA(At, 1, 0); PG8_STAGE(PG8_SA(0, 1), a2 + hstep, voffA);
;             PG8_WAIT_V(8); PG8_WAIT_L(0); PG8_BAR; PG8_MMA(0, 0, At, B0); PG8_MMA(0, 1, At, B1); PG8_BAR; PG8_SCHED;
;             PG8_LDA(At, 1, 1); PG8_STAGE(PG8_SB(1, 0), b3, voffB); PG8_STAGE(PG8_SB(1, 1), b3 + hstep, voffB); PG8_STAGE(PG8_SA(1, 0), a3, voffA);
;             PG8_WAIT_V(8); PG8_WAIT_L(0); PG8_BAR; PG8_MMA(1, 0, At, B0); PG8_MMA(1, 1, At, B1); PG8_BAR; PG8_SCHED;
;     ...
;         if constexpr (ALIGN_EPI) { if (wr == 0) PG8_BAR; }
	v_mfma_f32_16x16x32_bf16 v[132:135], v[120:123], v[160:163], v[132:135]
	v_mfma_f32_16x16x32_bf16 v[124:127], v[136:139], v[160:163], v[124:127]
	v_mfma_f32_16x16x32_bf16 v[108:111], v[120:123], v[168:171], v[108:111]
	v_mfma_f32_16x16x32_bf16 v[104:107], v[136:139], v[168:171], v[104:107]
	v_mfma_f32_16x16x32_bf16 v[92:95], v[120:123], v[176:179], v[92:95]
	v_mfma_f32_16x16x32_bf16 v[88:91], v[136:139], v[176:179], v[88:91]
	v_mfma_f32_16x16x32_bf16 v[76:79], v[120:123], v[184:187], v[76:79]
	v_mfma_f32_16x16x32_bf16 v[72:75], v[136:139], v[184:187], v[72:75]
	v_mfma_f32_16x16x32_bf16 v[132:135], v[128:131], v[164:167], v[132:135]
	v_mfma_f32_16x16x32_bf16 v[124:127], v[140:143], v[164:167], v[124:127]
	v_mfma_f32_16x16x32_bf16 v[108:111], v[128:131], v[172:175], v[108:111]
	v_mfma_f32_16x16x32_bf16 v[104:107], v[140:143], v[172:175], v[104:107]
	v_mfma_f32_16x16x32_bf16 v[92:95], v[128:131], v[180:183], v[92:95]
	v_mfma_f32_16x16x32_bf16 v[88:91], v[140:143], v[180:183], v[88:91]
	v_mfma_f32_16x16x32_bf16 v[76:79], v[128:131], v[188:191], v[76:79]
	v_mfma_f32_16x16x32_bf16 v[72:75], v[140:143], v[188:191], v[72:75]
	s_setprio 0
	s_setprio 1
	v_mfma_f32_16x16x32_bf16 v[116:119], v[144:147], v[160:163], v[116:119]
	v_mfma_f32_16x16x32_bf16 v[112:115], v[152:155], v[160:163], v[112:115]
	v_mfma_f32_16x16x32_bf16 v[100:103], v[144:147], v[168:171], v[100:103]
	v_mfma_f32_16x16x32_bf16 v[96:99], v[152:155], v[168:171], v[96:99]
	v_mfma_f32_16x16x32_bf16 v[84:87], v[144:147], v[176:179], v[84:87]
	v_mfma_f32_16x16x32_bf16 v[80:83], v[152:155], v[176:179], v[80:83]
	v_mfma_f32_16x16x32_bf16 v[68:71], v[144:147], v[184:187], v[68:71]
	v_mfma_f32_16x16x32_bf16 v[64:67], v[152:155], v[184:187], v[64:67]
	v_mfma_f32_16x16x32_bf16 v[116:119], v[148:151], v[164:167], v[116:119]
	v_mfma_f32_16x16x32_bf16 v[112:115], v[156:159], v[164:167], v[112:115]
	v_mfma_f32_16x16x32_bf16 v[100:103], v[148:151], v[172:175], v[100:103]
	v_mfma_f32_16x16x32_bf16 v[96:99], v[156:159], v[172:175], v[96:99]
	v_mfma_f32_16x16x32_bf16 v[84:87], v[148:151], v[180:183], v[84:87]
	v_mfma_f32_16x16x32_bf16 v[80:83], v[156:159], v[180:183], v[80:83]
	v_mfma_f32_16x16x32_bf16 v[68:71], v[148:151], v[188:191], v[68:71]
	v_mfma_f32_16x16x32_bf16 v[64:67], v[156:159], v[188:191], v[64:67]
	s_barrier
	s_setprio 0
	s_add_i32 s36, s58, s40
	v_lshl_add_u64 v[204:205], v[204:205], 0, s[16:17]
	s_mov_b32 m0, s36
	ds_read_b128 v[160:163], v247 offset:49152
	ds_read_b128 v[164:167], v247 offset:50176
	ds_read_b128 v[168:171], v247 offset:51200
	ds_read_b128 v[172:175], v247 offset:52224
	ds_read_b128 v[176:179], v247 offset:53248
	ds_read_b128 v[180:183], v247 offset:54272
	ds_read_b128 v[184:187], v247 offset:55296
	ds_read_b128 v[188:191], v247 offset:56320
	global_load_lds_dwordx4 v[204:205], off
	s_add_i32 m0, s36, 0x2000
	s_add_u32 s34, s34, 0x40080
	v_lshl_add_u64 v[204:205], v[206:207], 0, s[16:17]
	s_addc_u32 s35, s35, 0
	s_add_i32 s36, s59, s40
	global_load_lds_dwordx4 v[204:205], off
	v_lshl_add_u64 v[204:205], s[34:35], 0, v[194:195]
	s_mov_b32 m0, s36
	s_nop 0
	global_load_lds_dwordx4 v[204:205], off
	v_lshl_add_u64 v[204:205], s[34:35], 0, v[198:199]
	s_add_i32 m0, s36, 0x2000
	s_nop 0
	global_load_lds_dwordx4 v[204:205], off
	v_lshl_add_u64 v[204:205], v[208:209], 0, s[16:17]
	s_mov_b32 m0, s46
	s_nop 0
	global_load_lds_dwordx4 v[204:205], off
	v_lshl_add_u64 v[204:205], v[210:211], 0, s[16:17]
	s_mov_b32 m0, s47
	s_nop 0
	global_load_lds_dwordx4 v[204:205], off
	s_waitcnt vmcnt(8)
	s_waitcnt lgkmcnt(0)
	s_setprio 1
	s_barrier
	v_mfma_f32_16x16x32_bf16 v[60:63], v[120:123], v[160:163], v[60:63]
	v_mfma_f32_16x16x32_bf16 v[56:59], v[136:139], v[160:163], v[56:59]
	v_mfma_f32_16x16x32_bf16 v[44:47], v[120:123], v[168:171], v[44:47]
	v_mfma_f32_16x16x32_bf16 v[40:43], v[136:139], v[168:171], v[40:43]
	v_mfma_f32_16x16x32_bf16 v[28:31], v[120:123], v[176:179], v[28:31]
	v_mfma_f32_16x16x32_bf16 v[24:27], v[136:139], v[176:179], v[24:27]
	v_mfma_f32_16x16x32_bf16 v[12:15], v[120:123], v[184:187], v[12:15]
	v_mfma_f32_16x16x32_bf16 v[8:11], v[136:139], v[184:187], v[8:11]
	v_mfma_f32_16x16x32_bf16 v[60:63], v[128:131], v[164:167], v[60:63]
	v_mfma_f32_16x16x32_bf16 v[56:59], v[140:143], v[164:167], v[56:59]
	v_mfma_f32_16x16x32_bf16 v[44:47], v[128:131], v[172:175], v[44:47]
	v_mfma_f32_16x16x32_bf16 v[40:43], v[140:143], v[172:175], v[40:43]
	v_mfma_f32_16x16x32_bf16 v[28:31], v[128:131], v[180:183], v[28:31]
	v_mfma_f32_16x16x32_bf16 v[24:27], v[140:143], v[180:183], v[24:27]
	v_mfma_f32_16x16x32_bf16 v[12:15], v[128:131], v[188:191], v[12:15]
	v_mfma_f32_16x16x32_bf16 v[8:11], v[140:143], v[188:191], v[8:11]
	s_setprio 0
	s_setprio 1
	v_mfma_f32_16x16x32_bf16 v[52:55], v[144:147], v[160:163], v[52:55]
	v_mfma_f32_16x16x32_bf16 v[48:51], v[152:155], v[160:163], v[48:51]
	v_mfma_f32_16x16x32_bf16 v[36:39], v[144:147], v[168:171], v[36:39]
	v_mfma_f32_16x16x32_bf16 v[32:35], v[152:155], v[168:171], v[32:35]
	v_mfma_f32_16x16x32_bf16 v[20:23], v[144:147], v[176:179], v[20:23]
	v_mfma_f32_16x16x32_bf16 v[16:19], v[152:155], v[176:179], v[16:19]
	v_mfma_f32_16x16x32_bf16 v[4:7], v[144:147], v[184:187], v[4:7]
	v_mfma_f32_16x16x32_bf16 v[0:3], v[152:155], v[184:187], v[0:3]
	v_mfma_f32_16x16x32_bf16 v[52:55], v[148:151], v[164:167], v[52:55]
	v_mfma_f32_16x16x32_bf16 v[48:51], v[156:159], v[164:167], v[48:51]
	v_mfma_f32_16x16x32_bf16 v[36:39], v[148:151], v[172:175], v[36:39]
	v_mfma_f32_16x16x32_bf16 v[32:35], v[156:159], v[172:175], v[32:35]
	v_mfma_f32_16x16x32_bf16 v[20:23], v[148:151], v[180:183], v[20:23]
	v_mfma_f32_16x16x32_bf16 v[16:19], v[156:159], v[180:183], v[16:19]
	v_mfma_f32_16x16x32_bf16 v[4:7], v[148:151], v[188:191], v[4:7]
	v_mfma_f32_16x16x32_bf16 v[0:3], v[156:159], v[188:191], v[0:3]
	s_barrier
	s_setprio 0
	s_add_i32 s57, s57, 2
	s_add_u32 s30, s30, 0x100
	s_addc_u32 s31, s31, 0
	s_add_u32 s55, s55, 0x100
	s_addc_u32 s56, s56, 0
	s_cmp_gt_u32 s57, 13
	s_cbranch_scc0 .LBB0_960
	s_and_b64 vcc, exec, s[18:19]
	s_cbranch_vccz .LBB0_963
	s_barrier

; #define PG8_STAGE(bufoff, gbase, voff) do { _Pragma("unroll") for (int _i = 0; _i < 2; ++_i) \
;         __builtin_amdgcn_global_load_lds((const unsigned*)((const char*)(gbase) + (voff)[_i]), (PG8_LAS unsigned*)(lds + (bufoff) + ldsw + _i * 8192), 16, 0, 0); } while (0)
; #define PG8_LDA(dst, b, h) do { _Pragma("unroll") for (int m = 0; m < 4; ++m) _Pragma("unroll") for (int k = 0; k < 2; ++k) dst[m][k] = *(const PG8_LAS bf16x8*)(lds + PG8_SA(b, h) + aoff + m * 2048 + k * 1024); } while (0)
; template <class Epi, class Sched, bool ALIGN_EPI = false, bool SP2 = false>
; __device__ __forceinline__ void gemm_phase(PG8_LAS unsigned char* lds, const Gemm g, const Sched& S, const Epi& E) {
;     ...
;         const bool has_next = S.next(ui + 1, nxt);
;         const char* nA = has_next ? (const char*)g.A + (size_t)nxt.pm * tstep : cA; const char* nB = has_next ? (const char*)g.Bt + (size_t)nxt.pn * tstep : cB;
;         for (int t = 0; t < nt; t += 2) {
;             const bool last = (t == nt - 2);
;             const char* a1 = cA + (size_t)(t + 1) * kstep;
;             const char* a2 = last ? nA : cA + (size_t)(t + 2) * kstep; const char* b2 = last ? nB : cB + (size_t)(t + 2) * kstep;
;             const char* a3 = a2 + kstep; const char* b3 = b2 + kstep;
;             if (last && has_next) S.a_ready(nxt, ui + 1);
;             if constexpr (SP2) {
;             PG8_LDB(B0, 0, 0); PG8_LDB(B1, 0, 1); PG8_SCHED; PG8_LDA(At, 0, 0); PG8_STAGE(PG8_SA(1, 1), a1 + hstep, voffA);
;             PG8_WAIT_V(8); PG8_WAIT_L(0); PG8_BAR; PG8_MMA(0, 0, At, B0); PG8_MMA(0, 1, At, B1); PG8_BAR; PG8_SCHED;
;             PG8_LDA(At, 0, 1); PG8_STAGE(PG8_SB(0, 0), b2, voffB); PG8_STAGE(PG8_SB(0, 1), b2 + hstep, voffB); PG8_STAGE(PG8_SA(0, 0), a2, voffA);
;             PG8_WAIT_V(8); PG8_WAIT_L(0); PG8_BAR; PG8_MMA(1, 0, At, B0); PG8_MMA(1, 1, At, B1); PG8_BAR; PG8_SCHED;
;             PG8_LDB(B0, 1, 0); PG8_LDB(B1, 1, 1); PG8_SCHED; PG8_LDA(At, 1, 0); PG8_STAGE(PG8_SA(0, 1), a2 + hstep, voffA);
;             PG8_WAIT_V(8); PG8_WAIT_L(0); PG8_BAR; PG8_MMA(0, 0, At, B0); PG8_MMA(0, 1, At, B1); PG8_BAR; PG8_SCHED;
;             PG8_LDA(At, 1, 1); PG8_STAGE(PG8_SB(1, 0), b3, voffB); PG8_STAGE(PG8_SB(1, 1), b3 + hstep, voffB); PG8_STAGE(PG8_SA(1, 0), a3, voffA);
;             PG8_WAIT_V(8); PG8_WAIT_L(0); PG8_BAR; PG8_MMA(1, 0, At, B0); PG8_MMA(1, 1, At, B1); PG8_BAR; PG8_SCHED;
.LBB0_1048:
	s_ashr_i32 s17, s16, 31
	s_lshl_b64 s[18:19], s[16:17], 19
	s_add_u32 s18, s34, s18
	s_addc_u32 s19, s35, s19
	s_and_b64 s[20:21], s[0:1], exec
	s_cselect_b32 s17, s19, s25
	s_cselect_b32 s50, s18, s24
	s_ashr_i32 s15, s14, 31
	s_lshl_b64 s[20:21], s[14:15], 19
	s_add_u32 s20, s36, s20
	s_addc_u32 s21, s37, s21
	s_and_b64 s[28:29], s[0:1], exec
	s_cselect_b32 s15, s21, s27
	s_cselect_b32 s51, s20, s26
	s_add_u32 s24, s24, 0x40080
	s_addc_u32 s25, s25, 0
	s_add_u32 s52, s26, 0x100
	s_addc_u32 s53, s27, 0
	s_mov_b32 s54, -2
	s_add_u32 s26, s24, 0xfffc0080
	s_addc_u32 s27, s25, -1
	s_cmp_eq_u32 s54, 12
	s_cselect_b32 s29, s17, s27
	s_cselect_b32 s28, s50, s26
	s_cselect_b32 s27, s15, s53
	s_cselect_b32 s26, s51, s52
	v_lshl_add_u64 v[216:217], s[24:25], 0, v[136:137]
	s_add_i32 m0, s23, 0xc000
	global_load_lds_dwordx4 v[216:217], off
	v_lshl_add_u64 v[216:217], s[24:25], 0, v[138:139]
	s_add_i32 m0, s23, 0xe000
	s_nop 0
	global_load_lds_dwordx4 v[216:217], off
	s_waitcnt vmcnt(8)
	s_waitcnt lgkmcnt(0)
	s_setprio 1
	s_barrier
	v_mfma_f32_16x16x32_bf16 v[124:127], v[152:155], v[184:187], 0
	v_mfma_f32_16x16x32_bf16 v[120:123], v[160:163], v[184:187], 0
	v_mfma_f32_16x16x32_bf16 v[108:111], v[152:155], v[192:195], 0
	v_mfma_f32_16x16x32_bf16 v[104:107], v[160:163], v[192:195], 0
	v_mfma_f32_16x16x32_bf16 v[92:95], v[152:155], v[200:203], 0
	v_mfma_f32_16x16x32_bf16 v[88:91], v[160:163], v[200:203], 0
	v_mfma_f32_16x16x32_bf16 v[76:79], v[152:155], v[208:211], 0
	v_mfma_f32_16x16x32_bf16 v[72:75], v[160:163], v[208:211], 0
	v_mfma_f32_16x16x32_bf16 v[124:127], v[156:159], v[188:191], v[124:127]
	v_mfma_f32_16x16x32_bf16 v[120:123], v[164:167], v[188:191], v[120:123]
	v_mfma_f32_16x16x32_bf16 v[108:111], v[156:159], v[196:199], v[108:111]
	v_mfma_f32_16x16x32_bf16 v[104:107], v[164:167], v[196:199], v[104:107]
	v_mfma_f32_16x16x32_bf16 v[92:95], v[156:159], v[204:207], v[92:95]
	v_mfma_f32_16x16x32_bf16 v[88:91], v[164:167], v[204:207], v[88:91]
	v_mfma_f32_16x16x32_bf16 v[76:79], v[156:159], v[212:215], v[76:79]
	v_mfma_f32_16x16x32_bf16 v[72:75], v[164:167], v[212:215], v[72:75]
	s_setprio 0
	s_setprio 1
	v_mfma_f32_16x16x32_bf16 v[116:119], v[168:171], v[184:187], 0
	v_mfma_f32_16x16x32_bf16 v[112:115], v[176:179], v[184:187], 0
	v_mfma_f32_16x16x32_bf16 v[100:103], v[168:171], v[192:195], 0
	v_mfma_f32_16x16x32_bf16 v[96:99], v[176:179], v[192:195], 0
	v_mfma_f32_16x16x32_bf16 v[84:87], v[168:171], v[200:203], 0
	v_mfma_f32_16x16x32_bf16 v[80:83], v[176:179], v[200:203], 0
	v_mfma_f32_16x16x32_bf16 v[68:71], v[168:171], v[208:211], 0
	v_mfma_f32_16x16x32_bf16 v[64:67], v[176:179], v[208:211], 0
	v_mfma_f32_16x16x32_bf16 v[116:119], v[172:175], v[188:191], v[116:119]
	v_mfma_f32_16x16x32_bf16 v[112:115], v[180:183], v[188:191], v[112:115]
	v_mfma_f32_16x16x32_bf16 v[100:103], v[172:175], v[196:199], v[100:103]
	v_mfma_f32_16x16x32_bf16 v[96:99], v[180:183], v[196:199], v[96:99]
	v_mfma_f32_16x16x32_bf16 v[84:87], v[172:175], v[204:207], v[84:87]
	v_mfma_f32_16x16x32_bf16 v[80:83], v[180:183], v[204:207], v[80:83]
	v_mfma_f32_16x16x32_bf16 v[68:71], v[172:175], v[212:215], v[68:71]
	v_mfma_f32_16x16x32_bf16 v[64:67], v[180:183], v[212:215], v[64:67]
	s_barrier
	s_setprio 0
	s_add_i32 s55, s44, s33
	v_lshl_add_u64 v[216:217], s[26:27], 0, v[132:133]
	s_mov_b32 m0, s55
	ds_read_b128 v[184:187], v150 offset:16384
	ds_read_b128 v[188:191], v150 offset:17408
	ds_read_b128 v[192:195], v150 offset:18432
	ds_read_b128 v[196:199], v150 offset:19456
	ds_read_b128 v[200:203], v150 offset:20480
	ds_read_b128 v[204:207], v150 offset:21504
	ds_read_b128 v[208:211], v150 offset:22528
	ds_read_b128 v[212:215], v150 offset:23552
	global_load_lds_dwordx4 v[216:217], off
	s_add_i32 m0, s55, 0x2000
	s_add_u32 s56, s26, 0x40000
	v_lshl_add_u64 v[218:219], s[26:27], 0, v[128:129]
	s_addc_u32 s57, s27, 0
	s_add_i32 s55, s45, s33
	global_load_lds_dwordx4 v[218:219], off
	v_lshl_add_u64 v[220:221], s[56:57], 0, v[132:133]
	s_mov_b32 m0, s55
	v_lshl_add_u64 v[222:223], s[28:29], 0, v[130:131]
	global_load_lds_dwordx4 v[220:221], off
	v_lshl_add_u64 v[220:221], s[56:57], 0, v[128:129]
	s_add_i32 m0, s55, 0x2000
	s_nop 0
	global_load_lds_dwordx4 v[220:221], off
	v_lshl_add_u64 v[220:221], s[28:29], 0, v[134:135]
	s_mov_b32 m0, s23
	s_nop 0
	global_load_lds_dwordx4 v[220:221], off
	s_mov_b32 m0, s39
	s_nop 0
	global_load_lds_dwordx4 v[222:223], off
	s_waitcnt vmcnt(8)
	s_waitcnt lgkmcnt(0)
	s_setprio 1
	s_barrier
	v_mfma_f32_16x16x32_bf16 v[60:63], v[152:155], v[184:187], 0
	v_mfma_f32_16x16x32_bf16 v[56:59], v[160:163], v[184:187], 0
	v_mfma_f32_16x16x32_bf16 v[44:47], v[152:155], v[192:195], 0
	v_mfma_f32_16x16x32_bf16 v[40:43], v[160:163], v[192:195], 0
	v_mfma_f32_16x16x32_bf16 v[28:31], v[152:155], v[200:203], 0
	v_mfma_f32_16x16x32_bf16 v[24:27], v[160:163], v[200:203], 0
	v_mfma_f32_16x16x32_bf16 v[12:15], v[152:155], v[208:211], 0
	v_mfma_f32_16x16x32_bf16 v[8:11], v[160:163], v[208:211], 0
	v_mfma_f32_16x16x32_bf16 v[60:63], v[156:159], v[188:191], v[60:63]
	v_mfma_f32_16x16x32_bf16 v[56:59], v[164:167], v[188:191], v[56:59]
	v_mfma_f32_16x16x32_bf16 v[44:47], v[156:159], v[196:199], v[44:47]
	v_mfma_f32_16x16x32_bf16 v[40:43], v[164:167], v[196:199], v[40:43]
	v_mfma_f32_16x16x32_bf16 v[28:31], v[156:159], v[204:207], v[28:31]
	v_mfma_f32_16x16x32_bf16 v[24:27], v[164:167], v[204:207], v[24:27]
	v_mfma_f32_16x16x32_bf16 v[12:15], v[156:159], v[212:215], v[12:15]
	v_mfma_f32_16x16x32_bf16 v[8:11], v[164:167], v[212:215], v[8:11]
	s_setprio 0
	s_setprio 1
	v_mfma_f32_16x16x32_bf16 v[52:55], v[168:171], v[184:187], 0
	v_mfma_f32_16x16x32_bf16 v[48:51], v[176:179], v[184:187], 0
	v_mfma_f32_16x16x32_bf16 v[36:39], v[168:171], v[192:195], 0
	v_mfma_f32_16x16x32_bf16 v[32:35], v[176:179], v[192:195], 0
	v_mfma_f32_16x16x32_bf16 v[20:23], v[168:171], v[200:203], 0
	v_mfma_f32_16x16x32_bf16 v[16:19], v[176:179], v[200:203], 0
	v_mfma_f32_16x16x32_bf16 v[4:7], v[168:171], v[208:211], 0
	v_mfma_f32_16x16x32_bf16 v[0:3], v[176:179], v[208:211], 0
	v_mfma_f32_16x16x32_bf16 v[52:55], v[172:175], v[188:191], v[52:55]
	v_mfma_f32_16x16x32_bf16 v[48:51], v[180:183], v[188:191], v[48:51]
	v_mfma_f32_16x16x32_bf16 v[36:39], v[172:175], v[196:199], v[36:39]
	v_mfma_f32_16x16x32_bf16 v[32:35], v[180:183], v[196:199], v[32:35]
	v_mfma_f32_16x16x32_bf16 v[20:23], v[172:175], v[204:207], v[20:23]
	v_mfma_f32_16x16x32_bf16 v[16:19], v[180:183], v[204:207], v[16:19]
	v_mfma_f32_16x16x32_bf16 v[4:7], v[172:175], v[212:215], v[4:7]
	v_mfma_f32_16x16x32_bf16 v[0:3], v[180:183], v[212:215], v[0:3]
	s_barrier
; #define PG8_STAGE(bufoff, gbase, voff) do { _Pragma("unroll") for (int _i = 0; _i < 2; ++_i) \
;         __builtin_amdgcn_global_load_lds((const unsigned*)((const char*)(gbase) + (voff)[_i]), (PG8_LAS unsigned*)(lds + (bufoff) + ldsw + _i * 8192), 16, 0, 0); } while (0)
; #define PG8_LDA(dst, b, h) do { _Pragma("unroll") for (int m = 0; m < 4; ++m) _Pragma("unroll") for (int k = 0; k < 2; ++k) dst[m][k] = *(const PG8_LAS bf16x8*)(lds + PG8_SA(b, h) + aoff + m * 2048 + k * 1024); } while (0)
; #define PG8_LDB(dst, b, h) do { _Pragma("unroll") for (int n = 0; n < 2; ++n) _Pragma("unroll") for (int k = 0; k < 2; ++k) dst[n][k] = *(const PG8_LAS bf16x8*)(lds + PG8_SB(b, h) + boff + n * 2048 + k * 1024); } while (0)
; #define PG8_MMA(ai, bj, At, Bt) do { __builtin_amdgcn_s_setprio(1); _Pragma("unroll") for (int m = 0; m < 4; ++m) _Pragma("unroll") for (int n = 0; n < 2; ++n) _Pragma("unroll") for (int k = 0; k < 2; ++k) \
;         acc[ai][bj][m][n] = __builtin_amdgcn_mfma_f32_16x16x32_bf16(Bt[n][k], At[m][k], acc[ai][bj][m][n], 0, 0, 0); __builtin_amdgcn_s_setprio(0); } while (0)
; #define PG8_WAIT_V(n) asm volatile("s_waitcnt vmcnt(" #n ")" ::: "memory")
; template <class Epi, class Sched, bool ALIGN_EPI = false, bool SP2 = false>
; __device__ __forceinline__ void gemm_phase(PG8_LAS unsigned char* lds, const Gemm g, const Sched& S, const Epi& E) {
;     ...
;             PG8_LDB(B0, 0, 0); PG8_LDB(B1, 0, 1); PG8_SCHED; PG8_LDA(At, 0, 0); PG8_STAGE(PG8_SA(1, 1), a1 + hstep, voffA);
;             PG8_WAIT_V(8); PG8_WAIT_L(0); PG8_BAR; PG8_MMA(0, 0, At, B0); PG8_MMA(0, 1, At, B1); PG8_BAR; PG8_SCHED;
;             PG8_LDA(At, 0, 1); PG8_STAGE(PG8_SB(0, 0), b2, voffB); PG8_STAGE(PG8_SB(0, 1), b2 + hstep, voffB); PG8_STAGE(PG8_SA(0, 0), a2, voffA);
;             PG8_WAIT_V(8); PG8_WAIT_L(0); PG8_BAR; PG8_MMA(1, 0, At, B0); PG8_MMA(1, 1, At, B1); PG8_BAR; PG8_SCHED;
;             PG8_LDB(B0, 1, 0); PG8_LDB(B1, 1, 1); PG8_SCHED; PG8_LDA(At, 1, 0); PG8_STAGE(PG8_SA(0, 1), a2 + hstep, voffA);
;             PG8_WAIT_V(8); PG8_WAIT_L(0); PG8_BAR; PG8_MMA(0, 0, At, B0); PG8_MMA(0, 1, At, B1); PG8_BAR; PG8_SCHED;
;             PG8_LDA(At, 1, 1); PG8_STAGE(PG8_SB(1, 0), b3, voffB); PG8_STAGE(PG8_SB(1, 1), b3 + hstep, voffB); PG8_STAGE(PG8_SA(1, 0), a3, voffA);
;             PG8_WAIT_V(8); PG8_WAIT_L(0); PG8_BAR; PG8_MMA(1, 0, At, B0); PG8_MMA(1, 1, At, B1); PG8_BAR; PG8_SCHED;
	s_setprio 0
	s_add_i32 s55, 0, 0x18000
	v_add_u32_e32 v151, s55, v145
	s_add_i32 s56, 0, 0x1c000
	ds_read_b128 v[152:155], v151
	ds_read_b128 v[156:159], v151 offset:1024
	ds_read_b128 v[160:163], v151 offset:2048
	ds_read_b128 v[164:167], v151 offset:3072
	v_add_u32_e32 v151, s56, v145
	ds_read_b128 v[168:171], v151
	ds_read_b128 v[172:175], v151 offset:1024
	ds_read_b128 v[176:179], v151 offset:2048
	ds_read_b128 v[180:183], v151 offset:3072
	s_add_u32 s28, s28, 0x40000
	s_addc_u32 s29, s29, 0
	s_mov_b32 m0, s40
	v_lshl_add_u64 v[224:225], s[28:29], 0, v[134:135]
	ds_read_b128 v[184:187], v150 offset:32768
	ds_read_b128 v[188:191], v150 offset:33792
	ds_read_b128 v[192:195], v150 offset:34816
	ds_read_b128 v[196:199], v150 offset:35840
	ds_read_b128 v[200:203], v150 offset:36864
	ds_read_b128 v[204:207], v150 offset:37888
	ds_read_b128 v[208:211], v150 offset:38912
	ds_read_b128 v[212:215], v150 offset:39936
	global_load_lds_dwordx4 v[224:225], off
	v_lshl_add_u64 v[224:225], s[28:29], 0, v[130:131]
	s_mov_b32 m0, s41
	s_nop 0
	global_load_lds_dwordx4 v[224:225], off
	s_waitcnt vmcnt(8)
	s_waitcnt lgkmcnt(0)
	s_setprio 1
	s_barrier
	v_mfma_f32_16x16x32_bf16 v[124:127], v[152:155], v[184:187], v[124:127]
	v_mfma_f32_16x16x32_bf16 v[120:123], v[160:163], v[184:187], v[120:123]
	v_mfma_f32_16x16x32_bf16 v[108:111], v[152:155], v[192:195], v[108:111]
	v_mfma_f32_16x16x32_bf16 v[104:107], v[160:163], v[192:195], v[104:107]
	v_mfma_f32_16x16x32_bf16 v[92:95], v[152:155], v[200:203], v[92:95]
	v_mfma_f32_16x16x32_bf16 v[88:91], v[160:163], v[200:203], v[88:91]
	v_mfma_f32_16x16x32_bf16 v[76:79], v[152:155], v[208:211], v[76:79]
	v_mfma_f32_16x16x32_bf16 v[72:75], v[160:163], v[208:211], v[72:75]
	v_mfma_f32_16x16x32_bf16 v[124:127], v[156:159], v[188:191], v[124:127]
	v_mfma_f32_16x16x32_bf16 v[120:123], v[164:167], v[188:191], v[120:123]
	v_mfma_f32_16x16x32_bf16 v[108:111], v[156:159], v[196:199], v[108:111]
	v_mfma_f32_16x16x32_bf16 v[104:107], v[164:167], v[196:199], v[104:107]
	v_mfma_f32_16x16x32_bf16 v[92:95], v[156:159], v[204:207], v[92:95]
	v_mfma_f32_16x16x32_bf16 v[88:91], v[164:167], v[204:207], v[88:91]
	v_mfma_f32_16x16x32_bf16 v[76:79], v[156:159], v[212:215], v[76:79]
	v_mfma_f32_16x16x32_bf16 v[72:75], v[164:167], v[212:215], v[72:75]
	s_setprio 0
	s_setprio 1
	v_mfma_f32_16x16x32_bf16 v[116:119], v[168:171], v[184:187], v[116:119]
	v_mfma_f32_16x16x32_bf16 v[112:115], v[176:179], v[184:187], v[112:115]
	v_mfma_f32_16x16x32_bf16 v[100:103], v[168:171], v[192:195], v[100:103]
	v_mfma_f32_16x16x32_bf16 v[96:99], v[176:179], v[192:195], v[96:99]
	v_mfma_f32_16x16x32_bf16 v[84:87], v[168:171], v[200:203], v[84:87]
	v_mfma_f32_16x16x32_bf16 v[80:83], v[176:179], v[200:203], v[80:83]
	v_mfma_f32_16x16x32_bf16 v[68:71], v[168:171], v[208:211], v[68:71]
	v_mfma_f32_16x16x32_bf16 v[64:67], v[176:179], v[208:211], v[64:67]
	v_mfma_f32_16x16x32_bf16 v[116:119], v[172:175], v[188:191], v[116:119]
	v_mfma_f32_16x16x32_bf16 v[112:115], v[180:183], v[188:191], v[112:115]
	v_mfma_f32_16x16x32_bf16 v[100:103], v[172:175], v[196:199], v[100:103]
	v_mfma_f32_16x16x32_bf16 v[96:99], v[180:183], v[196:199], v[96:99]
	v_mfma_f32_16x16x32_bf16 v[84:87], v[172:175], v[204:207], v[84:87]
	v_mfma_f32_16x16x32_bf16 v[80:83], v[180:183], v[204:207], v[80:83]
	v_mfma_f32_16x16x32_bf16 v[68:71], v[172:175], v[212:215], v[68:71]
	v_mfma_f32_16x16x32_bf16 v[64:67], v[180:183], v[212:215], v[64:67]
	s_barrier
; #define PG8_STAGE(bufoff, gbase, voff) do { _Pragma("unroll") for (int _i = 0; _i < 2; ++_i) \
;         __builtin_amdgcn_global_load_lds((const unsigned*)((const char*)(gbase) + (voff)[_i]), (PG8_LAS unsigned*)(lds + (bufoff) + ldsw + _i * 8192), 16, 0, 0); } while (0)
; #define PG8_LDA(dst, b, h) do { _Pragma("unroll") for (int m = 0; m < 4; ++m) _Pragma("unroll") for (int k = 0; k < 2; ++k) dst[m][k] = *(const PG8_LAS bf16x8*)(lds + PG8_SA(b, h) + aoff + m * 2048 + k * 1024); } while (0)
; #define PG8_LDB(dst, b, h) do { _Pragma("unroll") for (int n = 0; n < 2; ++n) _Pragma("unroll") for (int k = 0; k < 2; ++k) dst[n][k] = *(const PG8_LAS bf16x8*)(lds + PG8_SB(b, h) + boff + n * 2048 + k * 1024); } while (0)
; #define PG8_MMA(ai, bj, At, Bt) do { __builtin_amdgcn_s_setprio(1); _Pragma("unroll") for (int m = 0; m < 4; ++m) _Pragma("unroll") for (int n = 0; n < 2; ++n) _Pragma("unroll") for (int k = 0; k < 2; ++k) \
;         acc[ai][bj][m][n] = __builtin_amdgcn_mfma_f32_16x16x32_bf16(Bt[n][k], At[m][k], acc[ai][bj][m][n], 0, 0, 0); __builtin_amdgcn_s_setprio(0); } while (0)
; #define PG8_WAIT_V(n) asm volatile("s_waitcnt vmcnt(" #n ")" ::: "memory")
; template <class Epi, class Sched, bool ALIGN_EPI = false, bool SP2 = false>
; __device__ __forceinline__ void gemm_phase(PG8_LAS unsigned char* lds, const Gemm g, const Sched& S, const Epi& E) {
;     ...
;             PG8_LDB(B0, 0, 0); PG8_LDB(B1, 0, 1); PG8_SCHED; PG8_LDA(At, 0, 0); PG8_STAGE(PG8_SA(1, 1), a1 + hstep, voffA);
;             PG8_WAIT_V(8); PG8_WAIT_L(0); PG8_BAR; PG8_MMA(0, 0, At, B0); PG8_MMA(0, 1, At, B1); PG8_BAR; PG8_SCHED;
;             PG8_LDA(At, 0, 1); PG8_STAGE(PG8_SB(0, 0), b2, voffB); PG8_STAGE(PG8_SB(0, 1), b2 + hstep, voffB); PG8_STAGE(PG8_SA(0, 0), a2, voffA);
;             PG8_WAIT_V(8); PG8_WAIT_L(0); PG8_BAR; PG8_MMA(1, 0, At, B0); PG8_MMA(1, 1, At, B1); PG8_BAR; PG8_SCHED;
;             PG8_LDB(B0, 1, 0); PG8_LDB(B1, 1, 1); PG8_SCHED; PG8_LDA(At, 1, 0); PG8_STAGE(PG8_SA(0, 1), a2 + hstep, voffA);
;             PG8_WAIT_V(8); PG8_WAIT_L(0); PG8_BAR; PG8_MMA(0, 0, At, B0); PG8_MMA(0, 1, At, B1); PG8_BAR; PG8_SCHED;
;             PG8_LDA(At, 1, 1); PG8_STAGE(PG8_SB(1, 0), b3, voffB); PG8_STAGE(PG8_SB(1, 1), b3 + hstep, voffB); PG8_STAGE(PG8_SA(1, 0), a3, voffA);
;             PG8_WAIT_V(8); PG8_WAIT_L(0); PG8_BAR; PG8_MMA(1, 0, At, B0); PG8_MMA(1, 1, At, B1); PG8_BAR; PG8_SCHED;
	s_setprio 0
	s_add_i32 s28, s55, s33
	v_lshl_add_u64 v[216:217], v[216:217], 0, s[8:9]
	s_mov_b32 m0, s28
	ds_read_b128 v[184:187], v150 offset:49152
	ds_read_b128 v[188:191], v150 offset:50176
	ds_read_b128 v[192:195], v150 offset:51200
	ds_read_b128 v[196:199], v150 offset:52224
	ds_read_b128 v[200:203], v150 offset:53248
	ds_read_b128 v[204:207], v150 offset:54272
	ds_read_b128 v[208:211], v150 offset:55296
	ds_read_b128 v[212:215], v150 offset:56320
	global_load_lds_dwordx4 v[216:217], off
	s_add_i32 m0, s28, 0x2000
	s_add_u32 s26, s26, 0x40080
	v_lshl_add_u64 v[216:217], v[218:219], 0, s[8:9]
	s_addc_u32 s27, s27, 0
	s_add_i32 s28, s56, s33
	global_load_lds_dwordx4 v[216:217], off
	v_lshl_add_u64 v[216:217], s[26:27], 0, v[132:133]
	s_mov_b32 m0, s28
	s_nop 0
	global_load_lds_dwordx4 v[216:217], off
	v_lshl_add_u64 v[216:217], s[26:27], 0, v[128:129]
	s_add_i32 m0, s28, 0x2000
	s_nop 0
	global_load_lds_dwordx4 v[216:217], off
	v_lshl_add_u64 v[216:217], v[220:221], 0, s[8:9]
	s_mov_b32 m0, s42
	s_nop 0
	global_load_lds_dwordx4 v[216:217], off
	v_lshl_add_u64 v[216:217], v[222:223], 0, s[8:9]
	s_mov_b32 m0, s43
	s_nop 0
	global_load_lds_dwordx4 v[216:217], off
	s_waitcnt vmcnt(8)
	s_waitcnt lgkmcnt(0)
	s_setprio 1
	s_barrier
	v_mfma_f32_16x16x32_bf16 v[60:63], v[152:155], v[184:187], v[60:63]
	v_mfma_f32_16x16x32_bf16 v[56:59], v[160:163], v[184:187], v[56:59]
	v_mfma_f32_16x16x32_bf16 v[44:47], v[152:155], v[192:195], v[44:47]
	v_mfma_f32_16x16x32_bf16 v[40:43], v[160:163], v[192:195], v[40:43]
	v_mfma_f32_16x16x32_bf16 v[28:31], v[152:155], v[200:203], v[28:31]
	v_mfma_f32_16x16x32_bf16 v[24:27], v[160:163], v[200:203], v[24:27]
	v_mfma_f32_16x16x32_bf16 v[12:15], v[152:155], v[208:211], v[12:15]
	v_mfma_f32_16x16x32_bf16 v[8:11], v[160:163], v[208:211], v[8:11]
	v_mfma_f32_16x16x32_bf16 v[60:63], v[156:159], v[188:191], v[60:63]
	v_mfma_f32_16x16x32_bf16 v[56:59], v[164:167], v[188:191], v[56:59]
	v_mfma_f32_16x16x32_bf16 v[44:47], v[156:159], v[196:199], v[44:47]
	v_mfma_f32_16x16x32_bf16 v[40:43], v[164:167], v[196:199], v[40:43]
	v_mfma_f32_16x16x32_bf16 v[28:31], v[156:159], v[204:207], v[28:31]
	v_mfma_f32_16x16x32_bf16 v[24:27], v[164:167], v[204:207], v[24:27]
	v_mfma_f32_16x16x32_bf16 v[12:15], v[156:159], v[212:215], v[12:15]
	v_mfma_f32_16x16x32_bf16 v[8:11], v[164:167], v[212:215], v[8:11]
	s_setprio 0
	s_setprio 1
	v_mfma_f32_16x16x32_bf16 v[52:55], v[168:171], v[184:187], v[52:55]
	v_mfma_f32_16x16x32_bf16 v[48:51], v[176:179], v[184:187], v[48:51]
	v_mfma_f32_16x16x32_bf16 v[36:39], v[168:171], v[192:195], v[36:39]
	v_mfma_f32_16x16x32_bf16 v[32:35], v[176:179], v[192:195], v[32:35]
	v_mfma_f32_16x16x32_bf16 v[20:23], v[168:171], v[200:203], v[20:23]
	v_mfma_f32_16x16x32_bf16 v[16:19], v[176:179], v[200:203], v[16:19]
	v_mfma_f32_16x16x32_bf16 v[4:7], v[168:171], v[208:211], v[4:7]
	v_mfma_f32_16x16x32_bf16 v[0:3], v[176:179], v[208:211], v[0:3]
	v_mfma_f32_16x16x32_bf16 v[52:55], v[172:175], v[188:191], v[52:55]
	v_mfma_f32_16x16x32_bf16 v[48:51], v[180:183], v[188:191], v[48:51]
	v_mfma_f32_16x16x32_bf16 v[36:39], v[172:175], v[196:199], v[36:39]
	v_mfma_f32_16x16x32_bf16 v[32:35], v[180:183], v[196:199], v[32:35]
	v_mfma_f32_16x16x32_bf16 v[20:23], v[172:175], v[204:207], v[20:23]
	v_mfma_f32_16x16x32_bf16 v[16:19], v[180:183], v[204:207], v[16:19]
	v_mfma_f32_16x16x32_bf16 v[4:7], v[172:175], v[212:215], v[4:7]
	v_mfma_f32_16x16x32_bf16 v[0:3], v[180:183], v[212:215], v[0:3]
	s_barrier
	s_setprio 0
	s_add_i32 s54, s54, 2
	s_add_u32 s24, s24, 0x100
	s_addc_u32 s25, s25, 0
	s_add_u32 s52, s52, 0x100
	s_addc_u32 s53, s53, 0
	s_cmp_gt_u32 s54, 13

; #define PG8_STAGE(bufoff, gbase, voff) do { _Pragma("unroll") for (int _i = 0; _i < 2; ++_i) \
;         __builtin_amdgcn_global_load_lds((const unsigned*)((const char*)(gbase) + (voff)[_i]), (PG8_LAS unsigned*)(lds + (bufoff) + ldsw + _i * 8192), 16, 0, 0); } while (0)
; #define PG8_LDA(dst, b, h) do { _Pragma("unroll") for (int m = 0; m < 4; ++m) _Pragma("unroll") for (int k = 0; k < 2; ++k) dst[m][k] = *(const PG8_LAS bf16x8*)(lds + PG8_SA(b, h) + aoff + m * 2048 + k * 1024); } while (0)
; #define PG8_LDB(dst, b, h) do { _Pragma("unroll") for (int n = 0; n < 2; ++n) _Pragma("unroll") for (int k = 0; k < 2; ++k) dst[n][k] = *(const PG8_LAS bf16x8*)(lds + PG8_SB(b, h) + boff + n * 2048 + k * 1024); } while (0)
; template <class Epi, class Sched, bool ALIGN_EPI = false, bool SP2 = false>
; __device__ __forceinline__ void gemm_phase(PG8_LAS unsigned char* lds, const Gemm g, const Sched& S, const Epi& E) {
;     ...
;         for (int t = 0; t < nt; t += 2) {
;             const bool last = (t == nt - 2);
;             const char* a1 = cA + (size_t)(t + 1) * kstep;
;             const char* a2 = last ? nA : cA + (size_t)(t + 2) * kstep; const char* b2 = last ? nB : cB + (size_t)(t + 2) * kstep;
;             const char* a3 = a2 + kstep; const char* b3 = b2 + kstep;
;             if (last && has_next) S.a_ready(nxt, ui + 1);
;             if constexpr (SP2) {
;             PG8_LDB(B0, 0, 0); PG8_LDB(B1, 0, 1); PG8_SCHED; PG8_LDA(At, 0, 0); PG8_STAGE(PG8_SA(1, 1), a1 + hstep, voffA);
;             PG8_WAIT_V(8); PG8_WAIT_L(0); PG8_BAR; PG8_MMA(0, 0, At, B0); PG8_MMA(0, 1, At, B1); PG8_BAR; PG8_SCHED;
;             PG8_LDA(At, 0, 1); PG8_STAGE(PG8_SB(0, 0), b2, voffB); PG8_STAGE(PG8_SB(0, 1), b2 + hstep, voffB); PG8_STAGE(PG8_SA(0, 0), a2, voffA);
;             PG8_WAIT_V(8); PG8_WAIT_L(0); PG8_BAR; PG8_MMA(1, 0, At, B0); PG8_MMA(1, 1, At, B1); PG8_BAR; PG8_SCHED;
;             PG8_LDB(B0, 1, 0); PG8_LDB(B1, 1, 1); PG8_SCHED; PG8_LDA(At, 1, 0); PG8_STAGE(PG8_SA(0, 1), a2 + hstep, voffA);
;             PG8_WAIT_V(8); PG8_WAIT_L(0); PG8_BAR; PG8_MMA(0, 0, At, B0); PG8_MMA(0, 1, At, B1); PG8_BAR; PG8_SCHED;
;             PG8_LDA(At, 1, 1); PG8_STAGE(PG8_SB(1, 0), b3, voffB); PG8_STAGE(PG8_SB(1, 1), b3 + hstep, voffB); PG8_STAGE(PG8_SA(1, 0), a3, voffA);
;             PG8_WAIT_V(8); PG8_WAIT_L(0); PG8_BAR; PG8_MMA(1, 0, At, B0); PG8_MMA(1, 1, At, B1); PG8_BAR; PG8_SCHED;
.LBB0_1129:
	s_add_u32 s24, s24, 0xb0080
	s_addc_u32 s25, s25, 0
	s_add_u32 s51, s26, 0x100
	s_addc_u32 s52, s27, 0
	s_mov_b32 s53, -2
	s_add_u32 s26, s24, 0xfff50080
	s_addc_u32 s27, s25, -1
	s_cmp_eq_u32 s53, 40
	s_cselect_b32 s29, s7, s27
	s_cselect_b32 s28, s6, s26
	s_cselect_b32 s27, s23, s52
	s_cselect_b32 s26, s22, s51
	v_lshl_add_u64 v[204:205], s[24:25], 0, v[200:201]
	s_add_i32 m0, s35, 0xc000
	global_load_lds_dwordx4 v[204:205], off
	v_lshl_add_u64 v[204:205], s[24:25], 0, v[202:203]
	s_add_i32 m0, s35, 0xe000
	s_nop 0
	global_load_lds_dwordx4 v[204:205], off
	s_waitcnt vmcnt(8)
	s_waitcnt lgkmcnt(0)
	s_setprio 1
	s_barrier
	v_mfma_f32_16x16x32_bf16 v[132:135], v[120:123], v[160:163], 0
	v_mfma_f32_16x16x32_bf16 v[124:127], v[136:139], v[160:163], 0
	v_mfma_f32_16x16x32_bf16 v[108:111], v[120:123], v[168:171], 0
	v_mfma_f32_16x16x32_bf16 v[104:107], v[136:139], v[168:171], 0
	v_mfma_f32_16x16x32_bf16 v[92:95], v[120:123], v[176:179], 0
	v_mfma_f32_16x16x32_bf16 v[88:91], v[136:139], v[176:179], 0
	v_mfma_f32_16x16x32_bf16 v[76:79], v[120:123], v[184:187], 0
	v_mfma_f32_16x16x32_bf16 v[72:75], v[136:139], v[184:187], 0
	v_mfma_f32_16x16x32_bf16 v[132:135], v[128:131], v[164:167], v[132:135]
	v_mfma_f32_16x16x32_bf16 v[124:127], v[140:143], v[164:167], v[124:127]
	v_mfma_f32_16x16x32_bf16 v[108:111], v[128:131], v[172:175], v[108:111]
	v_mfma_f32_16x16x32_bf16 v[104:107], v[140:143], v[172:175], v[104:107]
	v_mfma_f32_16x16x32_bf16 v[92:95], v[128:131], v[180:183], v[92:95]
	v_mfma_f32_16x16x32_bf16 v[88:91], v[140:143], v[180:183], v[88:91]
	v_mfma_f32_16x16x32_bf16 v[76:79], v[128:131], v[188:191], v[76:79]
	v_mfma_f32_16x16x32_bf16 v[72:75], v[140:143], v[188:191], v[72:75]
	s_setprio 0
	s_setprio 1
	v_mfma_f32_16x16x32_bf16 v[116:119], v[144:147], v[160:163], 0
	v_mfma_f32_16x16x32_bf16 v[112:115], v[152:155], v[160:163], 0
	v_mfma_f32_16x16x32_bf16 v[100:103], v[144:147], v[168:171], 0
	v_mfma_f32_16x16x32_bf16 v[96:99], v[152:155], v[168:171], 0
	v_mfma_f32_16x16x32_bf16 v[84:87], v[144:147], v[176:179], 0
	v_mfma_f32_16x16x32_bf16 v[80:83], v[152:155], v[176:179], 0
	v_mfma_f32_16x16x32_bf16 v[68:71], v[144:147], v[184:187], 0
	v_mfma_f32_16x16x32_bf16 v[64:67], v[152:155], v[184:187], 0
	v_mfma_f32_16x16x32_bf16 v[116:119], v[148:151], v[164:167], v[116:119]
	v_mfma_f32_16x16x32_bf16 v[112:115], v[156:159], v[164:167], v[112:115]
	v_mfma_f32_16x16x32_bf16 v[100:103], v[148:151], v[172:175], v[100:103]
	v_mfma_f32_16x16x32_bf16 v[96:99], v[156:159], v[172:175], v[96:99]
	v_mfma_f32_16x16x32_bf16 v[84:87], v[148:151], v[180:183], v[84:87]
	v_mfma_f32_16x16x32_bf16 v[80:83], v[156:159], v[180:183], v[80:83]
	v_mfma_f32_16x16x32_bf16 v[68:71], v[148:151], v[188:191], v[68:71]
	v_mfma_f32_16x16x32_bf16 v[64:67], v[156:159], v[188:191], v[64:67]
	s_barrier
	s_setprio 0
	s_add_i32 s54, s45, s34
	v_lshl_add_u64 v[204:205], s[26:27], 0, v[194:195]
	s_mov_b32 m0, s54
	ds_read_b128 v[160:163], v247 offset:16384
	ds_read_b128 v[164:167], v247 offset:17408
	ds_read_b128 v[168:171], v247 offset:18432
	ds_read_b128 v[172:175], v247 offset:19456
	ds_read_b128 v[176:179], v247 offset:20480
	ds_read_b128 v[180:183], v247 offset:21504
	ds_read_b128 v[184:187], v247 offset:22528
	ds_read_b128 v[188:191], v247 offset:23552
	global_load_lds_dwordx4 v[204:205], off
	s_add_i32 m0, s54, 0x2000
	s_add_u32 s54, s26, 0xb0000
	v_lshl_add_u64 v[206:207], s[26:27], 0, v[198:199]
	s_addc_u32 s55, s27, 0
	s_add_i32 s56, s46, s34
	global_load_lds_dwordx4 v[206:207], off
	v_lshl_add_u64 v[208:209], s[54:55], 0, v[194:195]
	s_mov_b32 m0, s56
	v_lshl_add_u64 v[210:211], s[28:29], 0, v[196:197]
	global_load_lds_dwordx4 v[208:209], off
	v_lshl_add_u64 v[208:209], s[54:55], 0, v[198:199]
	s_add_i32 m0, s56, 0x2000
	s_nop 0
	global_load_lds_dwordx4 v[208:209], off
	v_lshl_add_u64 v[208:209], s[28:29], 0, v[192:193]
	s_mov_b32 m0, s35
	s_nop 0
	global_load_lds_dwordx4 v[208:209], off
	s_mov_b32 m0, s36
	s_nop 0
	global_load_lds_dwordx4 v[210:211], off
	s_waitcnt vmcnt(8)
	s_waitcnt lgkmcnt(0)
	s_setprio 1
	s_barrier
	v_mfma_f32_16x16x32_bf16 v[60:63], v[120:123], v[160:163], 0
	v_mfma_f32_16x16x32_bf16 v[56:59], v[136:139], v[160:163], 0
	v_mfma_f32_16x16x32_bf16 v[44:47], v[120:123], v[168:171], 0
	v_mfma_f32_16x16x32_bf16 v[40:43], v[136:139], v[168:171], 0
	v_mfma_f32_16x16x32_bf16 v[28:31], v[120:123], v[176:179], 0
	v_mfma_f32_16x16x32_bf16 v[24:27], v[136:139], v[176:179], 0
	v_mfma_f32_16x16x32_bf16 v[12:15], v[120:123], v[184:187], 0
	v_mfma_f32_16x16x32_bf16 v[8:11], v[136:139], v[184:187], 0
	v_mfma_f32_16x16x32_bf16 v[60:63], v[128:131], v[164:167], v[60:63]
	v_mfma_f32_16x16x32_bf16 v[56:59], v[140:143], v[164:167], v[56:59]
	v_mfma_f32_16x16x32_bf16 v[44:47], v[128:131], v[172:175], v[44:47]
	v_mfma_f32_16x16x32_bf16 v[40:43], v[140:143], v[172:175], v[40:43]
	v_mfma_f32_16x16x32_bf16 v[28:31], v[128:131], v[180:183], v[28:31]
	v_mfma_f32_16x16x32_bf16 v[24:27], v[140:143], v[180:183], v[24:27]
	v_mfma_f32_16x16x32_bf16 v[12:15], v[128:131], v[188:191], v[12:15]
	v_mfma_f32_16x16x32_bf16 v[8:11], v[140:143], v[188:191], v[8:11]
	s_setprio 0
	s_setprio 1
	v_mfma_f32_16x16x32_bf16 v[52:55], v[144:147], v[160:163], 0
	v_mfma_f32_16x16x32_bf16 v[48:51], v[152:155], v[160:163], 0
	v_mfma_f32_16x16x32_bf16 v[36:39], v[144:147], v[168:171], 0
	v_mfma_f32_16x16x32_bf16 v[32:35], v[152:155], v[168:171], 0
	v_mfma_f32_16x16x32_bf16 v[20:23], v[144:147], v[176:179], 0
	v_mfma_f32_16x16x32_bf16 v[16:19], v[152:155], v[176:179], 0
	v_mfma_f32_16x16x32_bf16 v[4:7], v[144:147], v[184:187], 0
	v_mfma_f32_16x16x32_bf16 v[0:3], v[152:155], v[184:187], 0
	v_mfma_f32_16x16x32_bf16 v[52:55], v[148:151], v[164:167], v[52:55]
	v_mfma_f32_16x16x32_bf16 v[48:51], v[156:159], v[164:167], v[48:51]
	v_mfma_f32_16x16x32_bf16 v[36:39], v[148:151], v[172:175], v[36:39]
	v_mfma_f32_16x16x32_bf16 v[32:35], v[156:159], v[172:175], v[32:35]
	v_mfma_f32_16x16x32_bf16 v[20:23], v[148:151], v[180:183], v[20:23]
	v_mfma_f32_16x16x32_bf16 v[16:19], v[156:159], v[180:183], v[16:19]
	v_mfma_f32_16x16x32_bf16 v[4:7], v[148:151], v[188:191], v[4:7]
	v_mfma_f32_16x16x32_bf16 v[0:3], v[156:159], v[188:191], v[0:3]
	s_barrier
; #define PG8_STAGE(bufoff, gbase, voff) do { _Pragma("unroll") for (int _i = 0; _i < 2; ++_i) \
;         __builtin_amdgcn_global_load_lds((const unsigned*)((const char*)(gbase) + (voff)[_i]), (PG8_LAS unsigned*)(lds + (bufoff) + ldsw + _i * 8192), 16, 0, 0); } while (0)
; #define PG8_LDA(dst, b, h) do { _Pragma("unroll") for (int m = 0; m < 4; ++m) _Pragma("unroll") for (int k = 0; k < 2; ++k) dst[m][k] = *(const PG8_LAS bf16x8*)(lds + PG8_SA(b, h) + aoff + m * 2048 + k * 1024); } while (0)
; #define PG8_LDB(dst, b, h) do { _Pragma("unroll") for (int n = 0; n < 2; ++n) _Pragma("unroll") for (int k = 0; k < 2; ++k) dst[n][k] = *(const PG8_LAS bf16x8*)(lds + PG8_SB(b, h) + boff + n * 2048 + k * 1024); } while (0)
; #define PG8_MMA(ai, bj, At, Bt) do { __builtin_amdgcn_s_setprio(1); _Pragma("unroll") for (int m = 0; m < 4; ++m) _Pragma("unroll") for (int n = 0; n < 2; ++n) _Pragma("unroll") for (int k = 0; k < 2; ++k) \
;         acc[ai][bj][m][n] = __builtin_amdgcn_mfma_f32_16x16x32_bf16(Bt[n][k], At[m][k], acc[ai][bj][m][n], 0, 0, 0); __builtin_amdgcn_s_setprio(0); } while (0)
; #define PG8_WAIT_V(n) asm volatile("s_waitcnt vmcnt(" #n ")" ::: "memory")
; #define PG8_WAIT_L(n) asm volatile("s_waitcnt lgkmcnt(" #n ")" ::: "memory")
; #define PG8_BAR __builtin_amdgcn_s_barrier()
; #define PG8_SCHED __builtin_amdgcn_sched_barrier(0)
; template <class Epi, class Sched, bool ALIGN_EPI = false, bool SP2 = false>
; __device__ __forceinline__ void gemm_phase(PG8_LAS unsigned char* lds, const Gemm g, const Sched& S, const Epi& E) {
;     ...
;             PG8_LDB(B0, 1, 0); PG8_LDB(B1, 1, 1); PG8_SCHED; PG8_LDA(At, 1, 0); PG8_STAGE(PG8_SA(0, 1), a2 + hstep, voffA);
;             PG8_WAIT_V(8); PG8_WAIT_L(0); PG8_BAR; PG8_MMA(0, 0, At, B0); PG8_MMA(0, 1, At, B1); PG8_BAR; PG8_SCHED;
	s_setprio 0
	s_add_i32 s54, 0, 0x18000
	s_add_i32 s55, 0, 0x1c000
	v_add_u32_e32 v140, s54, v243
	v_add_u32_e32 v156, s55, v243
	ds_read_b128 v[120:123], v140
	ds_read_b128 v[128:131], v140 offset:1024
	ds_read_b128 v[136:139], v140 offset:2048
	ds_read_b128 v[140:143], v140 offset:3072
	ds_read_b128 v[144:147], v156
	ds_read_b128 v[148:151], v156 offset:1024
	ds_read_b128 v[152:155], v156 offset:2048
	ds_read_b128 v[156:159], v156 offset:3072
	s_add_u32 s28, s28, 0xb0000
	s_addc_u32 s29, s29, 0
	s_mov_b32 m0, s37
	v_lshl_add_u64 v[212:213], s[28:29], 0, v[192:193]
	ds_read_b128 v[160:163], v247 offset:32768
	ds_read_b128 v[164:167], v247 offset:33792
	ds_read_b128 v[168:171], v247 offset:34816
	ds_read_b128 v[172:175], v247 offset:35840
	ds_read_b128 v[176:179], v247 offset:36864
	ds_read_b128 v[180:183], v247 offset:37888
	ds_read_b128 v[184:187], v247 offset:38912
	ds_read_b128 v[188:191], v247 offset:39936
	global_load_lds_dwordx4 v[212:213], off
	v_lshl_add_u64 v[212:213], s[28:29], 0, v[196:197]
	s_mov_b32 m0, s38
	s_nop 0
	global_load_lds_dwordx4 v[212:213], off
	s_waitcnt vmcnt(8)
	s_waitcnt lgkmcnt(0)
	s_setprio 1
	s_barrier
	v_mfma_f32_16x16x32_bf16 v[132:135], v[120:123], v[160:163], v[132:135]
	v_mfma_f32_16x16x32_bf16 v[124:127], v[136:139], v[160:163], v[124:127]
	v_mfma_f32_16x16x32_bf16 v[108:111], v[120:123], v[168:171], v[108:111]
	v_mfma_f32_16x16x32_bf16 v[104:107], v[136:139], v[168:171], v[104:107]
	v_mfma_f32_16x16x32_bf16 v[92:95], v[120:123], v[176:179], v[92:95]
	v_mfma_f32_16x16x32_bf16 v[88:91], v[136:139], v[176:179], v[88:91]
	v_mfma_f32_16x16x32_bf16 v[76:79], v[120:123], v[184:187], v[76:79]
	v_mfma_f32_16x16x32_bf16 v[72:75], v[136:139], v[184:187], v[72:75]
	v_mfma_f32_16x16x32_bf16 v[132:135], v[128:131], v[164:167], v[132:135]
	v_mfma_f32_16x16x32_bf16 v[124:127], v[140:143], v[164:167], v[124:127]
	v_mfma_f32_16x16x32_bf16 v[108:111], v[128:131], v[172:175], v[108:111]
	v_mfma_f32_16x16x32_bf16 v[104:107], v[140:143], v[172:175], v[104:107]
	v_mfma_f32_16x16x32_bf16 v[92:95], v[128:131], v[180:183], v[92:95]
	v_mfma_f32_16x16x32_bf16 v[88:91], v[140:143], v[180:183], v[88:91]
	v_mfma_f32_16x16x32_bf16 v[76:79], v[128:131], v[188:191], v[76:79]
	v_mfma_f32_16x16x32_bf16 v[72:75], v[140:143], v[188:191], v[72:75]
	s_setprio 0
	s_setprio 1
	v_mfma_f32_16x16x32_bf16 v[116:119], v[144:147], v[160:163], v[116:119]
	v_mfma_f32_16x16x32_bf16 v[112:115], v[152:155], v[160:163], v[112:115]
	v_mfma_f32_16x16x32_bf16 v[100:103], v[144:147], v[168:171], v[100:103]
	v_mfma_f32_16x16x32_bf16 v[96:99], v[152:155], v[168:171], v[96:99]
	v_mfma_f32_16x16x32_bf16 v[84:87], v[144:147], v[176:179], v[84:87]
	v_mfma_f32_16x16x32_bf16 v[80:83], v[152:155], v[176:179], v[80:83]
	v_mfma_f32_16x16x32_bf16 v[68:71], v[144:147], v[184:187], v[68:71]
	v_mfma_f32_16x16x32_bf16 v[64:67], v[152:155], v[184:187], v[64:67]
	v_mfma_f32_16x16x32_bf16 v[116:119], v[148:151], v[164:167], v[116:119]
	v_mfma_f32_16x16x32_bf16 v[112:115], v[156:159], v[164:167], v[112:115]
	v_mfma_f32_16x16x32_bf16 v[100:103], v[148:151], v[172:175], v[100:103]
	v_mfma_f32_16x16x32_bf16 v[96:99], v[156:159], v[172:175], v[96:99]
	v_mfma_f32_16x16x32_bf16 v[84:87], v[148:151], v[180:183], v[84:87]
	v_mfma_f32_16x16x32_bf16 v[80:83], v[156:159], v[180:183], v[80:83]
	v_mfma_f32_16x16x32_bf16 v[68:71], v[148:151], v[188:191], v[68:71]
	v_mfma_f32_16x16x32_bf16 v[64:67], v[156:159], v[188:191], v[64:67]
	s_barrier
; #define PG8_STAGE(bufoff, gbase, voff) do { _Pragma("unroll") for (int _i = 0; _i < 2; ++_i) \
;         __builtin_amdgcn_global_load_lds((const unsigned*)((const char*)(gbase) + (voff)[_i]), (PG8_LAS unsigned*)(lds + (bufoff) + ldsw + _i * 8192), 16, 0, 0); } while (0)
; #define PG8_LDA(dst, b, h) do { _Pragma("unroll") for (int m = 0; m < 4; ++m) _Pragma("unroll") for (int k = 0; k < 2; ++k) dst[m][k] = *(const PG8_LAS bf16x8*)(lds + PG8_SA(b, h) + aoff + m * 2048 + k * 1024); } while (0)
; #define PG8_LDB(dst, b, h) do { _Pragma("unroll") for (int n = 0; n < 2; ++n) _Pragma("unroll") for (int k = 0; k < 2; ++k) dst[n][k] = *(const PG8_LAS bf16x8*)(lds + PG8_SB(b, h) + boff + n * 2048 + k * 1024); } while (0)
; #define PG8_MMA(ai, bj, At, Bt) do { __builtin_amdgcn_s_setprio(1); _Pragma("unroll") for (int m = 0; m < 4; ++m) _Pragma("unroll") for (int n = 0; n < 2; ++n) _Pragma("unroll") for (int k = 0; k < 2; ++k) \
;         acc[ai][bj][m][n] = __builtin_amdgcn_mfma_f32_16x16x32_bf16(Bt[n][k], At[m][k], acc[ai][bj][m][n], 0, 0, 0); __builtin_amdgcn_s_setprio(0); } while (0)
; #define PG8_WAIT_V(n) asm volatile("s_waitcnt vmcnt(" #n ")" ::: "memory")
; #define PG8_WAIT_L(n) asm volatile("s_waitcnt lgkmcnt(" #n ")" ::: "memory")
; #define PG8_BAR __builtin_amdgcn_s_barrier()
; #define PG8_SCHED __builtin_amdgcn_sched_barrier(0)
; template <class Epi, class Sched, bool ALIGN_EPI = false, bool SP2 = false>
; __device__ __forceinline__ void gemm_phase(PG8_LAS unsigned char* lds, const Gemm g, const Sched& S, const Epi& E) {
;     ...
;             PG8_LDB(B0, 1, 0); PG8_LDB(B1, 1, 1); PG8_SCHED; PG8_LDA(At, 1, 0); PG8_STAGE(PG8_SA(0, 1), a2 + hstep, voffA);
;             PG8_WAIT_V(8); PG8_WAIT_L(0); PG8_BAR; PG8_MMA(0, 0, At, B0); PG8_MMA(0, 1, At, B1); PG8_BAR; PG8_SCHED;
;             PG8_LDA(At, 1, 1); PG8_STAGE(PG8_SB(1, 0), b3, voffB); PG8_STAGE(PG8_SB(1, 1), b3 + hstep, voffB); PG8_STAGE(PG8_SA(1, 0), a3, voffA);
;             PG8_WAIT_V(8); PG8_WAIT_L(0); PG8_BAR; PG8_MMA(1, 0, At, B0); PG8_MMA(1, 1, At, B1); PG8_BAR; PG8_SCHED;
	s_setprio 0
	s_add_i32 s28, s54, s34
	v_lshl_add_u64 v[204:205], v[204:205], 0, s[18:19]
	s_mov_b32 m0, s28
	ds_read_b128 v[160:163], v247 offset:49152
	ds_read_b128 v[164:167], v247 offset:50176
	ds_read_b128 v[168:171], v247 offset:51200
	ds_read_b128 v[172:175], v247 offset:52224
	ds_read_b128 v[176:179], v247 offset:53248
	ds_read_b128 v[180:183], v247 offset:54272
	ds_read_b128 v[184:187], v247 offset:55296
	ds_read_b128 v[188:191], v247 offset:56320
	global_load_lds_dwordx4 v[204:205], off
	s_add_i32 m0, s28, 0x2000
	s_add_u32 s26, s26, 0xb0080
	v_lshl_add_u64 v[204:205], v[206:207], 0, s[18:19]
	s_addc_u32 s27, s27, 0
	s_add_i32 s28, s55, s34
	global_load_lds_dwordx4 v[204:205], off
	v_lshl_add_u64 v[204:205], s[26:27], 0, v[194:195]
	s_mov_b32 m0, s28
	s_nop 0
	global_load_lds_dwordx4 v[204:205], off
	v_lshl_add_u64 v[204:205], s[26:27], 0, v[198:199]
	s_add_i32 m0, s28, 0x2000
	s_nop 0
	global_load_lds_dwordx4 v[204:205], off
	v_lshl_add_u64 v[204:205], v[208:209], 0, s[18:19]
	s_mov_b32 m0, s40
	s_nop 0
	global_load_lds_dwordx4 v[204:205], off
	v_lshl_add_u64 v[204:205], v[210:211], 0, s[18:19]
	s_mov_b32 m0, s41
	s_nop 0
	global_load_lds_dwordx4 v[204:205], off
	s_waitcnt vmcnt(8)
	s_waitcnt lgkmcnt(0)
	s_setprio 1
	s_barrier
	v_mfma_f32_16x16x32_bf16 v[60:63], v[120:123], v[160:163], v[60:63]
	v_mfma_f32_16x16x32_bf16 v[56:59], v[136:139], v[160:163], v[56:59]
	v_mfma_f32_16x16x32_bf16 v[44:47], v[120:123], v[168:171], v[44:47]
	v_mfma_f32_16x16x32_bf16 v[40:43], v[136:139], v[168:171], v[40:43]
	v_mfma_f32_16x16x32_bf16 v[28:31], v[120:123], v[176:179], v[28:31]
	v_mfma_f32_16x16x32_bf16 v[24:27], v[136:139], v[176:179], v[24:27]
	v_mfma_f32_16x16x32_bf16 v[12:15], v[120:123], v[184:187], v[12:15]
	v_mfma_f32_16x16x32_bf16 v[8:11], v[136:139], v[184:187], v[8:11]
	v_mfma_f32_16x16x32_bf16 v[60:63], v[128:131], v[164:167], v[60:63]
	v_mfma_f32_16x16x32_bf16 v[56:59], v[140:143], v[164:167], v[56:59]
	v_mfma_f32_16x16x32_bf16 v[44:47], v[128:131], v[172:175], v[44:47]
	v_mfma_f32_16x16x32_bf16 v[40:43], v[140:143], v[172:175], v[40:43]
	v_mfma_f32_16x16x32_bf16 v[28:31], v[128:131], v[180:183], v[28:31]
	v_mfma_f32_16x16x32_bf16 v[24:27], v[140:143], v[180:183], v[24:27]
	v_mfma_f32_16x16x32_bf16 v[12:15], v[128:131], v[188:191], v[12:15]
	v_mfma_f32_16x16x32_bf16 v[8:11], v[140:143], v[188:191], v[8:11]
	s_setprio 0
	s_setprio 1
	v_mfma_f32_16x16x32_bf16 v[52:55], v[144:147], v[160:163], v[52:55]
	v_mfma_f32_16x16x32_bf16 v[48:51], v[152:155], v[160:163], v[48:51]
	v_mfma_f32_16x16x32_bf16 v[36:39], v[144:147], v[168:171], v[36:39]
	v_mfma_f32_16x16x32_bf16 v[32:35], v[152:155], v[168:171], v[32:35]
	v_mfma_f32_16x16x32_bf16 v[20:23], v[144:147], v[176:179], v[20:23]
	v_mfma_f32_16x16x32_bf16 v[16:19], v[152:155], v[176:179], v[16:19]
	v_mfma_f32_16x16x32_bf16 v[4:7], v[144:147], v[184:187], v[4:7]
	v_mfma_f32_16x16x32_bf16 v[0:3], v[152:155], v[184:187], v[0:3]
	v_mfma_f32_16x16x32_bf16 v[52:55], v[148:151], v[164:167], v[52:55]
	v_mfma_f32_16x16x32_bf16 v[48:51], v[156:159], v[164:167], v[48:51]
	v_mfma_f32_16x16x32_bf16 v[36:39], v[148:151], v[172:175], v[36:39]
	v_mfma_f32_16x16x32_bf16 v[32:35], v[156:159], v[172:175], v[32:35]
	v_mfma_f32_16x16x32_bf16 v[20:23], v[148:151], v[180:183], v[20:23]
	v_mfma_f32_16x16x32_bf16 v[16:19], v[156:159], v[180:183], v[16:19]
	v_mfma_f32_16x16x32_bf16 v[4:7], v[148:151], v[188:191], v[4:7]
	v_mfma_f32_16x16x32_bf16 v[0:3], v[156:159], v[188:191], v[0:3]
	s_barrier
	s_setprio 0
	s_add_i32 s53, s53, 2
	s_add_u32 s24, s24, 0x100
	s_addc_u32 s25, s25, 0
	s_add_u32 s51, s51, 0x100
	s_addc_u32 s52, s52, 0
	s_cmp_gt_u32 s53, 41

; #define PG8_STAGE(bufoff, gbase, voff) do { _Pragma("unroll") for (int _i = 0; _i < 2; ++_i) \
;         __builtin_amdgcn_global_load_lds((const unsigned*)((const char*)(gbase) + (voff)[_i]), (PG8_LAS unsigned*)(lds + (bufoff) + ldsw + _i * 8192), 16, 0, 0); } while (0)
; #define PG8_LDA(dst, b, h) do { _Pragma("unroll") for (int m = 0; m < 4; ++m) _Pragma("unroll") for (int k = 0; k < 2; ++k) dst[m][k] = *(const PG8_LAS bf16x8*)(lds + PG8_SA(b, h) + aoff + m * 2048 + k * 1024); } while (0)
; #define PG8_LDB(dst, b, h) do { _Pragma("unroll") for (int n = 0; n < 2; ++n) _Pragma("unroll") for (int k = 0; k < 2; ++k) dst[n][k] = *(const PG8_LAS bf16x8*)(lds + PG8_SB(b, h) + boff + n * 2048 + k * 1024); } while (0)
; #define PG8_WAIT_V(n) asm volatile("s_waitcnt vmcnt(" #n ")" ::: "memory")
; #define PG8_WAIT_L(n) asm volatile("s_waitcnt lgkmcnt(" #n ")" ::: "memory")
; #define PG8_BAR __builtin_amdgcn_s_barrier()
; #define PG8_SCHED __builtin_amdgcn_sched_barrier(0)
; template <class Epi, class Sched, bool ALIGN_EPI = false, bool SP2 = false>
; __device__ __forceinline__ void gemm_phase(PG8_LAS unsigned char* lds, const Gemm g, const Sched& S, const Epi& E) {
;     ...
;         const char* nA = has_next ? (const char*)g.A + (size_t)nxt.pm * tstep : cA; const char* nB = has_next ? (const char*)g.Bt + (size_t)nxt.pn * tstep : cB;
;         for (int t = 0; t < nt; t += 2) {
;             const bool last = (t == nt - 2);
;             const char* a1 = cA + (size_t)(t + 1) * kstep;
;             const char* a2 = last ? nA : cA + (size_t)(t + 2) * kstep; const char* b2 = last ? nB : cB + (size_t)(t + 2) * kstep;
;             const char* a3 = a2 + kstep; const char* b3 = b2 + kstep;
;             if (last && has_next) S.a_ready(nxt, ui + 1);
;             if constexpr (SP2) {
;             PG8_LDB(B0, 0, 0); PG8_LDB(B1, 0, 1); PG8_SCHED; PG8_LDA(At, 0, 0); PG8_STAGE(PG8_SA(1, 1), a1 + hstep, voffA);
;             PG8_WAIT_V(8); PG8_WAIT_L(0); PG8_BAR; PG8_MMA(0, 0, At, B0); PG8_MMA(0, 1, At, B1); PG8_BAR; PG8_SCHED;
;             PG8_LDA(At, 0, 1); PG8_STAGE(PG8_SB(0, 0), b2, voffB); PG8_STAGE(PG8_SB(0, 1), b2 + hstep, voffB); PG8_STAGE(PG8_SA(0, 0), a2, voffA);
;             PG8_WAIT_V(8); PG8_WAIT_L(0); PG8_BAR; PG8_MMA(1, 0, At, B0); PG8_MMA(1, 1, At, B1); PG8_BAR; PG8_SCHED;
.LBB0_1218:
	s_ashr_i32 s17, s16, 31
	s_lshl_b64 s[18:19], s[16:17], 19
	s_add_u32 s18, s36, s18
	s_addc_u32 s19, s37, s19
	s_and_b64 s[20:21], s[0:1], exec
	s_cselect_b32 s17, s19, s25
	s_cselect_b32 s50, s18, s24
	s_ashr_i32 s15, s14, 31
	s_lshl_b64 s[20:21], s[14:15], 19
	s_add_u32 s20, s34, s20
	s_addc_u32 s21, s35, s21
	s_and_b64 s[28:29], s[0:1], exec
	s_cselect_b32 s15, s21, s27
	s_cselect_b32 s51, s20, s26
	s_add_u32 s24, s24, 0x40080
	s_addc_u32 s25, s25, 0
	s_add_u32 s52, s26, 0x100
	s_addc_u32 s53, s27, 0
	s_mov_b32 s54, -2
	s_add_u32 s26, s24, 0xfffc0080
	s_addc_u32 s27, s25, -1
	s_cmp_eq_u32 s54, 12
	s_cselect_b32 s29, s17, s27
	s_cselect_b32 s28, s50, s26
	s_cselect_b32 s27, s15, s53
	s_cselect_b32 s26, s51, s52
	v_lshl_add_u64 v[216:217], s[24:25], 0, v[136:137]
	s_add_i32 m0, s23, 0xc000
	global_load_lds_dwordx4 v[216:217], off
	v_lshl_add_u64 v[216:217], s[24:25], 0, v[138:139]
	s_add_i32 m0, s23, 0xe000
	s_nop 0
	global_load_lds_dwordx4 v[216:217], off
	s_waitcnt vmcnt(8)
	s_waitcnt lgkmcnt(0)
	s_setprio 1
	s_barrier
	v_mfma_f32_16x16x32_bf16 v[124:127], v[152:155], v[184:187], 0
	v_mfma_f32_16x16x32_bf16 v[120:123], v[160:163], v[184:187], 0
	v_mfma_f32_16x16x32_bf16 v[108:111], v[152:155], v[192:195], 0
	v_mfma_f32_16x16x32_bf16 v[104:107], v[160:163], v[192:195], 0
	v_mfma_f32_16x16x32_bf16 v[92:95], v[152:155], v[200:203], 0
	v_mfma_f32_16x16x32_bf16 v[88:91], v[160:163], v[200:203], 0
	v_mfma_f32_16x16x32_bf16 v[76:79], v[152:155], v[208:211], 0
	v_mfma_f32_16x16x32_bf16 v[72:75], v[160:163], v[208:211], 0
	v_mfma_f32_16x16x32_bf16 v[124:127], v[156:159], v[188:191], v[124:127]
	v_mfma_f32_16x16x32_bf16 v[120:123], v[164:167], v[188:191], v[120:123]
	v_mfma_f32_16x16x32_bf16 v[108:111], v[156:159], v[196:199], v[108:111]
	v_mfma_f32_16x16x32_bf16 v[104:107], v[164:167], v[196:199], v[104:107]
	v_mfma_f32_16x16x32_bf16 v[92:95], v[156:159], v[204:207], v[92:95]
	v_mfma_f32_16x16x32_bf16 v[88:91], v[164:167], v[204:207], v[88:91]
	v_mfma_f32_16x16x32_bf16 v[76:79], v[156:159], v[212:215], v[76:79]
	v_mfma_f32_16x16x32_bf16 v[72:75], v[164:167], v[212:215], v[72:75]
	s_setprio 0
	s_setprio 1
	v_mfma_f32_16x16x32_bf16 v[116:119], v[168:171], v[184:187], 0
	v_mfma_f32_16x16x32_bf16 v[112:115], v[176:179], v[184:187], 0
	v_mfma_f32_16x16x32_bf16 v[100:103], v[168:171], v[192:195], 0
	v_mfma_f32_16x16x32_bf16 v[96:99], v[176:179], v[192:195], 0
	v_mfma_f32_16x16x32_bf16 v[84:87], v[168:171], v[200:203], 0
	v_mfma_f32_16x16x32_bf16 v[80:83], v[176:179], v[200:203], 0
	v_mfma_f32_16x16x32_bf16 v[68:71], v[168:171], v[208:211], 0
	v_mfma_f32_16x16x32_bf16 v[64:67], v[176:179], v[208:211], 0
	v_mfma_f32_16x16x32_bf16 v[116:119], v[172:175], v[188:191], v[116:119]
	v_mfma_f32_16x16x32_bf16 v[112:115], v[180:183], v[188:191], v[112:115]
	v_mfma_f32_16x16x32_bf16 v[100:103], v[172:175], v[196:199], v[100:103]
	v_mfma_f32_16x16x32_bf16 v[96:99], v[180:183], v[196:199], v[96:99]
	v_mfma_f32_16x16x32_bf16 v[84:87], v[172:175], v[204:207], v[84:87]
	v_mfma_f32_16x16x32_bf16 v[80:83], v[180:183], v[204:207], v[80:83]
	v_mfma_f32_16x16x32_bf16 v[68:71], v[172:175], v[212:215], v[68:71]
	v_mfma_f32_16x16x32_bf16 v[64:67], v[180:183], v[212:215], v[64:67]
	s_barrier
	s_setprio 0
	s_add_i32 s55, s44, s33
	v_lshl_add_u64 v[216:217], s[26:27], 0, v[132:133]
	s_mov_b32 m0, s55
	ds_read_b128 v[184:187], v150 offset:16384
	ds_read_b128 v[188:191], v150 offset:17408
	ds_read_b128 v[192:195], v150 offset:18432
	ds_read_b128 v[196:199], v150 offset:19456
	ds_read_b128 v[200:203], v150 offset:20480
	ds_read_b128 v[204:207], v150 offset:21504
	ds_read_b128 v[208:211], v150 offset:22528
	ds_read_b128 v[212:215], v150 offset:23552
	global_load_lds_dwordx4 v[216:217], off
	s_add_i32 m0, s55, 0x2000
	s_add_u32 s56, s26, 0x40000
	v_lshl_add_u64 v[218:219], s[26:27], 0, v[128:129]
	s_addc_u32 s57, s27, 0
	s_add_i32 s55, s45, s33
	global_load_lds_dwordx4 v[218:219], off
	v_lshl_add_u64 v[220:221], s[56:57], 0, v[132:133]
	s_mov_b32 m0, s55
	v_lshl_add_u64 v[222:223], s[28:29], 0, v[130:131]
	global_load_lds_dwordx4 v[220:221], off
	v_lshl_add_u64 v[220:221], s[56:57], 0, v[128:129]
	s_add_i32 m0, s55, 0x2000
	s_nop 0
	global_load_lds_dwordx4 v[220:221], off
	v_lshl_add_u64 v[220:221], s[28:29], 0, v[134:135]
	s_mov_b32 m0, s23
	s_nop 0
	global_load_lds_dwordx4 v[220:221], off
	s_mov_b32 m0, s39
	s_nop 0
	global_load_lds_dwordx4 v[222:223], off
	s_waitcnt vmcnt(8)
	s_waitcnt lgkmcnt(0)
	s_setprio 1
	s_barrier
	v_mfma_f32_16x16x32_bf16 v[60:63], v[152:155], v[184:187], 0
	v_mfma_f32_16x16x32_bf16 v[56:59], v[160:163], v[184:187], 0
	v_mfma_f32_16x16x32_bf16 v[44:47], v[152:155], v[192:195], 0
	v_mfma_f32_16x16x32_bf16 v[40:43], v[160:163], v[192:195], 0
	v_mfma_f32_16x16x32_bf16 v[28:31], v[152:155], v[200:203], 0
	v_mfma_f32_16x16x32_bf16 v[24:27], v[160:163], v[200:203], 0
	v_mfma_f32_16x16x32_bf16 v[12:15], v[152:155], v[208:211], 0
	v_mfma_f32_16x16x32_bf16 v[8:11], v[160:163], v[208:211], 0
	v_mfma_f32_16x16x32_bf16 v[60:63], v[156:159], v[188:191], v[60:63]
	v_mfma_f32_16x16x32_bf16 v[56:59], v[164:167], v[188:191], v[56:59]
	v_mfma_f32_16x16x32_bf16 v[44:47], v[156:159], v[196:199], v[44:47]
	v_mfma_f32_16x16x32_bf16 v[40:43], v[164:167], v[196:199], v[40:43]
	v_mfma_f32_16x16x32_bf16 v[28:31], v[156:159], v[204:207], v[28:31]
	v_mfma_f32_16x16x32_bf16 v[24:27], v[164:167], v[204:207], v[24:27]
	v_mfma_f32_16x16x32_bf16 v[12:15], v[156:159], v[212:215], v[12:15]
	v_mfma_f32_16x16x32_bf16 v[8:11], v[164:167], v[212:215], v[8:11]
	s_setprio 0
	s_setprio 1
	v_mfma_f32_16x16x32_bf16 v[52:55], v[168:171], v[184:187], 0
	v_mfma_f32_16x16x32_bf16 v[48:51], v[176:179], v[184:187], 0
	v_mfma_f32_16x16x32_bf16 v[36:39], v[168:171], v[192:195], 0
	v_mfma_f32_16x16x32_bf16 v[32:35], v[176:179], v[192:195], 0
	v_mfma_f32_16x16x32_bf16 v[20:23], v[168:171], v[200:203], 0
	v_mfma_f32_16x16x32_bf16 v[16:19], v[176:179], v[200:203], 0
	v_mfma_f32_16x16x32_bf16 v[4:7], v[168:171], v[208:211], 0
	v_mfma_f32_16x16x32_bf16 v[0:3], v[176:179], v[208:211], 0
	v_mfma_f32_16x16x32_bf16 v[52:55], v[172:175], v[188:191], v[52:55]
	v_mfma_f32_16x16x32_bf16 v[48:51], v[180:183], v[188:191], v[48:51]
	v_mfma_f32_16x16x32_bf16 v[36:39], v[172:175], v[196:199], v[36:39]
	v_mfma_f32_16x16x32_bf16 v[32:35], v[180:183], v[196:199], v[32:35]
	v_mfma_f32_16x16x32_bf16 v[20:23], v[172:175], v[204:207], v[20:23]
	v_mfma_f32_16x16x32_bf16 v[16:19], v[180:183], v[204:207], v[16:19]
	v_mfma_f32_16x16x32_bf16 v[4:7], v[172:175], v[212:215], v[4:7]
	v_mfma_f32_16x16x32_bf16 v[0:3], v[180:183], v[212:215], v[0:3]
	s_barrier
; #define PG8_STAGE(bufoff, gbase, voff) do { _Pragma("unroll") for (int _i = 0; _i < 2; ++_i) \
;         __builtin_amdgcn_global_load_lds((const unsigned*)((const char*)(gbase) + (voff)[_i]), (PG8_LAS unsigned*)(lds + (bufoff) + ldsw + _i * 8192), 16, 0, 0); } while (0)
; #define PG8_LDA(dst, b, h) do { _Pragma("unroll") for (int m = 0; m < 4; ++m) _Pragma("unroll") for (int k = 0; k < 2; ++k) dst[m][k] = *(const PG8_LAS bf16x8*)(lds + PG8_SA(b, h) + aoff + m * 2048 + k * 1024); } while (0)
; #define PG8_LDB(dst, b, h) do { _Pragma("unroll") for (int n = 0; n < 2; ++n) _Pragma("unroll") for (int k = 0; k < 2; ++k) dst[n][k] = *(const PG8_LAS bf16x8*)(lds + PG8_SB(b, h) + boff + n * 2048 + k * 1024); } while (0)
; #define PG8_MMA(ai, bj, At, Bt) do { __builtin_amdgcn_s_setprio(1); _Pragma("unroll") for (int m = 0; m < 4; ++m) _Pragma("unroll") for (int n = 0; n < 2; ++n) _Pragma("unroll") for (int k = 0; k < 2; ++k) \
;         acc[ai][bj][m][n] = __builtin_amdgcn_mfma_f32_16x16x32_bf16(Bt[n][k], At[m][k], acc[ai][bj][m][n], 0, 0, 0); __builtin_amdgcn_s_setprio(0); } while (0)
; #define PG8_WAIT_V(n) asm volatile("s_waitcnt vmcnt(" #n ")" ::: "memory")
; #define PG8_WAIT_L(n) asm volatile("s_waitcnt lgkmcnt(" #n ")" ::: "memory")
; #define PG8_BAR __builtin_amdgcn_s_barrier()
; #define PG8_SCHED __builtin_amdgcn_sched_barrier(0)
; template <class Epi, class Sched, bool ALIGN_EPI = false, bool SP2 = false>
; __device__ __forceinline__ void gemm_phase(PG8_LAS unsigned char* lds, const Gemm g, const Sched& S, const Epi& E) {
;     ...
;             PG8_WAIT_V(8); PG8_WAIT_L(0); PG8_BAR; PG8_MMA(1, 0, At, B0); PG8_MMA(1, 1, At, B1); PG8_BAR; PG8_SCHED;
;             PG8_LDB(B0, 1, 0); PG8_LDB(B1, 1, 1); PG8_SCHED; PG8_LDA(At, 1, 0); PG8_STAGE(PG8_SA(0, 1), a2 + hstep, voffA);
;             PG8_WAIT_V(8); PG8_WAIT_L(0); PG8_BAR; PG8_MMA(0, 0, At, B0); PG8_MMA(0, 1, At, B1); PG8_BAR; PG8_SCHED;
;             PG8_LDA(At, 1, 1); PG8_STAGE(PG8_SB(1, 0), b3, voffB); PG8_STAGE(PG8_SB(1, 1), b3 + hstep, voffB); PG8_STAGE(PG8_SA(1, 0), a3, voffA);
	s_setprio 0
	s_add_i32 s55, 0, 0x18000
	v_add_u32_e32 v151, s55, v145
	s_add_i32 s56, 0, 0x1c000
	ds_read_b128 v[152:155], v151
	ds_read_b128 v[156:159], v151 offset:1024
	ds_read_b128 v[160:163], v151 offset:2048
	ds_read_b128 v[164:167], v151 offset:3072
	v_add_u32_e32 v151, s56, v145
	ds_read_b128 v[168:171], v151
	ds_read_b128 v[172:175], v151 offset:1024
	ds_read_b128 v[176:179], v151 offset:2048
	ds_read_b128 v[180:183], v151 offset:3072
	s_add_u32 s28, s28, 0x40000
	s_addc_u32 s29, s29, 0
	s_mov_b32 m0, s40
	v_lshl_add_u64 v[224:225], s[28:29], 0, v[134:135]
	ds_read_b128 v[184:187], v150 offset:32768
	ds_read_b128 v[188:191], v150 offset:33792
	ds_read_b128 v[192:195], v150 offset:34816
	ds_read_b128 v[196:199], v150 offset:35840
	ds_read_b128 v[200:203], v150 offset:36864
	ds_read_b128 v[204:207], v150 offset:37888
	ds_read_b128 v[208:211], v150 offset:38912
	ds_read_b128 v[212:215], v150 offset:39936
	global_load_lds_dwordx4 v[224:225], off
	v_lshl_add_u64 v[224:225], s[28:29], 0, v[130:131]
	s_mov_b32 m0, s41
	s_nop 0
	global_load_lds_dwordx4 v[224:225], off
	s_waitcnt vmcnt(8)
	s_waitcnt lgkmcnt(0)
	s_setprio 1
	s_barrier
	v_mfma_f32_16x16x32_bf16 v[124:127], v[152:155], v[184:187], v[124:127]
	v_mfma_f32_16x16x32_bf16 v[120:123], v[160:163], v[184:187], v[120:123]
	v_mfma_f32_16x16x32_bf16 v[108:111], v[152:155], v[192:195], v[108:111]
	v_mfma_f32_16x16x32_bf16 v[104:107], v[160:163], v[192:195], v[104:107]
	v_mfma_f32_16x16x32_bf16 v[92:95], v[152:155], v[200:203], v[92:95]
	v_mfma_f32_16x16x32_bf16 v[88:91], v[160:163], v[200:203], v[88:91]
	v_mfma_f32_16x16x32_bf16 v[76:79], v[152:155], v[208:211], v[76:79]
	v_mfma_f32_16x16x32_bf16 v[72:75], v[160:163], v[208:211], v[72:75]
	v_mfma_f32_16x16x32_bf16 v[124:127], v[156:159], v[188:191], v[124:127]
	v_mfma_f32_16x16x32_bf16 v[120:123], v[164:167], v[188:191], v[120:123]
	v_mfma_f32_16x16x32_bf16 v[108:111], v[156:159], v[196:199], v[108:111]
	v_mfma_f32_16x16x32_bf16 v[104:107], v[164:167], v[196:199], v[104:107]
	v_mfma_f32_16x16x32_bf16 v[92:95], v[156:159], v[204:207], v[92:95]
	v_mfma_f32_16x16x32_bf16 v[88:91], v[164:167], v[204:207], v[88:91]
	v_mfma_f32_16x16x32_bf16 v[76:79], v[156:159], v[212:215], v[76:79]
	v_mfma_f32_16x16x32_bf16 v[72:75], v[164:167], v[212:215], v[72:75]
	s_setprio 0
	s_setprio 1
	v_mfma_f32_16x16x32_bf16 v[116:119], v[168:171], v[184:187], v[116:119]
	v_mfma_f32_16x16x32_bf16 v[112:115], v[176:179], v[184:187], v[112:115]
	v_mfma_f32_16x16x32_bf16 v[100:103], v[168:171], v[192:195], v[100:103]
	v_mfma_f32_16x16x32_bf16 v[96:99], v[176:179], v[192:195], v[96:99]
	v_mfma_f32_16x16x32_bf16 v[84:87], v[168:171], v[200:203], v[84:87]
	v_mfma_f32_16x16x32_bf16 v[80:83], v[176:179], v[200:203], v[80:83]
	v_mfma_f32_16x16x32_bf16 v[68:71], v[168:171], v[208:211], v[68:71]
	v_mfma_f32_16x16x32_bf16 v[64:67], v[176:179], v[208:211], v[64:67]
	v_mfma_f32_16x16x32_bf16 v[116:119], v[172:175], v[188:191], v[116:119]
	v_mfma_f32_16x16x32_bf16 v[112:115], v[180:183], v[188:191], v[112:115]
	v_mfma_f32_16x16x32_bf16 v[100:103], v[172:175], v[196:199], v[100:103]
	v_mfma_f32_16x16x32_bf16 v[96:99], v[180:183], v[196:199], v[96:99]
	v_mfma_f32_16x16x32_bf16 v[84:87], v[172:175], v[204:207], v[84:87]
	v_mfma_f32_16x16x32_bf16 v[80:83], v[180:183], v[204:207], v[80:83]
	v_mfma_f32_16x16x32_bf16 v[68:71], v[172:175], v[212:215], v[68:71]
	v_mfma_f32_16x16x32_bf16 v[64:67], v[180:183], v[212:215], v[64:67]
	s_barrier
	s_setprio 0
	s_add_i32 s28, s55, s33
	v_lshl_add_u64 v[216:217], v[216:217], 0, s[10:11]
	s_mov_b32 m0, s28
	ds_read_b128 v[184:187], v150 offset:49152
	ds_read_b128 v[188:191], v150 offset:50176
	ds_read_b128 v[192:195], v150 offset:51200
	ds_read_b128 v[196:199], v150 offset:52224
	ds_read_b128 v[200:203], v150 offset:53248
	ds_read_b128 v[204:207], v150 offset:54272
	ds_read_b128 v[208:211], v150 offset:55296
	ds_read_b128 v[212:215], v150 offset:56320
	global_load_lds_dwordx4 v[216:217], off
	s_add_i32 m0, s28, 0x2000
	s_add_u32 s26, s26, 0x40080
	v_lshl_add_u64 v[216:217], v[218:219], 0, s[10:11]
	s_addc_u32 s27, s27, 0
	s_add_i32 s28, s56, s33
	global_load_lds_dwordx4 v[216:217], off
	v_lshl_add_u64 v[216:217], s[26:27], 0, v[132:133]
	s_mov_b32 m0, s28
	s_nop 0
	global_load_lds_dwordx4 v[216:217], off
	v_lshl_add_u64 v[216:217], s[26:27], 0, v[128:129]
	s_add_i32 m0, s28, 0x2000
	s_nop 0
	global_load_lds_dwordx4 v[216:217], off
	v_lshl_add_u64 v[216:217], v[220:221], 0, s[10:11]
	s_mov_b32 m0, s42
	s_nop 0
	global_load_lds_dwordx4 v[216:217], off
	v_lshl_add_u64 v[216:217], v[222:223], 0, s[10:11]
	s_mov_b32 m0, s43
	s_nop 0
	global_load_lds_dwordx4 v[216:217], off
	s_waitcnt vmcnt(8)
	s_waitcnt lgkmcnt(0)
	s_setprio 1
	s_barrier
; #define PG8_STAGE(bufoff, gbase, voff) do { _Pragma("unroll") for (int _i = 0; _i < 2; ++_i) \
;         __builtin_amdgcn_global_load_lds((const unsigned*)((const char*)(gbase) + (voff)[_i]), (PG8_LAS unsigned*)(lds + (bufoff) + ldsw + _i * 8192), 16, 0, 0); } while (0)
; #define PG8_LDA(dst, b, h) do { _Pragma("unroll") for (int m = 0; m < 4; ++m) _Pragma("unroll") for (int k = 0; k < 2; ++k) dst[m][k] = *(const PG8_LAS bf16x8*)(lds + PG8_SA(b, h) + aoff + m * 2048 + k * 1024); } while (0)
; #define PG8_LDB(dst, b, h) do { _Pragma("unroll") for (int n = 0; n < 2; ++n) _Pragma("unroll") for (int k = 0; k < 2; ++k) dst[n][k] = *(const PG8_LAS bf16x8*)(lds + PG8_SB(b, h) + boff + n * 2048 + k * 1024); } while (0)
; #define PG8_MMA(ai, bj, At, Bt) do { __builtin_amdgcn_s_setprio(1); _Pragma("unroll") for (int m = 0; m < 4; ++m) _Pragma("unroll") for (int n = 0; n < 2; ++n) _Pragma("unroll") for (int k = 0; k < 2; ++k) \
;         acc[ai][bj][m][n] = __builtin_amdgcn_mfma_f32_16x16x32_bf16(Bt[n][k], At[m][k], acc[ai][bj][m][n], 0, 0, 0); __builtin_amdgcn_s_setprio(0); } while (0)
; #define PG8_WAIT_V(n) asm volatile("s_waitcnt vmcnt(" #n ")" ::: "memory")
; template <class Epi, class Sched, bool ALIGN_EPI = false, bool SP2 = false>
; __device__ __forceinline__ void gemm_phase(PG8_LAS unsigned char* lds, const Gemm g, const Sched& S, const Epi& E) {
;     ...
;             PG8_LDB(B0, 0, 0); PG8_LDB(B1, 0, 1); PG8_SCHED; PG8_LDA(At, 0, 0); PG8_STAGE(PG8_SA(1, 1), a1 + hstep, voffA);
;             PG8_WAIT_V(8); PG8_WAIT_L(0); PG8_BAR; PG8_MMA(0, 0, At, B0); PG8_MMA(0, 1, At, B1); PG8_BAR; PG8_SCHED;
;             PG8_LDA(At, 0, 1); PG8_STAGE(PG8_SB(0, 0), b2, voffB); PG8_STAGE(PG8_SB(0, 1), b2 + hstep, voffB); PG8_STAGE(PG8_SA(0, 0), a2, voffA);
;             PG8_WAIT_V(8); PG8_WAIT_L(0); PG8_BAR; PG8_MMA(1, 0, At, B0); PG8_MMA(1, 1, At, B1); PG8_BAR; PG8_SCHED;
;             PG8_LDB(B0, 1, 0); PG8_LDB(B1, 1, 1); PG8_SCHED; PG8_LDA(At, 1, 0); PG8_STAGE(PG8_SA(0, 1), a2 + hstep, voffA);
;             PG8_WAIT_V(8); PG8_WAIT_L(0); PG8_BAR; PG8_MMA(0, 0, At, B0); PG8_MMA(0, 1, At, B1); PG8_BAR; PG8_SCHED;
;             PG8_LDA(At, 1, 1); PG8_STAGE(PG8_SB(1, 0), b3, voffB); PG8_STAGE(PG8_SB(1, 1), b3 + hstep, voffB); PG8_STAGE(PG8_SA(1, 0), a3, voffA);
;             PG8_WAIT_V(8); PG8_WAIT_L(0); PG8_BAR; PG8_MMA(1, 0, At, B0); PG8_MMA(1, 1, At, B1); PG8_BAR; PG8_SCHED;
	v_mfma_f32_16x16x32_bf16 v[60:63], v[152:155], v[184:187], v[60:63]
	v_mfma_f32_16x16x32_bf16 v[56:59], v[160:163], v[184:187], v[56:59]
	v_mfma_f32_16x16x32_bf16 v[44:47], v[152:155], v[192:195], v[44:47]
	v_mfma_f32_16x16x32_bf16 v[40:43], v[160:163], v[192:195], v[40:43]
	v_mfma_f32_16x16x32_bf16 v[28:31], v[152:155], v[200:203], v[28:31]
	v_mfma_f32_16x16x32_bf16 v[24:27], v[160:163], v[200:203], v[24:27]
	v_mfma_f32_16x16x32_bf16 v[12:15], v[152:155], v[208:211], v[12:15]
	v_mfma_f32_16x16x32_bf16 v[8:11], v[160:163], v[208:211], v[8:11]
	v_mfma_f32_16x16x32_bf16 v[60:63], v[156:159], v[188:191], v[60:63]
	v_mfma_f32_16x16x32_bf16 v[56:59], v[164:167], v[188:191], v[56:59]
	v_mfma_f32_16x16x32_bf16 v[44:47], v[156:159], v[196:199], v[44:47]
	v_mfma_f32_16x16x32_bf16 v[40:43], v[164:167], v[196:199], v[40:43]
	v_mfma_f32_16x16x32_bf16 v[28:31], v[156:159], v[204:207], v[28:31]
	v_mfma_f32_16x16x32_bf16 v[24:27], v[164:167], v[204:207], v[24:27]
	v_mfma_f32_16x16x32_bf16 v[12:15], v[156:159], v[212:215], v[12:15]
	v_mfma_f32_16x16x32_bf16 v[8:11], v[164:167], v[212:215], v[8:11]
	s_setprio 0
	s_setprio 1
	v_mfma_f32_16x16x32_bf16 v[52:55], v[168:171], v[184:187], v[52:55]
	v_mfma_f32_16x16x32_bf16 v[48:51], v[176:179], v[184:187], v[48:51]
	v_mfma_f32_16x16x32_bf16 v[36:39], v[168:171], v[192:195], v[36:39]
	v_mfma_f32_16x16x32_bf16 v[32:35], v[176:179], v[192:195], v[32:35]
	v_mfma_f32_16x16x32_bf16 v[20:23], v[168:171], v[200:203], v[20:23]
	v_mfma_f32_16x16x32_bf16 v[16:19], v[176:179], v[200:203], v[16:19]
	v_mfma_f32_16x16x32_bf16 v[4:7], v[168:171], v[208:211], v[4:7]
	v_mfma_f32_16x16x32_bf16 v[0:3], v[176:179], v[208:211], v[0:3]
	v_mfma_f32_16x16x32_bf16 v[52:55], v[172:175], v[188:191], v[52:55]
	v_mfma_f32_16x16x32_bf16 v[48:51], v[180:183], v[188:191], v[48:51]
	v_mfma_f32_16x16x32_bf16 v[36:39], v[172:175], v[196:199], v[36:39]
	v_mfma_f32_16x16x32_bf16 v[32:35], v[180:183], v[196:199], v[32:35]
	v_mfma_f32_16x16x32_bf16 v[20:23], v[172:175], v[204:207], v[20:23]
	v_mfma_f32_16x16x32_bf16 v[16:19], v[180:183], v[204:207], v[16:19]
	v_mfma_f32_16x16x32_bf16 v[4:7], v[172:175], v[212:215], v[4:7]
	v_mfma_f32_16x16x32_bf16 v[0:3], v[180:183], v[212:215], v[0:3]
	s_barrier
	s_setprio 0
	s_add_i32 s54, s54, 2
	s_add_u32 s24, s24, 0x100
	s_addc_u32 s25, s25, 0
	s_add_u32 s52, s52, 0x100
	s_addc_u32 s53, s53, 0
	s_cmp_gt_u32 s54, 13
.LBB0_1219:
	ds_read_b128 v[152:155], v148
	ds_read_b128 v[156:159], v148 offset:1024
	ds_read_b128 v[160:163], v148 offset:2048
	ds_read_b128 v[164:167], v148 offset:3072
	ds_read_b128 v[168:171], v149
	ds_read_b128 v[172:175], v149 offset:1024
	ds_read_b128 v[176:179], v149 offset:2048
	ds_read_b128 v[180:183], v149 offset:3072
	s_add_u32 s26, s24, 0xfffc0080
	s_addc_u32 s27, s25, -1
	s_cmp_eq_u32 s54, 12
	s_cselect_b32 s29, s17, s27
	s_cselect_b32 s28, s50, s26
	s_cselect_b32 s27, s15, s53
	s_cselect_b32 s26, s51, s52
	v_lshl_add_u64 v[216:217], s[24:25], 0, v[136:137]
	s_add_i32 m0, s23, 0xc000
	ds_read_b128 v[184:187], v150
	ds_read_b128 v[188:191], v150 offset:1024
	ds_read_b128 v[192:195], v150 offset:2048
	ds_read_b128 v[196:199], v150 offset:3072
	ds_read_b128 v[200:203], v150 offset:4096
	ds_read_b128 v[204:207], v150 offset:5120
	ds_read_b128 v[208:211], v150 offset:6144
	ds_read_b128 v[212:215], v150 offset:7168
	global_load_lds_dwordx4 v[216:217], off
	v_lshl_add_u64 v[216:217], s[24:25], 0, v[138:139]
	s_add_i32 m0, s23, 0xe000
	s_nop 0
	global_load_lds_dwordx4 v[216:217], off
	s_waitcnt vmcnt(8)
	s_waitcnt lgkmcnt(0)
	s_setprio 1
	s_barrier
	v_mfma_f32_16x16x32_bf16 v[124:127], v[152:155], v[184:187], v[124:127]
	v_mfma_f32_16x16x32_bf16 v[120:123], v[160:163], v[184:187], v[120:123]
	v_mfma_f32_16x16x32_bf16 v[108:111], v[152:155], v[192:195], v[108:111]
	v_mfma_f32_16x16x32_bf16 v[104:107], v[160:163], v[192:195], v[104:107]
	v_mfma_f32_16x16x32_bf16 v[92:95], v[152:155], v[200:203], v[92:95]
	v_mfma_f32_16x16x32_bf16 v[88:91], v[160:163], v[200:203], v[88:91]
	v_mfma_f32_16x16x32_bf16 v[76:79], v[152:155], v[208:211], v[76:79]
	v_mfma_f32_16x16x32_bf16 v[72:75], v[160:163], v[208:211], v[72:75]
	v_mfma_f32_16x16x32_bf16 v[124:127], v[156:159], v[188:191], v[124:127]
	v_mfma_f32_16x16x32_bf16 v[120:123], v[164:167], v[188:191], v[120:123]
	v_mfma_f32_16x16x32_bf16 v[108:111], v[156:159], v[196:199], v[108:111]
	v_mfma_f32_16x16x32_bf16 v[104:107], v[164:167], v[196:199], v[104:107]
	v_mfma_f32_16x16x32_bf16 v[92:95], v[156:159], v[204:207], v[92:95]
	v_mfma_f32_16x16x32_bf16 v[88:91], v[164:167], v[204:207], v[88:91]
	v_mfma_f32_16x16x32_bf16 v[76:79], v[156:159], v[212:215], v[76:79]
	v_mfma_f32_16x16x32_bf16 v[72:75], v[164:167], v[212:215], v[72:75]
	s_setprio 0
	s_setprio 1
	v_mfma_f32_16x16x32_bf16 v[116:119], v[168:171], v[184:187], v[116:119]
	v_mfma_f32_16x16x32_bf16 v[112:115], v[176:179], v[184:187], v[112:115]
	v_mfma_f32_16x16x32_bf16 v[100:103], v[168:171], v[192:195], v[100:103]
	v_mfma_f32_16x16x32_bf16 v[96:99], v[176:179], v[192:195], v[96:99]
	v_mfma_f32_16x16x32_bf16 v[84:87], v[168:171], v[200:203], v[84:87]
	v_mfma_f32_16x16x32_bf16 v[80:83], v[176:179], v[200:203], v[80:83]
	v_mfma_f32_16x16x32_bf16 v[68:71], v[168:171], v[208:211], v[68:71]
	v_mfma_f32_16x16x32_bf16 v[64:67], v[176:179], v[208:211], v[64:67]
	v_mfma_f32_16x16x32_bf16 v[116:119], v[172:175], v[188:191], v[116:119]
	v_mfma_f32_16x16x32_bf16 v[112:115], v[180:183], v[188:191], v[112:115]
	v_mfma_f32_16x16x32_bf16 v[100:103], v[172:175], v[196:199], v[100:103]
	v_mfma_f32_16x16x32_bf16 v[96:99], v[180:183], v[196:199], v[96:99]
	v_mfma_f32_16x16x32_bf16 v[84:87], v[172:175], v[204:207], v[84:87]
	v_mfma_f32_16x16x32_bf16 v[80:83], v[180:183], v[204:207], v[80:83]
	v_mfma_f32_16x16x32_bf16 v[68:71], v[172:175], v[212:215], v[68:71]
	v_mfma_f32_16x16x32_bf16 v[64:67], v[180:183], v[212:215], v[64:67]
	s_barrier
; #define PG8_STAGE(bufoff, gbase, voff) do { _Pragma("unroll") for (int _i = 0; _i < 2; ++_i) \
;         __builtin_amdgcn_global_load_lds((const unsigned*)((const char*)(gbase) + (voff)[_i]), (PG8_LAS unsigned*)(lds + (bufoff) + ldsw + _i * 8192), 16, 0, 0); } while (0)
; #define PG8_LDA(dst, b, h) do { _Pragma("unroll") for (int m = 0; m < 4; ++m) _Pragma("unroll") for (int k = 0; k < 2; ++k) dst[m][k] = *(const PG8_LAS bf16x8*)(lds + PG8_SA(b, h) + aoff + m * 2048 + k * 1024); } while (0)
; #define PG8_LDB(dst, b, h) do { _Pragma("unroll") for (int n = 0; n < 2; ++n) _Pragma("unroll") for (int k = 0; k < 2; ++k) dst[n][k] = *(const PG8_LAS bf16x8*)(lds + PG8_SB(b, h) + boff + n * 2048 + k * 1024); } while (0)
; #define PG8_MMA(ai, bj, At, Bt) do { __builtin_amdgcn_s_setprio(1); _Pragma("unroll") for (int m = 0; m < 4; ++m) _Pragma("unroll") for (int n = 0; n < 2; ++n) _Pragma("unroll") for (int k = 0; k < 2; ++k) \
;         acc[ai][bj][m][n] = __builtin_amdgcn_mfma_f32_16x16x32_bf16(Bt[n][k], At[m][k], acc[ai][bj][m][n], 0, 0, 0); __builtin_amdgcn_s_setprio(0); } while (0)
; #define PG8_WAIT_V(n) asm volatile("s_waitcnt vmcnt(" #n ")" ::: "memory")
; #define PG8_WAIT_L(n) asm volatile("s_waitcnt lgkmcnt(" #n ")" ::: "memory")
; #define PG8_BAR __builtin_amdgcn_s_barrier()
; #define PG8_SCHED __builtin_amdgcn_sched_barrier(0)
; template <class Epi, class Sched, bool ALIGN_EPI = false, bool SP2 = false>
; __device__ __forceinline__ void gemm_phase(PG8_LAS unsigned char* lds, const Gemm g, const Sched& S, const Epi& E) {
;     ...
;             PG8_LDA(At, 0, 1); PG8_STAGE(PG8_SB(0, 0), b2, voffB); PG8_STAGE(PG8_SB(0, 1), b2 + hstep, voffB); PG8_STAGE(PG8_SA(0, 0), a2, voffA);
;             PG8_WAIT_V(8); PG8_WAIT_L(0); PG8_BAR; PG8_MMA(1, 0, At, B0); PG8_MMA(1, 1, At, B1); PG8_BAR; PG8_SCHED;
;             PG8_LDB(B0, 1, 0); PG8_LDB(B1, 1, 1); PG8_SCHED; PG8_LDA(At, 1, 0); PG8_STAGE(PG8_SA(0, 1), a2 + hstep, voffA);
;             PG8_WAIT_V(8); PG8_WAIT_L(0); PG8_BAR; PG8_MMA(0, 0, At, B0); PG8_MMA(0, 1, At, B1); PG8_BAR; PG8_SCHED;
	s_setprio 0
	s_add_i32 s55, s44, s33
	v_lshl_add_u64 v[216:217], s[26:27], 0, v[132:133]
	s_mov_b32 m0, s55
	ds_read_b128 v[184:187], v150 offset:16384
	ds_read_b128 v[188:191], v150 offset:17408
	ds_read_b128 v[192:195], v150 offset:18432
	ds_read_b128 v[196:199], v150 offset:19456
	ds_read_b128 v[200:203], v150 offset:20480
	ds_read_b128 v[204:207], v150 offset:21504
	ds_read_b128 v[208:211], v150 offset:22528
	ds_read_b128 v[212:215], v150 offset:23552
	global_load_lds_dwordx4 v[216:217], off
	s_add_i32 m0, s55, 0x2000
	s_add_u32 s56, s26, 0x40000
	v_lshl_add_u64 v[218:219], s[26:27], 0, v[128:129]
	s_addc_u32 s57, s27, 0
	s_add_i32 s55, s45, s33
	global_load_lds_dwordx4 v[218:219], off
	v_lshl_add_u64 v[220:221], s[56:57], 0, v[132:133]
	s_mov_b32 m0, s55
	v_lshl_add_u64 v[222:223], s[28:29], 0, v[130:131]
	global_load_lds_dwordx4 v[220:221], off
	v_lshl_add_u64 v[220:221], s[56:57], 0, v[128:129]
	s_add_i32 m0, s55, 0x2000
	s_nop 0
	global_load_lds_dwordx4 v[220:221], off
	v_lshl_add_u64 v[220:221], s[28:29], 0, v[134:135]
	s_mov_b32 m0, s23
	s_nop 0
	global_load_lds_dwordx4 v[220:221], off
	s_mov_b32 m0, s39
	s_nop 0
	global_load_lds_dwordx4 v[222:223], off
	s_waitcnt vmcnt(8)
	s_waitcnt lgkmcnt(0)
	s_setprio 1
	s_barrier
	v_mfma_f32_16x16x32_bf16 v[60:63], v[152:155], v[184:187], v[60:63]
	v_mfma_f32_16x16x32_bf16 v[56:59], v[160:163], v[184:187], v[56:59]
	v_mfma_f32_16x16x32_bf16 v[44:47], v[152:155], v[192:195], v[44:47]
	v_mfma_f32_16x16x32_bf16 v[40:43], v[160:163], v[192:195], v[40:43]
	v_mfma_f32_16x16x32_bf16 v[28:31], v[152:155], v[200:203], v[28:31]
	v_mfma_f32_16x16x32_bf16 v[24:27], v[160:163], v[200:203], v[24:27]
	v_mfma_f32_16x16x32_bf16 v[12:15], v[152:155], v[208:211], v[12:15]
	v_mfma_f32_16x16x32_bf16 v[8:11], v[160:163], v[208:211], v[8:11]
	v_mfma_f32_16x16x32_bf16 v[60:63], v[156:159], v[188:191], v[60:63]
	v_mfma_f32_16x16x32_bf16 v[56:59], v[164:167], v[188:191], v[56:59]
	v_mfma_f32_16x16x32_bf16 v[44:47], v[156:159], v[196:199], v[44:47]
	v_mfma_f32_16x16x32_bf16 v[40:43], v[164:167], v[196:199], v[40:43]
	v_mfma_f32_16x16x32_bf16 v[28:31], v[156:159], v[204:207], v[28:31]
	v_mfma_f32_16x16x32_bf16 v[24:27], v[164:167], v[204:207], v[24:27]
	v_mfma_f32_16x16x32_bf16 v[12:15], v[156:159], v[212:215], v[12:15]
	v_mfma_f32_16x16x32_bf16 v[8:11], v[164:167], v[212:215], v[8:11]
	s_setprio 0
	s_setprio 1
	v_mfma_f32_16x16x32_bf16 v[52:55], v[168:171], v[184:187], v[52:55]
	v_mfma_f32_16x16x32_bf16 v[48:51], v[176:179], v[184:187], v[48:51]
	v_mfma_f32_16x16x32_bf16 v[36:39], v[168:171], v[192:195], v[36:39]
	v_mfma_f32_16x16x32_bf16 v[32:35], v[176:179], v[192:195], v[32:35]
	v_mfma_f32_16x16x32_bf16 v[20:23], v[168:171], v[200:203], v[20:23]
	v_mfma_f32_16x16x32_bf16 v[16:19], v[176:179], v[200:203], v[16:19]
	v_mfma_f32_16x16x32_bf16 v[4:7], v[168:171], v[208:211], v[4:7]
	v_mfma_f32_16x16x32_bf16 v[0:3], v[176:179], v[208:211], v[0:3]
	v_mfma_f32_16x16x32_bf16 v[52:55], v[172:175], v[188:191], v[52:55]
	v_mfma_f32_16x16x32_bf16 v[48:51], v[180:183], v[188:191], v[48:51]
	v_mfma_f32_16x16x32_bf16 v[36:39], v[172:175], v[196:199], v[36:39]
	v_mfma_f32_16x16x32_bf16 v[32:35], v[180:183], v[196:199], v[32:35]
	v_mfma_f32_16x16x32_bf16 v[20:23], v[172:175], v[204:207], v[20:23]
	v_mfma_f32_16x16x32_bf16 v[16:19], v[180:183], v[204:207], v[16:19]
	v_mfma_f32_16x16x32_bf16 v[4:7], v[172:175], v[212:215], v[4:7]
	v_mfma_f32_16x16x32_bf16 v[0:3], v[180:183], v[212:215], v[0:3]
	s_barrier
	s_setprio 0
	s_add_i32 s55, 0, 0x18000
	v_add_u32_e32 v151, s55, v145
	s_add_i32 s56, 0, 0x1c000
	ds_read_b128 v[152:155], v151
	ds_read_b128 v[156:159], v151 offset:1024
	ds_read_b128 v[160:163], v151 offset:2048
	ds_read_b128 v[164:167], v151 offset:3072
	v_add_u32_e32 v151, s56, v145
	ds_read_b128 v[168:171], v151
	ds_read_b128 v[172:175], v151 offset:1024
	ds_read_b128 v[176:179], v151 offset:2048
	ds_read_b128 v[180:183], v151 offset:3072
	s_add_u32 s28, s28, 0x40000
	s_addc_u32 s29, s29, 0
	s_mov_b32 m0, s40
	v_lshl_add_u64 v[224:225], s[28:29], 0, v[134:135]
	ds_read_b128 v[184:187], v150 offset:32768
	ds_read_b128 v[188:191], v150 offset:33792
	ds_read_b128 v[192:195], v150 offset:34816
	ds_read_b128 v[196:199], v150 offset:35840
	ds_read_b128 v[200:203], v150 offset:36864
	ds_read_b128 v[204:207], v150 offset:37888
	ds_read_b128 v[208:211], v150 offset:38912
	ds_read_b128 v[212:215], v150 offset:39936
	global_load_lds_dwordx4 v[224:225], off
	v_lshl_add_u64 v[224:225], s[28:29], 0, v[130:131]
	s_mov_b32 m0, s41
	s_nop 0
	global_load_lds_dwordx4 v[224:225], off
	s_waitcnt vmcnt(8)
	s_waitcnt lgkmcnt(0)
	s_setprio 1
	s_barrier
; #define PG8_STAGE(bufoff, gbase, voff) do { _Pragma("unroll") for (int _i = 0; _i < 2; ++_i) \
;         __builtin_amdgcn_global_load_lds((const unsigned*)((const char*)(gbase) + (voff)[_i]), (PG8_LAS unsigned*)(lds + (bufoff) + ldsw + _i * 8192), 16, 0, 0); } while (0)
; #define PG8_BAR __builtin_amdgcn_s_barrier()
; template <class Epi, class Sched, bool ALIGN_EPI = false, bool SP2 = false>
; __device__ __forceinline__ void gemm_phase(PG8_LAS unsigned char* lds, const Gemm g, const Sched& S, const Epi& E) {
;     ...
;             PG8_LDB(B0, 1, 0); PG8_LDB(B1, 1, 1); PG8_SCHED; PG8_LDA(At, 1, 0); PG8_STAGE(PG8_SA(0, 1), a2 + hstep, voffA);
;             PG8_WAIT_V(8); PG8_WAIT_L(0); PG8_BAR; PG8_MMA(0, 0, At, B0); PG8_MMA(0, 1, At, B1); PG8_BAR; PG8_SCHED;
;             PG8_LDA(At, 1, 1); PG8_STAGE(PG8_SB(1, 0), b3, voffB); PG8_STAGE(PG8_SB(1, 1), b3 + hstep, voffB); PG8_STAGE(PG8_SA(1, 0), a3, voffA);
;             PG8_WAIT_V(8); PG8_WAIT_L(0); PG8_BAR; PG8_MMA(1, 0, At, B0); PG8_MMA(1, 1, At, B1); PG8_BAR; PG8_SCHED;
;             } else {
;             PG8_LDB(B0, 0, 0); PG8_SCHED; PG8_LDA(At, 0, 0); PG8_STAGE(PG8_SA(1, 1), a1 + hstep, voffA);
;             PG8_WAIT_L(8); PG8_BAR; PG8_WAIT_L(0); PG8_MMA(0, 0, At, B0); PG8_BAR; PG8_SCHED;
;             PG8_LDB(B1, 0, 1); PG8_STAGE(PG8_SB(0, 0), b2, voffB);
;             PG8_BAR; PG8_WAIT_L(0); PG8_MMA(0, 1, At, B1); PG8_BAR;
;             PG8_LDA(At, 0, 1); PG8_STAGE(PG8_SA(0, 0), a2, voffA);
;             PG8_BAR; PG8_WAIT_L(0); PG8_MMA(1, 0, At, B0); PG8_BAR; PG8_SCHED;
;             PG8_STAGE(PG8_SB(0, 1), b2 + hstep, voffB);
;             PG8_WAIT_V(6); PG8_BAR; PG8_MMA(1, 1, At, B1); PG8_BAR;
;             PG8_LDB(B0, 1, 0); PG8_SCHED; PG8_LDA(At, 1, 0); PG8_STAGE(PG8_SA(0, 1), a2 + hstep, voffA);
;             PG8_WAIT_L(8); PG8_BAR; PG8_WAIT_L(0); PG8_MMA(0, 0, At, B0); PG8_BAR; PG8_SCHED;
;             PG8_LDB(B1, 1, 1); PG8_STAGE(PG8_SB(1, 0), b3, voffB);
;             PG8_BAR; PG8_WAIT_L(0); PG8_MMA(0, 1, At, B1); PG8_BAR;
;             PG8_LDA(At, 1, 1); PG8_STAGE(PG8_SA(1, 0), a3, voffA);
;             PG8_BAR; PG8_WAIT_L(0); PG8_MMA(1, 0, At, B0); PG8_BAR; PG8_SCHED;
;             PG8_STAGE(PG8_SB(1, 1), b3 + hstep, voffB);
;             PG8_WAIT_V(6); PG8_BAR; PG8_MMA(1, 1, At, B1); PG8_BAR;
;             }
;         }
;         if constexpr (ALIGN_EPI) { if (wr == 0) PG8_BAR; }
	v_mfma_f32_16x16x32_bf16 v[124:127], v[152:155], v[184:187], v[124:127]
	v_mfma_f32_16x16x32_bf16 v[120:123], v[160:163], v[184:187], v[120:123]
	v_mfma_f32_16x16x32_bf16 v[108:111], v[152:155], v[192:195], v[108:111]
	v_mfma_f32_16x16x32_bf16 v[104:107], v[160:163], v[192:195], v[104:107]
	v_mfma_f32_16x16x32_bf16 v[92:95], v[152:155], v[200:203], v[92:95]
	v_mfma_f32_16x16x32_bf16 v[88:91], v[160:163], v[200:203], v[88:91]
	v_mfma_f32_16x16x32_bf16 v[76:79], v[152:155], v[208:211], v[76:79]
	v_mfma_f32_16x16x32_bf16 v[72:75], v[160:163], v[208:211], v[72:75]
	v_mfma_f32_16x16x32_bf16 v[124:127], v[156:159], v[188:191], v[124:127]
	v_mfma_f32_16x16x32_bf16 v[120:123], v[164:167], v[188:191], v[120:123]
	v_mfma_f32_16x16x32_bf16 v[108:111], v[156:159], v[196:199], v[108:111]
	v_mfma_f32_16x16x32_bf16 v[104:107], v[164:167], v[196:199], v[104:107]
	v_mfma_f32_16x16x32_bf16 v[92:95], v[156:159], v[204:207], v[92:95]
	v_mfma_f32_16x16x32_bf16 v[88:91], v[164:167], v[204:207], v[88:91]
	v_mfma_f32_16x16x32_bf16 v[76:79], v[156:159], v[212:215], v[76:79]
	v_mfma_f32_16x16x32_bf16 v[72:75], v[164:167], v[212:215], v[72:75]
	s_setprio 0
	s_setprio 1
	v_mfma_f32_16x16x32_bf16 v[116:119], v[168:171], v[184:187], v[116:119]
	v_mfma_f32_16x16x32_bf16 v[112:115], v[176:179], v[184:187], v[112:115]
	v_mfma_f32_16x16x32_bf16 v[100:103], v[168:171], v[192:195], v[100:103]
	v_mfma_f32_16x16x32_bf16 v[96:99], v[176:179], v[192:195], v[96:99]
	v_mfma_f32_16x16x32_bf16 v[84:87], v[168:171], v[200:203], v[84:87]
	v_mfma_f32_16x16x32_bf16 v[80:83], v[176:179], v[200:203], v[80:83]
	v_mfma_f32_16x16x32_bf16 v[68:71], v[168:171], v[208:211], v[68:71]
	v_mfma_f32_16x16x32_bf16 v[64:67], v[176:179], v[208:211], v[64:67]
	v_mfma_f32_16x16x32_bf16 v[116:119], v[172:175], v[188:191], v[116:119]
	v_mfma_f32_16x16x32_bf16 v[112:115], v[180:183], v[188:191], v[112:115]
	v_mfma_f32_16x16x32_bf16 v[100:103], v[172:175], v[196:199], v[100:103]
	v_mfma_f32_16x16x32_bf16 v[96:99], v[180:183], v[196:199], v[96:99]
	v_mfma_f32_16x16x32_bf16 v[84:87], v[172:175], v[204:207], v[84:87]
	v_mfma_f32_16x16x32_bf16 v[80:83], v[180:183], v[204:207], v[80:83]
	v_mfma_f32_16x16x32_bf16 v[68:71], v[172:175], v[212:215], v[68:71]
	v_mfma_f32_16x16x32_bf16 v[64:67], v[180:183], v[212:215], v[64:67]
	s_barrier
	s_setprio 0
	s_add_i32 s28, s55, s33
	v_lshl_add_u64 v[216:217], v[216:217], 0, s[10:11]
	s_mov_b32 m0, s28
	ds_read_b128 v[184:187], v150 offset:49152
	ds_read_b128 v[188:191], v150 offset:50176
	ds_read_b128 v[192:195], v150 offset:51200
	ds_read_b128 v[196:199], v150 offset:52224
	ds_read_b128 v[200:203], v150 offset:53248
	ds_read_b128 v[204:207], v150 offset:54272
	ds_read_b128 v[208:211], v150 offset:55296
	ds_read_b128 v[212:215], v150 offset:56320
	global_load_lds_dwordx4 v[216:217], off
	s_add_i32 m0, s28, 0x2000
	s_add_u32 s26, s26, 0x40080
	v_lshl_add_u64 v[216:217], v[218:219], 0, s[10:11]
	s_addc_u32 s27, s27, 0
	s_add_i32 s28, s56, s33
	global_load_lds_dwordx4 v[216:217], off
	v_lshl_add_u64 v[216:217], s[26:27], 0, v[132:133]
	s_mov_b32 m0, s28
	s_nop 0
	global_load_lds_dwordx4 v[216:217], off
	v_lshl_add_u64 v[216:217], s[26:27], 0, v[128:129]
	s_add_i32 m0, s28, 0x2000
	s_nop 0
	global_load_lds_dwordx4 v[216:217], off
	v_lshl_add_u64 v[216:217], v[220:221], 0, s[10:11]
	s_mov_b32 m0, s42
	s_nop 0
	global_load_lds_dwordx4 v[216:217], off
	v_lshl_add_u64 v[216:217], v[222:223], 0, s[10:11]
	s_mov_b32 m0, s43
	s_nop 0
	global_load_lds_dwordx4 v[216:217], off
	s_waitcnt vmcnt(8)
	s_waitcnt lgkmcnt(0)
	s_setprio 1
	s_barrier
	v_mfma_f32_16x16x32_bf16 v[60:63], v[152:155], v[184:187], v[60:63]
	v_mfma_f32_16x16x32_bf16 v[56:59], v[160:163], v[184:187], v[56:59]
	v_mfma_f32_16x16x32_bf16 v[44:47], v[152:155], v[192:195], v[44:47]
	v_mfma_f32_16x16x32_bf16 v[40:43], v[160:163], v[192:195], v[40:43]
	v_mfma_f32_16x16x32_bf16 v[28:31], v[152:155], v[200:203], v[28:31]
	v_mfma_f32_16x16x32_bf16 v[24:27], v[160:163], v[200:203], v[24:27]
	v_mfma_f32_16x16x32_bf16 v[12:15], v[152:155], v[208:211], v[12:15]
	v_mfma_f32_16x16x32_bf16 v[8:11], v[160:163], v[208:211], v[8:11]
	v_mfma_f32_16x16x32_bf16 v[60:63], v[156:159], v[188:191], v[60:63]
	v_mfma_f32_16x16x32_bf16 v[56:59], v[164:167], v[188:191], v[56:59]
	v_mfma_f32_16x16x32_bf16 v[44:47], v[156:159], v[196:199], v[44:47]
	v_mfma_f32_16x16x32_bf16 v[40:43], v[164:167], v[196:199], v[40:43]
	v_mfma_f32_16x16x32_bf16 v[28:31], v[156:159], v[204:207], v[28:31]
	v_mfma_f32_16x16x32_bf16 v[24:27], v[164:167], v[204:207], v[24:27]
	v_mfma_f32_16x16x32_bf16 v[12:15], v[156:159], v[212:215], v[12:15]
	v_mfma_f32_16x16x32_bf16 v[8:11], v[164:167], v[212:215], v[8:11]
	s_setprio 0
	s_setprio 1
	v_mfma_f32_16x16x32_bf16 v[52:55], v[168:171], v[184:187], v[52:55]
	v_mfma_f32_16x16x32_bf16 v[48:51], v[176:179], v[184:187], v[48:51]
	v_mfma_f32_16x16x32_bf16 v[36:39], v[168:171], v[192:195], v[36:39]
	v_mfma_f32_16x16x32_bf16 v[32:35], v[176:179], v[192:195], v[32:35]
	v_mfma_f32_16x16x32_bf16 v[20:23], v[168:171], v[200:203], v[20:23]
	v_mfma_f32_16x16x32_bf16 v[16:19], v[176:179], v[200:203], v[16:19]
	v_mfma_f32_16x16x32_bf16 v[4:7], v[168:171], v[208:211], v[4:7]
	v_mfma_f32_16x16x32_bf16 v[0:3], v[176:179], v[208:211], v[0:3]
	v_mfma_f32_16x16x32_bf16 v[52:55], v[172:175], v[188:191], v[52:55]
	v_mfma_f32_16x16x32_bf16 v[48:51], v[180:183], v[188:191], v[48:51]
	v_mfma_f32_16x16x32_bf16 v[36:39], v[172:175], v[196:199], v[36:39]
	v_mfma_f32_16x16x32_bf16 v[32:35], v[180:183], v[196:199], v[32:35]
	v_mfma_f32_16x16x32_bf16 v[20:23], v[172:175], v[204:207], v[20:23]
	v_mfma_f32_16x16x32_bf16 v[16:19], v[180:183], v[204:207], v[16:19]
	v_mfma_f32_16x16x32_bf16 v[4:7], v[172:175], v[212:215], v[4:7]
	v_mfma_f32_16x16x32_bf16 v[0:3], v[180:183], v[212:215], v[0:3]
	s_barrier
	s_setprio 0
	s_add_i32 s54, s54, 2
	s_add_u32 s24, s24, 0x100
	s_addc_u32 s25, s25, 0
	s_add_u32 s52, s52, 0x100
	s_addc_u32 s53, s53, 0
	s_cmp_gt_u32 s54, 13
	s_cbranch_scc0 .LBB0_1219
	s_and_b64 vcc, exec, s[12:13]
	s_cbranch_vccz .LBB0_1222
	s_barrier
